# code-placement check: same kernel without the 30 s_nop pads that 8-byte-align the MFMA segments
# speedup vs baseline: 1.0041x; 1.0041x over previous
.Lm4bp_31:
	s_waitcnt lgkmcnt(0)
	s_mov_b32 s100, 0
	s_barrier
	v_mfma_f32_16x16x32_bf16 v[60:63], v[128:131], v[162:165], 0
	v_mfma_f32_16x16x32_bf16 v[56:59], v[136:139], v[162:165], 0
	v_mfma_f32_16x16x32_bf16 v[48:51], v[128:131], v[170:173], 0
	v_mfma_f32_16x16x32_bf16 v[40:43], v[136:139], v[170:173], 0
	v_mfma_f32_16x16x32_bf16 v[32:35], v[128:131], v[178:181], 0
	v_mfma_f32_16x16x32_bf16 v[24:27], v[136:139], v[178:181], 0
	v_mfma_f32_16x16x32_bf16 v[16:19], v[128:131], v[194:197], 0
	v_mfma_f32_16x16x32_bf16 v[8:11], v[136:139], v[194:197], 0
	v_mfma_f32_16x16x32_bf16 v[60:63], v[132:135], v[166:169], v[60:63]
	v_mfma_f32_16x16x32_bf16 v[56:59], v[146:149], v[166:169], v[56:59]
	v_mfma_f32_16x16x32_bf16 v[48:51], v[132:135], v[174:177], v[48:51]
	v_mfma_f32_16x16x32_bf16 v[40:43], v[146:149], v[174:177], v[40:43]
	v_mfma_f32_16x16x32_bf16 v[32:35], v[132:135], v[182:185], v[32:35]
	v_mfma_f32_16x16x32_bf16 v[24:27], v[146:149], v[182:185], v[24:27]
	v_mfma_f32_16x16x32_bf16 v[16:19], v[132:135], v[210:213], v[16:19]
	v_mfma_f32_16x16x32_bf16 v[8:11], v[146:149], v[210:213], v[8:11]
	v_mfma_f32_16x16x32_bf16 v[52:55], v[214:217], v[162:165], 0
	v_mfma_f32_16x16x32_bf16 v[44:47], v[222:225], v[162:165], 0
	v_mfma_f32_16x16x32_bf16 v[36:39], v[214:217], v[170:173], 0
	v_mfma_f32_16x16x32_bf16 v[28:31], v[222:225], v[170:173], 0
	v_mfma_f32_16x16x32_bf16 v[20:23], v[214:217], v[178:181], 0
	v_mfma_f32_16x16x32_bf16 v[12:15], v[222:225], v[178:181], 0
	v_mfma_f32_16x16x32_bf16 v[4:7], v[214:217], v[194:197], 0
	v_mfma_f32_16x16x32_bf16 v[0:3], v[222:225], v[194:197], 0
	v_mfma_f32_16x16x32_bf16 v[52:55], v[218:221], v[166:169], v[52:55]
	v_mfma_f32_16x16x32_bf16 v[44:47], v[226:229], v[166:169], v[44:47]
	v_mfma_f32_16x16x32_bf16 v[36:39], v[218:221], v[174:177], v[36:39]
	v_mfma_f32_16x16x32_bf16 v[28:31], v[226:229], v[174:177], v[28:31]
	v_mfma_f32_16x16x32_bf16 v[20:23], v[218:221], v[182:185], v[20:23]
	v_mfma_f32_16x16x32_bf16 v[12:15], v[226:229], v[182:185], v[12:15]
	v_mfma_f32_16x16x32_bf16 v[4:7], v[218:221], v[210:213], v[4:7]
	v_mfma_f32_16x16x32_bf16 v[0:3], v[226:229], v[210:213], v[0:3]
	s_barrier
	s_add_i32 s6, 0, 0x18000
	v_add_u32_e32 v146, s6, v206
	ds_read_b128 v[128:131], v146
	ds_read_b128 v[132:135], v146 offset:1024
	ds_read_b128 v[136:139], v146 offset:2048
	ds_read_b128 v[146:149], v146 offset:3072
	s_add_u32 s50, s52, 0xb0000
	s_addc_u32 s51, s53, 0
	s_mov_b32 m0, s68
	v_lshl_add_u64 v[214:215], s[50:51], 0, v[154:155]
	ds_read_b128 v[162:165], v208 offset:32768
	ds_read_b128 v[166:169], v208 offset:33792
	ds_read_b128 v[170:173], v208 offset:34816
	ds_read_b128 v[174:177], v208 offset:35840
	ds_read_b128 v[178:181], v208 offset:36864
	ds_read_b128 v[182:185], v208 offset:37888
	ds_read_b128 v[194:197], v208 offset:38912
	ds_read_b128 v[210:213], v208 offset:39936
	global_load_lds_dwordx4 v[214:215], off
	v_lshl_add_u64 v[214:215], s[50:51], 0, v[152:153]
	s_mov_b32 m0, s69
	s_nop 0
	global_load_lds_dwordx4 v[214:215], off
	s_add_i32 s19, 0, 0x1c000
	v_add_u32_e32 v192, s19, v206
	ds_read_b128 v[214:217], v192
	ds_read_b128 v[218:221], v192 offset:1024
	ds_read_b128 v[222:225], v192 offset:2048
	ds_read_b128 v[226:229], v192 offset:3072
	s_waitcnt vmcnt(8)
	s_waitcnt lgkmcnt(0)
	s_barrier
	v_mfma_f32_16x16x32_bf16 v[124:127], v[128:131], v[162:165], v[124:127]
	v_mfma_f32_16x16x32_bf16 v[120:123], v[136:139], v[162:165], v[120:123]
	v_mfma_f32_16x16x32_bf16 v[108:111], v[128:131], v[170:173], v[108:111]
	v_mfma_f32_16x16x32_bf16 v[104:107], v[136:139], v[170:173], v[104:107]
	v_mfma_f32_16x16x32_bf16 v[96:99], v[128:131], v[178:181], v[96:99]
	v_mfma_f32_16x16x32_bf16 v[88:91], v[136:139], v[178:181], v[88:91]
	v_mfma_f32_16x16x32_bf16 v[84:87], v[128:131], v[194:197], v[84:87]
	v_mfma_f32_16x16x32_bf16 v[80:83], v[136:139], v[194:197], v[80:83]
	v_mfma_f32_16x16x32_bf16 v[124:127], v[132:135], v[166:169], v[124:127]
	v_mfma_f32_16x16x32_bf16 v[120:123], v[146:149], v[166:169], v[120:123]
	v_mfma_f32_16x16x32_bf16 v[108:111], v[132:135], v[174:177], v[108:111]
	v_mfma_f32_16x16x32_bf16 v[104:107], v[146:149], v[174:177], v[104:107]
	v_mfma_f32_16x16x32_bf16 v[96:99], v[132:135], v[182:185], v[96:99]
	v_mfma_f32_16x16x32_bf16 v[88:91], v[146:149], v[182:185], v[88:91]
	v_mfma_f32_16x16x32_bf16 v[84:87], v[132:135], v[210:213], v[84:87]
	v_mfma_f32_16x16x32_bf16 v[80:83], v[146:149], v[210:213], v[80:83]
	v_mfma_f32_16x16x32_bf16 v[116:119], v[214:217], v[162:165], v[116:119]
	v_mfma_f32_16x16x32_bf16 v[112:115], v[222:225], v[162:165], v[112:115]
	v_mfma_f32_16x16x32_bf16 v[100:103], v[214:217], v[170:173], v[100:103]
	v_mfma_f32_16x16x32_bf16 v[92:95], v[222:225], v[170:173], v[92:95]
	v_mfma_f32_16x16x32_bf16 v[76:79], v[214:217], v[178:181], v[76:79]
	v_mfma_f32_16x16x32_bf16 v[72:75], v[222:225], v[178:181], v[72:75]
	v_mfma_f32_16x16x32_bf16 v[68:71], v[214:217], v[194:197], v[68:71]
	v_mfma_f32_16x16x32_bf16 v[64:67], v[222:225], v[194:197], v[64:67]
	v_mfma_f32_16x16x32_bf16 v[116:119], v[218:221], v[166:169], v[116:119]
	v_mfma_f32_16x16x32_bf16 v[112:115], v[226:229], v[166:169], v[112:115]
	v_mfma_f32_16x16x32_bf16 v[100:103], v[218:221], v[174:177], v[100:103]
	v_mfma_f32_16x16x32_bf16 v[92:95], v[226:229], v[174:177], v[92:95]
	v_mfma_f32_16x16x32_bf16 v[76:79], v[218:221], v[182:185], v[76:79]
	v_mfma_f32_16x16x32_bf16 v[72:75], v[226:229], v[182:185], v[72:75]
	v_mfma_f32_16x16x32_bf16 v[68:71], v[218:221], v[210:213], v[68:71]
	v_mfma_f32_16x16x32_bf16 v[64:67], v[226:229], v[210:213], v[64:67]
	s_barrier
	s_add_i32 s6, s6, s57
	v_lshl_add_u64 v[230:231], v[230:231], 0, s[36:37]
	s_mov_b32 m0, s6
	s_nop 0
	global_load_lds_dwordx4 v[230:231], off
	v_lshl_add_u64 v[230:231], v[232:233], 0, s[36:37]
	s_add_i32 m0, s6, 0x2000
	s_nop 0
	global_load_lds_dwordx4 v[230:231], off
	s_mov_b32 m0, s70
	v_lshl_add_u64 v[230:231], v[234:235], 0, s[36:37]
	ds_read_b128 v[162:165], v208 offset:49152
	ds_read_b128 v[166:169], v208 offset:50176
	ds_read_b128 v[170:173], v208 offset:51200
	ds_read_b128 v[174:177], v208 offset:52224
	ds_read_b128 v[178:181], v208 offset:53248
	ds_read_b128 v[182:185], v208 offset:54272
	ds_read_b128 v[194:197], v208 offset:55296
	ds_read_b128 v[210:213], v208 offset:56320
	global_load_lds_dwordx4 v[230:231], off
	v_lshl_add_u64 v[230:231], v[236:237], 0, s[36:37]
	s_mov_b32 m0, s71
	s_nop 0
	global_load_lds_dwordx4 v[230:231], off
	s_add_u32 s48, s48, 0xb0080
	s_addc_u32 s49, s49, 0
	s_add_i32 s6, s19, s57
	v_lshl_add_u64 v[250:251], s[48:49], 0, v[140:141]
	s_mov_b32 m0, s6
	s_nop 0
	global_load_lds_dwordx4 v[250:251], off
	v_lshl_add_u64 v[250:251], s[48:49], 0, v[150:151]
	s_add_i32 m0, s6, 0x2000
	s_nop 0
	global_load_lds_dwordx4 v[250:251], off
	s_add_i32 s12, s12, 2
	s_add_u32 s10, s10, 0x100
	s_addc_u32 s11, s11, 0
	s_cmp_gt_u32 s12, 41
	s_mov_b64 s[50:51], s[46:47]
	s_waitcnt vmcnt(8)
	s_waitcnt lgkmcnt(0)
	s_barrier
	v_mfma_f32_16x16x32_bf16 v[60:63], v[128:131], v[162:165], v[60:63]
	v_mfma_f32_16x16x32_bf16 v[56:59], v[136:139], v[162:165], v[56:59]
	v_mfma_f32_16x16x32_bf16 v[48:51], v[128:131], v[170:173], v[48:51]
	v_mfma_f32_16x16x32_bf16 v[40:43], v[136:139], v[170:173], v[40:43]
	v_mfma_f32_16x16x32_bf16 v[32:35], v[128:131], v[178:181], v[32:35]
	v_mfma_f32_16x16x32_bf16 v[24:27], v[136:139], v[178:181], v[24:27]
	v_mfma_f32_16x16x32_bf16 v[16:19], v[128:131], v[194:197], v[16:19]
	v_mfma_f32_16x16x32_bf16 v[8:11], v[136:139], v[194:197], v[8:11]
	v_mfma_f32_16x16x32_bf16 v[60:63], v[132:135], v[166:169], v[60:63]
	v_mfma_f32_16x16x32_bf16 v[56:59], v[146:149], v[166:169], v[56:59]
	v_mfma_f32_16x16x32_bf16 v[48:51], v[132:135], v[174:177], v[48:51]
	v_mfma_f32_16x16x32_bf16 v[40:43], v[146:149], v[174:177], v[40:43]
	v_mfma_f32_16x16x32_bf16 v[32:35], v[132:135], v[182:185], v[32:35]
	v_mfma_f32_16x16x32_bf16 v[24:27], v[146:149], v[182:185], v[24:27]
	v_mfma_f32_16x16x32_bf16 v[16:19], v[132:135], v[210:213], v[16:19]
	v_mfma_f32_16x16x32_bf16 v[8:11], v[146:149], v[210:213], v[8:11]
	v_mfma_f32_16x16x32_bf16 v[52:55], v[214:217], v[162:165], v[52:55]
	v_mfma_f32_16x16x32_bf16 v[44:47], v[222:225], v[162:165], v[44:47]
	v_mfma_f32_16x16x32_bf16 v[36:39], v[214:217], v[170:173], v[36:39]
	v_mfma_f32_16x16x32_bf16 v[28:31], v[222:225], v[170:173], v[28:31]
	v_mfma_f32_16x16x32_bf16 v[20:23], v[214:217], v[178:181], v[20:23]
	v_mfma_f32_16x16x32_bf16 v[12:15], v[222:225], v[178:181], v[12:15]
	v_mfma_f32_16x16x32_bf16 v[4:7], v[214:217], v[194:197], v[4:7]
	v_mfma_f32_16x16x32_bf16 v[0:3], v[222:225], v[194:197], v[0:3]
	v_mfma_f32_16x16x32_bf16 v[52:55], v[218:221], v[166:169], v[52:55]
	v_mfma_f32_16x16x32_bf16 v[44:47], v[226:229], v[166:169], v[44:47]
	v_mfma_f32_16x16x32_bf16 v[36:39], v[218:221], v[174:177], v[36:39]
	v_mfma_f32_16x16x32_bf16 v[28:31], v[226:229], v[174:177], v[28:31]
	v_mfma_f32_16x16x32_bf16 v[20:23], v[218:221], v[182:185], v[20:23]
	v_mfma_f32_16x16x32_bf16 v[12:15], v[226:229], v[182:185], v[12:15]
	v_mfma_f32_16x16x32_bf16 v[4:7], v[218:221], v[210:213], v[4:7]
	v_mfma_f32_16x16x32_bf16 v[0:3], v[226:229], v[210:213], v[0:3]
	s_barrier
.LBB0_31:
	s_add_u32 s46, s50, 0x100
	s_addc_u32 s47, s51, 0
	s_add_i32 s6, 0, 0x10000
	v_add_u32_e32 v146, s6, v206
	ds_read_b128 v[128:131], v146
	ds_read_b128 v[132:135], v146 offset:1024
	ds_read_b128 v[136:139], v146 offset:2048
	ds_read_b128 v[146:149], v146 offset:3072
	s_cmp_eq_u32 s12, 40
	s_cselect_b32 s53, s31, s47
	s_cselect_b32 s52, s30, s46
	s_cselect_b32 s49, s35, s11
	s_cselect_b32 s48, s34, s10
	v_lshl_add_u64 v[214:215], s[50:51], 0, v[158:159]
	s_add_i32 m0, s58, 0xc000
	ds_read_b128 v[162:165], v208
	ds_read_b128 v[166:169], v208 offset:1024
	ds_read_b128 v[170:173], v208 offset:2048
	ds_read_b128 v[174:177], v208 offset:3072
	ds_read_b128 v[178:181], v208 offset:4096
	ds_read_b128 v[182:185], v208 offset:5120
	ds_read_b128 v[194:197], v208 offset:6144
	ds_read_b128 v[210:213], v208 offset:7168
	global_load_lds_dwordx4 v[214:215], off
	v_lshl_add_u64 v[214:215], s[50:51], 0, v[160:161]
	s_add_i32 m0, s58, 0xe000
	s_nop 0
	global_load_lds_dwordx4 v[214:215], off
	s_add_i32 s19, 0, 0x14000
	v_add_u32_e32 v192, s19, v206
	ds_read_b128 v[214:217], v192
	ds_read_b128 v[218:221], v192 offset:1024
	ds_read_b128 v[222:225], v192 offset:2048
	ds_read_b128 v[226:229], v192 offset:3072
	s_waitcnt vmcnt(8)
	s_waitcnt lgkmcnt(0)
	s_barrier
	v_mfma_f32_16x16x32_bf16 v[124:127], v[128:131], v[162:165], v[124:127]
	v_mfma_f32_16x16x32_bf16 v[120:123], v[136:139], v[162:165], v[120:123]
	v_mfma_f32_16x16x32_bf16 v[108:111], v[128:131], v[170:173], v[108:111]
	v_mfma_f32_16x16x32_bf16 v[104:107], v[136:139], v[170:173], v[104:107]
	v_mfma_f32_16x16x32_bf16 v[96:99], v[128:131], v[178:181], v[96:99]
	v_mfma_f32_16x16x32_bf16 v[88:91], v[136:139], v[178:181], v[88:91]
	v_mfma_f32_16x16x32_bf16 v[84:87], v[128:131], v[194:197], v[84:87]
	v_mfma_f32_16x16x32_bf16 v[80:83], v[136:139], v[194:197], v[80:83]
	v_mfma_f32_16x16x32_bf16 v[124:127], v[132:135], v[166:169], v[124:127]
	v_mfma_f32_16x16x32_bf16 v[120:123], v[146:149], v[166:169], v[120:123]
	v_mfma_f32_16x16x32_bf16 v[108:111], v[132:135], v[174:177], v[108:111]
	v_mfma_f32_16x16x32_bf16 v[104:107], v[146:149], v[174:177], v[104:107]
	v_mfma_f32_16x16x32_bf16 v[96:99], v[132:135], v[182:185], v[96:99]
	v_mfma_f32_16x16x32_bf16 v[88:91], v[146:149], v[182:185], v[88:91]
	v_mfma_f32_16x16x32_bf16 v[84:87], v[132:135], v[210:213], v[84:87]
	v_mfma_f32_16x16x32_bf16 v[80:83], v[146:149], v[210:213], v[80:83]
	v_mfma_f32_16x16x32_bf16 v[116:119], v[214:217], v[162:165], v[116:119]
	v_mfma_f32_16x16x32_bf16 v[112:115], v[222:225], v[162:165], v[112:115]
	v_mfma_f32_16x16x32_bf16 v[100:103], v[214:217], v[170:173], v[100:103]
	v_mfma_f32_16x16x32_bf16 v[92:95], v[222:225], v[170:173], v[92:95]
	v_mfma_f32_16x16x32_bf16 v[76:79], v[214:217], v[178:181], v[76:79]
	v_mfma_f32_16x16x32_bf16 v[72:75], v[222:225], v[178:181], v[72:75]
	v_mfma_f32_16x16x32_bf16 v[68:71], v[214:217], v[194:197], v[68:71]
	v_mfma_f32_16x16x32_bf16 v[64:67], v[222:225], v[194:197], v[64:67]
	v_mfma_f32_16x16x32_bf16 v[116:119], v[218:221], v[166:169], v[116:119]
	v_mfma_f32_16x16x32_bf16 v[112:115], v[226:229], v[166:169], v[112:115]
	v_mfma_f32_16x16x32_bf16 v[100:103], v[218:221], v[174:177], v[100:103]
	v_mfma_f32_16x16x32_bf16 v[92:95], v[226:229], v[174:177], v[92:95]
	v_mfma_f32_16x16x32_bf16 v[76:79], v[218:221], v[182:185], v[76:79]
	v_mfma_f32_16x16x32_bf16 v[72:75], v[226:229], v[182:185], v[72:75]
	v_mfma_f32_16x16x32_bf16 v[68:71], v[218:221], v[210:213], v[68:71]
	v_mfma_f32_16x16x32_bf16 v[64:67], v[226:229], v[210:213], v[64:67]
	s_barrier
	s_add_i32 s6, s6, s57
	v_lshl_add_u64 v[230:231], s[48:49], 0, v[140:141]
	s_mov_b32 m0, s6
	s_nop 0
	global_load_lds_dwordx4 v[230:231], off
	v_lshl_add_u64 v[232:233], s[48:49], 0, v[150:151]
	s_add_i32 m0, s6, 0x2000
	s_nop 0
	global_load_lds_dwordx4 v[232:233], off
	s_mov_b32 m0, s58
	v_lshl_add_u64 v[234:235], s[52:53], 0, v[154:155]
	ds_read_b128 v[162:165], v208 offset:16384
	ds_read_b128 v[166:169], v208 offset:17408
	ds_read_b128 v[170:173], v208 offset:18432
	ds_read_b128 v[174:177], v208 offset:19456
	ds_read_b128 v[178:181], v208 offset:20480
	ds_read_b128 v[182:185], v208 offset:21504
	ds_read_b128 v[194:197], v208 offset:22528
	ds_read_b128 v[210:213], v208 offset:23552
	global_load_lds_dwordx4 v[234:235], off
	v_lshl_add_u64 v[236:237], s[52:53], 0, v[152:153]
	s_mov_b32 m0, s59
	s_nop 0
	global_load_lds_dwordx4 v[236:237], off
	s_add_u32 s50, s48, 0xb0000
	s_addc_u32 s51, s49, 0
	s_add_i32 s6, s19, s57
	v_lshl_add_u64 v[250:251], s[50:51], 0, v[140:141]
	s_mov_b32 m0, s6
	s_nop 0
	global_load_lds_dwordx4 v[250:251], off
	v_lshl_add_u64 v[250:251], s[50:51], 0, v[150:151]
	s_add_i32 m0, s6, 0x2000
	s_nop 0
	global_load_lds_dwordx4 v[250:251], off
	s_waitcnt vmcnt(8)
	s_waitcnt lgkmcnt(0)
	s_barrier
	v_mfma_f32_16x16x32_bf16 v[60:63], v[128:131], v[162:165], v[60:63]
	v_mfma_f32_16x16x32_bf16 v[56:59], v[136:139], v[162:165], v[56:59]
	v_mfma_f32_16x16x32_bf16 v[48:51], v[128:131], v[170:173], v[48:51]
	v_mfma_f32_16x16x32_bf16 v[40:43], v[136:139], v[170:173], v[40:43]
	v_mfma_f32_16x16x32_bf16 v[32:35], v[128:131], v[178:181], v[32:35]
	v_mfma_f32_16x16x32_bf16 v[24:27], v[136:139], v[178:181], v[24:27]
	v_mfma_f32_16x16x32_bf16 v[16:19], v[128:131], v[194:197], v[16:19]
	v_mfma_f32_16x16x32_bf16 v[8:11], v[136:139], v[194:197], v[8:11]
	v_mfma_f32_16x16x32_bf16 v[60:63], v[132:135], v[166:169], v[60:63]
	v_mfma_f32_16x16x32_bf16 v[56:59], v[146:149], v[166:169], v[56:59]
	v_mfma_f32_16x16x32_bf16 v[48:51], v[132:135], v[174:177], v[48:51]
	v_mfma_f32_16x16x32_bf16 v[40:43], v[146:149], v[174:177], v[40:43]
	v_mfma_f32_16x16x32_bf16 v[32:35], v[132:135], v[182:185], v[32:35]
	v_mfma_f32_16x16x32_bf16 v[24:27], v[146:149], v[182:185], v[24:27]
	v_mfma_f32_16x16x32_bf16 v[16:19], v[132:135], v[210:213], v[16:19]
	v_mfma_f32_16x16x32_bf16 v[8:11], v[146:149], v[210:213], v[8:11]
	v_mfma_f32_16x16x32_bf16 v[52:55], v[214:217], v[162:165], v[52:55]
	v_mfma_f32_16x16x32_bf16 v[44:47], v[222:225], v[162:165], v[44:47]
	v_mfma_f32_16x16x32_bf16 v[36:39], v[214:217], v[170:173], v[36:39]
	v_mfma_f32_16x16x32_bf16 v[28:31], v[222:225], v[170:173], v[28:31]
	v_mfma_f32_16x16x32_bf16 v[20:23], v[214:217], v[178:181], v[20:23]
	v_mfma_f32_16x16x32_bf16 v[12:15], v[222:225], v[178:181], v[12:15]
	v_mfma_f32_16x16x32_bf16 v[4:7], v[214:217], v[194:197], v[4:7]
	v_mfma_f32_16x16x32_bf16 v[0:3], v[222:225], v[194:197], v[0:3]
	v_mfma_f32_16x16x32_bf16 v[52:55], v[218:221], v[166:169], v[52:55]
	v_mfma_f32_16x16x32_bf16 v[44:47], v[226:229], v[166:169], v[44:47]
	v_mfma_f32_16x16x32_bf16 v[36:39], v[218:221], v[174:177], v[36:39]
	v_mfma_f32_16x16x32_bf16 v[28:31], v[226:229], v[174:177], v[28:31]
	v_mfma_f32_16x16x32_bf16 v[20:23], v[218:221], v[182:185], v[20:23]
	v_mfma_f32_16x16x32_bf16 v[12:15], v[226:229], v[182:185], v[12:15]
	v_mfma_f32_16x16x32_bf16 v[4:7], v[218:221], v[210:213], v[4:7]
	v_mfma_f32_16x16x32_bf16 v[0:3], v[226:229], v[210:213], v[0:3]
	s_barrier
	s_add_i32 s6, 0, 0x18000
	v_add_u32_e32 v146, s6, v206
	ds_read_b128 v[128:131], v146
	ds_read_b128 v[132:135], v146 offset:1024
	ds_read_b128 v[136:139], v146 offset:2048
	ds_read_b128 v[146:149], v146 offset:3072
	s_add_u32 s50, s52, 0xb0000
	s_addc_u32 s51, s53, 0
	s_mov_b32 m0, s68
	v_lshl_add_u64 v[214:215], s[50:51], 0, v[154:155]
	ds_read_b128 v[162:165], v208 offset:32768
	ds_read_b128 v[166:169], v208 offset:33792
	ds_read_b128 v[170:173], v208 offset:34816
	ds_read_b128 v[174:177], v208 offset:35840
	ds_read_b128 v[178:181], v208 offset:36864
	ds_read_b128 v[182:185], v208 offset:37888
	ds_read_b128 v[194:197], v208 offset:38912
	ds_read_b128 v[210:213], v208 offset:39936
	global_load_lds_dwordx4 v[214:215], off
	v_lshl_add_u64 v[214:215], s[50:51], 0, v[152:153]
	s_mov_b32 m0, s69
	s_nop 0
	global_load_lds_dwordx4 v[214:215], off
	s_add_i32 s19, 0, 0x1c000
	v_add_u32_e32 v192, s19, v206
	ds_read_b128 v[214:217], v192
	ds_read_b128 v[218:221], v192 offset:1024
	ds_read_b128 v[222:225], v192 offset:2048
	ds_read_b128 v[226:229], v192 offset:3072
	s_waitcnt vmcnt(8)
	s_waitcnt lgkmcnt(0)
	s_barrier
	v_mfma_f32_16x16x32_bf16 v[124:127], v[128:131], v[162:165], v[124:127]
	v_mfma_f32_16x16x32_bf16 v[120:123], v[136:139], v[162:165], v[120:123]
	v_mfma_f32_16x16x32_bf16 v[108:111], v[128:131], v[170:173], v[108:111]
	v_mfma_f32_16x16x32_bf16 v[104:107], v[136:139], v[170:173], v[104:107]
	v_mfma_f32_16x16x32_bf16 v[96:99], v[128:131], v[178:181], v[96:99]
	v_mfma_f32_16x16x32_bf16 v[88:91], v[136:139], v[178:181], v[88:91]
	v_mfma_f32_16x16x32_bf16 v[84:87], v[128:131], v[194:197], v[84:87]
	v_mfma_f32_16x16x32_bf16 v[80:83], v[136:139], v[194:197], v[80:83]
	v_mfma_f32_16x16x32_bf16 v[124:127], v[132:135], v[166:169], v[124:127]
	v_mfma_f32_16x16x32_bf16 v[120:123], v[146:149], v[166:169], v[120:123]
	v_mfma_f32_16x16x32_bf16 v[108:111], v[132:135], v[174:177], v[108:111]
	v_mfma_f32_16x16x32_bf16 v[104:107], v[146:149], v[174:177], v[104:107]
	v_mfma_f32_16x16x32_bf16 v[96:99], v[132:135], v[182:185], v[96:99]
	v_mfma_f32_16x16x32_bf16 v[88:91], v[146:149], v[182:185], v[88:91]
	v_mfma_f32_16x16x32_bf16 v[84:87], v[132:135], v[210:213], v[84:87]
	v_mfma_f32_16x16x32_bf16 v[80:83], v[146:149], v[210:213], v[80:83]
	v_mfma_f32_16x16x32_bf16 v[116:119], v[214:217], v[162:165], v[116:119]
	v_mfma_f32_16x16x32_bf16 v[112:115], v[222:225], v[162:165], v[112:115]
	v_mfma_f32_16x16x32_bf16 v[100:103], v[214:217], v[170:173], v[100:103]
	v_mfma_f32_16x16x32_bf16 v[92:95], v[222:225], v[170:173], v[92:95]
	v_mfma_f32_16x16x32_bf16 v[76:79], v[214:217], v[178:181], v[76:79]
	v_mfma_f32_16x16x32_bf16 v[72:75], v[222:225], v[178:181], v[72:75]
	v_mfma_f32_16x16x32_bf16 v[68:71], v[214:217], v[194:197], v[68:71]
	v_mfma_f32_16x16x32_bf16 v[64:67], v[222:225], v[194:197], v[64:67]
	v_mfma_f32_16x16x32_bf16 v[116:119], v[218:221], v[166:169], v[116:119]
	v_mfma_f32_16x16x32_bf16 v[112:115], v[226:229], v[166:169], v[112:115]
	v_mfma_f32_16x16x32_bf16 v[100:103], v[218:221], v[174:177], v[100:103]
	v_mfma_f32_16x16x32_bf16 v[92:95], v[226:229], v[174:177], v[92:95]
	v_mfma_f32_16x16x32_bf16 v[76:79], v[218:221], v[182:185], v[76:79]
	v_mfma_f32_16x16x32_bf16 v[72:75], v[226:229], v[182:185], v[72:75]
	v_mfma_f32_16x16x32_bf16 v[68:71], v[218:221], v[210:213], v[68:71]
	v_mfma_f32_16x16x32_bf16 v[64:67], v[226:229], v[210:213], v[64:67]
	s_barrier
	s_add_i32 s6, s6, s57
	v_lshl_add_u64 v[230:231], v[230:231], 0, s[36:37]
	s_mov_b32 m0, s6
	s_nop 0
	global_load_lds_dwordx4 v[230:231], off
	v_lshl_add_u64 v[230:231], v[232:233], 0, s[36:37]
	s_add_i32 m0, s6, 0x2000
	s_nop 0
	global_load_lds_dwordx4 v[230:231], off
	s_mov_b32 m0, s70
	v_lshl_add_u64 v[230:231], v[234:235], 0, s[36:37]
	ds_read_b128 v[162:165], v208 offset:49152
	ds_read_b128 v[166:169], v208 offset:50176
	ds_read_b128 v[170:173], v208 offset:51200
	ds_read_b128 v[174:177], v208 offset:52224
	ds_read_b128 v[178:181], v208 offset:53248
	ds_read_b128 v[182:185], v208 offset:54272
	ds_read_b128 v[194:197], v208 offset:55296
	ds_read_b128 v[210:213], v208 offset:56320
	global_load_lds_dwordx4 v[230:231], off
	v_lshl_add_u64 v[230:231], v[236:237], 0, s[36:37]
	s_mov_b32 m0, s71
	s_nop 0
	global_load_lds_dwordx4 v[230:231], off
	s_add_u32 s48, s48, 0xb0080
	s_addc_u32 s49, s49, 0
	s_add_i32 s6, s19, s57
	v_lshl_add_u64 v[250:251], s[48:49], 0, v[140:141]
	s_mov_b32 m0, s6
	s_nop 0
	global_load_lds_dwordx4 v[250:251], off
	v_lshl_add_u64 v[250:251], s[48:49], 0, v[150:151]
	s_add_i32 m0, s6, 0x2000
	s_nop 0
	global_load_lds_dwordx4 v[250:251], off
	s_add_i32 s12, s12, 2
	s_add_u32 s10, s10, 0x100
	s_addc_u32 s11, s11, 0
	s_cmp_gt_u32 s12, 41
	s_mov_b64 s[50:51], s[46:47]
	s_waitcnt vmcnt(8)
	s_waitcnt lgkmcnt(0)
	s_barrier
	v_mfma_f32_16x16x32_bf16 v[60:63], v[128:131], v[162:165], v[60:63]
	v_mfma_f32_16x16x32_bf16 v[56:59], v[136:139], v[162:165], v[56:59]
	v_mfma_f32_16x16x32_bf16 v[48:51], v[128:131], v[170:173], v[48:51]
	v_mfma_f32_16x16x32_bf16 v[40:43], v[136:139], v[170:173], v[40:43]
	v_mfma_f32_16x16x32_bf16 v[32:35], v[128:131], v[178:181], v[32:35]
	v_mfma_f32_16x16x32_bf16 v[24:27], v[136:139], v[178:181], v[24:27]
	v_mfma_f32_16x16x32_bf16 v[16:19], v[128:131], v[194:197], v[16:19]
	v_mfma_f32_16x16x32_bf16 v[8:11], v[136:139], v[194:197], v[8:11]
	v_mfma_f32_16x16x32_bf16 v[60:63], v[132:135], v[166:169], v[60:63]
	v_mfma_f32_16x16x32_bf16 v[56:59], v[146:149], v[166:169], v[56:59]
	v_mfma_f32_16x16x32_bf16 v[48:51], v[132:135], v[174:177], v[48:51]
	v_mfma_f32_16x16x32_bf16 v[40:43], v[146:149], v[174:177], v[40:43]
	v_mfma_f32_16x16x32_bf16 v[32:35], v[132:135], v[182:185], v[32:35]
	v_mfma_f32_16x16x32_bf16 v[24:27], v[146:149], v[182:185], v[24:27]
	v_mfma_f32_16x16x32_bf16 v[16:19], v[132:135], v[210:213], v[16:19]
	v_mfma_f32_16x16x32_bf16 v[8:11], v[146:149], v[210:213], v[8:11]
	v_mfma_f32_16x16x32_bf16 v[52:55], v[214:217], v[162:165], v[52:55]
	v_mfma_f32_16x16x32_bf16 v[44:47], v[222:225], v[162:165], v[44:47]
	v_mfma_f32_16x16x32_bf16 v[36:39], v[214:217], v[170:173], v[36:39]
	v_mfma_f32_16x16x32_bf16 v[28:31], v[222:225], v[170:173], v[28:31]
	v_mfma_f32_16x16x32_bf16 v[20:23], v[214:217], v[178:181], v[20:23]
	v_mfma_f32_16x16x32_bf16 v[12:15], v[222:225], v[178:181], v[12:15]
	v_mfma_f32_16x16x32_bf16 v[4:7], v[214:217], v[194:197], v[4:7]
	v_mfma_f32_16x16x32_bf16 v[0:3], v[222:225], v[194:197], v[0:3]
	v_mfma_f32_16x16x32_bf16 v[52:55], v[218:221], v[166:169], v[52:55]
	v_mfma_f32_16x16x32_bf16 v[44:47], v[226:229], v[166:169], v[44:47]
	v_mfma_f32_16x16x32_bf16 v[36:39], v[218:221], v[174:177], v[36:39]
	v_mfma_f32_16x16x32_bf16 v[28:31], v[226:229], v[174:177], v[28:31]
	v_mfma_f32_16x16x32_bf16 v[20:23], v[218:221], v[182:185], v[20:23]
	v_mfma_f32_16x16x32_bf16 v[12:15], v[226:229], v[182:185], v[12:15]
	v_mfma_f32_16x16x32_bf16 v[4:7], v[218:221], v[210:213], v[4:7]
	v_mfma_f32_16x16x32_bf16 v[0:3], v[226:229], v[210:213], v[0:3]
	s_barrier
	s_cbranch_scc0 .LBB0_31
	s_mov_b32 s100, 1
	s_ashr_i32 s39, s38, 31
	v_lshl_or_b32 v128, s81, 8, v207
	s_lshl_b64 s[10:11], s[38:39], 8
	v_ashrrev_i32_e32 v129, 31, v128
	v_lshl_add_u64 v[168:169], s[10:11], 0, v[156:157]
	v_lshlrev_b64 v[170:171], 1, v[128:129]
	v_lshl_add_u64 v[174:175], s[4:5], 0, v[170:171]
	v_lshlrev_b64 v[172:173], 11, v[168:169]
	v_lshl_add_u64 v[128:129], v[174:175], 0, v[172:173]
	global_load_dwordx4 v[146:149], v[128:129], off
	global_load_dwordx4 v[182:185], v[128:129], off offset:256
	v_or_b32_e32 v166, 16, v168
	v_mov_b32_e32 v167, v169
	v_lshlrev_b64 v[176:177], 11, v[166:167]
	v_lshl_add_u64 v[128:129], v[174:175], 0, v[176:177]
	global_load_dwordx4 v[194:197], v[128:129], off
	global_load_dwordx4 v[210:213], v[128:129], off offset:256
	v_or_b32_e32 v164, 32, v168
	v_mov_b32_e32 v165, v169
	v_or_b32_e32 v162, 48, v168
	v_mov_b32_e32 v163, v169
	v_lshlrev_b64 v[180:181], 11, v[164:165]
	v_lshlrev_b64 v[178:179], 11, v[162:163]
	v_lshl_add_u64 v[128:129], v[174:175], 0, v[180:181]
	v_lshl_add_u64 v[130:131], v[174:175], 0, v[178:179]
	global_load_dwordx4 v[214:217], v[128:129], off
	global_load_dwordx4 v[136:139], v[128:129], off offset:256
	global_load_dwordx4 v[132:135], v[130:131], off
	s_nop 0
	global_load_dwordx4 v[128:131], v[130:131], off offset:256
	s_mov_b64 s[10:11], 0x90
	v_lshl_add_u64 v[172:173], s[28:29], 0, v[172:173]
	v_lshl_add_u64 v[172:173], v[172:173], 0, v[170:171]
	s_waitcnt vmcnt(0)
	v_lshlrev_b32_e32 v218, 16, v146
	v_and_b32_e32 v219, 0xffff0000, v146
	v_lshlrev_b32_e32 v220, 16, v148
	v_and_b32_e32 v221, 0xffff0000, v148
	v_lshlrev_b32_e32 v146, 16, v147
	v_and_b32_e32 v147, 0xffff0000, v147
	v_lshlrev_b32_e32 v222, 16, v182
	v_and_b32_e32 v223, 0xffff0000, v182
	v_lshlrev_b32_e32 v224, 16, v184
	v_and_b32_e32 v225, 0xffff0000, v184
	v_lshlrev_b32_e32 v182, 16, v183
	v_and_b32_e32 v183, 0xffff0000, v183
	v_pk_fma_f32 v[124:125], v[124:125], 0.5, v[218:219] op_sel_hi:[1,0,1]
	v_pk_fma_f32 v[120:121], v[120:121], 0.5, v[220:221] op_sel_hi:[1,0,1]
	v_pk_fma_f32 v[126:127], v[126:127], 0.5, v[146:147] op_sel_hi:[1,0,1]
	v_pk_fma_f32 v[116:117], v[116:117], 0.5, v[222:223] op_sel_hi:[1,0,1]
	v_pk_fma_f32 v[146:147], v[112:113], 0.5, v[224:225] op_sel_hi:[1,0,1]
	v_pk_fma_f32 v[118:119], v[118:119], 0.5, v[182:183] op_sel_hi:[1,0,1]
	v_pk_mul_f32 v[220:221], v[124:125], v[124:125]
	v_pk_mul_f32 v[222:223], v[126:127], v[126:127]
	v_cvt_pk_bf16_f32 v112, v124, v125
	v_cvt_pk_bf16_f32 v113, v126, v127
	v_pk_mul_f32 v[124:125], v[116:117], v[116:117]
	v_pk_mul_f32 v[126:127], v[118:119], v[118:119]
	v_pk_mul_f32 v[228:229], v[146:147], v[146:147]
	v_cvt_pk_bf16_f32 v116, v116, v117
	v_cvt_pk_bf16_f32 v117, v118, v119
	v_cvt_pk_bf16_f32 v118, v146, v147
	v_add_f32_e32 v146, v220, v221
	v_add_f32_e32 v146, v222, v146
	v_lshlrev_b32_e32 v148, 16, v149
	v_and_b32_e32 v149, 0xffff0000, v149
	v_pk_mul_f32 v[224:225], v[120:121], v[120:121]
	v_add_f32_e32 v146, v223, v146
	v_pk_fma_f32 v[122:123], v[122:123], 0.5, v[148:149] op_sel_hi:[1,0,1]
	v_add_f32_e32 v146, v224, v146
	v_pk_mul_f32 v[226:227], v[122:123], v[122:123]
	v_add_f32_e32 v146, v225, v146
	v_add_f32_e32 v146, v226, v146
	v_add_f32_e32 v146, v227, v146
	v_add_f32_e32 v124, v124, v146
	v_add_f32_e32 v124, v125, v124
	v_add_f32_e32 v124, v126, v124
	v_lshlrev_b32_e32 v184, 16, v185
	v_and_b32_e32 v185, 0xffff0000, v185
	v_add_f32_e32 v124, v127, v124
	v_pk_fma_f32 v[148:149], v[114:115], 0.5, v[184:185] op_sel_hi:[1,0,1]
	v_add_f32_e32 v124, v228, v124
	v_pk_mul_f32 v[230:231], v[148:149], v[148:149]
	v_add_f32_e32 v124, v229, v124
	v_add_f32_e32 v124, v230, v124
	v_add_f32_e32 v209, v231, v124
	v_lshlrev_b32_e32 v124, 16, v212
	v_and_b32_e32 v125, 0xffff0000, v212
	v_pk_fma_f32 v[124:125], v[92:93], 0.5, v[124:125] op_sel_hi:[1,0,1]
	v_lshlrev_b32_e32 v92, 16, v211
	v_and_b32_e32 v93, 0xffff0000, v211
	v_pk_fma_f32 v[102:103], v[102:103], 0.5, v[92:93] op_sel_hi:[1,0,1]
	v_lshlrev_b32_e32 v92, 16, v213
	v_and_b32_e32 v93, 0xffff0000, v213
	v_pk_fma_f32 v[126:127], v[94:95], 0.5, v[92:93] op_sel_hi:[1,0,1]
	v_lshlrev_b32_e32 v92, 16, v214
	v_and_b32_e32 v93, 0xffff0000, v214
	v_pk_fma_f32 v[92:93], v[96:97], 0.5, v[92:93] op_sel_hi:[1,0,1]
	v_lshlrev_b32_e32 v96, 16, v217
	v_and_b32_e32 v97, 0xffff0000, v217
	v_lshlrev_b32_e32 v94, 16, v216
	v_and_b32_e32 v95, 0xffff0000, v216
	v_pk_fma_f32 v[90:91], v[90:91], 0.5, v[96:97] op_sel_hi:[1,0,1]
	v_lshlrev_b32_e32 v96, 16, v136
	v_and_b32_e32 v97, 0xffff0000, v136
	v_lshlrev_b32_e32 v182, 16, v194
	v_and_b32_e32 v183, 0xffff0000, v194
	v_pk_fma_f32 v[88:89], v[88:89], 0.5, v[94:95] op_sel_hi:[1,0,1]
	v_lshlrev_b32_e32 v94, 16, v215
	v_and_b32_e32 v95, 0xffff0000, v215
	v_pk_fma_f32 v[96:97], v[76:77], 0.5, v[96:97] op_sel_hi:[1,0,1]
	v_lshl_add_u64 v[76:77], v[168:169], 0, s[36:37]
	v_lshlrev_b32_e32 v184, 16, v196
	v_and_b32_e32 v185, 0xffff0000, v196
	v_cvt_pk_bf16_f32 v114, v120, v121
	v_pk_fma_f32 v[120:121], v[108:109], 0.5, v[182:183] op_sel_hi:[1,0,1]
	v_pk_fma_f32 v[94:95], v[98:99], 0.5, v[94:95] op_sel_hi:[1,0,1]
	v_lshlrev_b64 v[182:183], 11, v[76:77]
	v_lshlrev_b32_e32 v98, 16, v138
	v_and_b32_e32 v99, 0xffff0000, v138
	v_pk_fma_f32 v[108:109], v[104:105], 0.5, v[184:185] op_sel_hi:[1,0,1]
	v_lshl_add_u64 v[184:185], v[174:175], 0, v[182:183]
	v_pk_fma_f32 v[98:99], v[72:73], 0.5, v[98:99] op_sel_hi:[1,0,1]
	v_lshlrev_b32_e32 v72, 16, v137
	v_and_b32_e32 v73, 0xffff0000, v137
	v_lshlrev_b32_e32 v218, 16, v210
	v_and_b32_e32 v219, 0xffff0000, v210
	global_load_dwordx4 v[210:213], v[184:185], off
	v_pk_fma_f32 v[136:137], v[78:79], 0.5, v[72:73] op_sel_hi:[1,0,1]
	v_lshlrev_b32_e32 v72, 16, v139
	v_and_b32_e32 v73, 0xffff0000, v139
	v_pk_fma_f32 v[138:139], v[74:75], 0.5, v[72:73] op_sel_hi:[1,0,1]
	v_lshlrev_b32_e32 v72, 16, v132
	v_and_b32_e32 v73, 0xffff0000, v132
	v_pk_fma_f32 v[74:75], v[84:85], 0.5, v[72:73] op_sel_hi:[1,0,1]
	v_lshlrev_b32_e32 v72, 16, v134
	v_and_b32_e32 v73, 0xffff0000, v134
	v_pk_fma_f32 v[78:79], v[80:81], 0.5, v[72:73] op_sel_hi:[1,0,1]
	v_lshlrev_b32_e32 v72, 16, v133
	v_and_b32_e32 v73, 0xffff0000, v133
	v_pk_fma_f32 v[100:101], v[100:101], 0.5, v[218:219] op_sel_hi:[1,0,1]
	global_load_dwordx4 v[218:221], v[184:185], off offset:256
	v_pk_fma_f32 v[80:81], v[86:87], 0.5, v[72:73] op_sel_hi:[1,0,1]
	v_lshlrev_b32_e32 v72, 16, v135
	v_and_b32_e32 v73, 0xffff0000, v135
	v_pk_fma_f32 v[82:83], v[82:83], 0.5, v[72:73] op_sel_hi:[1,0,1]
	v_lshl_add_u64 v[72:73], v[168:169], 0, s[10:11]
	v_lshlrev_b64 v[132:133], 11, v[72:73]
	v_lshl_add_u64 v[134:135], v[174:175], 0, v[132:133]
	v_lshlrev_b32_e32 v84, 16, v128
	v_and_b32_e32 v85, 0xffff0000, v128
	global_load_dwordx4 v[226:229], v[134:135], off
	global_load_dwordx4 v[234:237], v[134:135], off offset:256
	v_pk_fma_f32 v[84:85], v[68:69], 0.5, v[84:85] op_sel_hi:[1,0,1]
	v_lshlrev_b32_e32 v68, 16, v130
	v_and_b32_e32 v69, 0xffff0000, v130
	v_pk_fma_f32 v[86:87], v[64:65], 0.5, v[68:69] op_sel_hi:[1,0,1]
	v_lshlrev_b32_e32 v64, 16, v129
	v_and_b32_e32 v65, 0xffff0000, v129
	s_mov_b64 s[10:11], 0xa0
	v_pk_fma_f32 v[128:129], v[70:71], 0.5, v[64:65] op_sel_hi:[1,0,1]
	v_lshl_add_u64 v[70:71], v[168:169], 0, s[10:11]
	s_mov_b64 s[10:11], 0xb0
	v_lshlrev_b32_e32 v64, 16, v131
	v_and_b32_e32 v65, 0xffff0000, v131
	v_lshlrev_b64 v[134:135], 11, v[70:71]
	v_lshl_add_u64 v[68:69], v[168:169], 0, s[10:11]
	v_pk_fma_f32 v[130:131], v[66:67], 0.5, v[64:65] op_sel_hi:[1,0,1]
	v_lshl_add_u64 v[64:65], v[174:175], 0, v[134:135]
	v_lshlrev_b64 v[184:185], 11, v[68:69]
	global_load_dwordx4 v[238:241], v[64:65], off
	global_load_dwordx4 v[242:245], v[64:65], off offset:256
	v_lshl_add_u64 v[64:65], v[174:175], 0, v[184:185]
	global_load_dwordx4 v[246:249], v[64:65], off
	s_nop 0
	global_load_dwordx4 v[64:67], v[64:65], off offset:256
	v_lshlrev_b32_e32 v194, 16, v195
	v_and_b32_e32 v195, 0xffff0000, v195
	v_lshlrev_b32_e32 v196, 16, v197
	v_and_b32_e32 v197, 0xffff0000, v197
	v_cvt_pk_bf16_f32 v115, v122, v123
	v_cvt_pk_bf16_f32 v119, v148, v149
	v_pk_fma_f32 v[122:123], v[110:111], 0.5, v[194:195] op_sel_hi:[1,0,1]
	v_pk_fma_f32 v[110:111], v[106:107], 0.5, v[196:197] op_sel_hi:[1,0,1]
	global_store_dwordx4 v[172:173], v[112:115], off
	global_store_dwordx4 v[172:173], v[116:119], off offset:256
	v_cvt_pk_bf16_f32 v104, v120, v121
	v_lshl_add_u64 v[112:113], s[28:29], 0, v[176:177]
	v_cvt_pk_bf16_f32 v105, v122, v123
	v_cvt_pk_bf16_f32 v106, v108, v109
	v_cvt_pk_bf16_f32 v107, v110, v111
	v_lshl_add_u64 v[112:113], v[112:113], 0, v[170:171]
	v_cvt_pk_bf16_f32 v146, v100, v101
	v_cvt_pk_bf16_f32 v147, v102, v103
	v_cvt_pk_bf16_f32 v148, v124, v125
	v_cvt_pk_bf16_f32 v149, v126, v127
	global_store_dwordx4 v[112:113], v[104:107], off
	global_store_dwordx4 v[112:113], v[146:149], off offset:256
	v_cvt_pk_bf16_f32 v194, v92, v93
	v_lshl_add_u64 v[104:105], s[28:29], 0, v[180:181]
	v_cvt_pk_bf16_f32 v195, v94, v95
	v_cvt_pk_bf16_f32 v196, v88, v89
	v_cvt_pk_bf16_f32 v197, v90, v91
	v_lshl_add_u64 v[104:105], v[104:105], 0, v[170:171]
	v_cvt_pk_bf16_f32 v214, v96, v97
	v_cvt_pk_bf16_f32 v215, v136, v137
	v_cvt_pk_bf16_f32 v216, v98, v99
	v_cvt_pk_bf16_f32 v217, v138, v139
	global_store_dwordx4 v[104:105], v[194:197], off
	global_store_dwordx4 v[104:105], v[214:217], off offset:256
	v_lshl_add_u64 v[104:105], s[28:29], 0, v[178:179]
	v_cvt_pk_bf16_f32 v222, v74, v75
	v_cvt_pk_bf16_f32 v223, v80, v81
	v_cvt_pk_bf16_f32 v224, v78, v79
	v_cvt_pk_bf16_f32 v225, v82, v83
	v_lshl_add_u64 v[104:105], v[104:105], 0, v[170:171]
	v_cvt_pk_bf16_f32 v230, v84, v85
	v_cvt_pk_bf16_f32 v231, v128, v129
	v_cvt_pk_bf16_f32 v232, v86, v87
	v_cvt_pk_bf16_f32 v233, v130, v131
	global_store_dwordx4 v[104:105], v[222:225], off
	global_store_dwordx4 v[104:105], v[230:233], off offset:256
	s_waitcnt vmcnt(8)
	v_lshlrev_b32_e32 v104, 16, v210
	v_and_b32_e32 v105, 0xffff0000, v210
	v_pk_fma_f32 v[60:61], v[60:61], 0.5, v[104:105] op_sel_hi:[1,0,1]
	v_lshlrev_b32_e32 v104, 16, v212
	v_and_b32_e32 v105, 0xffff0000, v212
	v_pk_fma_f32 v[56:57], v[56:57], 0.5, v[104:105] op_sel_hi:[1,0,1]
	v_lshlrev_b32_e32 v104, 16, v211
	v_and_b32_e32 v105, 0xffff0000, v211
	v_pk_fma_f32 v[62:63], v[62:63], 0.5, v[104:105] op_sel_hi:[1,0,1]
	v_lshlrev_b32_e32 v104, 16, v213
	v_and_b32_e32 v105, 0xffff0000, v213
	v_pk_fma_f32 v[58:59], v[58:59], 0.5, v[104:105] op_sel_hi:[1,0,1]
	v_lshlrev_b32_e32 v104, 16, v218
	v_and_b32_e32 v105, 0xffff0000, v218
	v_pk_fma_f32 v[52:53], v[52:53], 0.5, v[104:105] op_sel_hi:[1,0,1]
	v_lshlrev_b32_e32 v104, 16, v220
	v_and_b32_e32 v105, 0xffff0000, v220
	v_pk_fma_f32 v[104:105], v[44:45], 0.5, v[104:105] op_sel_hi:[1,0,1]
	v_lshlrev_b32_e32 v44, 16, v219
	v_and_b32_e32 v45, 0xffff0000, v219
	v_pk_fma_f32 v[54:55], v[54:55], 0.5, v[44:45] op_sel_hi:[1,0,1]
	v_lshlrev_b32_e32 v44, 16, v221
	v_and_b32_e32 v45, 0xffff0000, v221
	v_pk_fma_f32 v[106:107], v[46:47], 0.5, v[44:45] op_sel_hi:[1,0,1]
	v_lshlrev_b32_e32 v44, 16, v226
	v_and_b32_e32 v45, 0xffff0000, v226
	v_pk_fma_f32 v[44:45], v[48:49], 0.5, v[44:45] op_sel_hi:[1,0,1]
	v_lshlrev_b32_e32 v48, 16, v229
	v_and_b32_e32 v49, 0xffff0000, v229
	v_pk_fma_f32 v[42:43], v[42:43], 0.5, v[48:49] op_sel_hi:[1,0,1]
	v_lshlrev_b32_e32 v48, 16, v234
	v_and_b32_e32 v49, 0xffff0000, v234
	v_pk_fma_f32 v[36:37], v[36:37], 0.5, v[48:49] op_sel_hi:[1,0,1]
	v_lshlrev_b32_e32 v48, 16, v236
	v_and_b32_e32 v49, 0xffff0000, v236
	v_lshlrev_b32_e32 v46, 16, v228
	v_and_b32_e32 v47, 0xffff0000, v228
	v_pk_fma_f32 v[48:49], v[28:29], 0.5, v[48:49] op_sel_hi:[1,0,1]
	v_lshlrev_b32_e32 v28, 16, v235
	v_and_b32_e32 v29, 0xffff0000, v235
	v_pk_fma_f32 v[40:41], v[40:41], 0.5, v[46:47] op_sel_hi:[1,0,1]
	v_lshlrev_b32_e32 v46, 16, v227
	v_and_b32_e32 v47, 0xffff0000, v227
	v_pk_fma_f32 v[38:39], v[38:39], 0.5, v[28:29] op_sel_hi:[1,0,1]
	v_lshlrev_b32_e32 v28, 16, v237
	v_and_b32_e32 v29, 0xffff0000, v237
	v_pk_fma_f32 v[46:47], v[50:51], 0.5, v[46:47] op_sel_hi:[1,0,1]
	v_pk_fma_f32 v[50:51], v[30:31], 0.5, v[28:29] op_sel_hi:[1,0,1]
	v_lshlrev_b32_e32 v28, 16, v238
	v_and_b32_e32 v29, 0xffff0000, v238
	v_lshlrev_b32_e32 v180, 16, v64
	v_and_b32_e32 v181, 0xffff0000, v64
	v_pk_fma_f32 v[28:29], v[32:33], 0.5, v[28:29] op_sel_hi:[1,0,1]
	v_lshlrev_b32_e32 v32, 16, v241
	v_and_b32_e32 v33, 0xffff0000, v241
	v_pk_fma_f32 v[4:5], v[4:5], 0.5, v[180:181] op_sel_hi:[1,0,1]
	v_lshlrev_b32_e32 v180, 16, v66
	v_and_b32_e32 v181, 0xffff0000, v66
	v_pk_fma_f32 v[26:27], v[26:27], 0.5, v[32:33] op_sel_hi:[1,0,1]
	v_lshlrev_b32_e32 v32, 16, v242
	v_and_b32_e32 v33, 0xffff0000, v242
	v_pk_fma_f32 v[0:1], v[0:1], 0.5, v[180:181] op_sel_hi:[1,0,1]
	v_lshl_add_u64 v[180:181], s[28:29], 0, v[182:183]
	v_cvt_pk_bf16_f32 v112, v60, v61
	v_cvt_pk_bf16_f32 v113, v62, v63
	v_cvt_pk_bf16_f32 v114, v56, v57
	v_cvt_pk_bf16_f32 v115, v58, v59
	v_pk_fma_f32 v[20:21], v[20:21], 0.5, v[32:33] op_sel_hi:[1,0,1]
	v_lshlrev_b32_e32 v32, 16, v244
	v_and_b32_e32 v33, 0xffff0000, v244
	v_lshl_add_u64 v[180:181], v[180:181], 0, v[170:171]
	v_cvt_pk_bf16_f32 v116, v52, v53
	v_cvt_pk_bf16_f32 v117, v54, v55
	v_cvt_pk_bf16_f32 v118, v104, v105
	v_cvt_pk_bf16_f32 v119, v106, v107
	v_lshlrev_b32_e32 v30, 16, v240
	v_and_b32_e32 v31, 0xffff0000, v240
	v_pk_fma_f32 v[32:33], v[12:13], 0.5, v[32:33] op_sel_hi:[1,0,1]
	v_lshlrev_b32_e32 v12, 16, v243
	v_and_b32_e32 v13, 0xffff0000, v243
	global_store_dwordx4 v[180:181], v[112:115], off
	global_store_dwordx4 v[180:181], v[116:119], off offset:256
	v_cvt_pk_bf16_f32 v146, v44, v45
	v_lshl_add_u64 v[112:113], s[28:29], 0, v[132:133]
	v_cvt_pk_bf16_f32 v147, v46, v47
	v_cvt_pk_bf16_f32 v148, v40, v41
	v_cvt_pk_bf16_f32 v149, v42, v43
	v_pk_fma_f32 v[24:25], v[24:25], 0.5, v[30:31] op_sel_hi:[1,0,1]
	v_lshlrev_b32_e32 v30, 16, v239
	v_and_b32_e32 v31, 0xffff0000, v239
	v_pk_fma_f32 v[22:23], v[22:23], 0.5, v[12:13] op_sel_hi:[1,0,1]
	v_lshlrev_b32_e32 v12, 16, v245
	v_and_b32_e32 v13, 0xffff0000, v245
	v_lshl_add_u64 v[112:113], v[112:113], 0, v[170:171]
	v_cvt_pk_bf16_f32 v172, v36, v37
	v_cvt_pk_bf16_f32 v173, v38, v39
	v_cvt_pk_bf16_f32 v174, v48, v49
	v_cvt_pk_bf16_f32 v175, v50, v51
	v_pk_fma_f32 v[30:31], v[34:35], 0.5, v[30:31] op_sel_hi:[1,0,1]
	v_pk_fma_f32 v[34:35], v[14:15], 0.5, v[12:13] op_sel_hi:[1,0,1]
	v_lshlrev_b32_e32 v12, 16, v246
	v_and_b32_e32 v13, 0xffff0000, v246
	v_lshlrev_b32_e32 v14, 16, v248
	v_and_b32_e32 v15, 0xffff0000, v248
	global_store_dwordx4 v[112:113], v[146:149], off
	global_store_dwordx4 v[112:113], v[172:175], off offset:256
	v_lshl_add_u64 v[112:113], s[28:29], 0, v[134:135]
	v_cvt_pk_bf16_f32 v176, v28, v29
	v_cvt_pk_bf16_f32 v177, v30, v31
	v_cvt_pk_bf16_f32 v178, v24, v25
	v_cvt_pk_bf16_f32 v179, v26, v27
	v_pk_fma_f32 v[12:13], v[16:17], 0.5, v[12:13] op_sel_hi:[1,0,1]
	v_pk_fma_f32 v[8:9], v[8:9], 0.5, v[14:15] op_sel_hi:[1,0,1]
	v_lshlrev_b32_e32 v14, 16, v247
	v_and_b32_e32 v15, 0xffff0000, v247
	v_lshlrev_b32_e32 v16, 16, v249
	v_and_b32_e32 v17, 0xffff0000, v249
	v_lshlrev_b32_e32 v64, 16, v65
	v_and_b32_e32 v65, 0xffff0000, v65
	v_lshl_add_u64 v[112:113], v[112:113], 0, v[170:171]
	v_cvt_pk_bf16_f32 v194, v20, v21
	v_cvt_pk_bf16_f32 v195, v22, v23
	v_cvt_pk_bf16_f32 v196, v32, v33
	v_cvt_pk_bf16_f32 v197, v34, v35
	v_pk_fma_f32 v[14:15], v[18:19], 0.5, v[14:15] op_sel_hi:[1,0,1]
	v_pk_fma_f32 v[10:11], v[10:11], 0.5, v[16:17] op_sel_hi:[1,0,1]
	v_pk_fma_f32 v[6:7], v[6:7], 0.5, v[64:65] op_sel_hi:[1,0,1]
	v_lshlrev_b32_e32 v64, 16, v67
	v_and_b32_e32 v65, 0xffff0000, v67
	global_store_dwordx4 v[112:113], v[176:179], off
	global_store_dwordx4 v[112:113], v[194:197], off offset:256
	v_lshl_add_u64 v[112:113], s[28:29], 0, v[184:185]
	v_cvt_pk_bf16_f32 v16, v12, v13
	v_cvt_pk_bf16_f32 v17, v14, v15
	v_cvt_pk_bf16_f32 v18, v8, v9
	v_cvt_pk_bf16_f32 v19, v10, v11
	v_pk_fma_f32 v[2:3], v[2:3], 0.5, v[64:65] op_sel_hi:[1,0,1]
	v_lshl_add_u64 v[112:113], v[112:113], 0, v[170:171]
	v_cvt_pk_bf16_f32 v64, v4, v5
	v_cvt_pk_bf16_f32 v65, v6, v7
	v_cvt_pk_bf16_f32 v66, v0, v1
	v_cvt_pk_bf16_f32 v67, v2, v3
	global_store_dwordx4 v[112:113], v[16:19], off
	global_store_dwordx4 v[112:113], v[64:67], off offset:256
	s_lshl_b32 s10, s81, 2
	v_and_b32_e32 v17, 64, v188
	v_xor_b32_e32 v16, 16, v188
	v_add_u32_e32 v17, 64, v17
	v_cmp_lt_i32_e32 vcc, v16, v17
	v_xor_b32_e32 v18, 32, v188
	s_ashr_i32 s11, s10, 31
	v_cndmask_b32_e32 v16, v188, v16, vcc
	v_lshlrev_b32_e32 v16, 2, v16
	v_mov_b32_e32 v132, v209
	v_cmp_lt_i32_e32 vcc, v18, v17
	s_lshl_b64 s[10:11], s[10:11], 2
	s_add_u32 s38, s73, s10
	v_cndmask_b32_e32 v17, v188, v18, vcc
	v_lshlrev_b32_e32 v17, 2, v17
	s_addc_u32 s39, s74, s11
	v_pk_mul_f32 v[18:19], v[120:121], v[120:121]
	v_pk_mul_f32 v[64:65], v[122:123], v[122:123]
	v_add_f32_e32 v18, v18, v19
	v_add_f32_e32 v18, v64, v18
	v_pk_mul_f32 v[66:67], v[108:109], v[108:109]
	v_add_f32_e32 v18, v65, v18
	v_add_f32_e32 v18, v66, v18
	v_pk_mul_f32 v[108:109], v[110:111], v[110:111]
	v_add_f32_e32 v18, v67, v18
	v_add_f32_e32 v18, v108, v18
	v_pk_mul_f32 v[100:101], v[100:101], v[100:101]
	v_add_f32_e32 v18, v109, v18
	v_add_f32_e32 v18, v100, v18
	v_pk_mul_f32 v[102:103], v[102:103], v[102:103]
	v_add_f32_e32 v18, v101, v18
	v_add_f32_e32 v18, v102, v18
	v_pk_mul_f32 v[110:111], v[124:125], v[124:125]
	v_add_f32_e32 v18, v103, v18
	v_add_f32_e32 v18, v110, v18
	v_pk_mul_f32 v[112:113], v[126:127], v[126:127]
	v_add_f32_e32 v18, v111, v18
	v_add_f32_e32 v18, v112, v18
	v_add_f32_e32 v18, v113, v18
	v_mov_b32_e32 v133, v18
	v_pk_mul_f32 v[18:19], v[92:93], v[92:93]
	v_pk_mul_f32 v[64:65], v[94:95], v[94:95]
	v_add_f32_e32 v18, v18, v19
	v_add_f32_e32 v18, v64, v18
	v_pk_mul_f32 v[66:67], v[88:89], v[88:89]
	v_add_f32_e32 v18, v65, v18
	v_add_f32_e32 v18, v66, v18
	v_pk_mul_f32 v[88:89], v[90:91], v[90:91]
	v_add_f32_e32 v18, v67, v18
	v_add_f32_e32 v18, v88, v18
	v_pk_mul_f32 v[90:91], v[96:97], v[96:97]
	v_add_f32_e32 v18, v89, v18
	v_add_f32_e32 v18, v90, v18
	v_pk_mul_f32 v[92:93], v[136:137], v[136:137]
	v_add_f32_e32 v18, v91, v18
	v_add_f32_e32 v18, v92, v18
	v_pk_mul_f32 v[94:95], v[98:99], v[98:99]
	v_add_f32_e32 v18, v93, v18
	v_add_f32_e32 v18, v94, v18
	v_pk_mul_f32 v[96:97], v[138:139], v[138:139]
	v_add_f32_e32 v18, v95, v18
	v_add_f32_e32 v18, v96, v18
	v_add_f32_e32 v18, v97, v18
	v_mov_b32_e32 v134, v18
	v_pk_mul_f32 v[18:19], v[74:75], v[74:75]
	v_pk_mul_f32 v[210:211], v[60:61], v[60:61]
	v_pk_mul_f32 v[64:65], v[80:81], v[80:81]
	v_pk_mul_f32 v[60:61], v[62:63], v[62:63]
	v_add_f32_e32 v18, v18, v19
	v_add_f32_e32 v210, v210, v211
	v_add_f32_e32 v18, v64, v18
	v_add_f32_e32 v210, v60, v210
	v_pk_mul_f32 v[66:67], v[78:79], v[78:79]
	v_pk_mul_f32 v[56:57], v[56:57], v[56:57]
	v_add_f32_e32 v18, v65, v18
	v_add_f32_e32 v210, v61, v210
	v_add_f32_e32 v18, v66, v18
	v_add_f32_e32 v210, v56, v210
	v_pk_mul_f32 v[74:75], v[82:83], v[82:83]
	v_pk_mul_f32 v[58:59], v[58:59], v[58:59]
	v_add_f32_e32 v18, v67, v18
	v_add_f32_e32 v210, v57, v210
	v_add_f32_e32 v18, v74, v18
	v_add_f32_e32 v210, v58, v210
	v_pk_mul_f32 v[78:79], v[84:85], v[84:85]
	v_pk_mul_f32 v[52:53], v[52:53], v[52:53]
	v_add_f32_e32 v18, v75, v18
	v_add_f32_e32 v210, v59, v210
	v_add_f32_e32 v18, v78, v18
	v_add_f32_e32 v210, v52, v210
	v_pk_mul_f32 v[80:81], v[128:129], v[128:129]
	v_pk_mul_f32 v[54:55], v[54:55], v[54:55]
	v_add_f32_e32 v18, v79, v18
	v_add_f32_e32 v210, v53, v210
	v_add_f32_e32 v18, v80, v18
	v_add_f32_e32 v210, v54, v210
	v_pk_mul_f32 v[82:83], v[86:87], v[86:87]
	v_pk_mul_f32 v[62:63], v[104:105], v[104:105]
	v_add_f32_e32 v18, v81, v18
	v_add_f32_e32 v210, v55, v210
	v_add_f32_e32 v18, v82, v18
	v_add_f32_e32 v210, v62, v210
	v_pk_mul_f32 v[84:85], v[130:131], v[130:131]
	v_pk_mul_f32 v[212:213], v[106:107], v[106:107]
	v_add_f32_e32 v18, v83, v18
	v_add_f32_e32 v210, v63, v210
	v_add_f32_e32 v18, v84, v18
	v_add_f32_e32 v210, v212, v210
	v_add_f32_e32 v18, v85, v18
	v_add_f32_e32 v210, v213, v210
	v_mov_b32_e32 v135, v18
	v_mov_b32_e32 v146, v210
	v_pk_mul_f32 v[18:19], v[44:45], v[44:45]
	v_pk_mul_f32 v[210:211], v[28:29], v[28:29]
	v_pk_mul_f32 v[44:45], v[46:47], v[46:47]
	v_pk_mul_f32 v[28:29], v[30:31], v[30:31]
	v_add_f32_e32 v18, v18, v19
	v_add_f32_e32 v210, v210, v211
	v_add_f32_e32 v18, v44, v18
	v_add_f32_e32 v210, v28, v210
	v_pk_mul_f32 v[40:41], v[40:41], v[40:41]
	v_pk_mul_f32 v[24:25], v[24:25], v[24:25]
	v_add_f32_e32 v18, v45, v18
	v_add_f32_e32 v210, v29, v210
	v_add_f32_e32 v18, v40, v18
	v_add_f32_e32 v210, v24, v210
	v_pk_mul_f32 v[42:43], v[42:43], v[42:43]
	v_pk_mul_f32 v[26:27], v[26:27], v[26:27]
	v_add_f32_e32 v18, v41, v18
	v_add_f32_e32 v210, v25, v210
	v_add_f32_e32 v18, v42, v18
	v_add_f32_e32 v210, v26, v210
	v_pk_mul_f32 v[36:37], v[36:37], v[36:37]
	v_pk_mul_f32 v[20:21], v[20:21], v[20:21]
	v_add_f32_e32 v18, v43, v18
	v_add_f32_e32 v210, v27, v210
	v_add_f32_e32 v18, v36, v18
	v_add_f32_e32 v210, v20, v210
	v_pk_mul_f32 v[38:39], v[38:39], v[38:39]
	v_pk_mul_f32 v[22:23], v[22:23], v[22:23]
	v_add_f32_e32 v18, v37, v18
	v_add_f32_e32 v210, v21, v210
	v_add_f32_e32 v18, v38, v18
	v_add_f32_e32 v210, v22, v210
	v_pk_mul_f32 v[46:47], v[48:49], v[48:49]
	v_pk_mul_f32 v[30:31], v[32:33], v[32:33]
	v_add_f32_e32 v18, v39, v18
	v_add_f32_e32 v210, v23, v210
	v_add_f32_e32 v18, v46, v18
	v_add_f32_e32 v210, v30, v210
	v_pk_mul_f32 v[48:49], v[50:51], v[50:51]
	v_pk_mul_f32 v[32:33], v[34:35], v[34:35]
	v_add_f32_e32 v18, v47, v18
	v_add_f32_e32 v210, v31, v210
	v_add_f32_e32 v18, v48, v18
	v_add_f32_e32 v210, v32, v210
	v_add_f32_e32 v18, v49, v18
	v_add_f32_e32 v210, v33, v210
	v_mov_b32_e32 v147, v18
	v_mov_b32_e32 v148, v210
	v_pk_mul_f32 v[12:13], v[12:13], v[12:13]
	v_pk_mul_f32 v[14:15], v[14:15], v[14:15]
	v_add_f32_e32 v12, v12, v13
	v_add_f32_e32 v12, v14, v12
	v_pk_mul_f32 v[8:9], v[8:9], v[8:9]
	v_add_f32_e32 v12, v15, v12
	v_add_f32_e32 v8, v8, v12
	v_pk_mul_f32 v[10:11], v[10:11], v[10:11]
	v_add_f32_e32 v8, v9, v8
	v_add_f32_e32 v8, v10, v8
	v_pk_mul_f32 v[4:5], v[4:5], v[4:5]
	v_add_f32_e32 v8, v11, v8
	v_add_f32_e32 v4, v4, v8
	v_pk_mul_f32 v[6:7], v[6:7], v[6:7]
	v_add_f32_e32 v4, v5, v4
	v_add_f32_e32 v4, v6, v4
	v_pk_mul_f32 v[0:1], v[0:1], v[0:1]
	v_add_f32_e32 v4, v7, v4
	v_add_f32_e32 v0, v0, v4
	v_pk_mul_f32 v[2:3], v[2:3], v[2:3]
	v_add_f32_e32 v0, v1, v0
	v_add_f32_e32 v0, v2, v0
	v_add_f32_e32 v0, v3, v0
	v_mov_b32_e32 v149, v0
	ds_bpermute_b32 v172, v16, v132
	ds_bpermute_b32 v173, v16, v133
	ds_bpermute_b32 v174, v16, v134
	ds_bpermute_b32 v175, v16, v135
	ds_bpermute_b32 v180, v16, v146
	ds_bpermute_b32 v181, v16, v147
	ds_bpermute_b32 v182, v16, v148
	ds_bpermute_b32 v183, v16, v149
	s_waitcnt lgkmcnt(0)
	v_add_f32_e32 v132, v132, v172
	v_add_f32_e32 v133, v133, v173
	v_add_f32_e32 v134, v134, v174
	v_add_f32_e32 v135, v135, v175
	v_add_f32_e32 v146, v146, v180
	v_add_f32_e32 v147, v147, v181
	v_add_f32_e32 v148, v148, v182
	v_add_f32_e32 v149, v149, v183
	ds_bpermute_b32 v172, v17, v132
	ds_bpermute_b32 v173, v17, v133
	ds_bpermute_b32 v174, v17, v134
	ds_bpermute_b32 v175, v17, v135
	ds_bpermute_b32 v180, v17, v146
	ds_bpermute_b32 v181, v17, v147
	ds_bpermute_b32 v182, v17, v148
	ds_bpermute_b32 v183, v17, v149
	s_and_saveexec_b64 s[46:47], s[42:43]
	s_cbranch_execz .LBB0_19
	s_waitcnt lgkmcnt(0)
	v_add_f32_e32 v132, v132, v172
	v_lshlrev_b64 v[18:19], 6, v[168:169]
	v_lshl_add_u64 v[18:19], s[38:39], 0, v[18:19]
	global_store_dword v[18:19], v132, off
	v_add_f32_e32 v133, v133, v173
	v_lshlrev_b64 v[18:19], 6, v[166:167]
	v_lshl_add_u64 v[18:19], s[38:39], 0, v[18:19]
	global_store_dword v[18:19], v133, off
	v_add_f32_e32 v134, v134, v174
	v_lshlrev_b64 v[18:19], 6, v[164:165]
	v_lshl_add_u64 v[18:19], s[38:39], 0, v[18:19]
	global_store_dword v[18:19], v134, off
	v_add_f32_e32 v135, v135, v175
	v_lshlrev_b64 v[18:19], 6, v[162:163]
	v_lshl_add_u64 v[18:19], s[38:39], 0, v[18:19]
	global_store_dword v[18:19], v135, off
	v_add_f32_e32 v146, v146, v180
	v_lshlrev_b64 v[18:19], 6, v[76:77]
	v_lshl_add_u64 v[18:19], s[38:39], 0, v[18:19]
	global_store_dword v[18:19], v146, off
	v_add_f32_e32 v147, v147, v181
	v_lshlrev_b64 v[18:19], 6, v[72:73]
	v_lshl_add_u64 v[18:19], s[38:39], 0, v[18:19]
	global_store_dword v[18:19], v147, off
	v_add_f32_e32 v148, v148, v182
	v_lshlrev_b64 v[18:19], 6, v[70:71]
	v_lshl_add_u64 v[18:19], s[38:39], 0, v[18:19]
	global_store_dword v[18:19], v148, off
	v_add_f32_e32 v149, v149, v183
	v_lshlrev_b64 v[18:19], 6, v[68:69]
	v_lshl_add_u64 v[18:19], s[38:39], 0, v[18:19]
	global_store_dword v[18:19], v149, off
	s_branch .LBB0_19

.Lm4bp_77:
	s_waitcnt lgkmcnt(0)
	s_mov_b32 s100, 0
	s_barrier
	v_mfma_f32_16x16x32_bf16 v[60:63], v[158:161], v[174:177], 0
	v_mfma_f32_16x16x32_bf16 v[56:59], v[166:169], v[174:177], 0
	v_mfma_f32_16x16x32_bf16 v[52:55], v[158:161], v[182:185], 0
	v_mfma_f32_16x16x32_bf16 v[48:51], v[166:169], v[182:185], 0
	v_mfma_f32_16x16x32_bf16 v[44:47], v[158:161], v[210:213], 0
	v_mfma_f32_16x16x32_bf16 v[40:43], v[166:169], v[210:213], 0
	v_mfma_f32_16x16x32_bf16 v[36:39], v[158:161], v[218:221], 0
	v_mfma_f32_16x16x32_bf16 v[32:35], v[166:169], v[218:221], 0
	v_mfma_f32_16x16x32_bf16 v[60:63], v[162:165], v[178:181], v[60:63]
	v_mfma_f32_16x16x32_bf16 v[56:59], v[170:173], v[178:181], v[56:59]
	v_mfma_f32_16x16x32_bf16 v[52:55], v[162:165], v[206:209], v[52:55]
	v_mfma_f32_16x16x32_bf16 v[48:51], v[170:173], v[206:209], v[48:51]
	v_mfma_f32_16x16x32_bf16 v[44:47], v[162:165], v[214:217], v[44:47]
	v_mfma_f32_16x16x32_bf16 v[40:43], v[170:173], v[214:217], v[40:43]
	v_mfma_f32_16x16x32_bf16 v[36:39], v[162:165], v[222:225], v[36:39]
	v_mfma_f32_16x16x32_bf16 v[32:35], v[170:173], v[222:225], v[32:35]
	v_mfma_f32_16x16x32_bf16 v[28:31], v[226:229], v[174:177], 0
	v_mfma_f32_16x16x32_bf16 v[24:27], v[234:237], v[174:177], 0
	v_mfma_f32_16x16x32_bf16 v[20:23], v[226:229], v[182:185], 0
	v_mfma_f32_16x16x32_bf16 v[16:19], v[234:237], v[182:185], 0
	v_mfma_f32_16x16x32_bf16 v[12:15], v[226:229], v[210:213], 0
	v_mfma_f32_16x16x32_bf16 v[8:11], v[234:237], v[210:213], 0
	v_mfma_f32_16x16x32_bf16 v[4:7], v[226:229], v[218:221], 0
	v_mfma_f32_16x16x32_bf16 v[0:3], v[234:237], v[218:221], 0
	v_mfma_f32_16x16x32_bf16 v[28:31], v[230:233], v[178:181], v[28:31]
	v_mfma_f32_16x16x32_bf16 v[24:27], v[238:241], v[178:181], v[24:27]
	v_mfma_f32_16x16x32_bf16 v[20:23], v[230:233], v[206:209], v[20:23]
	v_mfma_f32_16x16x32_bf16 v[16:19], v[238:241], v[206:209], v[16:19]
	v_mfma_f32_16x16x32_bf16 v[12:15], v[230:233], v[214:217], v[12:15]
	v_mfma_f32_16x16x32_bf16 v[8:11], v[238:241], v[214:217], v[8:11]
	v_mfma_f32_16x16x32_bf16 v[4:7], v[230:233], v[222:225], v[4:7]
	v_mfma_f32_16x16x32_bf16 v[0:3], v[238:241], v[222:225], v[0:3]
	s_barrier
	s_add_i32 s6, 0, 0x18000
	v_add_u32_e32 v170, s6, v154
	ds_read_b128 v[158:161], v170
	ds_read_b128 v[162:165], v170 offset:1024
	ds_read_b128 v[166:169], v170 offset:2048
	ds_read_b128 v[170:173], v170 offset:3072
	s_add_u32 s54, s54, 0x40000
	s_addc_u32 s55, s55, 0
	s_mov_b32 m0, s70
	v_lshl_add_u64 v[226:227], s[54:55], 0, v[128:129]
	ds_read_b128 v[174:177], v157 offset:32768
	ds_read_b128 v[178:181], v157 offset:33792
	ds_read_b128 v[182:185], v157 offset:34816
	ds_read_b128 v[206:209], v157 offset:35840
	ds_read_b128 v[210:213], v157 offset:36864
	ds_read_b128 v[214:217], v157 offset:37888
	ds_read_b128 v[218:221], v157 offset:38912
	ds_read_b128 v[222:225], v157 offset:39936
	global_load_lds_dwordx4 v[226:227], off
	v_lshl_add_u64 v[226:227], s[54:55], 0, v[130:131]
	s_mov_b32 m0, s71
	s_nop 0
	global_load_lds_dwordx4 v[226:227], off
	s_add_i32 s19, 0, 0x1c000
	v_add_u32_e32 v192, s19, v154
	ds_read_b128 v[226:229], v192
	ds_read_b128 v[230:233], v192 offset:1024
	ds_read_b128 v[234:237], v192 offset:2048
	ds_read_b128 v[238:241], v192 offset:3072
	s_waitcnt vmcnt(8)
	s_waitcnt lgkmcnt(0)
	s_barrier
	v_mfma_f32_16x16x32_bf16 v[124:127], v[158:161], v[174:177], v[124:127]
	v_mfma_f32_16x16x32_bf16 v[120:123], v[166:169], v[174:177], v[120:123]
	v_mfma_f32_16x16x32_bf16 v[116:119], v[158:161], v[182:185], v[116:119]
	v_mfma_f32_16x16x32_bf16 v[112:115], v[166:169], v[182:185], v[112:115]
	v_mfma_f32_16x16x32_bf16 v[108:111], v[158:161], v[210:213], v[108:111]
	v_mfma_f32_16x16x32_bf16 v[104:107], v[166:169], v[210:213], v[104:107]
	v_mfma_f32_16x16x32_bf16 v[100:103], v[158:161], v[218:221], v[100:103]
	v_mfma_f32_16x16x32_bf16 v[96:99], v[166:169], v[218:221], v[96:99]
	v_mfma_f32_16x16x32_bf16 v[124:127], v[162:165], v[178:181], v[124:127]
	v_mfma_f32_16x16x32_bf16 v[120:123], v[170:173], v[178:181], v[120:123]
	v_mfma_f32_16x16x32_bf16 v[116:119], v[162:165], v[206:209], v[116:119]
	v_mfma_f32_16x16x32_bf16 v[112:115], v[170:173], v[206:209], v[112:115]
	v_mfma_f32_16x16x32_bf16 v[108:111], v[162:165], v[214:217], v[108:111]
	v_mfma_f32_16x16x32_bf16 v[104:107], v[170:173], v[214:217], v[104:107]
	v_mfma_f32_16x16x32_bf16 v[100:103], v[162:165], v[222:225], v[100:103]
	v_mfma_f32_16x16x32_bf16 v[96:99], v[170:173], v[222:225], v[96:99]
	v_mfma_f32_16x16x32_bf16 v[92:95], v[226:229], v[174:177], v[92:95]
	v_mfma_f32_16x16x32_bf16 v[88:91], v[234:237], v[174:177], v[88:91]
	v_mfma_f32_16x16x32_bf16 v[84:87], v[226:229], v[182:185], v[84:87]
	v_mfma_f32_16x16x32_bf16 v[80:83], v[234:237], v[182:185], v[80:83]
	v_mfma_f32_16x16x32_bf16 v[76:79], v[226:229], v[210:213], v[76:79]
	v_mfma_f32_16x16x32_bf16 v[72:75], v[234:237], v[210:213], v[72:75]
	v_mfma_f32_16x16x32_bf16 v[68:71], v[226:229], v[218:221], v[68:71]
	v_mfma_f32_16x16x32_bf16 v[64:67], v[234:237], v[218:221], v[64:67]
	v_mfma_f32_16x16x32_bf16 v[92:95], v[230:233], v[178:181], v[92:95]
	v_mfma_f32_16x16x32_bf16 v[88:91], v[238:241], v[178:181], v[88:91]
	v_mfma_f32_16x16x32_bf16 v[84:87], v[230:233], v[206:209], v[84:87]
	v_mfma_f32_16x16x32_bf16 v[80:83], v[238:241], v[206:209], v[80:83]
	v_mfma_f32_16x16x32_bf16 v[76:79], v[230:233], v[214:217], v[76:79]
	v_mfma_f32_16x16x32_bf16 v[72:75], v[238:241], v[214:217], v[72:75]
	v_mfma_f32_16x16x32_bf16 v[68:71], v[230:233], v[222:225], v[68:71]
	v_mfma_f32_16x16x32_bf16 v[64:67], v[238:241], v[222:225], v[64:67]
	s_barrier
	s_add_i32 s6, s6, s59
	v_lshl_add_u64 v[146:147], v[146:147], 0, s[36:37]
	s_mov_b32 m0, s6
	s_nop 0
	global_load_lds_dwordx4 v[146:147], off
	v_lshl_add_u64 v[146:147], v[148:149], 0, s[36:37]
	s_add_i32 m0, s6, 0x2000
	s_nop 0
	global_load_lds_dwordx4 v[146:147], off
	s_mov_b32 m0, s72
	v_lshl_add_u64 v[146:147], v[194:195], 0, s[36:37]
	ds_read_b128 v[174:177], v157 offset:49152
	ds_read_b128 v[178:181], v157 offset:50176
	ds_read_b128 v[182:185], v157 offset:51200
	ds_read_b128 v[206:209], v157 offset:52224
	ds_read_b128 v[210:213], v157 offset:53248
	ds_read_b128 v[214:217], v157 offset:54272
	ds_read_b128 v[218:221], v157 offset:55296
	ds_read_b128 v[222:225], v157 offset:56320
	global_load_lds_dwordx4 v[146:147], off
	v_lshl_add_u64 v[146:147], v[196:197], 0, s[36:37]
	s_mov_b32 m0, s73
	s_nop 0
	global_load_lds_dwordx4 v[146:147], off
	s_add_u32 s52, s52, 0x40080
	s_addc_u32 s53, s53, 0
	s_add_i32 s6, s19, s59
	v_lshl_add_u64 v[146:147], s[52:53], 0, v[140:141]
	s_mov_b32 m0, s6
	s_nop 0
	global_load_lds_dwordx4 v[146:147], off
	v_lshl_add_u64 v[146:147], s[52:53], 0, v[132:133]
	s_add_i32 m0, s6, 0x2000
	s_nop 0
	global_load_lds_dwordx4 v[146:147], off
	s_add_i32 s81, s81, 2
	s_add_u32 s50, s50, 0x100
	s_addc_u32 s51, s51, 0
	s_cmp_gt_u32 s81, 13
	s_waitcnt vmcnt(8)
	s_waitcnt lgkmcnt(0)
	s_barrier
	v_mfma_f32_16x16x32_bf16 v[60:63], v[158:161], v[174:177], v[60:63]
	v_mfma_f32_16x16x32_bf16 v[56:59], v[166:169], v[174:177], v[56:59]
	v_mfma_f32_16x16x32_bf16 v[52:55], v[158:161], v[182:185], v[52:55]
	v_mfma_f32_16x16x32_bf16 v[48:51], v[166:169], v[182:185], v[48:51]
	v_mfma_f32_16x16x32_bf16 v[44:47], v[158:161], v[210:213], v[44:47]
	v_mfma_f32_16x16x32_bf16 v[40:43], v[166:169], v[210:213], v[40:43]
	v_mfma_f32_16x16x32_bf16 v[36:39], v[158:161], v[218:221], v[36:39]
	v_mfma_f32_16x16x32_bf16 v[32:35], v[166:169], v[218:221], v[32:35]
	v_mfma_f32_16x16x32_bf16 v[60:63], v[162:165], v[178:181], v[60:63]
	v_mfma_f32_16x16x32_bf16 v[56:59], v[170:173], v[178:181], v[56:59]
	v_mfma_f32_16x16x32_bf16 v[52:55], v[162:165], v[206:209], v[52:55]
	v_mfma_f32_16x16x32_bf16 v[48:51], v[170:173], v[206:209], v[48:51]
	v_mfma_f32_16x16x32_bf16 v[44:47], v[162:165], v[214:217], v[44:47]
	v_mfma_f32_16x16x32_bf16 v[40:43], v[170:173], v[214:217], v[40:43]
	v_mfma_f32_16x16x32_bf16 v[36:39], v[162:165], v[222:225], v[36:39]
	v_mfma_f32_16x16x32_bf16 v[32:35], v[170:173], v[222:225], v[32:35]
	v_mfma_f32_16x16x32_bf16 v[28:31], v[226:229], v[174:177], v[28:31]
	v_mfma_f32_16x16x32_bf16 v[24:27], v[234:237], v[174:177], v[24:27]
	v_mfma_f32_16x16x32_bf16 v[20:23], v[226:229], v[182:185], v[20:23]
	v_mfma_f32_16x16x32_bf16 v[16:19], v[234:237], v[182:185], v[16:19]
	v_mfma_f32_16x16x32_bf16 v[12:15], v[226:229], v[210:213], v[12:15]
	v_mfma_f32_16x16x32_bf16 v[8:11], v[234:237], v[210:213], v[8:11]
	v_mfma_f32_16x16x32_bf16 v[4:7], v[226:229], v[218:221], v[4:7]
	v_mfma_f32_16x16x32_bf16 v[0:3], v[234:237], v[218:221], v[0:3]
	v_mfma_f32_16x16x32_bf16 v[28:31], v[230:233], v[178:181], v[28:31]
	v_mfma_f32_16x16x32_bf16 v[24:27], v[238:241], v[178:181], v[24:27]
	v_mfma_f32_16x16x32_bf16 v[20:23], v[230:233], v[206:209], v[20:23]
	v_mfma_f32_16x16x32_bf16 v[16:19], v[238:241], v[206:209], v[16:19]
	v_mfma_f32_16x16x32_bf16 v[12:15], v[230:233], v[214:217], v[12:15]
	v_mfma_f32_16x16x32_bf16 v[8:11], v[238:241], v[214:217], v[8:11]
	v_mfma_f32_16x16x32_bf16 v[4:7], v[230:233], v[222:225], v[4:7]
	v_mfma_f32_16x16x32_bf16 v[0:3], v[238:241], v[222:225], v[0:3]
	s_barrier
.LBB0_77:
	s_add_u32 s6, s26, s50
	s_addc_u32 s19, s27, s51
	s_add_u32 s6, s6, 0x100
	s_addc_u32 s19, s19, 0
	s_add_u32 s23, s10, s50
	s_addc_u32 s52, s11, s51
	s_add_i32 s82, 0, 0x10000
	v_add_u32_e32 v146, s82, v154
	ds_read_b128 v[158:161], v146
	ds_read_b128 v[162:165], v146 offset:1024
	ds_read_b128 v[166:169], v146 offset:2048
	ds_read_b128 v[170:173], v146 offset:3072
	s_cmpk_eq_i32 s50, 0x700
	s_cselect_b32 s55, s12, s19
	s_cselect_b32 s54, s31, s6
	s_cselect_b32 s53, s35, s52
	s_cselect_b32 s52, s39, s23
	v_lshl_add_u64 v[146:147], v[150:151], 0, s[50:51]
	s_add_i32 m0, s68, 0xc000
	ds_read_b128 v[174:177], v157
	ds_read_b128 v[178:181], v157 offset:1024
	ds_read_b128 v[182:185], v157 offset:2048
	ds_read_b128 v[206:209], v157 offset:3072
	ds_read_b128 v[210:213], v157 offset:4096
	ds_read_b128 v[214:217], v157 offset:5120
	ds_read_b128 v[218:221], v157 offset:6144
	ds_read_b128 v[222:225], v157 offset:7168
	global_load_lds_dwordx4 v[146:147], off
	v_lshl_add_u64 v[146:147], v[152:153], 0, s[50:51]
	s_add_i32 m0, s68, 0xe000
	s_nop 0
	global_load_lds_dwordx4 v[146:147], off
	s_add_i32 s6, 0, 0x14000
	v_add_u32_e32 v146, s6, v154
	ds_read_b128 v[226:229], v146
	ds_read_b128 v[230:233], v146 offset:1024
	ds_read_b128 v[234:237], v146 offset:2048
	ds_read_b128 v[238:241], v146 offset:3072
	s_waitcnt vmcnt(8)
	s_waitcnt lgkmcnt(0)
	s_barrier
	v_mfma_f32_16x16x32_bf16 v[124:127], v[158:161], v[174:177], v[124:127]
	v_mfma_f32_16x16x32_bf16 v[120:123], v[166:169], v[174:177], v[120:123]
	v_mfma_f32_16x16x32_bf16 v[116:119], v[158:161], v[182:185], v[116:119]
	v_mfma_f32_16x16x32_bf16 v[112:115], v[166:169], v[182:185], v[112:115]
	v_mfma_f32_16x16x32_bf16 v[108:111], v[158:161], v[210:213], v[108:111]
	v_mfma_f32_16x16x32_bf16 v[104:107], v[166:169], v[210:213], v[104:107]
	v_mfma_f32_16x16x32_bf16 v[100:103], v[158:161], v[218:221], v[100:103]
	v_mfma_f32_16x16x32_bf16 v[96:99], v[166:169], v[218:221], v[96:99]
	v_mfma_f32_16x16x32_bf16 v[124:127], v[162:165], v[178:181], v[124:127]
	v_mfma_f32_16x16x32_bf16 v[120:123], v[170:173], v[178:181], v[120:123]
	v_mfma_f32_16x16x32_bf16 v[116:119], v[162:165], v[206:209], v[116:119]
	v_mfma_f32_16x16x32_bf16 v[112:115], v[170:173], v[206:209], v[112:115]
	v_mfma_f32_16x16x32_bf16 v[108:111], v[162:165], v[214:217], v[108:111]
	v_mfma_f32_16x16x32_bf16 v[104:107], v[170:173], v[214:217], v[104:107]
	v_mfma_f32_16x16x32_bf16 v[100:103], v[162:165], v[222:225], v[100:103]
	v_mfma_f32_16x16x32_bf16 v[96:99], v[170:173], v[222:225], v[96:99]
	v_mfma_f32_16x16x32_bf16 v[92:95], v[226:229], v[174:177], v[92:95]
	v_mfma_f32_16x16x32_bf16 v[88:91], v[234:237], v[174:177], v[88:91]
	v_mfma_f32_16x16x32_bf16 v[84:87], v[226:229], v[182:185], v[84:87]
	v_mfma_f32_16x16x32_bf16 v[80:83], v[234:237], v[182:185], v[80:83]
	v_mfma_f32_16x16x32_bf16 v[76:79], v[226:229], v[210:213], v[76:79]
	v_mfma_f32_16x16x32_bf16 v[72:75], v[234:237], v[210:213], v[72:75]
	v_mfma_f32_16x16x32_bf16 v[68:71], v[226:229], v[218:221], v[68:71]
	v_mfma_f32_16x16x32_bf16 v[64:67], v[234:237], v[218:221], v[64:67]
	v_mfma_f32_16x16x32_bf16 v[92:95], v[230:233], v[178:181], v[92:95]
	v_mfma_f32_16x16x32_bf16 v[88:91], v[238:241], v[178:181], v[88:91]
	v_mfma_f32_16x16x32_bf16 v[84:87], v[230:233], v[206:209], v[84:87]
	v_mfma_f32_16x16x32_bf16 v[80:83], v[238:241], v[206:209], v[80:83]
	v_mfma_f32_16x16x32_bf16 v[76:79], v[230:233], v[214:217], v[76:79]
	v_mfma_f32_16x16x32_bf16 v[72:75], v[238:241], v[214:217], v[72:75]
	v_mfma_f32_16x16x32_bf16 v[68:71], v[230:233], v[222:225], v[68:71]
	v_mfma_f32_16x16x32_bf16 v[64:67], v[238:241], v[222:225], v[64:67]
	s_barrier
	s_add_i32 s19, s82, s59
	v_lshl_add_u64 v[146:147], s[52:53], 0, v[140:141]
	s_mov_b32 m0, s19
	v_lshl_add_u64 v[148:149], s[52:53], 0, v[132:133]
	global_load_lds_dwordx4 v[146:147], off
	s_add_i32 m0, s19, 0x2000
	s_nop 0
	global_load_lds_dwordx4 v[148:149], off
	s_mov_b32 m0, s68
	v_lshl_add_u64 v[194:195], s[54:55], 0, v[128:129]
	ds_read_b128 v[174:177], v157 offset:16384
	ds_read_b128 v[178:181], v157 offset:17408
	ds_read_b128 v[182:185], v157 offset:18432
	ds_read_b128 v[206:209], v157 offset:19456
	ds_read_b128 v[210:213], v157 offset:20480
	ds_read_b128 v[214:217], v157 offset:21504
	ds_read_b128 v[218:221], v157 offset:22528
	ds_read_b128 v[222:225], v157 offset:23552
	global_load_lds_dwordx4 v[194:195], off
	v_lshl_add_u64 v[196:197], s[54:55], 0, v[130:131]
	s_mov_b32 m0, s69
	s_nop 0
	global_load_lds_dwordx4 v[196:197], off
	s_add_u32 s82, s52, 0x40000
	s_addc_u32 s83, s53, 0
	s_add_i32 s6, s6, s59
	v_lshl_add_u64 v[250:251], s[82:83], 0, v[140:141]
	s_mov_b32 m0, s6
	s_nop 0
	global_load_lds_dwordx4 v[250:251], off
	v_lshl_add_u64 v[250:251], s[82:83], 0, v[132:133]
	s_add_i32 m0, s6, 0x2000
	s_nop 0
	global_load_lds_dwordx4 v[250:251], off
	s_waitcnt vmcnt(8)
	s_waitcnt lgkmcnt(0)
	s_barrier
	v_mfma_f32_16x16x32_bf16 v[60:63], v[158:161], v[174:177], v[60:63]
	v_mfma_f32_16x16x32_bf16 v[56:59], v[166:169], v[174:177], v[56:59]
	v_mfma_f32_16x16x32_bf16 v[52:55], v[158:161], v[182:185], v[52:55]
	v_mfma_f32_16x16x32_bf16 v[48:51], v[166:169], v[182:185], v[48:51]
	v_mfma_f32_16x16x32_bf16 v[44:47], v[158:161], v[210:213], v[44:47]
	v_mfma_f32_16x16x32_bf16 v[40:43], v[166:169], v[210:213], v[40:43]
	v_mfma_f32_16x16x32_bf16 v[36:39], v[158:161], v[218:221], v[36:39]
	v_mfma_f32_16x16x32_bf16 v[32:35], v[166:169], v[218:221], v[32:35]
	v_mfma_f32_16x16x32_bf16 v[60:63], v[162:165], v[178:181], v[60:63]
	v_mfma_f32_16x16x32_bf16 v[56:59], v[170:173], v[178:181], v[56:59]
	v_mfma_f32_16x16x32_bf16 v[52:55], v[162:165], v[206:209], v[52:55]
	v_mfma_f32_16x16x32_bf16 v[48:51], v[170:173], v[206:209], v[48:51]
	v_mfma_f32_16x16x32_bf16 v[44:47], v[162:165], v[214:217], v[44:47]
	v_mfma_f32_16x16x32_bf16 v[40:43], v[170:173], v[214:217], v[40:43]
	v_mfma_f32_16x16x32_bf16 v[36:39], v[162:165], v[222:225], v[36:39]
	v_mfma_f32_16x16x32_bf16 v[32:35], v[170:173], v[222:225], v[32:35]
	v_mfma_f32_16x16x32_bf16 v[28:31], v[226:229], v[174:177], v[28:31]
	v_mfma_f32_16x16x32_bf16 v[24:27], v[234:237], v[174:177], v[24:27]
	v_mfma_f32_16x16x32_bf16 v[20:23], v[226:229], v[182:185], v[20:23]
	v_mfma_f32_16x16x32_bf16 v[16:19], v[234:237], v[182:185], v[16:19]
	v_mfma_f32_16x16x32_bf16 v[12:15], v[226:229], v[210:213], v[12:15]
	v_mfma_f32_16x16x32_bf16 v[8:11], v[234:237], v[210:213], v[8:11]
	v_mfma_f32_16x16x32_bf16 v[4:7], v[226:229], v[218:221], v[4:7]
	v_mfma_f32_16x16x32_bf16 v[0:3], v[234:237], v[218:221], v[0:3]
	v_mfma_f32_16x16x32_bf16 v[28:31], v[230:233], v[178:181], v[28:31]
	v_mfma_f32_16x16x32_bf16 v[24:27], v[238:241], v[178:181], v[24:27]
	v_mfma_f32_16x16x32_bf16 v[20:23], v[230:233], v[206:209], v[20:23]
	v_mfma_f32_16x16x32_bf16 v[16:19], v[238:241], v[206:209], v[16:19]
	v_mfma_f32_16x16x32_bf16 v[12:15], v[230:233], v[214:217], v[12:15]
	v_mfma_f32_16x16x32_bf16 v[8:11], v[238:241], v[214:217], v[8:11]
	v_mfma_f32_16x16x32_bf16 v[4:7], v[230:233], v[222:225], v[4:7]
	v_mfma_f32_16x16x32_bf16 v[0:3], v[238:241], v[222:225], v[0:3]
	s_barrier
	s_add_i32 s6, 0, 0x18000
	v_add_u32_e32 v170, s6, v154
	ds_read_b128 v[158:161], v170
	ds_read_b128 v[162:165], v170 offset:1024
	ds_read_b128 v[166:169], v170 offset:2048
	ds_read_b128 v[170:173], v170 offset:3072
	s_add_u32 s54, s54, 0x40000
	s_addc_u32 s55, s55, 0
	s_mov_b32 m0, s70
	v_lshl_add_u64 v[226:227], s[54:55], 0, v[128:129]
	ds_read_b128 v[174:177], v157 offset:32768
	ds_read_b128 v[178:181], v157 offset:33792
	ds_read_b128 v[182:185], v157 offset:34816
	ds_read_b128 v[206:209], v157 offset:35840
	ds_read_b128 v[210:213], v157 offset:36864
	ds_read_b128 v[214:217], v157 offset:37888
	ds_read_b128 v[218:221], v157 offset:38912
	ds_read_b128 v[222:225], v157 offset:39936
	global_load_lds_dwordx4 v[226:227], off
	v_lshl_add_u64 v[226:227], s[54:55], 0, v[130:131]
	s_mov_b32 m0, s71
	s_nop 0
	global_load_lds_dwordx4 v[226:227], off
	s_add_i32 s19, 0, 0x1c000
	v_add_u32_e32 v192, s19, v154
	ds_read_b128 v[226:229], v192
	ds_read_b128 v[230:233], v192 offset:1024
	ds_read_b128 v[234:237], v192 offset:2048
	ds_read_b128 v[238:241], v192 offset:3072
	s_waitcnt vmcnt(8)
	s_waitcnt lgkmcnt(0)
	s_barrier
	v_mfma_f32_16x16x32_bf16 v[124:127], v[158:161], v[174:177], v[124:127]
	v_mfma_f32_16x16x32_bf16 v[120:123], v[166:169], v[174:177], v[120:123]
	v_mfma_f32_16x16x32_bf16 v[116:119], v[158:161], v[182:185], v[116:119]
	v_mfma_f32_16x16x32_bf16 v[112:115], v[166:169], v[182:185], v[112:115]
	v_mfma_f32_16x16x32_bf16 v[108:111], v[158:161], v[210:213], v[108:111]
	v_mfma_f32_16x16x32_bf16 v[104:107], v[166:169], v[210:213], v[104:107]
	v_mfma_f32_16x16x32_bf16 v[100:103], v[158:161], v[218:221], v[100:103]
	v_mfma_f32_16x16x32_bf16 v[96:99], v[166:169], v[218:221], v[96:99]
	v_mfma_f32_16x16x32_bf16 v[124:127], v[162:165], v[178:181], v[124:127]
	v_mfma_f32_16x16x32_bf16 v[120:123], v[170:173], v[178:181], v[120:123]
	v_mfma_f32_16x16x32_bf16 v[116:119], v[162:165], v[206:209], v[116:119]
	v_mfma_f32_16x16x32_bf16 v[112:115], v[170:173], v[206:209], v[112:115]
	v_mfma_f32_16x16x32_bf16 v[108:111], v[162:165], v[214:217], v[108:111]
	v_mfma_f32_16x16x32_bf16 v[104:107], v[170:173], v[214:217], v[104:107]
	v_mfma_f32_16x16x32_bf16 v[100:103], v[162:165], v[222:225], v[100:103]
	v_mfma_f32_16x16x32_bf16 v[96:99], v[170:173], v[222:225], v[96:99]
	v_mfma_f32_16x16x32_bf16 v[92:95], v[226:229], v[174:177], v[92:95]
	v_mfma_f32_16x16x32_bf16 v[88:91], v[234:237], v[174:177], v[88:91]
	v_mfma_f32_16x16x32_bf16 v[84:87], v[226:229], v[182:185], v[84:87]
	v_mfma_f32_16x16x32_bf16 v[80:83], v[234:237], v[182:185], v[80:83]
	v_mfma_f32_16x16x32_bf16 v[76:79], v[226:229], v[210:213], v[76:79]
	v_mfma_f32_16x16x32_bf16 v[72:75], v[234:237], v[210:213], v[72:75]
	v_mfma_f32_16x16x32_bf16 v[68:71], v[226:229], v[218:221], v[68:71]
	v_mfma_f32_16x16x32_bf16 v[64:67], v[234:237], v[218:221], v[64:67]
	v_mfma_f32_16x16x32_bf16 v[92:95], v[230:233], v[178:181], v[92:95]
	v_mfma_f32_16x16x32_bf16 v[88:91], v[238:241], v[178:181], v[88:91]
	v_mfma_f32_16x16x32_bf16 v[84:87], v[230:233], v[206:209], v[84:87]
	v_mfma_f32_16x16x32_bf16 v[80:83], v[238:241], v[206:209], v[80:83]
	v_mfma_f32_16x16x32_bf16 v[76:79], v[230:233], v[214:217], v[76:79]
	v_mfma_f32_16x16x32_bf16 v[72:75], v[238:241], v[214:217], v[72:75]
	v_mfma_f32_16x16x32_bf16 v[68:71], v[230:233], v[222:225], v[68:71]
	v_mfma_f32_16x16x32_bf16 v[64:67], v[238:241], v[222:225], v[64:67]
	s_barrier
	s_add_i32 s6, s6, s59
	v_lshl_add_u64 v[146:147], v[146:147], 0, s[36:37]
	s_mov_b32 m0, s6
	s_nop 0
	global_load_lds_dwordx4 v[146:147], off
	v_lshl_add_u64 v[146:147], v[148:149], 0, s[36:37]
	s_add_i32 m0, s6, 0x2000
	s_nop 0
	global_load_lds_dwordx4 v[146:147], off
	s_mov_b32 m0, s72
	v_lshl_add_u64 v[146:147], v[194:195], 0, s[36:37]
	ds_read_b128 v[174:177], v157 offset:49152
	ds_read_b128 v[178:181], v157 offset:50176
	ds_read_b128 v[182:185], v157 offset:51200
	ds_read_b128 v[206:209], v157 offset:52224
	ds_read_b128 v[210:213], v157 offset:53248
	ds_read_b128 v[214:217], v157 offset:54272
	ds_read_b128 v[218:221], v157 offset:55296
	ds_read_b128 v[222:225], v157 offset:56320
	global_load_lds_dwordx4 v[146:147], off
	v_lshl_add_u64 v[146:147], v[196:197], 0, s[36:37]
	s_mov_b32 m0, s73
	s_nop 0
	global_load_lds_dwordx4 v[146:147], off
	s_add_u32 s52, s52, 0x40080
	s_addc_u32 s53, s53, 0
	s_add_i32 s6, s19, s59
	v_lshl_add_u64 v[146:147], s[52:53], 0, v[140:141]
	s_mov_b32 m0, s6
	s_nop 0
	global_load_lds_dwordx4 v[146:147], off
	v_lshl_add_u64 v[146:147], s[52:53], 0, v[132:133]
	s_add_i32 m0, s6, 0x2000
	s_nop 0
	global_load_lds_dwordx4 v[146:147], off
	s_add_i32 s81, s81, 2
	s_add_u32 s50, s50, 0x100
	s_addc_u32 s51, s51, 0
	s_cmp_gt_u32 s81, 13
	s_waitcnt vmcnt(8)
	s_waitcnt lgkmcnt(0)
	s_barrier
	v_mfma_f32_16x16x32_bf16 v[60:63], v[158:161], v[174:177], v[60:63]
	v_mfma_f32_16x16x32_bf16 v[56:59], v[166:169], v[174:177], v[56:59]
	v_mfma_f32_16x16x32_bf16 v[52:55], v[158:161], v[182:185], v[52:55]
	v_mfma_f32_16x16x32_bf16 v[48:51], v[166:169], v[182:185], v[48:51]
	v_mfma_f32_16x16x32_bf16 v[44:47], v[158:161], v[210:213], v[44:47]
	v_mfma_f32_16x16x32_bf16 v[40:43], v[166:169], v[210:213], v[40:43]
	v_mfma_f32_16x16x32_bf16 v[36:39], v[158:161], v[218:221], v[36:39]
	v_mfma_f32_16x16x32_bf16 v[32:35], v[166:169], v[218:221], v[32:35]
	v_mfma_f32_16x16x32_bf16 v[60:63], v[162:165], v[178:181], v[60:63]
	v_mfma_f32_16x16x32_bf16 v[56:59], v[170:173], v[178:181], v[56:59]
	v_mfma_f32_16x16x32_bf16 v[52:55], v[162:165], v[206:209], v[52:55]
	v_mfma_f32_16x16x32_bf16 v[48:51], v[170:173], v[206:209], v[48:51]
	v_mfma_f32_16x16x32_bf16 v[44:47], v[162:165], v[214:217], v[44:47]
	v_mfma_f32_16x16x32_bf16 v[40:43], v[170:173], v[214:217], v[40:43]
	v_mfma_f32_16x16x32_bf16 v[36:39], v[162:165], v[222:225], v[36:39]
	v_mfma_f32_16x16x32_bf16 v[32:35], v[170:173], v[222:225], v[32:35]
	v_mfma_f32_16x16x32_bf16 v[28:31], v[226:229], v[174:177], v[28:31]
	v_mfma_f32_16x16x32_bf16 v[24:27], v[234:237], v[174:177], v[24:27]
	v_mfma_f32_16x16x32_bf16 v[20:23], v[226:229], v[182:185], v[20:23]
	v_mfma_f32_16x16x32_bf16 v[16:19], v[234:237], v[182:185], v[16:19]
	v_mfma_f32_16x16x32_bf16 v[12:15], v[226:229], v[210:213], v[12:15]
	v_mfma_f32_16x16x32_bf16 v[8:11], v[234:237], v[210:213], v[8:11]
	v_mfma_f32_16x16x32_bf16 v[4:7], v[226:229], v[218:221], v[4:7]
	v_mfma_f32_16x16x32_bf16 v[0:3], v[234:237], v[218:221], v[0:3]
	v_mfma_f32_16x16x32_bf16 v[28:31], v[230:233], v[178:181], v[28:31]
	v_mfma_f32_16x16x32_bf16 v[24:27], v[238:241], v[178:181], v[24:27]
	v_mfma_f32_16x16x32_bf16 v[20:23], v[230:233], v[206:209], v[20:23]
	v_mfma_f32_16x16x32_bf16 v[16:19], v[238:241], v[206:209], v[16:19]
	v_mfma_f32_16x16x32_bf16 v[12:15], v[230:233], v[214:217], v[12:15]
	v_mfma_f32_16x16x32_bf16 v[8:11], v[238:241], v[214:217], v[8:11]
	v_mfma_f32_16x16x32_bf16 v[4:7], v[230:233], v[222:225], v[4:7]
	v_mfma_f32_16x16x32_bf16 v[0:3], v[238:241], v[222:225], v[0:3]
	s_barrier
	s_cbranch_scc0 .LBB0_77
	s_mov_b32 s100, 1
	v_lshl_add_u32 v158, s75, 10, v155
	ds_read2_b32 v[146:147], v158 offset1:16
	ds_read2_b32 v[208:209], v158 offset0:32 offset1:48
	ds_read2_b32 v[210:211], v158 offset0:128 offset1:144
	ds_read2_b32 v[212:213], v158 offset0:160 offset1:176
	s_add_u32 s50, s10, 0xffffff00
	s_addc_u32 s51, s11, -1
	s_ashr_i32 s31, s30, 31
	s_lshl_b64 s[10:11], s[30:31], 8
	s_waitcnt lgkmcnt(0)
	v_mul_f32_e32 v184, 0xbfb8aa3b, v146
	v_mul_f32_e32 v206, v146, v146
	v_pk_mul_f32 v[168:169], v[124:125], v[184:185] op_sel_hi:[1,0]
	v_pk_mul_f32 v[170:171], v[126:127], v[184:185] op_sel_hi:[1,0]
	v_pk_mul_f32 v[172:173], v[120:121], v[184:185] op_sel_hi:[1,0]
	v_pk_mul_f32 v[174:175], v[122:123], v[184:185] op_sel_hi:[1,0]
	v_exp_f32_e32 v168, v168
	v_exp_f32_e32 v169, v169
	v_exp_f32_e32 v170, v170
	v_exp_f32_e32 v171, v171
	v_exp_f32_e32 v172, v172
	v_exp_f32_e32 v173, v173
	v_exp_f32_e32 v174, v174
	v_exp_f32_e32 v175, v175
	v_pk_mul_f32 v[176:177], v[124:125], v[92:93]
	v_pk_mul_f32 v[178:179], v[126:127], v[94:95]
	v_pk_mul_f32 v[180:181], v[120:121], v[88:89]
	v_pk_mul_f32 v[182:183], v[122:123], v[90:91]
	v_pk_add_f32 v[168:169], v[168:169], 1.0 op_sel_hi:[1,0]
	v_pk_add_f32 v[170:171], v[170:171], 1.0 op_sel_hi:[1,0]
	v_pk_add_f32 v[172:173], v[172:173], 1.0 op_sel_hi:[1,0]
	v_pk_add_f32 v[174:175], v[174:175], 1.0 op_sel_hi:[1,0]
	v_rcp_f32_e32 v168, v168
	v_rcp_f32_e32 v169, v169
	v_rcp_f32_e32 v170, v170
	v_rcp_f32_e32 v171, v171
	v_rcp_f32_e32 v172, v172
	v_rcp_f32_e32 v173, v173
	v_rcp_f32_e32 v174, v174
	v_rcp_f32_e32 v175, v175
	v_pk_mul_f32 v[176:177], v[176:177], v[206:207] op_sel_hi:[1,0]
	v_pk_mul_f32 v[178:179], v[178:179], v[206:207] op_sel_hi:[1,0]
	v_pk_mul_f32 v[180:181], v[180:181], v[206:207] op_sel_hi:[1,0]
	v_pk_mul_f32 v[182:183], v[182:183], v[206:207] op_sel_hi:[1,0]
	v_pk_mul_f32 v[176:177], v[176:177], v[168:169]
	v_pk_mul_f32 v[178:179], v[178:179], v[170:171]
	v_pk_mul_f32 v[180:181], v[180:181], v[172:173]
	v_pk_mul_f32 v[182:183], v[182:183], v[174:175]
	v_cvt_pk_bf16_f32 v160, v176, v177
	v_cvt_pk_bf16_f32 v161, v178, v179
	v_cvt_pk_bf16_f32 v162, v180, v181
	v_cvt_pk_bf16_f32 v163, v182, v183
	v_lshl_add_u64 v[152:153], v[134:135], 0, s[10:11]
	s_movk_i32 s6, 0x1600
	v_lshl_or_b32 v150, s74, 7, v156
	v_ashrrev_i32_e32 v151, 31, v150
	s_nop 1
	v_mov_b64_e32 v[148:149], s[28:29]
	v_mad_u64_u32 v[148:149], s[10:11], v152, s6, v[148:149]
	v_mov_b32_e32 v146, v149
	v_mad_u64_u32 v[152:153], s[10:11], v153, s6, v[146:147]
	v_mov_b32_e32 v149, v152
	v_mov_b32_e32 v146, v147
	v_lshl_add_u64 v[150:151], v[150:151], 1, v[148:149]
	global_store_dwordx4 v[150:151], v[160:163], off
	v_mul_f32_e32 v184, 0xbfb8aa3b, v146
	v_mul_f32_e32 v206, v146, v146
	v_pk_mul_f32 v[168:169], v[116:117], v[184:185] op_sel_hi:[1,0]
	v_pk_mul_f32 v[170:171], v[118:119], v[184:185] op_sel_hi:[1,0]
	v_pk_mul_f32 v[172:173], v[112:113], v[184:185] op_sel_hi:[1,0]
	v_pk_mul_f32 v[174:175], v[114:115], v[184:185] op_sel_hi:[1,0]
	v_exp_f32_e32 v168, v168
	v_exp_f32_e32 v169, v169
	v_exp_f32_e32 v170, v170
	v_exp_f32_e32 v171, v171
	v_exp_f32_e32 v172, v172
	v_exp_f32_e32 v173, v173
	v_exp_f32_e32 v174, v174
	v_exp_f32_e32 v175, v175
	v_pk_mul_f32 v[176:177], v[116:117], v[84:85]
	v_pk_mul_f32 v[178:179], v[118:119], v[86:87]
	v_pk_mul_f32 v[180:181], v[112:113], v[80:81]
	v_pk_mul_f32 v[182:183], v[114:115], v[82:83]
	v_pk_add_f32 v[168:169], v[168:169], 1.0 op_sel_hi:[1,0]
	v_pk_add_f32 v[170:171], v[170:171], 1.0 op_sel_hi:[1,0]
	v_pk_add_f32 v[172:173], v[172:173], 1.0 op_sel_hi:[1,0]
	v_pk_add_f32 v[174:175], v[174:175], 1.0 op_sel_hi:[1,0]
	v_rcp_f32_e32 v168, v168
	v_rcp_f32_e32 v169, v169
	v_rcp_f32_e32 v170, v170
	v_rcp_f32_e32 v171, v171
	v_rcp_f32_e32 v172, v172
	v_rcp_f32_e32 v173, v173
	v_rcp_f32_e32 v174, v174
	v_rcp_f32_e32 v175, v175
	v_pk_mul_f32 v[176:177], v[176:177], v[206:207] op_sel_hi:[1,0]
	v_pk_mul_f32 v[178:179], v[178:179], v[206:207] op_sel_hi:[1,0]
	v_pk_mul_f32 v[180:181], v[180:181], v[206:207] op_sel_hi:[1,0]
	v_pk_mul_f32 v[182:183], v[182:183], v[206:207] op_sel_hi:[1,0]
	v_pk_mul_f32 v[176:177], v[176:177], v[168:169]
	v_pk_mul_f32 v[178:179], v[178:179], v[170:171]
	v_pk_mul_f32 v[180:181], v[180:181], v[172:173]
	v_pk_mul_f32 v[182:183], v[182:183], v[174:175]
	v_cvt_pk_bf16_f32 v160, v176, v177
	v_cvt_pk_bf16_f32 v161, v178, v179
	v_cvt_pk_bf16_f32 v162, v180, v181
	v_cvt_pk_bf16_f32 v163, v182, v183
	s_mov_b32 s6, 0x16000
	s_nop 1
	v_add_co_u32_e32 v146, vcc, s6, v150
	s_nop 0
	v_addc_co_u32_e32 v147, vcc, 0, v151, vcc
	global_store_dwordx4 v[146:147], v[160:163], off
	v_mov_b32_e32 v146, v208
	v_mov_b32_e32 v147, v209
	s_mov_b32 s6, 0x2c000
	s_waitcnt lgkmcnt(0)
	v_mul_f32_e32 v184, 0xbfb8aa3b, v146
	v_mul_f32_e32 v206, v146, v146
	v_pk_mul_f32 v[168:169], v[108:109], v[184:185] op_sel_hi:[1,0]
	v_pk_mul_f32 v[170:171], v[110:111], v[184:185] op_sel_hi:[1,0]
	v_pk_mul_f32 v[172:173], v[104:105], v[184:185] op_sel_hi:[1,0]
	v_pk_mul_f32 v[174:175], v[106:107], v[184:185] op_sel_hi:[1,0]
	v_exp_f32_e32 v168, v168
	v_exp_f32_e32 v169, v169
	v_exp_f32_e32 v170, v170
	v_exp_f32_e32 v171, v171
	v_exp_f32_e32 v172, v172
	v_exp_f32_e32 v173, v173
	v_exp_f32_e32 v174, v174
	v_exp_f32_e32 v175, v175
	v_pk_mul_f32 v[176:177], v[108:109], v[76:77]
	v_pk_mul_f32 v[178:179], v[110:111], v[78:79]
	v_pk_mul_f32 v[180:181], v[104:105], v[72:73]
	v_pk_mul_f32 v[182:183], v[106:107], v[74:75]
	v_pk_add_f32 v[168:169], v[168:169], 1.0 op_sel_hi:[1,0]
	v_pk_add_f32 v[170:171], v[170:171], 1.0 op_sel_hi:[1,0]
	v_pk_add_f32 v[172:173], v[172:173], 1.0 op_sel_hi:[1,0]
	v_pk_add_f32 v[174:175], v[174:175], 1.0 op_sel_hi:[1,0]
	v_rcp_f32_e32 v168, v168
	v_rcp_f32_e32 v169, v169
	v_rcp_f32_e32 v170, v170
	v_rcp_f32_e32 v171, v171
	v_rcp_f32_e32 v172, v172
	v_rcp_f32_e32 v173, v173
	v_rcp_f32_e32 v174, v174
	v_rcp_f32_e32 v175, v175
	v_pk_mul_f32 v[176:177], v[176:177], v[206:207] op_sel_hi:[1,0]
	v_pk_mul_f32 v[178:179], v[178:179], v[206:207] op_sel_hi:[1,0]
	v_pk_mul_f32 v[180:181], v[180:181], v[206:207] op_sel_hi:[1,0]
	v_pk_mul_f32 v[182:183], v[182:183], v[206:207] op_sel_hi:[1,0]
	v_pk_mul_f32 v[176:177], v[176:177], v[168:169]
	v_pk_mul_f32 v[178:179], v[178:179], v[170:171]
	v_pk_mul_f32 v[180:181], v[180:181], v[172:173]
	v_pk_mul_f32 v[182:183], v[182:183], v[174:175]
	v_cvt_pk_bf16_f32 v160, v176, v177
	v_cvt_pk_bf16_f32 v161, v178, v179
	v_cvt_pk_bf16_f32 v162, v180, v181
	v_cvt_pk_bf16_f32 v163, v182, v183
	s_nop 1
	v_mov_b32_e32 v146, v147
	v_add_co_u32_e32 v148, vcc, s6, v150
	v_addc_co_u32_e32 v149, vcc, 0, v151, vcc
	global_store_dwordx4 v[148:149], v[160:163], off
	v_mul_f32_e32 v184, 0xbfb8aa3b, v146
	v_mul_f32_e32 v206, v146, v146
	v_pk_mul_f32 v[168:169], v[100:101], v[184:185] op_sel_hi:[1,0]
	v_pk_mul_f32 v[170:171], v[102:103], v[184:185] op_sel_hi:[1,0]
	v_pk_mul_f32 v[172:173], v[96:97], v[184:185] op_sel_hi:[1,0]
	v_pk_mul_f32 v[174:175], v[98:99], v[184:185] op_sel_hi:[1,0]
	v_exp_f32_e32 v168, v168
	v_exp_f32_e32 v169, v169
	v_exp_f32_e32 v170, v170
	v_exp_f32_e32 v171, v171
	v_exp_f32_e32 v172, v172
	v_exp_f32_e32 v173, v173
	v_exp_f32_e32 v174, v174
	v_exp_f32_e32 v175, v175
	v_pk_mul_f32 v[176:177], v[100:101], v[68:69]
	v_pk_mul_f32 v[178:179], v[102:103], v[70:71]
	v_pk_mul_f32 v[180:181], v[96:97], v[64:65]
	v_pk_mul_f32 v[182:183], v[98:99], v[66:67]
	v_pk_add_f32 v[168:169], v[168:169], 1.0 op_sel_hi:[1,0]
	v_pk_add_f32 v[170:171], v[170:171], 1.0 op_sel_hi:[1,0]
	v_pk_add_f32 v[172:173], v[172:173], 1.0 op_sel_hi:[1,0]
	v_pk_add_f32 v[174:175], v[174:175], 1.0 op_sel_hi:[1,0]
	v_rcp_f32_e32 v168, v168
	v_rcp_f32_e32 v169, v169
	v_rcp_f32_e32 v170, v170
	v_rcp_f32_e32 v171, v171
	v_rcp_f32_e32 v172, v172
	v_rcp_f32_e32 v173, v173
	v_rcp_f32_e32 v174, v174
	v_rcp_f32_e32 v175, v175
	v_pk_mul_f32 v[176:177], v[176:177], v[206:207] op_sel_hi:[1,0]
	v_pk_mul_f32 v[178:179], v[178:179], v[206:207] op_sel_hi:[1,0]
	v_pk_mul_f32 v[180:181], v[180:181], v[206:207] op_sel_hi:[1,0]
	v_pk_mul_f32 v[182:183], v[182:183], v[206:207] op_sel_hi:[1,0]
	v_pk_mul_f32 v[176:177], v[176:177], v[168:169]
	v_pk_mul_f32 v[178:179], v[178:179], v[170:171]
	v_pk_mul_f32 v[180:181], v[180:181], v[172:173]
	v_pk_mul_f32 v[182:183], v[182:183], v[174:175]
	v_cvt_pk_bf16_f32 v160, v176, v177
	v_cvt_pk_bf16_f32 v161, v178, v179
	v_cvt_pk_bf16_f32 v162, v180, v181
	v_cvt_pk_bf16_f32 v163, v182, v183
	s_mov_b32 s6, 0x42000
	s_nop 1
	v_add_co_u32_e32 v146, vcc, s6, v150
	s_nop 0
	v_addc_co_u32_e32 v147, vcc, 0, v151, vcc
	global_store_dwordx4 v[146:147], v[160:163], off
	v_mov_b32_e32 v146, v210
	v_mov_b32_e32 v147, v211
	s_mov_b32 s6, 0xb0000
	s_waitcnt lgkmcnt(0)
	v_mul_f32_e32 v184, 0xbfb8aa3b, v146
	v_mul_f32_e32 v206, v146, v146
	v_pk_mul_f32 v[168:169], v[60:61], v[184:185] op_sel_hi:[1,0]
	v_pk_mul_f32 v[170:171], v[62:63], v[184:185] op_sel_hi:[1,0]
	v_pk_mul_f32 v[172:173], v[56:57], v[184:185] op_sel_hi:[1,0]
	v_pk_mul_f32 v[174:175], v[58:59], v[184:185] op_sel_hi:[1,0]
	v_exp_f32_e32 v168, v168
	v_exp_f32_e32 v169, v169
	v_exp_f32_e32 v170, v170
	v_exp_f32_e32 v171, v171
	v_exp_f32_e32 v172, v172
	v_exp_f32_e32 v173, v173
	v_exp_f32_e32 v174, v174
	v_exp_f32_e32 v175, v175
	v_pk_mul_f32 v[176:177], v[60:61], v[28:29]
	v_pk_mul_f32 v[178:179], v[62:63], v[30:31]
	v_pk_mul_f32 v[180:181], v[56:57], v[24:25]
	v_pk_mul_f32 v[182:183], v[58:59], v[26:27]
	v_pk_add_f32 v[168:169], v[168:169], 1.0 op_sel_hi:[1,0]
	v_pk_add_f32 v[170:171], v[170:171], 1.0 op_sel_hi:[1,0]
	v_pk_add_f32 v[172:173], v[172:173], 1.0 op_sel_hi:[1,0]
	v_pk_add_f32 v[174:175], v[174:175], 1.0 op_sel_hi:[1,0]
	v_rcp_f32_e32 v168, v168
	v_rcp_f32_e32 v169, v169
	v_rcp_f32_e32 v170, v170
	v_rcp_f32_e32 v171, v171
	v_rcp_f32_e32 v172, v172
	v_rcp_f32_e32 v173, v173
	v_rcp_f32_e32 v174, v174
	v_rcp_f32_e32 v175, v175
	v_pk_mul_f32 v[176:177], v[176:177], v[206:207] op_sel_hi:[1,0]
	v_pk_mul_f32 v[178:179], v[178:179], v[206:207] op_sel_hi:[1,0]
	v_pk_mul_f32 v[180:181], v[180:181], v[206:207] op_sel_hi:[1,0]
	v_pk_mul_f32 v[182:183], v[182:183], v[206:207] op_sel_hi:[1,0]
	v_pk_mul_f32 v[176:177], v[176:177], v[168:169]
	v_pk_mul_f32 v[178:179], v[178:179], v[170:171]
	v_pk_mul_f32 v[180:181], v[180:181], v[172:173]
	v_pk_mul_f32 v[182:183], v[182:183], v[174:175]
	v_cvt_pk_bf16_f32 v160, v176, v177
	v_cvt_pk_bf16_f32 v161, v178, v179
	v_cvt_pk_bf16_f32 v162, v180, v181
	v_cvt_pk_bf16_f32 v163, v182, v183
	s_nop 1
	v_mov_b32_e32 v146, v147
	v_add_co_u32_e32 v148, vcc, s6, v150
	v_addc_co_u32_e32 v149, vcc, 0, v151, vcc
	global_store_dwordx4 v[148:149], v[160:163], off
	v_mul_f32_e32 v184, 0xbfb8aa3b, v146
	v_mul_f32_e32 v206, v146, v146
	v_pk_mul_f32 v[168:169], v[52:53], v[184:185] op_sel_hi:[1,0]
	v_pk_mul_f32 v[170:171], v[54:55], v[184:185] op_sel_hi:[1,0]
	v_pk_mul_f32 v[172:173], v[48:49], v[184:185] op_sel_hi:[1,0]
	v_pk_mul_f32 v[174:175], v[50:51], v[184:185] op_sel_hi:[1,0]
	v_exp_f32_e32 v168, v168
	v_exp_f32_e32 v169, v169
	v_exp_f32_e32 v170, v170
	v_exp_f32_e32 v171, v171
	v_exp_f32_e32 v172, v172
	v_exp_f32_e32 v173, v173
	v_exp_f32_e32 v174, v174
	v_exp_f32_e32 v175, v175
	v_pk_mul_f32 v[176:177], v[52:53], v[20:21]
	v_pk_mul_f32 v[178:179], v[54:55], v[22:23]
	v_pk_mul_f32 v[180:181], v[48:49], v[16:17]
	v_pk_mul_f32 v[182:183], v[50:51], v[18:19]
	v_pk_add_f32 v[168:169], v[168:169], 1.0 op_sel_hi:[1,0]
	v_pk_add_f32 v[170:171], v[170:171], 1.0 op_sel_hi:[1,0]
	v_pk_add_f32 v[172:173], v[172:173], 1.0 op_sel_hi:[1,0]
	v_pk_add_f32 v[174:175], v[174:175], 1.0 op_sel_hi:[1,0]
	v_rcp_f32_e32 v168, v168
	v_rcp_f32_e32 v169, v169
	v_rcp_f32_e32 v170, v170
	v_rcp_f32_e32 v171, v171
	v_rcp_f32_e32 v172, v172
	v_rcp_f32_e32 v173, v173
	v_rcp_f32_e32 v174, v174
	v_rcp_f32_e32 v175, v175
	v_pk_mul_f32 v[176:177], v[176:177], v[206:207] op_sel_hi:[1,0]
	v_pk_mul_f32 v[178:179], v[178:179], v[206:207] op_sel_hi:[1,0]
	v_pk_mul_f32 v[180:181], v[180:181], v[206:207] op_sel_hi:[1,0]
	v_pk_mul_f32 v[182:183], v[182:183], v[206:207] op_sel_hi:[1,0]
	v_pk_mul_f32 v[176:177], v[176:177], v[168:169]
	v_pk_mul_f32 v[178:179], v[178:179], v[170:171]
	v_pk_mul_f32 v[180:181], v[180:181], v[172:173]
	v_pk_mul_f32 v[182:183], v[182:183], v[174:175]
	v_cvt_pk_bf16_f32 v160, v176, v177
	v_cvt_pk_bf16_f32 v161, v178, v179
	v_cvt_pk_bf16_f32 v162, v180, v181
	v_cvt_pk_bf16_f32 v163, v182, v183
	s_mov_b32 s6, 0xc6000
	s_nop 1
	v_add_co_u32_e32 v146, vcc, s6, v150
	s_nop 0
	v_addc_co_u32_e32 v147, vcc, 0, v151, vcc
	global_store_dwordx4 v[146:147], v[160:163], off
	v_mov_b32_e32 v146, v212
	v_mov_b32_e32 v147, v213
	s_mov_b32 s6, 0xdc000
	s_waitcnt lgkmcnt(0)
	v_mul_f32_e32 v184, 0xbfb8aa3b, v146
	v_mul_f32_e32 v206, v146, v146
	v_pk_mul_f32 v[168:169], v[44:45], v[184:185] op_sel_hi:[1,0]
	v_pk_mul_f32 v[170:171], v[46:47], v[184:185] op_sel_hi:[1,0]
	v_pk_mul_f32 v[172:173], v[40:41], v[184:185] op_sel_hi:[1,0]
	v_pk_mul_f32 v[174:175], v[42:43], v[184:185] op_sel_hi:[1,0]
	v_exp_f32_e32 v168, v168
	v_exp_f32_e32 v169, v169
	v_exp_f32_e32 v170, v170
	v_exp_f32_e32 v171, v171
	v_exp_f32_e32 v172, v172
	v_exp_f32_e32 v173, v173
	v_exp_f32_e32 v174, v174
	v_exp_f32_e32 v175, v175
	v_pk_mul_f32 v[176:177], v[44:45], v[12:13]
	v_pk_mul_f32 v[178:179], v[46:47], v[14:15]
	v_pk_mul_f32 v[180:181], v[40:41], v[8:9]
	v_pk_mul_f32 v[182:183], v[42:43], v[10:11]
	v_pk_add_f32 v[168:169], v[168:169], 1.0 op_sel_hi:[1,0]
	v_pk_add_f32 v[170:171], v[170:171], 1.0 op_sel_hi:[1,0]
	v_pk_add_f32 v[172:173], v[172:173], 1.0 op_sel_hi:[1,0]
	v_pk_add_f32 v[174:175], v[174:175], 1.0 op_sel_hi:[1,0]
	v_rcp_f32_e32 v168, v168
	v_rcp_f32_e32 v169, v169
	v_rcp_f32_e32 v170, v170
	v_rcp_f32_e32 v171, v171
	v_rcp_f32_e32 v172, v172
	v_rcp_f32_e32 v173, v173
	v_rcp_f32_e32 v174, v174
	v_rcp_f32_e32 v175, v175
	v_pk_mul_f32 v[176:177], v[176:177], v[206:207] op_sel_hi:[1,0]
	v_pk_mul_f32 v[178:179], v[178:179], v[206:207] op_sel_hi:[1,0]
	v_pk_mul_f32 v[180:181], v[180:181], v[206:207] op_sel_hi:[1,0]
	v_pk_mul_f32 v[182:183], v[182:183], v[206:207] op_sel_hi:[1,0]
	v_pk_mul_f32 v[176:177], v[176:177], v[168:169]
	v_pk_mul_f32 v[178:179], v[178:179], v[170:171]
	v_pk_mul_f32 v[180:181], v[180:181], v[172:173]
	v_pk_mul_f32 v[182:183], v[182:183], v[174:175]
	v_cvt_pk_bf16_f32 v158, v176, v177
	v_cvt_pk_bf16_f32 v159, v178, v179
	v_cvt_pk_bf16_f32 v160, v180, v181
	v_cvt_pk_bf16_f32 v161, v182, v183
	s_nop 1
	v_mov_b32_e32 v146, v147
	v_add_co_u32_e32 v148, vcc, s6, v150
	v_addc_co_u32_e32 v149, vcc, 0, v151, vcc
	global_store_dwordx4 v[148:149], v[158:161], off
	v_mul_f32_e32 v184, 0xbfb8aa3b, v146
	v_mul_f32_e32 v206, v146, v146
	v_pk_mul_f32 v[168:169], v[36:37], v[184:185] op_sel_hi:[1,0]
	v_pk_mul_f32 v[170:171], v[38:39], v[184:185] op_sel_hi:[1,0]
	v_pk_mul_f32 v[172:173], v[32:33], v[184:185] op_sel_hi:[1,0]
	v_pk_mul_f32 v[174:175], v[34:35], v[184:185] op_sel_hi:[1,0]
	v_exp_f32_e32 v168, v168
	v_exp_f32_e32 v169, v169
	v_exp_f32_e32 v170, v170
	v_exp_f32_e32 v171, v171
	v_exp_f32_e32 v172, v172
	v_exp_f32_e32 v173, v173
	v_exp_f32_e32 v174, v174
	v_exp_f32_e32 v175, v175
	v_pk_mul_f32 v[176:177], v[36:37], v[4:5]
	v_pk_mul_f32 v[178:179], v[38:39], v[6:7]
	v_pk_mul_f32 v[180:181], v[32:33], v[0:1]
	v_pk_mul_f32 v[182:183], v[34:35], v[2:3]
	v_pk_add_f32 v[168:169], v[168:169], 1.0 op_sel_hi:[1,0]
	v_pk_add_f32 v[170:171], v[170:171], 1.0 op_sel_hi:[1,0]
	v_pk_add_f32 v[172:173], v[172:173], 1.0 op_sel_hi:[1,0]
	v_pk_add_f32 v[174:175], v[174:175], 1.0 op_sel_hi:[1,0]
	v_rcp_f32_e32 v168, v168
	v_rcp_f32_e32 v169, v169
	v_rcp_f32_e32 v170, v170
	v_rcp_f32_e32 v171, v171
	v_rcp_f32_e32 v172, v172
	v_rcp_f32_e32 v173, v173
	v_rcp_f32_e32 v174, v174
	v_rcp_f32_e32 v175, v175
	v_pk_mul_f32 v[176:177], v[176:177], v[206:207] op_sel_hi:[1,0]
	v_pk_mul_f32 v[178:179], v[178:179], v[206:207] op_sel_hi:[1,0]
	v_pk_mul_f32 v[180:181], v[180:181], v[206:207] op_sel_hi:[1,0]
	v_pk_mul_f32 v[182:183], v[182:183], v[206:207] op_sel_hi:[1,0]
	v_pk_mul_f32 v[176:177], v[176:177], v[168:169]
	v_pk_mul_f32 v[178:179], v[178:179], v[170:171]
	v_pk_mul_f32 v[180:181], v[180:181], v[172:173]
	v_pk_mul_f32 v[182:183], v[182:183], v[174:175]
	v_cvt_pk_bf16_f32 v158, v176, v177
	v_cvt_pk_bf16_f32 v159, v178, v179
	v_cvt_pk_bf16_f32 v160, v180, v181
	v_cvt_pk_bf16_f32 v161, v182, v183
	s_nop 1
	v_add_co_u32_e32 v146, vcc, 0xf2000, v150
	s_nop 0
	v_addc_co_u32_e32 v147, vcc, 0, v151, vcc
	s_andn2_b64 vcc, exec, s[44:45]
	global_store_dwordx4 v[146:147], v[158:161], off
	s_cbranch_vccz .LBB0_73
	s_mov_b64 s[46:47], s[50:51]
	s_andn2_b64 vcc, exec, s[42:43]
	s_mov_b64 s[50:51], s[46:47]
	s_cbranch_vccnz .LBB0_74

.Lm4bp_103:
	s_waitcnt lgkmcnt(0)
	s_mov_b32 s100, 0
	s_barrier
	v_mfma_f32_16x16x32_bf16 v[60:63], v[128:131], v[162:165], 0
	v_mfma_f32_16x16x32_bf16 v[56:59], v[136:139], v[162:165], 0
	v_mfma_f32_16x16x32_bf16 v[48:51], v[128:131], v[170:173], 0
	v_mfma_f32_16x16x32_bf16 v[40:43], v[136:139], v[170:173], 0
	v_mfma_f32_16x16x32_bf16 v[32:35], v[128:131], v[178:181], 0
	v_mfma_f32_16x16x32_bf16 v[24:27], v[136:139], v[178:181], 0
	v_mfma_f32_16x16x32_bf16 v[16:19], v[128:131], v[194:197], 0
	v_mfma_f32_16x16x32_bf16 v[8:11], v[136:139], v[194:197], 0
	v_mfma_f32_16x16x32_bf16 v[60:63], v[132:135], v[166:169], v[60:63]
	v_mfma_f32_16x16x32_bf16 v[56:59], v[146:149], v[166:169], v[56:59]
	v_mfma_f32_16x16x32_bf16 v[48:51], v[132:135], v[174:177], v[48:51]
	v_mfma_f32_16x16x32_bf16 v[40:43], v[146:149], v[174:177], v[40:43]
	v_mfma_f32_16x16x32_bf16 v[32:35], v[132:135], v[182:185], v[32:35]
	v_mfma_f32_16x16x32_bf16 v[24:27], v[146:149], v[182:185], v[24:27]
	v_mfma_f32_16x16x32_bf16 v[16:19], v[132:135], v[210:213], v[16:19]
	v_mfma_f32_16x16x32_bf16 v[8:11], v[146:149], v[210:213], v[8:11]
	v_mfma_f32_16x16x32_bf16 v[52:55], v[214:217], v[162:165], 0
	v_mfma_f32_16x16x32_bf16 v[44:47], v[222:225], v[162:165], 0
	v_mfma_f32_16x16x32_bf16 v[36:39], v[214:217], v[170:173], 0
	v_mfma_f32_16x16x32_bf16 v[28:31], v[222:225], v[170:173], 0
	v_mfma_f32_16x16x32_bf16 v[20:23], v[214:217], v[178:181], 0
	v_mfma_f32_16x16x32_bf16 v[12:15], v[222:225], v[178:181], 0
	v_mfma_f32_16x16x32_bf16 v[4:7], v[214:217], v[194:197], 0
	v_mfma_f32_16x16x32_bf16 v[0:3], v[222:225], v[194:197], 0
	v_mfma_f32_16x16x32_bf16 v[52:55], v[218:221], v[166:169], v[52:55]
	v_mfma_f32_16x16x32_bf16 v[44:47], v[226:229], v[166:169], v[44:47]
	v_mfma_f32_16x16x32_bf16 v[36:39], v[218:221], v[174:177], v[36:39]
	v_mfma_f32_16x16x32_bf16 v[28:31], v[226:229], v[174:177], v[28:31]
	v_mfma_f32_16x16x32_bf16 v[20:23], v[218:221], v[182:185], v[20:23]
	v_mfma_f32_16x16x32_bf16 v[12:15], v[226:229], v[182:185], v[12:15]
	v_mfma_f32_16x16x32_bf16 v[4:7], v[218:221], v[210:213], v[4:7]
	v_mfma_f32_16x16x32_bf16 v[0:3], v[226:229], v[210:213], v[0:3]
	s_barrier
	s_add_i32 s6, 0, 0x18000
	v_add_u32_e32 v146, s6, v206
	ds_read_b128 v[128:131], v146
	ds_read_b128 v[132:135], v146 offset:1024
	ds_read_b128 v[136:139], v146 offset:2048
	ds_read_b128 v[146:149], v146 offset:3072
	s_add_u32 s68, s68, 0x40000
	s_addc_u32 s69, s69, 0
	s_mov_b32 m0, s74
	v_lshl_add_u64 v[214:215], s[68:69], 0, v[154:155]
	ds_read_b128 v[162:165], v208 offset:32768
	ds_read_b128 v[166:169], v208 offset:33792
	ds_read_b128 v[170:173], v208 offset:34816
	ds_read_b128 v[174:177], v208 offset:35840
	ds_read_b128 v[178:181], v208 offset:36864
	ds_read_b128 v[182:185], v208 offset:37888
	ds_read_b128 v[194:197], v208 offset:38912
	ds_read_b128 v[210:213], v208 offset:39936
	global_load_lds_dwordx4 v[214:215], off
	v_lshl_add_u64 v[214:215], s[68:69], 0, v[152:153]
	s_mov_b32 m0, s75
	s_nop 0
	global_load_lds_dwordx4 v[214:215], off
	s_add_i32 s19, 0, 0x1c000
	v_add_u32_e32 v209, s19, v206
	ds_read_b128 v[214:217], v209
	ds_read_b128 v[218:221], v209 offset:1024
	ds_read_b128 v[222:225], v209 offset:2048
	ds_read_b128 v[226:229], v209 offset:3072
	s_waitcnt vmcnt(8)
	s_waitcnt lgkmcnt(0)
	s_barrier
	v_mfma_f32_16x16x32_bf16 v[124:127], v[128:131], v[162:165], v[124:127]
	v_mfma_f32_16x16x32_bf16 v[120:123], v[136:139], v[162:165], v[120:123]
	v_mfma_f32_16x16x32_bf16 v[108:111], v[128:131], v[170:173], v[108:111]
	v_mfma_f32_16x16x32_bf16 v[104:107], v[136:139], v[170:173], v[104:107]
	v_mfma_f32_16x16x32_bf16 v[96:99], v[128:131], v[178:181], v[96:99]
	v_mfma_f32_16x16x32_bf16 v[88:91], v[136:139], v[178:181], v[88:91]
	v_mfma_f32_16x16x32_bf16 v[84:87], v[128:131], v[194:197], v[84:87]
	v_mfma_f32_16x16x32_bf16 v[80:83], v[136:139], v[194:197], v[80:83]
	v_mfma_f32_16x16x32_bf16 v[124:127], v[132:135], v[166:169], v[124:127]
	v_mfma_f32_16x16x32_bf16 v[120:123], v[146:149], v[166:169], v[120:123]
	v_mfma_f32_16x16x32_bf16 v[108:111], v[132:135], v[174:177], v[108:111]
	v_mfma_f32_16x16x32_bf16 v[104:107], v[146:149], v[174:177], v[104:107]
	v_mfma_f32_16x16x32_bf16 v[96:99], v[132:135], v[182:185], v[96:99]
	v_mfma_f32_16x16x32_bf16 v[88:91], v[146:149], v[182:185], v[88:91]
	v_mfma_f32_16x16x32_bf16 v[84:87], v[132:135], v[210:213], v[84:87]
	v_mfma_f32_16x16x32_bf16 v[80:83], v[146:149], v[210:213], v[80:83]
	v_mfma_f32_16x16x32_bf16 v[116:119], v[214:217], v[162:165], v[116:119]
	v_mfma_f32_16x16x32_bf16 v[112:115], v[222:225], v[162:165], v[112:115]
	v_mfma_f32_16x16x32_bf16 v[100:103], v[214:217], v[170:173], v[100:103]
	v_mfma_f32_16x16x32_bf16 v[92:95], v[222:225], v[170:173], v[92:95]
	v_mfma_f32_16x16x32_bf16 v[76:79], v[214:217], v[178:181], v[76:79]
	v_mfma_f32_16x16x32_bf16 v[72:75], v[222:225], v[178:181], v[72:75]
	v_mfma_f32_16x16x32_bf16 v[68:71], v[214:217], v[194:197], v[68:71]
	v_mfma_f32_16x16x32_bf16 v[64:67], v[222:225], v[194:197], v[64:67]
	v_mfma_f32_16x16x32_bf16 v[116:119], v[218:221], v[166:169], v[116:119]
	v_mfma_f32_16x16x32_bf16 v[112:115], v[226:229], v[166:169], v[112:115]
	v_mfma_f32_16x16x32_bf16 v[100:103], v[218:221], v[174:177], v[100:103]
	v_mfma_f32_16x16x32_bf16 v[92:95], v[226:229], v[174:177], v[92:95]
	v_mfma_f32_16x16x32_bf16 v[76:79], v[218:221], v[182:185], v[76:79]
	v_mfma_f32_16x16x32_bf16 v[72:75], v[226:229], v[182:185], v[72:75]
	v_mfma_f32_16x16x32_bf16 v[68:71], v[218:221], v[210:213], v[68:71]
	v_mfma_f32_16x16x32_bf16 v[64:67], v[226:229], v[210:213], v[64:67]
	s_barrier
	s_add_i32 s6, s6, s71
	v_lshl_add_u64 v[192:193], v[192:193], 0, s[36:37]
	s_mov_b32 m0, s6
	s_nop 0
	global_load_lds_dwordx4 v[192:193], off
	v_lshl_add_u64 v[192:193], v[230:231], 0, s[36:37]
	s_add_i32 m0, s6, 0x2000
	s_nop 0
	global_load_lds_dwordx4 v[192:193], off
	s_mov_b32 m0, s80
	v_lshl_add_u64 v[192:193], v[232:233], 0, s[36:37]
	ds_read_b128 v[162:165], v208 offset:49152
	ds_read_b128 v[166:169], v208 offset:50176
	ds_read_b128 v[170:173], v208 offset:51200
	ds_read_b128 v[174:177], v208 offset:52224
	ds_read_b128 v[178:181], v208 offset:53248
	ds_read_b128 v[182:185], v208 offset:54272
	ds_read_b128 v[194:197], v208 offset:55296
	ds_read_b128 v[210:213], v208 offset:56320
	global_load_lds_dwordx4 v[192:193], off
	v_lshl_add_u64 v[192:193], v[234:235], 0, s[36:37]
	s_mov_b32 m0, s81
	s_nop 0
	global_load_lds_dwordx4 v[192:193], off
	s_add_u32 s58, s58, 0x40080
	s_addc_u32 s59, s59, 0
	s_add_i32 s6, s19, s71
	v_lshl_add_u64 v[250:251], s[58:59], 0, v[140:141]
	s_mov_b32 m0, s6
	s_nop 0
	global_load_lds_dwordx4 v[250:251], off
	v_lshl_add_u64 v[250:251], s[58:59], 0, v[150:151]
	s_add_i32 m0, s6, 0x2000
	s_nop 0
	global_load_lds_dwordx4 v[250:251], off
	s_add_i32 s12, s12, 2
	s_add_u32 s54, s54, 0x100
	s_addc_u32 s55, s55, 0
	s_add_u32 s10, s10, 0x100
	s_addc_u32 s11, s11, 0
	s_cmp_gt_u32 s12, 13
	s_waitcnt vmcnt(8)
	s_waitcnt lgkmcnt(0)
	s_barrier
	v_mfma_f32_16x16x32_bf16 v[60:63], v[128:131], v[162:165], v[60:63]
	v_mfma_f32_16x16x32_bf16 v[56:59], v[136:139], v[162:165], v[56:59]
	v_mfma_f32_16x16x32_bf16 v[48:51], v[128:131], v[170:173], v[48:51]
	v_mfma_f32_16x16x32_bf16 v[40:43], v[136:139], v[170:173], v[40:43]
	v_mfma_f32_16x16x32_bf16 v[32:35], v[128:131], v[178:181], v[32:35]
	v_mfma_f32_16x16x32_bf16 v[24:27], v[136:139], v[178:181], v[24:27]
	v_mfma_f32_16x16x32_bf16 v[16:19], v[128:131], v[194:197], v[16:19]
	v_mfma_f32_16x16x32_bf16 v[8:11], v[136:139], v[194:197], v[8:11]
	v_mfma_f32_16x16x32_bf16 v[60:63], v[132:135], v[166:169], v[60:63]
	v_mfma_f32_16x16x32_bf16 v[56:59], v[146:149], v[166:169], v[56:59]
	v_mfma_f32_16x16x32_bf16 v[48:51], v[132:135], v[174:177], v[48:51]
	v_mfma_f32_16x16x32_bf16 v[40:43], v[146:149], v[174:177], v[40:43]
	v_mfma_f32_16x16x32_bf16 v[32:35], v[132:135], v[182:185], v[32:35]
	v_mfma_f32_16x16x32_bf16 v[24:27], v[146:149], v[182:185], v[24:27]
	v_mfma_f32_16x16x32_bf16 v[16:19], v[132:135], v[210:213], v[16:19]
	v_mfma_f32_16x16x32_bf16 v[8:11], v[146:149], v[210:213], v[8:11]
	v_mfma_f32_16x16x32_bf16 v[52:55], v[214:217], v[162:165], v[52:55]
	v_mfma_f32_16x16x32_bf16 v[44:47], v[222:225], v[162:165], v[44:47]
	v_mfma_f32_16x16x32_bf16 v[36:39], v[214:217], v[170:173], v[36:39]
	v_mfma_f32_16x16x32_bf16 v[28:31], v[222:225], v[170:173], v[28:31]
	v_mfma_f32_16x16x32_bf16 v[20:23], v[214:217], v[178:181], v[20:23]
	v_mfma_f32_16x16x32_bf16 v[12:15], v[222:225], v[178:181], v[12:15]
	v_mfma_f32_16x16x32_bf16 v[4:7], v[214:217], v[194:197], v[4:7]
	v_mfma_f32_16x16x32_bf16 v[0:3], v[222:225], v[194:197], v[0:3]
	v_mfma_f32_16x16x32_bf16 v[52:55], v[218:221], v[166:169], v[52:55]
	v_mfma_f32_16x16x32_bf16 v[44:47], v[226:229], v[166:169], v[44:47]
	v_mfma_f32_16x16x32_bf16 v[36:39], v[218:221], v[174:177], v[36:39]
	v_mfma_f32_16x16x32_bf16 v[28:31], v[226:229], v[174:177], v[28:31]
	v_mfma_f32_16x16x32_bf16 v[20:23], v[218:221], v[182:185], v[20:23]
	v_mfma_f32_16x16x32_bf16 v[12:15], v[226:229], v[182:185], v[12:15]
	v_mfma_f32_16x16x32_bf16 v[4:7], v[218:221], v[210:213], v[4:7]
	v_mfma_f32_16x16x32_bf16 v[0:3], v[226:229], v[210:213], v[0:3]
	s_barrier
.LBB0_103:
	s_add_u32 s6, s54, 0xfffc0080
	s_addc_u32 s19, s55, -1
	s_add_i32 s23, 0, 0x10000
	v_add_u32_e32 v146, s23, v206
	ds_read_b128 v[128:131], v146
	ds_read_b128 v[132:135], v146 offset:1024
	ds_read_b128 v[136:139], v146 offset:2048
	ds_read_b128 v[146:149], v146 offset:3072
	s_cmp_eq_u32 s12, 12
	s_cselect_b32 s69, s47, s19
	s_cselect_b32 s68, s46, s6
	s_cselect_b32 s59, s49, s11
	s_cselect_b32 s58, s48, s10
	v_lshl_add_u64 v[192:193], s[54:55], 0, v[158:159]
	s_add_i32 m0, s72, 0xc000
	ds_read_b128 v[162:165], v208
	ds_read_b128 v[166:169], v208 offset:1024
	ds_read_b128 v[170:173], v208 offset:2048
	ds_read_b128 v[174:177], v208 offset:3072
	ds_read_b128 v[178:181], v208 offset:4096
	ds_read_b128 v[182:185], v208 offset:5120
	ds_read_b128 v[194:197], v208 offset:6144
	ds_read_b128 v[210:213], v208 offset:7168
	global_load_lds_dwordx4 v[192:193], off
	v_lshl_add_u64 v[192:193], s[54:55], 0, v[160:161]
	s_add_i32 m0, s72, 0xe000
	s_nop 0
	global_load_lds_dwordx4 v[192:193], off
	s_add_i32 s6, 0, 0x14000
	v_add_u32_e32 v192, s6, v206
	ds_read_b128 v[214:217], v192
	ds_read_b128 v[218:221], v192 offset:1024
	ds_read_b128 v[222:225], v192 offset:2048
	ds_read_b128 v[226:229], v192 offset:3072
	s_waitcnt vmcnt(8)
	s_waitcnt lgkmcnt(0)
	s_barrier
	v_mfma_f32_16x16x32_bf16 v[124:127], v[128:131], v[162:165], v[124:127]
	v_mfma_f32_16x16x32_bf16 v[120:123], v[136:139], v[162:165], v[120:123]
	v_mfma_f32_16x16x32_bf16 v[108:111], v[128:131], v[170:173], v[108:111]
	v_mfma_f32_16x16x32_bf16 v[104:107], v[136:139], v[170:173], v[104:107]
	v_mfma_f32_16x16x32_bf16 v[96:99], v[128:131], v[178:181], v[96:99]
	v_mfma_f32_16x16x32_bf16 v[88:91], v[136:139], v[178:181], v[88:91]
	v_mfma_f32_16x16x32_bf16 v[84:87], v[128:131], v[194:197], v[84:87]
	v_mfma_f32_16x16x32_bf16 v[80:83], v[136:139], v[194:197], v[80:83]
	v_mfma_f32_16x16x32_bf16 v[124:127], v[132:135], v[166:169], v[124:127]
	v_mfma_f32_16x16x32_bf16 v[120:123], v[146:149], v[166:169], v[120:123]
	v_mfma_f32_16x16x32_bf16 v[108:111], v[132:135], v[174:177], v[108:111]
	v_mfma_f32_16x16x32_bf16 v[104:107], v[146:149], v[174:177], v[104:107]
	v_mfma_f32_16x16x32_bf16 v[96:99], v[132:135], v[182:185], v[96:99]
	v_mfma_f32_16x16x32_bf16 v[88:91], v[146:149], v[182:185], v[88:91]
	v_mfma_f32_16x16x32_bf16 v[84:87], v[132:135], v[210:213], v[84:87]
	v_mfma_f32_16x16x32_bf16 v[80:83], v[146:149], v[210:213], v[80:83]
	v_mfma_f32_16x16x32_bf16 v[116:119], v[214:217], v[162:165], v[116:119]
	v_mfma_f32_16x16x32_bf16 v[112:115], v[222:225], v[162:165], v[112:115]
	v_mfma_f32_16x16x32_bf16 v[100:103], v[214:217], v[170:173], v[100:103]
	v_mfma_f32_16x16x32_bf16 v[92:95], v[222:225], v[170:173], v[92:95]
	v_mfma_f32_16x16x32_bf16 v[76:79], v[214:217], v[178:181], v[76:79]
	v_mfma_f32_16x16x32_bf16 v[72:75], v[222:225], v[178:181], v[72:75]
	v_mfma_f32_16x16x32_bf16 v[68:71], v[214:217], v[194:197], v[68:71]
	v_mfma_f32_16x16x32_bf16 v[64:67], v[222:225], v[194:197], v[64:67]
	v_mfma_f32_16x16x32_bf16 v[116:119], v[218:221], v[166:169], v[116:119]
	v_mfma_f32_16x16x32_bf16 v[112:115], v[226:229], v[166:169], v[112:115]
	v_mfma_f32_16x16x32_bf16 v[100:103], v[218:221], v[174:177], v[100:103]
	v_mfma_f32_16x16x32_bf16 v[92:95], v[226:229], v[174:177], v[92:95]
	v_mfma_f32_16x16x32_bf16 v[76:79], v[218:221], v[182:185], v[76:79]
	v_mfma_f32_16x16x32_bf16 v[72:75], v[226:229], v[182:185], v[72:75]
	v_mfma_f32_16x16x32_bf16 v[68:71], v[218:221], v[210:213], v[68:71]
	v_mfma_f32_16x16x32_bf16 v[64:67], v[226:229], v[210:213], v[64:67]
	s_barrier
	s_add_i32 s19, s23, s71
	v_lshl_add_u64 v[192:193], s[58:59], 0, v[140:141]
	s_mov_b32 m0, s19
	v_lshl_add_u64 v[230:231], s[58:59], 0, v[150:151]
	global_load_lds_dwordx4 v[192:193], off
	s_add_i32 m0, s19, 0x2000
	s_nop 0
	global_load_lds_dwordx4 v[230:231], off
	s_mov_b32 m0, s72
	v_lshl_add_u64 v[232:233], s[68:69], 0, v[154:155]
	ds_read_b128 v[162:165], v208 offset:16384
	ds_read_b128 v[166:169], v208 offset:17408
	ds_read_b128 v[170:173], v208 offset:18432
	ds_read_b128 v[174:177], v208 offset:19456
	ds_read_b128 v[178:181], v208 offset:20480
	ds_read_b128 v[182:185], v208 offset:21504
	ds_read_b128 v[194:197], v208 offset:22528
	ds_read_b128 v[210:213], v208 offset:23552
	global_load_lds_dwordx4 v[232:233], off
	v_lshl_add_u64 v[234:235], s[68:69], 0, v[152:153]
	s_mov_b32 m0, s73
	s_nop 0
	global_load_lds_dwordx4 v[234:235], off
	s_add_u32 s86, s58, 0x40000
	s_addc_u32 s87, s59, 0
	s_add_i32 s6, s6, s71
	v_lshl_add_u64 v[250:251], s[86:87], 0, v[140:141]
	s_mov_b32 m0, s6
	s_nop 0
	global_load_lds_dwordx4 v[250:251], off
	v_lshl_add_u64 v[250:251], s[86:87], 0, v[150:151]
	s_add_i32 m0, s6, 0x2000
	s_nop 0
	global_load_lds_dwordx4 v[250:251], off
	s_waitcnt vmcnt(8)
	s_waitcnt lgkmcnt(0)
	s_barrier
	v_mfma_f32_16x16x32_bf16 v[60:63], v[128:131], v[162:165], v[60:63]
	v_mfma_f32_16x16x32_bf16 v[56:59], v[136:139], v[162:165], v[56:59]
	v_mfma_f32_16x16x32_bf16 v[48:51], v[128:131], v[170:173], v[48:51]
	v_mfma_f32_16x16x32_bf16 v[40:43], v[136:139], v[170:173], v[40:43]
	v_mfma_f32_16x16x32_bf16 v[32:35], v[128:131], v[178:181], v[32:35]
	v_mfma_f32_16x16x32_bf16 v[24:27], v[136:139], v[178:181], v[24:27]
	v_mfma_f32_16x16x32_bf16 v[16:19], v[128:131], v[194:197], v[16:19]
	v_mfma_f32_16x16x32_bf16 v[8:11], v[136:139], v[194:197], v[8:11]
	v_mfma_f32_16x16x32_bf16 v[60:63], v[132:135], v[166:169], v[60:63]
	v_mfma_f32_16x16x32_bf16 v[56:59], v[146:149], v[166:169], v[56:59]
	v_mfma_f32_16x16x32_bf16 v[48:51], v[132:135], v[174:177], v[48:51]
	v_mfma_f32_16x16x32_bf16 v[40:43], v[146:149], v[174:177], v[40:43]
	v_mfma_f32_16x16x32_bf16 v[32:35], v[132:135], v[182:185], v[32:35]
	v_mfma_f32_16x16x32_bf16 v[24:27], v[146:149], v[182:185], v[24:27]
	v_mfma_f32_16x16x32_bf16 v[16:19], v[132:135], v[210:213], v[16:19]
	v_mfma_f32_16x16x32_bf16 v[8:11], v[146:149], v[210:213], v[8:11]
	v_mfma_f32_16x16x32_bf16 v[52:55], v[214:217], v[162:165], v[52:55]
	v_mfma_f32_16x16x32_bf16 v[44:47], v[222:225], v[162:165], v[44:47]
	v_mfma_f32_16x16x32_bf16 v[36:39], v[214:217], v[170:173], v[36:39]
	v_mfma_f32_16x16x32_bf16 v[28:31], v[222:225], v[170:173], v[28:31]
	v_mfma_f32_16x16x32_bf16 v[20:23], v[214:217], v[178:181], v[20:23]
	v_mfma_f32_16x16x32_bf16 v[12:15], v[222:225], v[178:181], v[12:15]
	v_mfma_f32_16x16x32_bf16 v[4:7], v[214:217], v[194:197], v[4:7]
	v_mfma_f32_16x16x32_bf16 v[0:3], v[222:225], v[194:197], v[0:3]
	v_mfma_f32_16x16x32_bf16 v[52:55], v[218:221], v[166:169], v[52:55]
	v_mfma_f32_16x16x32_bf16 v[44:47], v[226:229], v[166:169], v[44:47]
	v_mfma_f32_16x16x32_bf16 v[36:39], v[218:221], v[174:177], v[36:39]
	v_mfma_f32_16x16x32_bf16 v[28:31], v[226:229], v[174:177], v[28:31]
	v_mfma_f32_16x16x32_bf16 v[20:23], v[218:221], v[182:185], v[20:23]
	v_mfma_f32_16x16x32_bf16 v[12:15], v[226:229], v[182:185], v[12:15]
	v_mfma_f32_16x16x32_bf16 v[4:7], v[218:221], v[210:213], v[4:7]
	v_mfma_f32_16x16x32_bf16 v[0:3], v[226:229], v[210:213], v[0:3]
	s_barrier
	s_add_i32 s6, 0, 0x18000
	v_add_u32_e32 v146, s6, v206
	ds_read_b128 v[128:131], v146
	ds_read_b128 v[132:135], v146 offset:1024
	ds_read_b128 v[136:139], v146 offset:2048
	ds_read_b128 v[146:149], v146 offset:3072
	s_add_u32 s68, s68, 0x40000
	s_addc_u32 s69, s69, 0
	s_mov_b32 m0, s74
	v_lshl_add_u64 v[214:215], s[68:69], 0, v[154:155]
	ds_read_b128 v[162:165], v208 offset:32768
	ds_read_b128 v[166:169], v208 offset:33792
	ds_read_b128 v[170:173], v208 offset:34816
	ds_read_b128 v[174:177], v208 offset:35840
	ds_read_b128 v[178:181], v208 offset:36864
	ds_read_b128 v[182:185], v208 offset:37888
	ds_read_b128 v[194:197], v208 offset:38912
	ds_read_b128 v[210:213], v208 offset:39936
	global_load_lds_dwordx4 v[214:215], off
	v_lshl_add_u64 v[214:215], s[68:69], 0, v[152:153]
	s_mov_b32 m0, s75
	s_nop 0
	global_load_lds_dwordx4 v[214:215], off
	s_add_i32 s19, 0, 0x1c000
	v_add_u32_e32 v209, s19, v206
	ds_read_b128 v[214:217], v209
	ds_read_b128 v[218:221], v209 offset:1024
	ds_read_b128 v[222:225], v209 offset:2048
	ds_read_b128 v[226:229], v209 offset:3072
	s_waitcnt vmcnt(8)
	s_waitcnt lgkmcnt(0)
	s_barrier
	v_mfma_f32_16x16x32_bf16 v[124:127], v[128:131], v[162:165], v[124:127]
	v_mfma_f32_16x16x32_bf16 v[120:123], v[136:139], v[162:165], v[120:123]
	v_mfma_f32_16x16x32_bf16 v[108:111], v[128:131], v[170:173], v[108:111]
	v_mfma_f32_16x16x32_bf16 v[104:107], v[136:139], v[170:173], v[104:107]
	v_mfma_f32_16x16x32_bf16 v[96:99], v[128:131], v[178:181], v[96:99]
	v_mfma_f32_16x16x32_bf16 v[88:91], v[136:139], v[178:181], v[88:91]
	v_mfma_f32_16x16x32_bf16 v[84:87], v[128:131], v[194:197], v[84:87]
	v_mfma_f32_16x16x32_bf16 v[80:83], v[136:139], v[194:197], v[80:83]
	v_mfma_f32_16x16x32_bf16 v[124:127], v[132:135], v[166:169], v[124:127]
	v_mfma_f32_16x16x32_bf16 v[120:123], v[146:149], v[166:169], v[120:123]
	v_mfma_f32_16x16x32_bf16 v[108:111], v[132:135], v[174:177], v[108:111]
	v_mfma_f32_16x16x32_bf16 v[104:107], v[146:149], v[174:177], v[104:107]
	v_mfma_f32_16x16x32_bf16 v[96:99], v[132:135], v[182:185], v[96:99]
	v_mfma_f32_16x16x32_bf16 v[88:91], v[146:149], v[182:185], v[88:91]
	v_mfma_f32_16x16x32_bf16 v[84:87], v[132:135], v[210:213], v[84:87]
	v_mfma_f32_16x16x32_bf16 v[80:83], v[146:149], v[210:213], v[80:83]
	v_mfma_f32_16x16x32_bf16 v[116:119], v[214:217], v[162:165], v[116:119]
	v_mfma_f32_16x16x32_bf16 v[112:115], v[222:225], v[162:165], v[112:115]
	v_mfma_f32_16x16x32_bf16 v[100:103], v[214:217], v[170:173], v[100:103]
	v_mfma_f32_16x16x32_bf16 v[92:95], v[222:225], v[170:173], v[92:95]
	v_mfma_f32_16x16x32_bf16 v[76:79], v[214:217], v[178:181], v[76:79]
	v_mfma_f32_16x16x32_bf16 v[72:75], v[222:225], v[178:181], v[72:75]
	v_mfma_f32_16x16x32_bf16 v[68:71], v[214:217], v[194:197], v[68:71]
	v_mfma_f32_16x16x32_bf16 v[64:67], v[222:225], v[194:197], v[64:67]
	v_mfma_f32_16x16x32_bf16 v[116:119], v[218:221], v[166:169], v[116:119]
	v_mfma_f32_16x16x32_bf16 v[112:115], v[226:229], v[166:169], v[112:115]
	v_mfma_f32_16x16x32_bf16 v[100:103], v[218:221], v[174:177], v[100:103]
	v_mfma_f32_16x16x32_bf16 v[92:95], v[226:229], v[174:177], v[92:95]
	v_mfma_f32_16x16x32_bf16 v[76:79], v[218:221], v[182:185], v[76:79]
	v_mfma_f32_16x16x32_bf16 v[72:75], v[226:229], v[182:185], v[72:75]
	v_mfma_f32_16x16x32_bf16 v[68:71], v[218:221], v[210:213], v[68:71]
	v_mfma_f32_16x16x32_bf16 v[64:67], v[226:229], v[210:213], v[64:67]
	s_barrier
	s_add_i32 s6, s6, s71
	v_lshl_add_u64 v[192:193], v[192:193], 0, s[36:37]
	s_mov_b32 m0, s6
	s_nop 0
	global_load_lds_dwordx4 v[192:193], off
	v_lshl_add_u64 v[192:193], v[230:231], 0, s[36:37]
	s_add_i32 m0, s6, 0x2000
	s_nop 0
	global_load_lds_dwordx4 v[192:193], off
	s_mov_b32 m0, s80
	v_lshl_add_u64 v[192:193], v[232:233], 0, s[36:37]
	ds_read_b128 v[162:165], v208 offset:49152
	ds_read_b128 v[166:169], v208 offset:50176
	ds_read_b128 v[170:173], v208 offset:51200
	ds_read_b128 v[174:177], v208 offset:52224
	ds_read_b128 v[178:181], v208 offset:53248
	ds_read_b128 v[182:185], v208 offset:54272
	ds_read_b128 v[194:197], v208 offset:55296
	ds_read_b128 v[210:213], v208 offset:56320
	global_load_lds_dwordx4 v[192:193], off
	v_lshl_add_u64 v[192:193], v[234:235], 0, s[36:37]
	s_mov_b32 m0, s81
	s_nop 0
	global_load_lds_dwordx4 v[192:193], off
	s_add_u32 s58, s58, 0x40080
	s_addc_u32 s59, s59, 0
	s_add_i32 s6, s19, s71
	v_lshl_add_u64 v[250:251], s[58:59], 0, v[140:141]
	s_mov_b32 m0, s6
	s_nop 0
	global_load_lds_dwordx4 v[250:251], off
	v_lshl_add_u64 v[250:251], s[58:59], 0, v[150:151]
	s_add_i32 m0, s6, 0x2000
	s_nop 0
	global_load_lds_dwordx4 v[250:251], off
	s_add_i32 s12, s12, 2
	s_add_u32 s54, s54, 0x100
	s_addc_u32 s55, s55, 0
	s_add_u32 s10, s10, 0x100
	s_addc_u32 s11, s11, 0
	s_cmp_gt_u32 s12, 13
	s_waitcnt vmcnt(8)
	s_waitcnt lgkmcnt(0)
	s_barrier
	v_mfma_f32_16x16x32_bf16 v[60:63], v[128:131], v[162:165], v[60:63]
	v_mfma_f32_16x16x32_bf16 v[56:59], v[136:139], v[162:165], v[56:59]
	v_mfma_f32_16x16x32_bf16 v[48:51], v[128:131], v[170:173], v[48:51]
	v_mfma_f32_16x16x32_bf16 v[40:43], v[136:139], v[170:173], v[40:43]
	v_mfma_f32_16x16x32_bf16 v[32:35], v[128:131], v[178:181], v[32:35]
	v_mfma_f32_16x16x32_bf16 v[24:27], v[136:139], v[178:181], v[24:27]
	v_mfma_f32_16x16x32_bf16 v[16:19], v[128:131], v[194:197], v[16:19]
	v_mfma_f32_16x16x32_bf16 v[8:11], v[136:139], v[194:197], v[8:11]
	v_mfma_f32_16x16x32_bf16 v[60:63], v[132:135], v[166:169], v[60:63]
	v_mfma_f32_16x16x32_bf16 v[56:59], v[146:149], v[166:169], v[56:59]
	v_mfma_f32_16x16x32_bf16 v[48:51], v[132:135], v[174:177], v[48:51]
	v_mfma_f32_16x16x32_bf16 v[40:43], v[146:149], v[174:177], v[40:43]
	v_mfma_f32_16x16x32_bf16 v[32:35], v[132:135], v[182:185], v[32:35]
	v_mfma_f32_16x16x32_bf16 v[24:27], v[146:149], v[182:185], v[24:27]
	v_mfma_f32_16x16x32_bf16 v[16:19], v[132:135], v[210:213], v[16:19]
	v_mfma_f32_16x16x32_bf16 v[8:11], v[146:149], v[210:213], v[8:11]
	v_mfma_f32_16x16x32_bf16 v[52:55], v[214:217], v[162:165], v[52:55]
	v_mfma_f32_16x16x32_bf16 v[44:47], v[222:225], v[162:165], v[44:47]
	v_mfma_f32_16x16x32_bf16 v[36:39], v[214:217], v[170:173], v[36:39]
	v_mfma_f32_16x16x32_bf16 v[28:31], v[222:225], v[170:173], v[28:31]
	v_mfma_f32_16x16x32_bf16 v[20:23], v[214:217], v[178:181], v[20:23]
	v_mfma_f32_16x16x32_bf16 v[12:15], v[222:225], v[178:181], v[12:15]
	v_mfma_f32_16x16x32_bf16 v[4:7], v[214:217], v[194:197], v[4:7]
	v_mfma_f32_16x16x32_bf16 v[0:3], v[222:225], v[194:197], v[0:3]
	v_mfma_f32_16x16x32_bf16 v[52:55], v[218:221], v[166:169], v[52:55]
	v_mfma_f32_16x16x32_bf16 v[44:47], v[226:229], v[166:169], v[44:47]
	v_mfma_f32_16x16x32_bf16 v[36:39], v[218:221], v[174:177], v[36:39]
	v_mfma_f32_16x16x32_bf16 v[28:31], v[226:229], v[174:177], v[28:31]
	v_mfma_f32_16x16x32_bf16 v[20:23], v[218:221], v[182:185], v[20:23]
	v_mfma_f32_16x16x32_bf16 v[12:15], v[226:229], v[182:185], v[12:15]
	v_mfma_f32_16x16x32_bf16 v[4:7], v[218:221], v[210:213], v[4:7]
	v_mfma_f32_16x16x32_bf16 v[0:3], v[226:229], v[210:213], v[0:3]
	s_barrier
	s_cbranch_scc0 .LBB0_103
	s_mov_b32 s100, 1
	s_ashr_i32 s51, s50, 31
	s_ashr_i32 s53, s52, 31
	s_lshl_b64 s[10:11], s[50:51], 13
	s_lshl_b64 s[50:51], s[52:53], 8
	s_add_u32 s10, s50, s10
	v_lshl_or_b32 v128, s85, 8, v207
	s_addc_u32 s11, s51, s11
	v_ashrrev_i32_e32 v129, 31, v128
	v_lshl_add_u64 v[168:169], s[10:11], 0, v[156:157]
	v_lshlrev_b64 v[170:171], 1, v[128:129]
	v_lshl_add_u64 v[174:175], s[26:27], 0, v[170:171]
	v_lshlrev_b64 v[172:173], 11, v[168:169]
	v_or_b32_e32 v166, 16, v168
	v_mov_b32_e32 v167, v169
	v_lshl_add_u64 v[128:129], v[174:175], 0, v[172:173]
	v_lshlrev_b64 v[176:177], 11, v[166:167]
	global_load_dwordx4 v[146:149], v[128:129], off
	global_load_dwordx4 v[182:185], v[128:129], off offset:256
	v_lshl_add_u64 v[128:129], v[174:175], 0, v[176:177]
	global_load_dwordx4 v[194:197], v[128:129], off
	global_load_dwordx4 v[210:213], v[128:129], off offset:256
	v_or_b32_e32 v164, 32, v168
	v_mov_b32_e32 v165, v169
	v_or_b32_e32 v162, 48, v168
	v_mov_b32_e32 v163, v169
	v_lshlrev_b64 v[180:181], 11, v[164:165]
	v_lshlrev_b64 v[178:179], 11, v[162:163]
	v_lshl_add_u64 v[128:129], v[174:175], 0, v[180:181]
	v_lshl_add_u64 v[130:131], v[174:175], 0, v[178:179]
	global_load_dwordx4 v[214:217], v[128:129], off
	global_load_dwordx4 v[136:139], v[128:129], off offset:256
	global_load_dwordx4 v[132:135], v[130:131], off
	s_nop 0
	global_load_dwordx4 v[128:131], v[130:131], off offset:256
	s_mov_b64 s[10:11], 0x90
	v_lshl_add_u64 v[172:173], s[28:29], 0, v[172:173]
	v_lshl_add_u64 v[172:173], v[172:173], 0, v[170:171]
	s_waitcnt vmcnt(0)
	v_lshlrev_b32_e32 v192, 16, v146
	v_and_b32_e32 v193, 0xffff0000, v146
	v_lshlrev_b32_e32 v218, 16, v148
	v_and_b32_e32 v219, 0xffff0000, v148
	v_lshlrev_b32_e32 v146, 16, v147
	v_and_b32_e32 v147, 0xffff0000, v147
	v_lshlrev_b32_e32 v148, 16, v149
	v_and_b32_e32 v149, 0xffff0000, v149
	v_lshlrev_b32_e32 v220, 16, v182
	v_and_b32_e32 v221, 0xffff0000, v182
	v_lshlrev_b32_e32 v222, 16, v184
	v_and_b32_e32 v223, 0xffff0000, v184
	v_lshlrev_b32_e32 v182, 16, v183
	v_and_b32_e32 v183, 0xffff0000, v183
	v_lshlrev_b32_e32 v184, 16, v185
	v_and_b32_e32 v185, 0xffff0000, v185
	v_pk_add_f32 v[124:125], v[124:125], v[192:193]
	v_pk_add_f32 v[126:127], v[126:127], v[146:147]
	v_pk_add_f32 v[122:123], v[122:123], v[148:149]
	v_pk_add_f32 v[116:117], v[116:117], v[220:221]
	v_pk_add_f32 v[146:147], v[112:113], v[222:223]
	v_pk_add_f32 v[118:119], v[118:119], v[182:183]
	v_pk_add_f32 v[148:149], v[114:115], v[184:185]
	v_lshlrev_b32_e32 v182, 16, v194
	v_and_b32_e32 v183, 0xffff0000, v194
	v_lshlrev_b32_e32 v184, 16, v196
	v_and_b32_e32 v185, 0xffff0000, v196
	v_lshlrev_b32_e32 v192, 16, v195
	v_and_b32_e32 v193, 0xffff0000, v195
	v_lshlrev_b32_e32 v194, 16, v197
	v_and_b32_e32 v195, 0xffff0000, v197
	v_pk_mul_f32 v[196:197], v[124:125], v[124:125]
	v_pk_add_f32 v[120:121], v[120:121], v[218:219]
	v_pk_mul_f32 v[218:219], v[126:127], v[126:127]
	v_cvt_pk_bf16_f32 v112, v124, v125
	v_cvt_pk_bf16_f32 v113, v126, v127
	v_pk_mul_f32 v[124:125], v[116:117], v[116:117]
	v_pk_mul_f32 v[126:127], v[118:119], v[118:119]
	v_pk_mul_f32 v[224:225], v[146:147], v[146:147]
	v_cvt_pk_bf16_f32 v116, v116, v117
	v_cvt_pk_bf16_f32 v117, v118, v119
	v_cvt_pk_bf16_f32 v118, v146, v147
	v_add_f32_e32 v146, v196, v197
	v_add_f32_e32 v146, v218, v146
	v_pk_mul_f32 v[220:221], v[120:121], v[120:121]
	v_add_f32_e32 v146, v219, v146
	v_add_f32_e32 v146, v220, v146
	v_pk_mul_f32 v[222:223], v[122:123], v[122:123]
	v_add_f32_e32 v146, v221, v146
	v_add_f32_e32 v146, v222, v146
	v_add_f32_e32 v146, v223, v146
	v_add_f32_e32 v124, v124, v146
	v_add_f32_e32 v124, v125, v124
	v_add_f32_e32 v124, v126, v124
	v_add_f32_e32 v124, v127, v124
	v_add_f32_e32 v124, v224, v124
	v_pk_mul_f32 v[226:227], v[148:149], v[148:149]
	v_add_f32_e32 v124, v225, v124
	v_add_f32_e32 v124, v226, v124
	v_add_f32_e32 v209, v227, v124
	v_lshlrev_b32_e32 v124, 16, v210
	v_and_b32_e32 v125, 0xffff0000, v210
	v_pk_add_f32 v[100:101], v[100:101], v[124:125]
	v_lshlrev_b32_e32 v124, 16, v212
	v_and_b32_e32 v125, 0xffff0000, v212
	v_pk_add_f32 v[124:125], v[92:93], v[124:125]
	v_lshlrev_b32_e32 v92, 16, v211
	v_and_b32_e32 v93, 0xffff0000, v211
	v_pk_add_f32 v[102:103], v[102:103], v[92:93]
	v_lshlrev_b32_e32 v92, 16, v213
	v_and_b32_e32 v93, 0xffff0000, v213
	v_pk_add_f32 v[126:127], v[94:95], v[92:93]
	v_lshlrev_b32_e32 v92, 16, v214
	v_and_b32_e32 v93, 0xffff0000, v214
	v_pk_add_f32 v[92:93], v[96:97], v[92:93]
	v_lshlrev_b32_e32 v96, 16, v217
	v_and_b32_e32 v97, 0xffff0000, v217
	v_lshlrev_b32_e32 v94, 16, v216
	v_and_b32_e32 v95, 0xffff0000, v216
	v_pk_add_f32 v[90:91], v[90:91], v[96:97]
	v_lshlrev_b32_e32 v96, 16, v136
	v_and_b32_e32 v97, 0xffff0000, v136
	v_pk_add_f32 v[88:89], v[88:89], v[94:95]
	v_lshlrev_b32_e32 v94, 16, v215
	v_and_b32_e32 v95, 0xffff0000, v215
	v_pk_add_f32 v[96:97], v[76:77], v[96:97]
	v_lshl_add_u64 v[76:77], v[168:169], 0, s[36:37]
	v_cvt_pk_bf16_f32 v114, v120, v121
	v_pk_add_f32 v[120:121], v[108:109], v[182:183]
	v_pk_add_f32 v[94:95], v[98:99], v[94:95]
	v_lshlrev_b64 v[182:183], 11, v[76:77]
	v_lshlrev_b32_e32 v98, 16, v138
	v_and_b32_e32 v99, 0xffff0000, v138
	v_pk_add_f32 v[108:109], v[104:105], v[184:185]
	v_lshl_add_u64 v[184:185], v[174:175], 0, v[182:183]
	v_pk_add_f32 v[98:99], v[72:73], v[98:99]
	v_lshlrev_b32_e32 v72, 16, v137
	v_and_b32_e32 v73, 0xffff0000, v137
	global_load_dwordx4 v[210:213], v[184:185], off
	global_load_dwordx4 v[218:221], v[184:185], off offset:256
	v_pk_add_f32 v[136:137], v[78:79], v[72:73]
	v_lshlrev_b32_e32 v72, 16, v139
	v_and_b32_e32 v73, 0xffff0000, v139
	v_pk_add_f32 v[138:139], v[74:75], v[72:73]
	v_lshlrev_b32_e32 v72, 16, v132
	v_and_b32_e32 v73, 0xffff0000, v132
	v_pk_add_f32 v[74:75], v[84:85], v[72:73]
	v_lshlrev_b32_e32 v72, 16, v134
	v_and_b32_e32 v73, 0xffff0000, v134
	v_pk_add_f32 v[78:79], v[80:81], v[72:73]
	v_lshlrev_b32_e32 v72, 16, v133
	v_and_b32_e32 v73, 0xffff0000, v133
	v_pk_add_f32 v[80:81], v[86:87], v[72:73]
	v_lshlrev_b32_e32 v72, 16, v135
	v_and_b32_e32 v73, 0xffff0000, v135
	v_pk_add_f32 v[82:83], v[82:83], v[72:73]
	v_lshl_add_u64 v[72:73], v[168:169], 0, s[10:11]
	v_lshlrev_b64 v[132:133], 11, v[72:73]
	v_lshl_add_u64 v[134:135], v[174:175], 0, v[132:133]
	v_lshlrev_b32_e32 v84, 16, v128
	v_and_b32_e32 v85, 0xffff0000, v128
	global_load_dwordx4 v[226:229], v[134:135], off
	global_load_dwordx4 v[234:237], v[134:135], off offset:256
	v_pk_add_f32 v[84:85], v[68:69], v[84:85]
	v_lshlrev_b32_e32 v68, 16, v130
	v_and_b32_e32 v69, 0xffff0000, v130
	v_pk_add_f32 v[86:87], v[64:65], v[68:69]
	v_lshlrev_b32_e32 v64, 16, v129
	v_and_b32_e32 v65, 0xffff0000, v129
	s_mov_b64 s[10:11], 0xa0
	v_pk_add_f32 v[128:129], v[70:71], v[64:65]
	v_lshl_add_u64 v[70:71], v[168:169], 0, s[10:11]
	s_mov_b64 s[10:11], 0xb0
	v_lshlrev_b32_e32 v64, 16, v131
	v_and_b32_e32 v65, 0xffff0000, v131
	v_lshlrev_b64 v[134:135], 11, v[70:71]
	v_lshl_add_u64 v[68:69], v[168:169], 0, s[10:11]
	v_pk_add_f32 v[130:131], v[66:67], v[64:65]
	v_lshl_add_u64 v[64:65], v[174:175], 0, v[134:135]
	v_lshlrev_b64 v[184:185], 11, v[68:69]
	global_load_dwordx4 v[238:241], v[64:65], off
	global_load_dwordx4 v[242:245], v[64:65], off offset:256
	v_lshl_add_u64 v[64:65], v[174:175], 0, v[184:185]
	global_load_dwordx4 v[246:249], v[64:65], off
	s_nop 0
	global_load_dwordx4 v[64:67], v[64:65], off offset:256
	v_cvt_pk_bf16_f32 v115, v122, v123
	v_cvt_pk_bf16_f32 v119, v148, v149
	v_pk_add_f32 v[110:111], v[110:111], v[192:193]
	v_pk_add_f32 v[122:123], v[106:107], v[194:195]
	global_store_dwordx4 v[172:173], v[112:115], off
	global_store_dwordx4 v[172:173], v[116:119], off offset:256
	v_cvt_pk_bf16_f32 v104, v120, v121
	v_lshl_add_u64 v[112:113], s[28:29], 0, v[176:177]
	v_cvt_pk_bf16_f32 v105, v110, v111
	v_cvt_pk_bf16_f32 v106, v108, v109
	v_cvt_pk_bf16_f32 v107, v122, v123
	v_lshl_add_u64 v[112:113], v[112:113], 0, v[170:171]
	v_cvt_pk_bf16_f32 v146, v100, v101
	v_cvt_pk_bf16_f32 v147, v102, v103
	v_cvt_pk_bf16_f32 v148, v124, v125
	v_cvt_pk_bf16_f32 v149, v126, v127
	global_store_dwordx4 v[112:113], v[104:107], off
	global_store_dwordx4 v[112:113], v[146:149], off offset:256
	v_cvt_pk_bf16_f32 v194, v92, v93
	v_lshl_add_u64 v[104:105], s[28:29], 0, v[180:181]
	v_cvt_pk_bf16_f32 v195, v94, v95
	v_cvt_pk_bf16_f32 v196, v88, v89
	v_cvt_pk_bf16_f32 v197, v90, v91
	v_lshl_add_u64 v[104:105], v[104:105], 0, v[170:171]
	v_cvt_pk_bf16_f32 v214, v96, v97
	v_cvt_pk_bf16_f32 v215, v136, v137
	v_cvt_pk_bf16_f32 v216, v98, v99
	v_cvt_pk_bf16_f32 v217, v138, v139
	global_store_dwordx4 v[104:105], v[194:197], off
	global_store_dwordx4 v[104:105], v[214:217], off offset:256
	v_lshl_add_u64 v[104:105], s[28:29], 0, v[178:179]
	v_cvt_pk_bf16_f32 v222, v74, v75
	v_cvt_pk_bf16_f32 v223, v80, v81
	v_cvt_pk_bf16_f32 v224, v78, v79
	v_cvt_pk_bf16_f32 v225, v82, v83
	v_lshl_add_u64 v[104:105], v[104:105], 0, v[170:171]
	v_cvt_pk_bf16_f32 v230, v84, v85
	v_cvt_pk_bf16_f32 v231, v128, v129
	v_cvt_pk_bf16_f32 v232, v86, v87
	v_cvt_pk_bf16_f32 v233, v130, v131
	global_store_dwordx4 v[104:105], v[222:225], off
	global_store_dwordx4 v[104:105], v[230:233], off offset:256
	s_waitcnt vmcnt(8)
	v_lshlrev_b32_e32 v104, 16, v210
	v_and_b32_e32 v105, 0xffff0000, v210
	v_pk_add_f32 v[60:61], v[60:61], v[104:105]
	v_lshlrev_b32_e32 v104, 16, v212
	v_and_b32_e32 v105, 0xffff0000, v212
	v_pk_add_f32 v[56:57], v[56:57], v[104:105]
	v_lshlrev_b32_e32 v104, 16, v211
	v_and_b32_e32 v105, 0xffff0000, v211
	v_pk_add_f32 v[62:63], v[62:63], v[104:105]
	v_lshlrev_b32_e32 v104, 16, v213
	v_and_b32_e32 v105, 0xffff0000, v213
	v_pk_add_f32 v[58:59], v[58:59], v[104:105]
	v_lshlrev_b32_e32 v104, 16, v218
	v_and_b32_e32 v105, 0xffff0000, v218
	v_pk_add_f32 v[52:53], v[52:53], v[104:105]
	v_lshlrev_b32_e32 v104, 16, v220
	v_and_b32_e32 v105, 0xffff0000, v220
	v_pk_add_f32 v[104:105], v[44:45], v[104:105]
	v_lshlrev_b32_e32 v44, 16, v219
	v_and_b32_e32 v45, 0xffff0000, v219
	v_pk_add_f32 v[54:55], v[54:55], v[44:45]
	v_lshlrev_b32_e32 v44, 16, v221
	v_and_b32_e32 v45, 0xffff0000, v221
	v_pk_add_f32 v[106:107], v[46:47], v[44:45]
	v_lshlrev_b32_e32 v44, 16, v226
	v_and_b32_e32 v45, 0xffff0000, v226
	v_pk_add_f32 v[44:45], v[48:49], v[44:45]
	v_lshlrev_b32_e32 v48, 16, v229
	v_and_b32_e32 v49, 0xffff0000, v229
	v_pk_add_f32 v[42:43], v[42:43], v[48:49]
	v_lshlrev_b32_e32 v48, 16, v234
	v_and_b32_e32 v49, 0xffff0000, v234
	v_pk_add_f32 v[36:37], v[36:37], v[48:49]
	v_lshlrev_b32_e32 v48, 16, v236
	v_and_b32_e32 v49, 0xffff0000, v236
	v_lshlrev_b32_e32 v46, 16, v228
	v_and_b32_e32 v47, 0xffff0000, v228
	v_pk_add_f32 v[48:49], v[28:29], v[48:49]
	v_lshlrev_b32_e32 v28, 16, v235
	v_and_b32_e32 v29, 0xffff0000, v235
	v_pk_add_f32 v[40:41], v[40:41], v[46:47]
	v_lshlrev_b32_e32 v46, 16, v227
	v_and_b32_e32 v47, 0xffff0000, v227
	v_pk_add_f32 v[38:39], v[38:39], v[28:29]
	v_lshlrev_b32_e32 v28, 16, v237
	v_and_b32_e32 v29, 0xffff0000, v237
	v_pk_add_f32 v[46:47], v[50:51], v[46:47]
	v_pk_add_f32 v[50:51], v[30:31], v[28:29]
	v_lshlrev_b32_e32 v28, 16, v238
	v_and_b32_e32 v29, 0xffff0000, v238
	v_lshlrev_b32_e32 v180, 16, v64
	v_and_b32_e32 v181, 0xffff0000, v64
	v_pk_add_f32 v[28:29], v[32:33], v[28:29]
	v_lshlrev_b32_e32 v32, 16, v241
	v_and_b32_e32 v33, 0xffff0000, v241
	v_pk_add_f32 v[4:5], v[4:5], v[180:181]
	v_lshlrev_b32_e32 v180, 16, v66
	v_and_b32_e32 v181, 0xffff0000, v66
	v_pk_add_f32 v[26:27], v[26:27], v[32:33]
	v_lshlrev_b32_e32 v32, 16, v242
	v_and_b32_e32 v33, 0xffff0000, v242
	v_pk_add_f32 v[0:1], v[0:1], v[180:181]
	v_lshl_add_u64 v[180:181], s[28:29], 0, v[182:183]
	v_cvt_pk_bf16_f32 v112, v60, v61
	v_cvt_pk_bf16_f32 v113, v62, v63
	v_cvt_pk_bf16_f32 v114, v56, v57
	v_cvt_pk_bf16_f32 v115, v58, v59
	v_pk_add_f32 v[20:21], v[20:21], v[32:33]
	v_lshlrev_b32_e32 v32, 16, v244
	v_and_b32_e32 v33, 0xffff0000, v244
	v_lshl_add_u64 v[180:181], v[180:181], 0, v[170:171]
	v_cvt_pk_bf16_f32 v116, v52, v53
	v_cvt_pk_bf16_f32 v117, v54, v55
	v_cvt_pk_bf16_f32 v118, v104, v105
	v_cvt_pk_bf16_f32 v119, v106, v107
	v_lshlrev_b32_e32 v30, 16, v240
	v_and_b32_e32 v31, 0xffff0000, v240
	v_pk_add_f32 v[32:33], v[12:13], v[32:33]
	v_lshlrev_b32_e32 v12, 16, v243
	v_and_b32_e32 v13, 0xffff0000, v243
	global_store_dwordx4 v[180:181], v[112:115], off
	global_store_dwordx4 v[180:181], v[116:119], off offset:256
	v_cvt_pk_bf16_f32 v146, v44, v45
	v_lshl_add_u64 v[112:113], s[28:29], 0, v[132:133]
	v_cvt_pk_bf16_f32 v147, v46, v47
	v_cvt_pk_bf16_f32 v148, v40, v41
	v_cvt_pk_bf16_f32 v149, v42, v43
	v_pk_add_f32 v[24:25], v[24:25], v[30:31]
	v_lshlrev_b32_e32 v30, 16, v239
	v_and_b32_e32 v31, 0xffff0000, v239
	v_pk_add_f32 v[22:23], v[22:23], v[12:13]
	v_lshlrev_b32_e32 v12, 16, v245
	v_and_b32_e32 v13, 0xffff0000, v245
	v_lshl_add_u64 v[112:113], v[112:113], 0, v[170:171]
	v_cvt_pk_bf16_f32 v172, v36, v37
	v_cvt_pk_bf16_f32 v173, v38, v39
	v_cvt_pk_bf16_f32 v174, v48, v49
	v_cvt_pk_bf16_f32 v175, v50, v51
	v_pk_add_f32 v[30:31], v[34:35], v[30:31]
	v_pk_add_f32 v[34:35], v[14:15], v[12:13]
	v_lshlrev_b32_e32 v12, 16, v246
	v_and_b32_e32 v13, 0xffff0000, v246
	v_lshlrev_b32_e32 v14, 16, v248
	v_and_b32_e32 v15, 0xffff0000, v248
	global_store_dwordx4 v[112:113], v[146:149], off
	global_store_dwordx4 v[112:113], v[172:175], off offset:256
	v_lshl_add_u64 v[112:113], s[28:29], 0, v[134:135]
	v_cvt_pk_bf16_f32 v176, v28, v29
	v_cvt_pk_bf16_f32 v177, v30, v31
	v_cvt_pk_bf16_f32 v178, v24, v25
	v_cvt_pk_bf16_f32 v179, v26, v27
	v_pk_add_f32 v[12:13], v[16:17], v[12:13]
	v_pk_add_f32 v[8:9], v[8:9], v[14:15]
	v_lshlrev_b32_e32 v14, 16, v247
	v_and_b32_e32 v15, 0xffff0000, v247
	v_lshlrev_b32_e32 v16, 16, v249
	v_and_b32_e32 v17, 0xffff0000, v249
	v_lshlrev_b32_e32 v64, 16, v65
	v_and_b32_e32 v65, 0xffff0000, v65
	v_lshl_add_u64 v[112:113], v[112:113], 0, v[170:171]
	v_cvt_pk_bf16_f32 v194, v20, v21
	v_cvt_pk_bf16_f32 v195, v22, v23
	v_cvt_pk_bf16_f32 v196, v32, v33
	v_cvt_pk_bf16_f32 v197, v34, v35
	v_pk_add_f32 v[14:15], v[18:19], v[14:15]
	v_pk_add_f32 v[10:11], v[10:11], v[16:17]
	v_pk_add_f32 v[6:7], v[6:7], v[64:65]
	v_lshlrev_b32_e32 v64, 16, v67
	v_and_b32_e32 v65, 0xffff0000, v67
	global_store_dwordx4 v[112:113], v[176:179], off
	global_store_dwordx4 v[112:113], v[194:197], off offset:256
	v_lshl_add_u64 v[112:113], s[28:29], 0, v[184:185]
	v_cvt_pk_bf16_f32 v16, v12, v13
	v_cvt_pk_bf16_f32 v17, v14, v15
	v_cvt_pk_bf16_f32 v18, v8, v9
	v_cvt_pk_bf16_f32 v19, v10, v11
	v_pk_add_f32 v[2:3], v[2:3], v[64:65]
	v_lshl_add_u64 v[112:113], v[112:113], 0, v[170:171]
	v_cvt_pk_bf16_f32 v64, v4, v5
	v_cvt_pk_bf16_f32 v65, v6, v7
	v_cvt_pk_bf16_f32 v66, v0, v1
	v_cvt_pk_bf16_f32 v67, v2, v3
	global_store_dwordx4 v[112:113], v[16:19], off
	global_store_dwordx4 v[112:113], v[64:67], off offset:256
	s_lshl_b32 s10, s85, 2
	v_and_b32_e32 v17, 64, v188
	v_xor_b32_e32 v16, 16, v188
	v_add_u32_e32 v17, 64, v17
	v_cmp_lt_i32_e32 vcc, v16, v17
	v_xor_b32_e32 v18, 32, v188
	s_ashr_i32 s11, s10, 31
	v_cndmask_b32_e32 v16, v188, v16, vcc
	v_lshlrev_b32_e32 v16, 2, v16
	v_mov_b32_e32 v132, v209
	v_cmp_lt_i32_e32 vcc, v18, v17
	s_lshl_b64 s[10:11], s[10:11], 2
	s_add_u32 s50, s83, s10
	v_cndmask_b32_e32 v17, v188, v18, vcc
	v_lshlrev_b32_e32 v17, 2, v17
	s_addc_u32 s51, s84, s11
	v_pk_mul_f32 v[18:19], v[120:121], v[120:121]
	v_pk_mul_f32 v[64:65], v[110:111], v[110:111]
	v_add_f32_e32 v18, v18, v19
	v_add_f32_e32 v18, v64, v18
	v_pk_mul_f32 v[66:67], v[108:109], v[108:109]
	v_add_f32_e32 v18, v65, v18
	v_add_f32_e32 v18, v66, v18
	v_pk_mul_f32 v[108:109], v[122:123], v[122:123]
	v_add_f32_e32 v18, v67, v18
	v_add_f32_e32 v18, v108, v18
	v_pk_mul_f32 v[100:101], v[100:101], v[100:101]
	v_add_f32_e32 v18, v109, v18
	v_add_f32_e32 v18, v100, v18
	v_pk_mul_f32 v[102:103], v[102:103], v[102:103]
	v_add_f32_e32 v18, v101, v18
	v_add_f32_e32 v18, v102, v18
	v_pk_mul_f32 v[110:111], v[124:125], v[124:125]
	v_add_f32_e32 v18, v103, v18
	v_add_f32_e32 v18, v110, v18
	v_pk_mul_f32 v[112:113], v[126:127], v[126:127]
	v_add_f32_e32 v18, v111, v18
	v_add_f32_e32 v18, v112, v18
	v_add_f32_e32 v18, v113, v18
	v_mov_b32_e32 v133, v18
	v_pk_mul_f32 v[18:19], v[92:93], v[92:93]
	v_pk_mul_f32 v[64:65], v[94:95], v[94:95]
	v_add_f32_e32 v18, v18, v19
	v_add_f32_e32 v18, v64, v18
	v_pk_mul_f32 v[66:67], v[88:89], v[88:89]
	v_add_f32_e32 v18, v65, v18
	v_add_f32_e32 v18, v66, v18
	v_pk_mul_f32 v[88:89], v[90:91], v[90:91]
	v_add_f32_e32 v18, v67, v18
	v_add_f32_e32 v18, v88, v18
	v_pk_mul_f32 v[90:91], v[96:97], v[96:97]
	v_add_f32_e32 v18, v89, v18
	v_add_f32_e32 v18, v90, v18
	v_pk_mul_f32 v[92:93], v[136:137], v[136:137]
	v_add_f32_e32 v18, v91, v18
	v_add_f32_e32 v18, v92, v18
	v_pk_mul_f32 v[94:95], v[98:99], v[98:99]
	v_add_f32_e32 v18, v93, v18
	v_add_f32_e32 v18, v94, v18
	v_pk_mul_f32 v[96:97], v[138:139], v[138:139]
	v_add_f32_e32 v18, v95, v18
	v_add_f32_e32 v18, v96, v18
	v_add_f32_e32 v18, v97, v18
	v_mov_b32_e32 v134, v18
	v_pk_mul_f32 v[18:19], v[74:75], v[74:75]
	v_pk_mul_f32 v[192:193], v[60:61], v[60:61]
	v_pk_mul_f32 v[64:65], v[80:81], v[80:81]
	v_pk_mul_f32 v[60:61], v[62:63], v[62:63]
	v_add_f32_e32 v18, v18, v19
	v_add_f32_e32 v192, v192, v193
	v_add_f32_e32 v18, v64, v18
	v_add_f32_e32 v192, v60, v192
	v_pk_mul_f32 v[66:67], v[78:79], v[78:79]
	v_pk_mul_f32 v[56:57], v[56:57], v[56:57]
	v_add_f32_e32 v18, v65, v18
	v_add_f32_e32 v192, v61, v192
	v_add_f32_e32 v18, v66, v18
	v_add_f32_e32 v192, v56, v192
	v_pk_mul_f32 v[74:75], v[82:83], v[82:83]
	v_pk_mul_f32 v[58:59], v[58:59], v[58:59]
	v_add_f32_e32 v18, v67, v18
	v_add_f32_e32 v192, v57, v192
	v_add_f32_e32 v18, v74, v18
	v_add_f32_e32 v192, v58, v192
	v_pk_mul_f32 v[78:79], v[84:85], v[84:85]
	v_pk_mul_f32 v[52:53], v[52:53], v[52:53]
	v_add_f32_e32 v18, v75, v18
	v_add_f32_e32 v192, v59, v192
	v_add_f32_e32 v18, v78, v18
	v_add_f32_e32 v192, v52, v192
	v_pk_mul_f32 v[80:81], v[128:129], v[128:129]
	v_pk_mul_f32 v[54:55], v[54:55], v[54:55]
	v_add_f32_e32 v18, v79, v18
	v_add_f32_e32 v192, v53, v192
	v_add_f32_e32 v18, v80, v18
	v_add_f32_e32 v192, v54, v192
	v_pk_mul_f32 v[82:83], v[86:87], v[86:87]
	v_pk_mul_f32 v[62:63], v[104:105], v[104:105]
	v_add_f32_e32 v18, v81, v18
	v_add_f32_e32 v192, v55, v192
	v_add_f32_e32 v18, v82, v18
	v_add_f32_e32 v192, v62, v192
	v_pk_mul_f32 v[84:85], v[130:131], v[130:131]
	v_pk_mul_f32 v[210:211], v[106:107], v[106:107]
	v_add_f32_e32 v18, v83, v18
	v_add_f32_e32 v192, v63, v192
	v_add_f32_e32 v18, v84, v18
	v_add_f32_e32 v192, v210, v192
	v_add_f32_e32 v18, v85, v18
	v_add_f32_e32 v192, v211, v192
	v_mov_b32_e32 v135, v18
	v_mov_b32_e32 v146, v192
	v_pk_mul_f32 v[18:19], v[44:45], v[44:45]
	v_pk_mul_f32 v[192:193], v[28:29], v[28:29]
	v_pk_mul_f32 v[44:45], v[46:47], v[46:47]
	v_pk_mul_f32 v[28:29], v[30:31], v[30:31]
	v_add_f32_e32 v18, v18, v19
	v_add_f32_e32 v192, v192, v193
	v_add_f32_e32 v18, v44, v18
	v_add_f32_e32 v192, v28, v192
	v_pk_mul_f32 v[40:41], v[40:41], v[40:41]
	v_pk_mul_f32 v[24:25], v[24:25], v[24:25]
	v_add_f32_e32 v18, v45, v18
	v_add_f32_e32 v192, v29, v192
	v_add_f32_e32 v18, v40, v18
	v_add_f32_e32 v192, v24, v192
	v_pk_mul_f32 v[42:43], v[42:43], v[42:43]
	v_pk_mul_f32 v[26:27], v[26:27], v[26:27]
	v_add_f32_e32 v18, v41, v18
	v_add_f32_e32 v192, v25, v192
	v_add_f32_e32 v18, v42, v18
	v_add_f32_e32 v192, v26, v192
	v_pk_mul_f32 v[36:37], v[36:37], v[36:37]
	v_pk_mul_f32 v[20:21], v[20:21], v[20:21]
	v_add_f32_e32 v18, v43, v18
	v_add_f32_e32 v192, v27, v192
	v_add_f32_e32 v18, v36, v18
	v_add_f32_e32 v192, v20, v192
	v_pk_mul_f32 v[38:39], v[38:39], v[38:39]
	v_pk_mul_f32 v[22:23], v[22:23], v[22:23]
	v_add_f32_e32 v18, v37, v18
	v_add_f32_e32 v192, v21, v192
	v_add_f32_e32 v18, v38, v18
	v_add_f32_e32 v192, v22, v192
	v_pk_mul_f32 v[46:47], v[48:49], v[48:49]
	v_pk_mul_f32 v[30:31], v[32:33], v[32:33]
	v_add_f32_e32 v18, v39, v18
	v_add_f32_e32 v192, v23, v192
	v_add_f32_e32 v18, v46, v18
	v_add_f32_e32 v192, v30, v192
	v_pk_mul_f32 v[48:49], v[50:51], v[50:51]
	v_pk_mul_f32 v[32:33], v[34:35], v[34:35]
	v_add_f32_e32 v18, v47, v18
	v_add_f32_e32 v192, v31, v192
	v_add_f32_e32 v18, v48, v18
	v_add_f32_e32 v192, v32, v192
	v_add_f32_e32 v18, v49, v18
	v_add_f32_e32 v192, v33, v192
	v_mov_b32_e32 v147, v18
	v_mov_b32_e32 v148, v192
	v_pk_mul_f32 v[12:13], v[12:13], v[12:13]
	v_pk_mul_f32 v[14:15], v[14:15], v[14:15]
	v_add_f32_e32 v12, v12, v13
	v_add_f32_e32 v12, v14, v12
	v_pk_mul_f32 v[8:9], v[8:9], v[8:9]
	v_add_f32_e32 v12, v15, v12
	v_add_f32_e32 v8, v8, v12
	v_pk_mul_f32 v[10:11], v[10:11], v[10:11]
	v_add_f32_e32 v8, v9, v8
	v_add_f32_e32 v8, v10, v8
	v_pk_mul_f32 v[4:5], v[4:5], v[4:5]
	v_add_f32_e32 v8, v11, v8
	v_add_f32_e32 v4, v4, v8
	v_pk_mul_f32 v[6:7], v[6:7], v[6:7]
	v_add_f32_e32 v4, v5, v4
	v_add_f32_e32 v4, v6, v4
	v_pk_mul_f32 v[0:1], v[0:1], v[0:1]
	v_add_f32_e32 v4, v7, v4
	v_add_f32_e32 v0, v0, v4
	v_pk_mul_f32 v[2:3], v[2:3], v[2:3]
	v_add_f32_e32 v0, v1, v0
	v_add_f32_e32 v0, v2, v0
	v_add_f32_e32 v0, v3, v0
	v_mov_b32_e32 v149, v0
	ds_bpermute_b32 v172, v16, v132
	ds_bpermute_b32 v173, v16, v133
	ds_bpermute_b32 v174, v16, v134
	ds_bpermute_b32 v175, v16, v135
	ds_bpermute_b32 v180, v16, v146
	ds_bpermute_b32 v181, v16, v147
	ds_bpermute_b32 v182, v16, v148
	ds_bpermute_b32 v183, v16, v149
	s_waitcnt lgkmcnt(0)
	v_add_f32_e32 v132, v132, v172
	v_add_f32_e32 v133, v133, v173
	v_add_f32_e32 v134, v134, v174
	v_add_f32_e32 v135, v135, v175
	v_add_f32_e32 v146, v146, v180
	v_add_f32_e32 v147, v147, v181
	v_add_f32_e32 v148, v148, v182
	v_add_f32_e32 v149, v149, v183
	ds_bpermute_b32 v172, v17, v132
	ds_bpermute_b32 v173, v17, v133
	ds_bpermute_b32 v174, v17, v134
	ds_bpermute_b32 v175, v17, v135
	ds_bpermute_b32 v180, v17, v146
	ds_bpermute_b32 v181, v17, v147
	ds_bpermute_b32 v182, v17, v148
	ds_bpermute_b32 v183, v17, v149
	s_and_saveexec_b64 s[52:53], s[42:43]
	s_cbranch_execz .LBB0_91
	s_waitcnt lgkmcnt(0)
	v_add_f32_e32 v132, v132, v172
	v_lshlrev_b64 v[18:19], 6, v[168:169]
	v_lshl_add_u64 v[18:19], s[50:51], 0, v[18:19]
	global_store_dword v[18:19], v132, off
	v_add_f32_e32 v133, v133, v173
	v_lshlrev_b64 v[18:19], 6, v[166:167]
	v_lshl_add_u64 v[18:19], s[50:51], 0, v[18:19]
	global_store_dword v[18:19], v133, off
	v_add_f32_e32 v134, v134, v174
	v_lshlrev_b64 v[18:19], 6, v[164:165]
	v_lshl_add_u64 v[18:19], s[50:51], 0, v[18:19]
	global_store_dword v[18:19], v134, off
	v_add_f32_e32 v135, v135, v175
	v_lshlrev_b64 v[18:19], 6, v[162:163]
	v_lshl_add_u64 v[18:19], s[50:51], 0, v[18:19]
	global_store_dword v[18:19], v135, off
	v_add_f32_e32 v146, v146, v180
	v_lshlrev_b64 v[18:19], 6, v[76:77]
	v_lshl_add_u64 v[18:19], s[50:51], 0, v[18:19]
	global_store_dword v[18:19], v146, off
	v_add_f32_e32 v147, v147, v181
	v_lshlrev_b64 v[18:19], 6, v[72:73]
	v_lshl_add_u64 v[18:19], s[50:51], 0, v[18:19]
	global_store_dword v[18:19], v147, off
	v_add_f32_e32 v148, v148, v182
	v_lshlrev_b64 v[18:19], 6, v[70:71]
	v_lshl_add_u64 v[18:19], s[50:51], 0, v[18:19]
	global_store_dword v[18:19], v148, off
	v_add_f32_e32 v149, v149, v183
	v_lshlrev_b64 v[18:19], 6, v[68:69]
	v_lshl_add_u64 v[18:19], s[50:51], 0, v[18:19]
	global_store_dword v[18:19], v149, off
	s_branch .LBB0_91

.Lm4bp_248:
	s_waitcnt lgkmcnt(0)
	s_mov_b32 s100, 0
	s_barrier
	v_mfma_f32_16x16x32_bf16 v[60:63], v[128:131], v[162:165], 0
	v_mfma_f32_16x16x32_bf16 v[56:59], v[136:139], v[162:165], 0
	v_mfma_f32_16x16x32_bf16 v[48:51], v[128:131], v[170:173], 0
	v_mfma_f32_16x16x32_bf16 v[40:43], v[136:139], v[170:173], 0
	v_mfma_f32_16x16x32_bf16 v[32:35], v[128:131], v[178:181], 0
	v_mfma_f32_16x16x32_bf16 v[24:27], v[136:139], v[178:181], 0
	v_mfma_f32_16x16x32_bf16 v[16:19], v[128:131], v[194:197], 0
	v_mfma_f32_16x16x32_bf16 v[8:11], v[136:139], v[194:197], 0
	v_mfma_f32_16x16x32_bf16 v[60:63], v[132:135], v[166:169], v[60:63]
	v_mfma_f32_16x16x32_bf16 v[56:59], v[146:149], v[166:169], v[56:59]
	v_mfma_f32_16x16x32_bf16 v[48:51], v[132:135], v[174:177], v[48:51]
	v_mfma_f32_16x16x32_bf16 v[40:43], v[146:149], v[174:177], v[40:43]
	v_mfma_f32_16x16x32_bf16 v[32:35], v[132:135], v[182:185], v[32:35]
	v_mfma_f32_16x16x32_bf16 v[24:27], v[146:149], v[182:185], v[24:27]
	v_mfma_f32_16x16x32_bf16 v[16:19], v[132:135], v[210:213], v[16:19]
	v_mfma_f32_16x16x32_bf16 v[8:11], v[146:149], v[210:213], v[8:11]
	v_mfma_f32_16x16x32_bf16 v[52:55], v[214:217], v[162:165], 0
	v_mfma_f32_16x16x32_bf16 v[44:47], v[222:225], v[162:165], 0
	v_mfma_f32_16x16x32_bf16 v[36:39], v[214:217], v[170:173], 0
	v_mfma_f32_16x16x32_bf16 v[28:31], v[222:225], v[170:173], 0
	v_mfma_f32_16x16x32_bf16 v[20:23], v[214:217], v[178:181], 0
	v_mfma_f32_16x16x32_bf16 v[12:15], v[222:225], v[178:181], 0
	v_mfma_f32_16x16x32_bf16 v[4:7], v[214:217], v[194:197], 0
	v_mfma_f32_16x16x32_bf16 v[0:3], v[222:225], v[194:197], 0
	v_mfma_f32_16x16x32_bf16 v[52:55], v[218:221], v[166:169], v[52:55]
	v_mfma_f32_16x16x32_bf16 v[44:47], v[226:229], v[166:169], v[44:47]
	v_mfma_f32_16x16x32_bf16 v[36:39], v[218:221], v[174:177], v[36:39]
	v_mfma_f32_16x16x32_bf16 v[28:31], v[226:229], v[174:177], v[28:31]
	v_mfma_f32_16x16x32_bf16 v[20:23], v[218:221], v[182:185], v[20:23]
	v_mfma_f32_16x16x32_bf16 v[12:15], v[226:229], v[182:185], v[12:15]
	v_mfma_f32_16x16x32_bf16 v[4:7], v[218:221], v[210:213], v[4:7]
	v_mfma_f32_16x16x32_bf16 v[0:3], v[226:229], v[210:213], v[0:3]
	s_barrier
	s_add_i32 s6, 0, 0x18000
	v_add_u32_e32 v146, s6, v206
	ds_read_b128 v[128:131], v146
	ds_read_b128 v[132:135], v146 offset:1024
	ds_read_b128 v[136:139], v146 offset:2048
	ds_read_b128 v[146:149], v146 offset:3072
	s_add_u32 s58, s58, 0x40000
	s_addc_u32 s59, s59, 0
	s_mov_b32 m0, s70
	v_lshl_add_u64 v[214:215], s[58:59], 0, v[154:155]
	ds_read_b128 v[162:165], v208 offset:32768
	ds_read_b128 v[166:169], v208 offset:33792
	ds_read_b128 v[170:173], v208 offset:34816
	ds_read_b128 v[174:177], v208 offset:35840
	ds_read_b128 v[178:181], v208 offset:36864
	ds_read_b128 v[182:185], v208 offset:37888
	ds_read_b128 v[194:197], v208 offset:38912
	ds_read_b128 v[210:213], v208 offset:39936
	global_load_lds_dwordx4 v[214:215], off
	v_lshl_add_u64 v[214:215], s[58:59], 0, v[152:153]
	s_mov_b32 m0, s71
	s_nop 0
	global_load_lds_dwordx4 v[214:215], off
	s_add_i32 s19, 0, 0x1c000
	v_add_u32_e32 v192, s19, v206
	ds_read_b128 v[214:217], v192
	ds_read_b128 v[218:221], v192 offset:1024
	ds_read_b128 v[222:225], v192 offset:2048
	ds_read_b128 v[226:229], v192 offset:3072
	s_waitcnt vmcnt(8)
	s_waitcnt lgkmcnt(0)
	s_barrier
	v_mfma_f32_16x16x32_bf16 v[124:127], v[128:131], v[162:165], v[124:127]
	v_mfma_f32_16x16x32_bf16 v[120:123], v[136:139], v[162:165], v[120:123]
	v_mfma_f32_16x16x32_bf16 v[108:111], v[128:131], v[170:173], v[108:111]
	v_mfma_f32_16x16x32_bf16 v[104:107], v[136:139], v[170:173], v[104:107]
	v_mfma_f32_16x16x32_bf16 v[96:99], v[128:131], v[178:181], v[96:99]
	v_mfma_f32_16x16x32_bf16 v[88:91], v[136:139], v[178:181], v[88:91]
	v_mfma_f32_16x16x32_bf16 v[84:87], v[128:131], v[194:197], v[84:87]
	v_mfma_f32_16x16x32_bf16 v[80:83], v[136:139], v[194:197], v[80:83]
	v_mfma_f32_16x16x32_bf16 v[124:127], v[132:135], v[166:169], v[124:127]
	v_mfma_f32_16x16x32_bf16 v[120:123], v[146:149], v[166:169], v[120:123]
	v_mfma_f32_16x16x32_bf16 v[108:111], v[132:135], v[174:177], v[108:111]
	v_mfma_f32_16x16x32_bf16 v[104:107], v[146:149], v[174:177], v[104:107]
	v_mfma_f32_16x16x32_bf16 v[96:99], v[132:135], v[182:185], v[96:99]
	v_mfma_f32_16x16x32_bf16 v[88:91], v[146:149], v[182:185], v[88:91]
	v_mfma_f32_16x16x32_bf16 v[84:87], v[132:135], v[210:213], v[84:87]
	v_mfma_f32_16x16x32_bf16 v[80:83], v[146:149], v[210:213], v[80:83]
	v_mfma_f32_16x16x32_bf16 v[116:119], v[214:217], v[162:165], v[116:119]
	v_mfma_f32_16x16x32_bf16 v[112:115], v[222:225], v[162:165], v[112:115]
	v_mfma_f32_16x16x32_bf16 v[100:103], v[214:217], v[170:173], v[100:103]
	v_mfma_f32_16x16x32_bf16 v[92:95], v[222:225], v[170:173], v[92:95]
	v_mfma_f32_16x16x32_bf16 v[76:79], v[214:217], v[178:181], v[76:79]
	v_mfma_f32_16x16x32_bf16 v[72:75], v[222:225], v[178:181], v[72:75]
	v_mfma_f32_16x16x32_bf16 v[68:71], v[214:217], v[194:197], v[68:71]
	v_mfma_f32_16x16x32_bf16 v[64:67], v[222:225], v[194:197], v[64:67]
	v_mfma_f32_16x16x32_bf16 v[116:119], v[218:221], v[166:169], v[116:119]
	v_mfma_f32_16x16x32_bf16 v[112:115], v[226:229], v[166:169], v[112:115]
	v_mfma_f32_16x16x32_bf16 v[100:103], v[218:221], v[174:177], v[100:103]
	v_mfma_f32_16x16x32_bf16 v[92:95], v[226:229], v[174:177], v[92:95]
	v_mfma_f32_16x16x32_bf16 v[76:79], v[218:221], v[182:185], v[76:79]
	v_mfma_f32_16x16x32_bf16 v[72:75], v[226:229], v[182:185], v[72:75]
	v_mfma_f32_16x16x32_bf16 v[68:71], v[218:221], v[210:213], v[68:71]
	v_mfma_f32_16x16x32_bf16 v[64:67], v[226:229], v[210:213], v[64:67]
	s_barrier
	s_add_i32 s6, s6, s57
	v_lshl_add_u64 v[230:231], v[230:231], 0, s[36:37]
	s_mov_b32 m0, s6
	s_nop 0
	global_load_lds_dwordx4 v[230:231], off
	v_lshl_add_u64 v[230:231], v[232:233], 0, s[36:37]
	s_add_i32 m0, s6, 0x2000
	s_nop 0
	global_load_lds_dwordx4 v[230:231], off
	s_mov_b32 m0, s72
	v_lshl_add_u64 v[230:231], v[234:235], 0, s[36:37]
	ds_read_b128 v[162:165], v208 offset:49152
	ds_read_b128 v[166:169], v208 offset:50176
	ds_read_b128 v[170:173], v208 offset:51200
	ds_read_b128 v[174:177], v208 offset:52224
	ds_read_b128 v[178:181], v208 offset:53248
	ds_read_b128 v[182:185], v208 offset:54272
	ds_read_b128 v[194:197], v208 offset:55296
	ds_read_b128 v[210:213], v208 offset:56320
	global_load_lds_dwordx4 v[230:231], off
	v_lshl_add_u64 v[230:231], v[236:237], 0, s[36:37]
	s_mov_b32 m0, s73
	s_nop 0
	global_load_lds_dwordx4 v[230:231], off
	s_add_u32 s54, s54, 0x40080
	s_addc_u32 s55, s55, 0
	s_add_i32 s6, s19, s57
	v_lshl_add_u64 v[250:251], s[54:55], 0, v[140:141]
	s_mov_b32 m0, s6
	s_nop 0
	global_load_lds_dwordx4 v[250:251], off
	v_lshl_add_u64 v[250:251], s[54:55], 0, v[150:151]
	s_add_i32 m0, s6, 0x2000
	s_nop 0
	global_load_lds_dwordx4 v[250:251], off
	s_add_i32 s82, s82, 2
	s_add_u32 s52, s52, 0x100
	s_addc_u32 s53, s53, 0
	s_add_u32 s39, s39, 0x100
	s_addc_u32 s51, s51, 0
	s_cmp_gt_u32 s82, 13
	s_waitcnt vmcnt(8)
	s_waitcnt lgkmcnt(0)
	s_barrier
	v_mfma_f32_16x16x32_bf16 v[60:63], v[128:131], v[162:165], v[60:63]
	v_mfma_f32_16x16x32_bf16 v[56:59], v[136:139], v[162:165], v[56:59]
	v_mfma_f32_16x16x32_bf16 v[48:51], v[128:131], v[170:173], v[48:51]
	v_mfma_f32_16x16x32_bf16 v[40:43], v[136:139], v[170:173], v[40:43]
	v_mfma_f32_16x16x32_bf16 v[32:35], v[128:131], v[178:181], v[32:35]
	v_mfma_f32_16x16x32_bf16 v[24:27], v[136:139], v[178:181], v[24:27]
	v_mfma_f32_16x16x32_bf16 v[16:19], v[128:131], v[194:197], v[16:19]
	v_mfma_f32_16x16x32_bf16 v[8:11], v[136:139], v[194:197], v[8:11]
	v_mfma_f32_16x16x32_bf16 v[60:63], v[132:135], v[166:169], v[60:63]
	v_mfma_f32_16x16x32_bf16 v[56:59], v[146:149], v[166:169], v[56:59]
	v_mfma_f32_16x16x32_bf16 v[48:51], v[132:135], v[174:177], v[48:51]
	v_mfma_f32_16x16x32_bf16 v[40:43], v[146:149], v[174:177], v[40:43]
	v_mfma_f32_16x16x32_bf16 v[32:35], v[132:135], v[182:185], v[32:35]
	v_mfma_f32_16x16x32_bf16 v[24:27], v[146:149], v[182:185], v[24:27]
	v_mfma_f32_16x16x32_bf16 v[16:19], v[132:135], v[210:213], v[16:19]
	v_mfma_f32_16x16x32_bf16 v[8:11], v[146:149], v[210:213], v[8:11]
	v_mfma_f32_16x16x32_bf16 v[52:55], v[214:217], v[162:165], v[52:55]
	v_mfma_f32_16x16x32_bf16 v[44:47], v[222:225], v[162:165], v[44:47]
	v_mfma_f32_16x16x32_bf16 v[36:39], v[214:217], v[170:173], v[36:39]
	v_mfma_f32_16x16x32_bf16 v[28:31], v[222:225], v[170:173], v[28:31]
	v_mfma_f32_16x16x32_bf16 v[20:23], v[214:217], v[178:181], v[20:23]
	v_mfma_f32_16x16x32_bf16 v[12:15], v[222:225], v[178:181], v[12:15]
	v_mfma_f32_16x16x32_bf16 v[4:7], v[214:217], v[194:197], v[4:7]
	v_mfma_f32_16x16x32_bf16 v[0:3], v[222:225], v[194:197], v[0:3]
	v_mfma_f32_16x16x32_bf16 v[52:55], v[218:221], v[166:169], v[52:55]
	v_mfma_f32_16x16x32_bf16 v[44:47], v[226:229], v[166:169], v[44:47]
	v_mfma_f32_16x16x32_bf16 v[36:39], v[218:221], v[174:177], v[36:39]
	v_mfma_f32_16x16x32_bf16 v[28:31], v[226:229], v[174:177], v[28:31]
	v_mfma_f32_16x16x32_bf16 v[20:23], v[218:221], v[182:185], v[20:23]
	v_mfma_f32_16x16x32_bf16 v[12:15], v[226:229], v[182:185], v[12:15]
	v_mfma_f32_16x16x32_bf16 v[4:7], v[218:221], v[210:213], v[4:7]
	v_mfma_f32_16x16x32_bf16 v[0:3], v[226:229], v[210:213], v[0:3]
	s_barrier
.LBB0_248:
	s_add_u32 s6, s52, 0xfffc0080
	s_addc_u32 s19, s53, -1
	s_add_i32 s23, 0, 0x10000
	v_add_u32_e32 v146, s23, v206
	ds_read_b128 v[128:131], v146
	ds_read_b128 v[132:135], v146 offset:1024
	ds_read_b128 v[136:139], v146 offset:2048
	ds_read_b128 v[146:149], v146 offset:3072
	s_cmp_eq_u32 s82, 12
	s_cselect_b32 s59, s10, s19
	s_cselect_b32 s58, s11, s6
	s_cselect_b32 s55, s12, s51
	s_cselect_b32 s54, s35, s39
	v_lshl_add_u64 v[214:215], s[52:53], 0, v[158:159]
	s_add_i32 m0, s68, 0xc000
	ds_read_b128 v[162:165], v208
	ds_read_b128 v[166:169], v208 offset:1024
	ds_read_b128 v[170:173], v208 offset:2048
	ds_read_b128 v[174:177], v208 offset:3072
	ds_read_b128 v[178:181], v208 offset:4096
	ds_read_b128 v[182:185], v208 offset:5120
	ds_read_b128 v[194:197], v208 offset:6144
	ds_read_b128 v[210:213], v208 offset:7168
	global_load_lds_dwordx4 v[214:215], off
	v_lshl_add_u64 v[214:215], s[52:53], 0, v[160:161]
	s_add_i32 m0, s68, 0xe000
	s_nop 0
	global_load_lds_dwordx4 v[214:215], off
	s_add_i32 s6, 0, 0x14000
	v_add_u32_e32 v192, s6, v206
	ds_read_b128 v[214:217], v192
	ds_read_b128 v[218:221], v192 offset:1024
	ds_read_b128 v[222:225], v192 offset:2048
	ds_read_b128 v[226:229], v192 offset:3072
	s_waitcnt vmcnt(8)
	s_waitcnt lgkmcnt(0)
	s_barrier
	v_mfma_f32_16x16x32_bf16 v[124:127], v[128:131], v[162:165], v[124:127]
	v_mfma_f32_16x16x32_bf16 v[120:123], v[136:139], v[162:165], v[120:123]
	v_mfma_f32_16x16x32_bf16 v[108:111], v[128:131], v[170:173], v[108:111]
	v_mfma_f32_16x16x32_bf16 v[104:107], v[136:139], v[170:173], v[104:107]
	v_mfma_f32_16x16x32_bf16 v[96:99], v[128:131], v[178:181], v[96:99]
	v_mfma_f32_16x16x32_bf16 v[88:91], v[136:139], v[178:181], v[88:91]
	v_mfma_f32_16x16x32_bf16 v[84:87], v[128:131], v[194:197], v[84:87]
	v_mfma_f32_16x16x32_bf16 v[80:83], v[136:139], v[194:197], v[80:83]
	v_mfma_f32_16x16x32_bf16 v[124:127], v[132:135], v[166:169], v[124:127]
	v_mfma_f32_16x16x32_bf16 v[120:123], v[146:149], v[166:169], v[120:123]
	v_mfma_f32_16x16x32_bf16 v[108:111], v[132:135], v[174:177], v[108:111]
	v_mfma_f32_16x16x32_bf16 v[104:107], v[146:149], v[174:177], v[104:107]
	v_mfma_f32_16x16x32_bf16 v[96:99], v[132:135], v[182:185], v[96:99]
	v_mfma_f32_16x16x32_bf16 v[88:91], v[146:149], v[182:185], v[88:91]
	v_mfma_f32_16x16x32_bf16 v[84:87], v[132:135], v[210:213], v[84:87]
	v_mfma_f32_16x16x32_bf16 v[80:83], v[146:149], v[210:213], v[80:83]
	v_mfma_f32_16x16x32_bf16 v[116:119], v[214:217], v[162:165], v[116:119]
	v_mfma_f32_16x16x32_bf16 v[112:115], v[222:225], v[162:165], v[112:115]
	v_mfma_f32_16x16x32_bf16 v[100:103], v[214:217], v[170:173], v[100:103]
	v_mfma_f32_16x16x32_bf16 v[92:95], v[222:225], v[170:173], v[92:95]
	v_mfma_f32_16x16x32_bf16 v[76:79], v[214:217], v[178:181], v[76:79]
	v_mfma_f32_16x16x32_bf16 v[72:75], v[222:225], v[178:181], v[72:75]
	v_mfma_f32_16x16x32_bf16 v[68:71], v[214:217], v[194:197], v[68:71]
	v_mfma_f32_16x16x32_bf16 v[64:67], v[222:225], v[194:197], v[64:67]
	v_mfma_f32_16x16x32_bf16 v[116:119], v[218:221], v[166:169], v[116:119]
	v_mfma_f32_16x16x32_bf16 v[112:115], v[226:229], v[166:169], v[112:115]
	v_mfma_f32_16x16x32_bf16 v[100:103], v[218:221], v[174:177], v[100:103]
	v_mfma_f32_16x16x32_bf16 v[92:95], v[226:229], v[174:177], v[92:95]
	v_mfma_f32_16x16x32_bf16 v[76:79], v[218:221], v[182:185], v[76:79]
	v_mfma_f32_16x16x32_bf16 v[72:75], v[226:229], v[182:185], v[72:75]
	v_mfma_f32_16x16x32_bf16 v[68:71], v[218:221], v[210:213], v[68:71]
	v_mfma_f32_16x16x32_bf16 v[64:67], v[226:229], v[210:213], v[64:67]
	s_barrier
	s_add_i32 s19, s23, s57
	v_lshl_add_u64 v[230:231], s[54:55], 0, v[140:141]
	s_mov_b32 m0, s19
	s_nop 0
	global_load_lds_dwordx4 v[230:231], off
	v_lshl_add_u64 v[232:233], s[54:55], 0, v[150:151]
	s_add_i32 m0, s19, 0x2000
	s_nop 0
	global_load_lds_dwordx4 v[232:233], off
	s_mov_b32 m0, s68
	v_lshl_add_u64 v[234:235], s[58:59], 0, v[154:155]
	ds_read_b128 v[162:165], v208 offset:16384
	ds_read_b128 v[166:169], v208 offset:17408
	ds_read_b128 v[170:173], v208 offset:18432
	ds_read_b128 v[174:177], v208 offset:19456
	ds_read_b128 v[178:181], v208 offset:20480
	ds_read_b128 v[182:185], v208 offset:21504
	ds_read_b128 v[194:197], v208 offset:22528
	ds_read_b128 v[210:213], v208 offset:23552
	global_load_lds_dwordx4 v[234:235], off
	v_lshl_add_u64 v[236:237], s[58:59], 0, v[152:153]
	s_mov_b32 m0, s69
	s_nop 0
	global_load_lds_dwordx4 v[236:237], off
	s_add_u32 s84, s54, 0x40000
	s_addc_u32 s85, s55, 0
	s_add_i32 s6, s6, s57
	v_lshl_add_u64 v[250:251], s[84:85], 0, v[140:141]
	s_mov_b32 m0, s6
	s_nop 0
	global_load_lds_dwordx4 v[250:251], off
	v_lshl_add_u64 v[250:251], s[84:85], 0, v[150:151]
	s_add_i32 m0, s6, 0x2000
	s_nop 0
	global_load_lds_dwordx4 v[250:251], off
	s_waitcnt vmcnt(8)
	s_waitcnt lgkmcnt(0)
	s_barrier
	v_mfma_f32_16x16x32_bf16 v[60:63], v[128:131], v[162:165], v[60:63]
	v_mfma_f32_16x16x32_bf16 v[56:59], v[136:139], v[162:165], v[56:59]
	v_mfma_f32_16x16x32_bf16 v[48:51], v[128:131], v[170:173], v[48:51]
	v_mfma_f32_16x16x32_bf16 v[40:43], v[136:139], v[170:173], v[40:43]
	v_mfma_f32_16x16x32_bf16 v[32:35], v[128:131], v[178:181], v[32:35]
	v_mfma_f32_16x16x32_bf16 v[24:27], v[136:139], v[178:181], v[24:27]
	v_mfma_f32_16x16x32_bf16 v[16:19], v[128:131], v[194:197], v[16:19]
	v_mfma_f32_16x16x32_bf16 v[8:11], v[136:139], v[194:197], v[8:11]
	v_mfma_f32_16x16x32_bf16 v[60:63], v[132:135], v[166:169], v[60:63]
	v_mfma_f32_16x16x32_bf16 v[56:59], v[146:149], v[166:169], v[56:59]
	v_mfma_f32_16x16x32_bf16 v[48:51], v[132:135], v[174:177], v[48:51]
	v_mfma_f32_16x16x32_bf16 v[40:43], v[146:149], v[174:177], v[40:43]
	v_mfma_f32_16x16x32_bf16 v[32:35], v[132:135], v[182:185], v[32:35]
	v_mfma_f32_16x16x32_bf16 v[24:27], v[146:149], v[182:185], v[24:27]
	v_mfma_f32_16x16x32_bf16 v[16:19], v[132:135], v[210:213], v[16:19]
	v_mfma_f32_16x16x32_bf16 v[8:11], v[146:149], v[210:213], v[8:11]
	v_mfma_f32_16x16x32_bf16 v[52:55], v[214:217], v[162:165], v[52:55]
	v_mfma_f32_16x16x32_bf16 v[44:47], v[222:225], v[162:165], v[44:47]
	v_mfma_f32_16x16x32_bf16 v[36:39], v[214:217], v[170:173], v[36:39]
	v_mfma_f32_16x16x32_bf16 v[28:31], v[222:225], v[170:173], v[28:31]
	v_mfma_f32_16x16x32_bf16 v[20:23], v[214:217], v[178:181], v[20:23]
	v_mfma_f32_16x16x32_bf16 v[12:15], v[222:225], v[178:181], v[12:15]
	v_mfma_f32_16x16x32_bf16 v[4:7], v[214:217], v[194:197], v[4:7]
	v_mfma_f32_16x16x32_bf16 v[0:3], v[222:225], v[194:197], v[0:3]
	v_mfma_f32_16x16x32_bf16 v[52:55], v[218:221], v[166:169], v[52:55]
	v_mfma_f32_16x16x32_bf16 v[44:47], v[226:229], v[166:169], v[44:47]
	v_mfma_f32_16x16x32_bf16 v[36:39], v[218:221], v[174:177], v[36:39]
	v_mfma_f32_16x16x32_bf16 v[28:31], v[226:229], v[174:177], v[28:31]
	v_mfma_f32_16x16x32_bf16 v[20:23], v[218:221], v[182:185], v[20:23]
	v_mfma_f32_16x16x32_bf16 v[12:15], v[226:229], v[182:185], v[12:15]
	v_mfma_f32_16x16x32_bf16 v[4:7], v[218:221], v[210:213], v[4:7]
	v_mfma_f32_16x16x32_bf16 v[0:3], v[226:229], v[210:213], v[0:3]
	s_barrier
	s_add_i32 s6, 0, 0x18000
	v_add_u32_e32 v146, s6, v206
	ds_read_b128 v[128:131], v146
	ds_read_b128 v[132:135], v146 offset:1024
	ds_read_b128 v[136:139], v146 offset:2048
	ds_read_b128 v[146:149], v146 offset:3072
	s_add_u32 s58, s58, 0x40000
	s_addc_u32 s59, s59, 0
	s_mov_b32 m0, s70
	v_lshl_add_u64 v[214:215], s[58:59], 0, v[154:155]
	ds_read_b128 v[162:165], v208 offset:32768
	ds_read_b128 v[166:169], v208 offset:33792
	ds_read_b128 v[170:173], v208 offset:34816
	ds_read_b128 v[174:177], v208 offset:35840
	ds_read_b128 v[178:181], v208 offset:36864
	ds_read_b128 v[182:185], v208 offset:37888
	ds_read_b128 v[194:197], v208 offset:38912
	ds_read_b128 v[210:213], v208 offset:39936
	global_load_lds_dwordx4 v[214:215], off
	v_lshl_add_u64 v[214:215], s[58:59], 0, v[152:153]
	s_mov_b32 m0, s71
	s_nop 0
	global_load_lds_dwordx4 v[214:215], off
	s_add_i32 s19, 0, 0x1c000
	v_add_u32_e32 v192, s19, v206
	ds_read_b128 v[214:217], v192
	ds_read_b128 v[218:221], v192 offset:1024
	ds_read_b128 v[222:225], v192 offset:2048
	ds_read_b128 v[226:229], v192 offset:3072
	s_waitcnt vmcnt(8)
	s_waitcnt lgkmcnt(0)
	s_barrier
	v_mfma_f32_16x16x32_bf16 v[124:127], v[128:131], v[162:165], v[124:127]
	v_mfma_f32_16x16x32_bf16 v[120:123], v[136:139], v[162:165], v[120:123]
	v_mfma_f32_16x16x32_bf16 v[108:111], v[128:131], v[170:173], v[108:111]
	v_mfma_f32_16x16x32_bf16 v[104:107], v[136:139], v[170:173], v[104:107]
	v_mfma_f32_16x16x32_bf16 v[96:99], v[128:131], v[178:181], v[96:99]
	v_mfma_f32_16x16x32_bf16 v[88:91], v[136:139], v[178:181], v[88:91]
	v_mfma_f32_16x16x32_bf16 v[84:87], v[128:131], v[194:197], v[84:87]
	v_mfma_f32_16x16x32_bf16 v[80:83], v[136:139], v[194:197], v[80:83]
	v_mfma_f32_16x16x32_bf16 v[124:127], v[132:135], v[166:169], v[124:127]
	v_mfma_f32_16x16x32_bf16 v[120:123], v[146:149], v[166:169], v[120:123]
	v_mfma_f32_16x16x32_bf16 v[108:111], v[132:135], v[174:177], v[108:111]
	v_mfma_f32_16x16x32_bf16 v[104:107], v[146:149], v[174:177], v[104:107]
	v_mfma_f32_16x16x32_bf16 v[96:99], v[132:135], v[182:185], v[96:99]
	v_mfma_f32_16x16x32_bf16 v[88:91], v[146:149], v[182:185], v[88:91]
	v_mfma_f32_16x16x32_bf16 v[84:87], v[132:135], v[210:213], v[84:87]
	v_mfma_f32_16x16x32_bf16 v[80:83], v[146:149], v[210:213], v[80:83]
	v_mfma_f32_16x16x32_bf16 v[116:119], v[214:217], v[162:165], v[116:119]
	v_mfma_f32_16x16x32_bf16 v[112:115], v[222:225], v[162:165], v[112:115]
	v_mfma_f32_16x16x32_bf16 v[100:103], v[214:217], v[170:173], v[100:103]
	v_mfma_f32_16x16x32_bf16 v[92:95], v[222:225], v[170:173], v[92:95]
	v_mfma_f32_16x16x32_bf16 v[76:79], v[214:217], v[178:181], v[76:79]
	v_mfma_f32_16x16x32_bf16 v[72:75], v[222:225], v[178:181], v[72:75]
	v_mfma_f32_16x16x32_bf16 v[68:71], v[214:217], v[194:197], v[68:71]
	v_mfma_f32_16x16x32_bf16 v[64:67], v[222:225], v[194:197], v[64:67]
	v_mfma_f32_16x16x32_bf16 v[116:119], v[218:221], v[166:169], v[116:119]
	v_mfma_f32_16x16x32_bf16 v[112:115], v[226:229], v[166:169], v[112:115]
	v_mfma_f32_16x16x32_bf16 v[100:103], v[218:221], v[174:177], v[100:103]
	v_mfma_f32_16x16x32_bf16 v[92:95], v[226:229], v[174:177], v[92:95]
	v_mfma_f32_16x16x32_bf16 v[76:79], v[218:221], v[182:185], v[76:79]
	v_mfma_f32_16x16x32_bf16 v[72:75], v[226:229], v[182:185], v[72:75]
	v_mfma_f32_16x16x32_bf16 v[68:71], v[218:221], v[210:213], v[68:71]
	v_mfma_f32_16x16x32_bf16 v[64:67], v[226:229], v[210:213], v[64:67]
	s_barrier
	s_add_i32 s6, s6, s57
	v_lshl_add_u64 v[230:231], v[230:231], 0, s[36:37]
	s_mov_b32 m0, s6
	s_nop 0
	global_load_lds_dwordx4 v[230:231], off
	v_lshl_add_u64 v[230:231], v[232:233], 0, s[36:37]
	s_add_i32 m0, s6, 0x2000
	s_nop 0
	global_load_lds_dwordx4 v[230:231], off
	s_mov_b32 m0, s72
	v_lshl_add_u64 v[230:231], v[234:235], 0, s[36:37]
	ds_read_b128 v[162:165], v208 offset:49152
	ds_read_b128 v[166:169], v208 offset:50176
	ds_read_b128 v[170:173], v208 offset:51200
	ds_read_b128 v[174:177], v208 offset:52224
	ds_read_b128 v[178:181], v208 offset:53248
	ds_read_b128 v[182:185], v208 offset:54272
	ds_read_b128 v[194:197], v208 offset:55296
	ds_read_b128 v[210:213], v208 offset:56320
	global_load_lds_dwordx4 v[230:231], off
	v_lshl_add_u64 v[230:231], v[236:237], 0, s[36:37]
	s_mov_b32 m0, s73
	s_nop 0
	global_load_lds_dwordx4 v[230:231], off
	s_add_u32 s54, s54, 0x40080
	s_addc_u32 s55, s55, 0
	s_add_i32 s6, s19, s57
	v_lshl_add_u64 v[250:251], s[54:55], 0, v[140:141]
	s_mov_b32 m0, s6
	s_nop 0
	global_load_lds_dwordx4 v[250:251], off
	v_lshl_add_u64 v[250:251], s[54:55], 0, v[150:151]
	s_add_i32 m0, s6, 0x2000
	s_nop 0
	global_load_lds_dwordx4 v[250:251], off
	s_add_i32 s82, s82, 2
	s_add_u32 s52, s52, 0x100
	s_addc_u32 s53, s53, 0
	s_add_u32 s39, s39, 0x100
	s_addc_u32 s51, s51, 0
	s_cmp_gt_u32 s82, 13
	s_waitcnt vmcnt(8)
	s_waitcnt lgkmcnt(0)
	s_barrier
	v_mfma_f32_16x16x32_bf16 v[60:63], v[128:131], v[162:165], v[60:63]
	v_mfma_f32_16x16x32_bf16 v[56:59], v[136:139], v[162:165], v[56:59]
	v_mfma_f32_16x16x32_bf16 v[48:51], v[128:131], v[170:173], v[48:51]
	v_mfma_f32_16x16x32_bf16 v[40:43], v[136:139], v[170:173], v[40:43]
	v_mfma_f32_16x16x32_bf16 v[32:35], v[128:131], v[178:181], v[32:35]
	v_mfma_f32_16x16x32_bf16 v[24:27], v[136:139], v[178:181], v[24:27]
	v_mfma_f32_16x16x32_bf16 v[16:19], v[128:131], v[194:197], v[16:19]
	v_mfma_f32_16x16x32_bf16 v[8:11], v[136:139], v[194:197], v[8:11]
	v_mfma_f32_16x16x32_bf16 v[60:63], v[132:135], v[166:169], v[60:63]
	v_mfma_f32_16x16x32_bf16 v[56:59], v[146:149], v[166:169], v[56:59]
	v_mfma_f32_16x16x32_bf16 v[48:51], v[132:135], v[174:177], v[48:51]
	v_mfma_f32_16x16x32_bf16 v[40:43], v[146:149], v[174:177], v[40:43]
	v_mfma_f32_16x16x32_bf16 v[32:35], v[132:135], v[182:185], v[32:35]
	v_mfma_f32_16x16x32_bf16 v[24:27], v[146:149], v[182:185], v[24:27]
	v_mfma_f32_16x16x32_bf16 v[16:19], v[132:135], v[210:213], v[16:19]
	v_mfma_f32_16x16x32_bf16 v[8:11], v[146:149], v[210:213], v[8:11]
	v_mfma_f32_16x16x32_bf16 v[52:55], v[214:217], v[162:165], v[52:55]
	v_mfma_f32_16x16x32_bf16 v[44:47], v[222:225], v[162:165], v[44:47]
	v_mfma_f32_16x16x32_bf16 v[36:39], v[214:217], v[170:173], v[36:39]
	v_mfma_f32_16x16x32_bf16 v[28:31], v[222:225], v[170:173], v[28:31]
	v_mfma_f32_16x16x32_bf16 v[20:23], v[214:217], v[178:181], v[20:23]
	v_mfma_f32_16x16x32_bf16 v[12:15], v[222:225], v[178:181], v[12:15]
	v_mfma_f32_16x16x32_bf16 v[4:7], v[214:217], v[194:197], v[4:7]
	v_mfma_f32_16x16x32_bf16 v[0:3], v[222:225], v[194:197], v[0:3]
	v_mfma_f32_16x16x32_bf16 v[52:55], v[218:221], v[166:169], v[52:55]
	v_mfma_f32_16x16x32_bf16 v[44:47], v[226:229], v[166:169], v[44:47]
	v_mfma_f32_16x16x32_bf16 v[36:39], v[218:221], v[174:177], v[36:39]
	v_mfma_f32_16x16x32_bf16 v[28:31], v[226:229], v[174:177], v[28:31]
	v_mfma_f32_16x16x32_bf16 v[20:23], v[218:221], v[182:185], v[20:23]
	v_mfma_f32_16x16x32_bf16 v[12:15], v[226:229], v[182:185], v[12:15]
	v_mfma_f32_16x16x32_bf16 v[4:7], v[218:221], v[210:213], v[4:7]
	v_mfma_f32_16x16x32_bf16 v[0:3], v[226:229], v[210:213], v[0:3]
	s_barrier
	s_cbranch_scc0 .LBB0_248
	s_mov_b32 s100, 1
	s_ashr_i32 s51, s50, 31
	v_lshl_or_b32 v128, s81, 8, v207
	s_lshl_b64 s[10:11], s[50:51], 8
	v_ashrrev_i32_e32 v129, 31, v128
	v_lshl_add_u64 v[168:169], s[10:11], 0, v[156:157]
	v_lshlrev_b64 v[170:171], 1, v[128:129]
	v_lshl_add_u64 v[174:175], s[28:29], 0, v[170:171]
	v_lshlrev_b64 v[172:173], 11, v[168:169]
	v_lshl_add_u64 v[128:129], v[174:175], 0, v[172:173]
	global_load_dwordx4 v[146:149], v[128:129], off
	global_load_dwordx4 v[182:185], v[128:129], off offset:256
	v_or_b32_e32 v166, 16, v168
	v_mov_b32_e32 v167, v169
	v_lshlrev_b64 v[176:177], 11, v[166:167]
	v_lshl_add_u64 v[128:129], v[174:175], 0, v[176:177]
	global_load_dwordx4 v[194:197], v[128:129], off
	global_load_dwordx4 v[210:213], v[128:129], off offset:256
	v_or_b32_e32 v164, 32, v168
	v_mov_b32_e32 v165, v169
	v_or_b32_e32 v162, 48, v168
	v_mov_b32_e32 v163, v169
	v_lshlrev_b64 v[180:181], 11, v[164:165]
	v_lshlrev_b64 v[178:179], 11, v[162:163]
	v_lshl_add_u64 v[128:129], v[174:175], 0, v[180:181]
	v_lshl_add_u64 v[130:131], v[174:175], 0, v[178:179]
	global_load_dwordx4 v[214:217], v[128:129], off
	global_load_dwordx4 v[136:139], v[128:129], off offset:256
	global_load_dwordx4 v[132:135], v[130:131], off
	s_nop 0
	global_load_dwordx4 v[128:131], v[130:131], off offset:256
	s_mov_b64 s[10:11], 0x90
	v_lshl_add_u64 v[172:173], s[30:31], 0, v[172:173]
	v_lshl_add_u64 v[172:173], v[172:173], 0, v[170:171]
	s_waitcnt vmcnt(0)
	v_lshlrev_b32_e32 v218, 16, v146
	v_and_b32_e32 v219, 0xffff0000, v146
	v_lshlrev_b32_e32 v220, 16, v148
	v_and_b32_e32 v221, 0xffff0000, v148
	v_lshlrev_b32_e32 v146, 16, v147
	v_and_b32_e32 v147, 0xffff0000, v147
	v_lshlrev_b32_e32 v222, 16, v182
	v_and_b32_e32 v223, 0xffff0000, v182
	v_lshlrev_b32_e32 v224, 16, v184
	v_and_b32_e32 v225, 0xffff0000, v184
	v_lshlrev_b32_e32 v182, 16, v183
	v_and_b32_e32 v183, 0xffff0000, v183
	v_pk_add_f32 v[124:125], v[124:125], v[218:219]
	v_pk_add_f32 v[120:121], v[120:121], v[220:221]
	v_pk_add_f32 v[126:127], v[126:127], v[146:147]
	v_pk_add_f32 v[116:117], v[116:117], v[222:223]
	v_pk_add_f32 v[146:147], v[112:113], v[224:225]
	v_pk_add_f32 v[118:119], v[118:119], v[182:183]
	v_pk_mul_f32 v[220:221], v[124:125], v[124:125]
	v_pk_mul_f32 v[222:223], v[126:127], v[126:127]
	v_cvt_pk_bf16_f32 v112, v124, v125
	v_cvt_pk_bf16_f32 v113, v126, v127
	v_pk_mul_f32 v[124:125], v[116:117], v[116:117]
	v_pk_mul_f32 v[126:127], v[118:119], v[118:119]
	v_pk_mul_f32 v[228:229], v[146:147], v[146:147]
	v_cvt_pk_bf16_f32 v116, v116, v117
	v_cvt_pk_bf16_f32 v117, v118, v119
	v_cvt_pk_bf16_f32 v118, v146, v147
	v_add_f32_e32 v146, v220, v221
	v_add_f32_e32 v146, v222, v146
	v_lshlrev_b32_e32 v148, 16, v149
	v_and_b32_e32 v149, 0xffff0000, v149
	v_pk_mul_f32 v[224:225], v[120:121], v[120:121]
	v_add_f32_e32 v146, v223, v146
	v_pk_add_f32 v[122:123], v[122:123], v[148:149]
	v_add_f32_e32 v146, v224, v146
	v_pk_mul_f32 v[226:227], v[122:123], v[122:123]
	v_add_f32_e32 v146, v225, v146
	v_add_f32_e32 v146, v226, v146
	v_add_f32_e32 v146, v227, v146
	v_add_f32_e32 v124, v124, v146
	v_add_f32_e32 v124, v125, v124
	v_add_f32_e32 v124, v126, v124
	v_lshlrev_b32_e32 v184, 16, v185
	v_and_b32_e32 v185, 0xffff0000, v185
	v_add_f32_e32 v124, v127, v124
	v_pk_add_f32 v[148:149], v[114:115], v[184:185]
	v_add_f32_e32 v124, v228, v124
	v_pk_mul_f32 v[230:231], v[148:149], v[148:149]
	v_add_f32_e32 v124, v229, v124
	v_add_f32_e32 v124, v230, v124
	v_add_f32_e32 v209, v231, v124
	v_lshlrev_b32_e32 v124, 16, v212
	v_and_b32_e32 v125, 0xffff0000, v212
	v_pk_add_f32 v[124:125], v[92:93], v[124:125]
	v_lshlrev_b32_e32 v92, 16, v211
	v_and_b32_e32 v93, 0xffff0000, v211
	v_pk_add_f32 v[102:103], v[102:103], v[92:93]
	v_lshlrev_b32_e32 v92, 16, v213
	v_and_b32_e32 v93, 0xffff0000, v213
	v_pk_add_f32 v[126:127], v[94:95], v[92:93]
	v_lshlrev_b32_e32 v92, 16, v214
	v_and_b32_e32 v93, 0xffff0000, v214
	v_pk_add_f32 v[92:93], v[96:97], v[92:93]
	v_lshlrev_b32_e32 v96, 16, v217
	v_and_b32_e32 v97, 0xffff0000, v217
	v_lshlrev_b32_e32 v94, 16, v216
	v_and_b32_e32 v95, 0xffff0000, v216
	v_pk_add_f32 v[90:91], v[90:91], v[96:97]
	v_lshlrev_b32_e32 v96, 16, v136
	v_and_b32_e32 v97, 0xffff0000, v136
	v_lshlrev_b32_e32 v182, 16, v194
	v_and_b32_e32 v183, 0xffff0000, v194
	v_pk_add_f32 v[88:89], v[88:89], v[94:95]
	v_lshlrev_b32_e32 v94, 16, v215
	v_and_b32_e32 v95, 0xffff0000, v215
	v_pk_add_f32 v[96:97], v[76:77], v[96:97]
	v_lshl_add_u64 v[76:77], v[168:169], 0, s[36:37]
	v_lshlrev_b32_e32 v184, 16, v196
	v_and_b32_e32 v185, 0xffff0000, v196
	v_cvt_pk_bf16_f32 v114, v120, v121
	v_pk_add_f32 v[120:121], v[108:109], v[182:183]
	v_pk_add_f32 v[94:95], v[98:99], v[94:95]
	v_lshlrev_b64 v[182:183], 11, v[76:77]
	v_lshlrev_b32_e32 v98, 16, v138
	v_and_b32_e32 v99, 0xffff0000, v138
	v_pk_add_f32 v[108:109], v[104:105], v[184:185]
	v_lshl_add_u64 v[184:185], v[174:175], 0, v[182:183]
	v_pk_add_f32 v[98:99], v[72:73], v[98:99]
	v_lshlrev_b32_e32 v72, 16, v137
	v_and_b32_e32 v73, 0xffff0000, v137
	v_lshlrev_b32_e32 v218, 16, v210
	v_and_b32_e32 v219, 0xffff0000, v210
	global_load_dwordx4 v[210:213], v[184:185], off
	v_pk_add_f32 v[136:137], v[78:79], v[72:73]
	v_lshlrev_b32_e32 v72, 16, v139
	v_and_b32_e32 v73, 0xffff0000, v139
	v_pk_add_f32 v[138:139], v[74:75], v[72:73]
	v_lshlrev_b32_e32 v72, 16, v132
	v_and_b32_e32 v73, 0xffff0000, v132
	v_pk_add_f32 v[74:75], v[84:85], v[72:73]
	v_lshlrev_b32_e32 v72, 16, v134
	v_and_b32_e32 v73, 0xffff0000, v134
	v_pk_add_f32 v[78:79], v[80:81], v[72:73]
	v_lshlrev_b32_e32 v72, 16, v133
	v_and_b32_e32 v73, 0xffff0000, v133
	v_pk_add_f32 v[100:101], v[100:101], v[218:219]
	global_load_dwordx4 v[218:221], v[184:185], off offset:256
	v_pk_add_f32 v[80:81], v[86:87], v[72:73]
	v_lshlrev_b32_e32 v72, 16, v135
	v_and_b32_e32 v73, 0xffff0000, v135
	v_pk_add_f32 v[82:83], v[82:83], v[72:73]
	v_lshl_add_u64 v[72:73], v[168:169], 0, s[10:11]
	v_lshlrev_b64 v[132:133], 11, v[72:73]
	v_lshl_add_u64 v[134:135], v[174:175], 0, v[132:133]
	v_lshlrev_b32_e32 v84, 16, v128
	v_and_b32_e32 v85, 0xffff0000, v128
	global_load_dwordx4 v[226:229], v[134:135], off
	global_load_dwordx4 v[234:237], v[134:135], off offset:256
	v_pk_add_f32 v[84:85], v[68:69], v[84:85]
	v_lshlrev_b32_e32 v68, 16, v130
	v_and_b32_e32 v69, 0xffff0000, v130
	v_pk_add_f32 v[86:87], v[64:65], v[68:69]
	v_lshlrev_b32_e32 v64, 16, v129
	v_and_b32_e32 v65, 0xffff0000, v129
	s_mov_b64 s[10:11], 0xa0
	v_pk_add_f32 v[128:129], v[70:71], v[64:65]
	v_lshl_add_u64 v[70:71], v[168:169], 0, s[10:11]
	s_mov_b64 s[10:11], 0xb0
	v_lshlrev_b32_e32 v64, 16, v131
	v_and_b32_e32 v65, 0xffff0000, v131
	v_lshlrev_b64 v[134:135], 11, v[70:71]
	v_lshl_add_u64 v[68:69], v[168:169], 0, s[10:11]
	v_pk_add_f32 v[130:131], v[66:67], v[64:65]
	v_lshl_add_u64 v[64:65], v[174:175], 0, v[134:135]
	v_lshlrev_b64 v[184:185], 11, v[68:69]
	global_load_dwordx4 v[238:241], v[64:65], off
	global_load_dwordx4 v[242:245], v[64:65], off offset:256
	v_lshl_add_u64 v[64:65], v[174:175], 0, v[184:185]
	global_load_dwordx4 v[246:249], v[64:65], off
	s_nop 0
	global_load_dwordx4 v[64:67], v[64:65], off offset:256
	v_lshlrev_b32_e32 v194, 16, v195
	v_and_b32_e32 v195, 0xffff0000, v195
	v_lshlrev_b32_e32 v196, 16, v197
	v_and_b32_e32 v197, 0xffff0000, v197
	v_cvt_pk_bf16_f32 v115, v122, v123
	v_cvt_pk_bf16_f32 v119, v148, v149
	v_pk_add_f32 v[122:123], v[110:111], v[194:195]
	v_pk_add_f32 v[110:111], v[106:107], v[196:197]
	global_store_dwordx4 v[172:173], v[112:115], off
	global_store_dwordx4 v[172:173], v[116:119], off offset:256
	v_cvt_pk_bf16_f32 v104, v120, v121
	v_lshl_add_u64 v[112:113], s[30:31], 0, v[176:177]
	v_cvt_pk_bf16_f32 v105, v122, v123
	v_cvt_pk_bf16_f32 v106, v108, v109
	v_cvt_pk_bf16_f32 v107, v110, v111
	v_lshl_add_u64 v[112:113], v[112:113], 0, v[170:171]
	v_cvt_pk_bf16_f32 v146, v100, v101
	v_cvt_pk_bf16_f32 v147, v102, v103
	v_cvt_pk_bf16_f32 v148, v124, v125
	v_cvt_pk_bf16_f32 v149, v126, v127
	global_store_dwordx4 v[112:113], v[104:107], off
	global_store_dwordx4 v[112:113], v[146:149], off offset:256
	v_cvt_pk_bf16_f32 v194, v92, v93
	v_lshl_add_u64 v[104:105], s[30:31], 0, v[180:181]
	v_cvt_pk_bf16_f32 v195, v94, v95
	v_cvt_pk_bf16_f32 v196, v88, v89
	v_cvt_pk_bf16_f32 v197, v90, v91
	v_lshl_add_u64 v[104:105], v[104:105], 0, v[170:171]
	v_cvt_pk_bf16_f32 v214, v96, v97
	v_cvt_pk_bf16_f32 v215, v136, v137
	v_cvt_pk_bf16_f32 v216, v98, v99
	v_cvt_pk_bf16_f32 v217, v138, v139
	global_store_dwordx4 v[104:105], v[194:197], off
	global_store_dwordx4 v[104:105], v[214:217], off offset:256
	v_lshl_add_u64 v[104:105], s[30:31], 0, v[178:179]
	v_cvt_pk_bf16_f32 v222, v74, v75
	v_cvt_pk_bf16_f32 v223, v80, v81
	v_cvt_pk_bf16_f32 v224, v78, v79
	v_cvt_pk_bf16_f32 v225, v82, v83
	v_lshl_add_u64 v[104:105], v[104:105], 0, v[170:171]
	v_cvt_pk_bf16_f32 v230, v84, v85
	v_cvt_pk_bf16_f32 v231, v128, v129
	v_cvt_pk_bf16_f32 v232, v86, v87
	v_cvt_pk_bf16_f32 v233, v130, v131
	global_store_dwordx4 v[104:105], v[222:225], off
	global_store_dwordx4 v[104:105], v[230:233], off offset:256
	s_waitcnt vmcnt(8)
	v_lshlrev_b32_e32 v104, 16, v210
	v_and_b32_e32 v105, 0xffff0000, v210
	v_pk_add_f32 v[60:61], v[60:61], v[104:105]
	v_lshlrev_b32_e32 v104, 16, v212
	v_and_b32_e32 v105, 0xffff0000, v212
	v_pk_add_f32 v[56:57], v[56:57], v[104:105]
	v_lshlrev_b32_e32 v104, 16, v211
	v_and_b32_e32 v105, 0xffff0000, v211
	v_pk_add_f32 v[62:63], v[62:63], v[104:105]
	v_lshlrev_b32_e32 v104, 16, v213
	v_and_b32_e32 v105, 0xffff0000, v213
	v_pk_add_f32 v[58:59], v[58:59], v[104:105]
	v_lshlrev_b32_e32 v104, 16, v218
	v_and_b32_e32 v105, 0xffff0000, v218
	v_pk_add_f32 v[52:53], v[52:53], v[104:105]
	v_lshlrev_b32_e32 v104, 16, v220
	v_and_b32_e32 v105, 0xffff0000, v220
	v_pk_add_f32 v[104:105], v[44:45], v[104:105]
	v_lshlrev_b32_e32 v44, 16, v219
	v_and_b32_e32 v45, 0xffff0000, v219
	v_pk_add_f32 v[54:55], v[54:55], v[44:45]
	v_lshlrev_b32_e32 v44, 16, v221
	v_and_b32_e32 v45, 0xffff0000, v221
	v_pk_add_f32 v[106:107], v[46:47], v[44:45]
	v_lshlrev_b32_e32 v44, 16, v226
	v_and_b32_e32 v45, 0xffff0000, v226
	v_pk_add_f32 v[44:45], v[48:49], v[44:45]
	v_lshlrev_b32_e32 v48, 16, v229
	v_and_b32_e32 v49, 0xffff0000, v229
	v_pk_add_f32 v[42:43], v[42:43], v[48:49]
	v_lshlrev_b32_e32 v48, 16, v234
	v_and_b32_e32 v49, 0xffff0000, v234
	v_pk_add_f32 v[36:37], v[36:37], v[48:49]
	v_lshlrev_b32_e32 v48, 16, v236
	v_and_b32_e32 v49, 0xffff0000, v236
	v_lshlrev_b32_e32 v46, 16, v228
	v_and_b32_e32 v47, 0xffff0000, v228
	v_pk_add_f32 v[48:49], v[28:29], v[48:49]
	v_lshlrev_b32_e32 v28, 16, v235
	v_and_b32_e32 v29, 0xffff0000, v235
	v_pk_add_f32 v[40:41], v[40:41], v[46:47]
	v_lshlrev_b32_e32 v46, 16, v227
	v_and_b32_e32 v47, 0xffff0000, v227
	v_pk_add_f32 v[38:39], v[38:39], v[28:29]
	v_lshlrev_b32_e32 v28, 16, v237
	v_and_b32_e32 v29, 0xffff0000, v237
	v_pk_add_f32 v[46:47], v[50:51], v[46:47]
	v_pk_add_f32 v[50:51], v[30:31], v[28:29]
	v_lshlrev_b32_e32 v28, 16, v238
	v_and_b32_e32 v29, 0xffff0000, v238
	v_lshlrev_b32_e32 v180, 16, v64
	v_and_b32_e32 v181, 0xffff0000, v64
	v_pk_add_f32 v[28:29], v[32:33], v[28:29]
	v_lshlrev_b32_e32 v32, 16, v241
	v_and_b32_e32 v33, 0xffff0000, v241
	v_pk_add_f32 v[4:5], v[4:5], v[180:181]
	v_lshlrev_b32_e32 v180, 16, v66
	v_and_b32_e32 v181, 0xffff0000, v66
	v_pk_add_f32 v[26:27], v[26:27], v[32:33]
	v_lshlrev_b32_e32 v32, 16, v242
	v_and_b32_e32 v33, 0xffff0000, v242
	v_pk_add_f32 v[0:1], v[0:1], v[180:181]
	v_lshl_add_u64 v[180:181], s[30:31], 0, v[182:183]
	v_cvt_pk_bf16_f32 v112, v60, v61
	v_cvt_pk_bf16_f32 v113, v62, v63
	v_cvt_pk_bf16_f32 v114, v56, v57
	v_cvt_pk_bf16_f32 v115, v58, v59
	v_pk_add_f32 v[20:21], v[20:21], v[32:33]
	v_lshlrev_b32_e32 v32, 16, v244
	v_and_b32_e32 v33, 0xffff0000, v244
	v_lshl_add_u64 v[180:181], v[180:181], 0, v[170:171]
	v_cvt_pk_bf16_f32 v116, v52, v53
	v_cvt_pk_bf16_f32 v117, v54, v55
	v_cvt_pk_bf16_f32 v118, v104, v105
	v_cvt_pk_bf16_f32 v119, v106, v107
	v_lshlrev_b32_e32 v30, 16, v240
	v_and_b32_e32 v31, 0xffff0000, v240
	v_pk_add_f32 v[32:33], v[12:13], v[32:33]
	v_lshlrev_b32_e32 v12, 16, v243
	v_and_b32_e32 v13, 0xffff0000, v243
	global_store_dwordx4 v[180:181], v[112:115], off
	global_store_dwordx4 v[180:181], v[116:119], off offset:256
	v_cvt_pk_bf16_f32 v146, v44, v45
	v_lshl_add_u64 v[112:113], s[30:31], 0, v[132:133]
	v_cvt_pk_bf16_f32 v147, v46, v47
	v_cvt_pk_bf16_f32 v148, v40, v41
	v_cvt_pk_bf16_f32 v149, v42, v43
	v_pk_add_f32 v[24:25], v[24:25], v[30:31]
	v_lshlrev_b32_e32 v30, 16, v239
	v_and_b32_e32 v31, 0xffff0000, v239
	v_pk_add_f32 v[22:23], v[22:23], v[12:13]
	v_lshlrev_b32_e32 v12, 16, v245
	v_and_b32_e32 v13, 0xffff0000, v245
	v_lshl_add_u64 v[112:113], v[112:113], 0, v[170:171]
	v_cvt_pk_bf16_f32 v172, v36, v37
	v_cvt_pk_bf16_f32 v173, v38, v39
	v_cvt_pk_bf16_f32 v174, v48, v49
	v_cvt_pk_bf16_f32 v175, v50, v51
	v_pk_add_f32 v[30:31], v[34:35], v[30:31]
	v_pk_add_f32 v[34:35], v[14:15], v[12:13]
	v_lshlrev_b32_e32 v12, 16, v246
	v_and_b32_e32 v13, 0xffff0000, v246
	v_lshlrev_b32_e32 v14, 16, v248
	v_and_b32_e32 v15, 0xffff0000, v248
	global_store_dwordx4 v[112:113], v[146:149], off
	global_store_dwordx4 v[112:113], v[172:175], off offset:256
	v_lshl_add_u64 v[112:113], s[30:31], 0, v[134:135]
	v_cvt_pk_bf16_f32 v176, v28, v29
	v_cvt_pk_bf16_f32 v177, v30, v31
	v_cvt_pk_bf16_f32 v178, v24, v25
	v_cvt_pk_bf16_f32 v179, v26, v27
	v_pk_add_f32 v[12:13], v[16:17], v[12:13]
	v_pk_add_f32 v[8:9], v[8:9], v[14:15]
	v_lshlrev_b32_e32 v14, 16, v247
	v_and_b32_e32 v15, 0xffff0000, v247
	v_lshlrev_b32_e32 v16, 16, v249
	v_and_b32_e32 v17, 0xffff0000, v249
	v_lshlrev_b32_e32 v64, 16, v65
	v_and_b32_e32 v65, 0xffff0000, v65
	v_lshl_add_u64 v[112:113], v[112:113], 0, v[170:171]
	v_cvt_pk_bf16_f32 v194, v20, v21
	v_cvt_pk_bf16_f32 v195, v22, v23
	v_cvt_pk_bf16_f32 v196, v32, v33
	v_cvt_pk_bf16_f32 v197, v34, v35
	v_pk_add_f32 v[14:15], v[18:19], v[14:15]
	v_pk_add_f32 v[10:11], v[10:11], v[16:17]
	v_pk_add_f32 v[6:7], v[6:7], v[64:65]
	v_lshlrev_b32_e32 v64, 16, v67
	v_and_b32_e32 v65, 0xffff0000, v67
	global_store_dwordx4 v[112:113], v[176:179], off
	global_store_dwordx4 v[112:113], v[194:197], off offset:256
	v_lshl_add_u64 v[112:113], s[30:31], 0, v[184:185]
	v_cvt_pk_bf16_f32 v16, v12, v13
	v_cvt_pk_bf16_f32 v17, v14, v15
	v_cvt_pk_bf16_f32 v18, v8, v9
	v_cvt_pk_bf16_f32 v19, v10, v11
	v_pk_add_f32 v[2:3], v[2:3], v[64:65]
	v_lshl_add_u64 v[112:113], v[112:113], 0, v[170:171]
	v_cvt_pk_bf16_f32 v64, v4, v5
	v_cvt_pk_bf16_f32 v65, v6, v7
	v_cvt_pk_bf16_f32 v66, v0, v1
	v_cvt_pk_bf16_f32 v67, v2, v3
	global_store_dwordx4 v[112:113], v[16:19], off
	global_store_dwordx4 v[112:113], v[64:67], off offset:256
	s_lshl_b32 s10, s81, 2
	v_and_b32_e32 v17, 64, v188
	v_xor_b32_e32 v16, 16, v188
	v_add_u32_e32 v17, 64, v17
	v_cmp_lt_i32_e32 vcc, v16, v17
	v_xor_b32_e32 v18, 32, v188
	s_ashr_i32 s11, s10, 31
	v_cndmask_b32_e32 v16, v188, v16, vcc
	v_lshlrev_b32_e32 v16, 2, v16
	v_mov_b32_e32 v132, v209
	v_cmp_lt_i32_e32 vcc, v18, v17
	s_lshl_b64 s[10:11], s[10:11], 2
	s_add_u32 s50, s75, s10
	v_cndmask_b32_e32 v17, v188, v18, vcc
	v_lshlrev_b32_e32 v17, 2, v17
	s_addc_u32 s51, s80, s11
	v_pk_mul_f32 v[18:19], v[120:121], v[120:121]
	v_pk_mul_f32 v[64:65], v[122:123], v[122:123]
	v_add_f32_e32 v18, v18, v19
	v_add_f32_e32 v18, v64, v18
	v_pk_mul_f32 v[66:67], v[108:109], v[108:109]
	v_add_f32_e32 v18, v65, v18
	v_add_f32_e32 v18, v66, v18
	v_pk_mul_f32 v[108:109], v[110:111], v[110:111]
	v_add_f32_e32 v18, v67, v18
	v_add_f32_e32 v18, v108, v18
	v_pk_mul_f32 v[100:101], v[100:101], v[100:101]
	v_add_f32_e32 v18, v109, v18
	v_add_f32_e32 v18, v100, v18
	v_pk_mul_f32 v[102:103], v[102:103], v[102:103]
	v_add_f32_e32 v18, v101, v18
	v_add_f32_e32 v18, v102, v18
	v_pk_mul_f32 v[110:111], v[124:125], v[124:125]
	v_add_f32_e32 v18, v103, v18
	v_add_f32_e32 v18, v110, v18
	v_pk_mul_f32 v[112:113], v[126:127], v[126:127]
	v_add_f32_e32 v18, v111, v18
	v_add_f32_e32 v18, v112, v18
	v_add_f32_e32 v18, v113, v18
	v_mov_b32_e32 v133, v18
	v_pk_mul_f32 v[18:19], v[92:93], v[92:93]
	v_pk_mul_f32 v[64:65], v[94:95], v[94:95]
	v_add_f32_e32 v18, v18, v19
	v_add_f32_e32 v18, v64, v18
	v_pk_mul_f32 v[66:67], v[88:89], v[88:89]
	v_add_f32_e32 v18, v65, v18
	v_add_f32_e32 v18, v66, v18
	v_pk_mul_f32 v[88:89], v[90:91], v[90:91]
	v_add_f32_e32 v18, v67, v18
	v_add_f32_e32 v18, v88, v18
	v_pk_mul_f32 v[90:91], v[96:97], v[96:97]
	v_add_f32_e32 v18, v89, v18
	v_add_f32_e32 v18, v90, v18
	v_pk_mul_f32 v[92:93], v[136:137], v[136:137]
	v_add_f32_e32 v18, v91, v18
	v_add_f32_e32 v18, v92, v18
	v_pk_mul_f32 v[94:95], v[98:99], v[98:99]
	v_add_f32_e32 v18, v93, v18
	v_add_f32_e32 v18, v94, v18
	v_pk_mul_f32 v[96:97], v[138:139], v[138:139]
	v_add_f32_e32 v18, v95, v18
	v_add_f32_e32 v18, v96, v18
	v_add_f32_e32 v18, v97, v18
	v_mov_b32_e32 v134, v18
	v_pk_mul_f32 v[18:19], v[74:75], v[74:75]
	v_pk_mul_f32 v[210:211], v[60:61], v[60:61]
	v_pk_mul_f32 v[64:65], v[80:81], v[80:81]
	v_pk_mul_f32 v[60:61], v[62:63], v[62:63]
	v_add_f32_e32 v18, v18, v19
	v_add_f32_e32 v210, v210, v211
	v_add_f32_e32 v18, v64, v18
	v_add_f32_e32 v210, v60, v210
	v_pk_mul_f32 v[66:67], v[78:79], v[78:79]
	v_pk_mul_f32 v[56:57], v[56:57], v[56:57]
	v_add_f32_e32 v18, v65, v18
	v_add_f32_e32 v210, v61, v210
	v_add_f32_e32 v18, v66, v18
	v_add_f32_e32 v210, v56, v210
	v_pk_mul_f32 v[74:75], v[82:83], v[82:83]
	v_pk_mul_f32 v[58:59], v[58:59], v[58:59]
	v_add_f32_e32 v18, v67, v18
	v_add_f32_e32 v210, v57, v210
	v_add_f32_e32 v18, v74, v18
	v_add_f32_e32 v210, v58, v210
	v_pk_mul_f32 v[78:79], v[84:85], v[84:85]
	v_pk_mul_f32 v[52:53], v[52:53], v[52:53]
	v_add_f32_e32 v18, v75, v18
	v_add_f32_e32 v210, v59, v210
	v_add_f32_e32 v18, v78, v18
	v_add_f32_e32 v210, v52, v210
	v_pk_mul_f32 v[80:81], v[128:129], v[128:129]
	v_pk_mul_f32 v[54:55], v[54:55], v[54:55]
	v_add_f32_e32 v18, v79, v18
	v_add_f32_e32 v210, v53, v210
	v_add_f32_e32 v18, v80, v18
	v_add_f32_e32 v210, v54, v210
	v_pk_mul_f32 v[82:83], v[86:87], v[86:87]
	v_pk_mul_f32 v[62:63], v[104:105], v[104:105]
	v_add_f32_e32 v18, v81, v18
	v_add_f32_e32 v210, v55, v210
	v_add_f32_e32 v18, v82, v18
	v_add_f32_e32 v210, v62, v210
	v_pk_mul_f32 v[84:85], v[130:131], v[130:131]
	v_pk_mul_f32 v[212:213], v[106:107], v[106:107]
	v_add_f32_e32 v18, v83, v18
	v_add_f32_e32 v210, v63, v210
	v_add_f32_e32 v18, v84, v18
	v_add_f32_e32 v210, v212, v210
	v_add_f32_e32 v18, v85, v18
	v_add_f32_e32 v210, v213, v210
	v_mov_b32_e32 v135, v18
	v_mov_b32_e32 v146, v210
	v_pk_mul_f32 v[18:19], v[44:45], v[44:45]
	v_pk_mul_f32 v[210:211], v[28:29], v[28:29]
	v_pk_mul_f32 v[44:45], v[46:47], v[46:47]
	v_pk_mul_f32 v[28:29], v[30:31], v[30:31]
	v_add_f32_e32 v18, v18, v19
	v_add_f32_e32 v210, v210, v211
	v_add_f32_e32 v18, v44, v18
	v_add_f32_e32 v210, v28, v210
	v_pk_mul_f32 v[40:41], v[40:41], v[40:41]
	v_pk_mul_f32 v[24:25], v[24:25], v[24:25]
	v_add_f32_e32 v18, v45, v18
	v_add_f32_e32 v210, v29, v210
	v_add_f32_e32 v18, v40, v18
	v_add_f32_e32 v210, v24, v210
	v_pk_mul_f32 v[42:43], v[42:43], v[42:43]
	v_pk_mul_f32 v[26:27], v[26:27], v[26:27]
	v_add_f32_e32 v18, v41, v18
	v_add_f32_e32 v210, v25, v210
	v_add_f32_e32 v18, v42, v18
	v_add_f32_e32 v210, v26, v210
	v_pk_mul_f32 v[36:37], v[36:37], v[36:37]
	v_pk_mul_f32 v[20:21], v[20:21], v[20:21]
	v_add_f32_e32 v18, v43, v18
	v_add_f32_e32 v210, v27, v210
	v_add_f32_e32 v18, v36, v18
	v_add_f32_e32 v210, v20, v210
	v_pk_mul_f32 v[38:39], v[38:39], v[38:39]
	v_pk_mul_f32 v[22:23], v[22:23], v[22:23]
	v_add_f32_e32 v18, v37, v18
	v_add_f32_e32 v210, v21, v210
	v_add_f32_e32 v18, v38, v18
	v_add_f32_e32 v210, v22, v210
	v_pk_mul_f32 v[46:47], v[48:49], v[48:49]
	v_pk_mul_f32 v[30:31], v[32:33], v[32:33]
	v_add_f32_e32 v18, v39, v18
	v_add_f32_e32 v210, v23, v210
	v_add_f32_e32 v18, v46, v18
	v_add_f32_e32 v210, v30, v210
	v_pk_mul_f32 v[48:49], v[50:51], v[50:51]
	v_pk_mul_f32 v[32:33], v[34:35], v[34:35]
	v_add_f32_e32 v18, v47, v18
	v_add_f32_e32 v210, v31, v210
	v_add_f32_e32 v18, v48, v18
	v_add_f32_e32 v210, v32, v210
	v_add_f32_e32 v18, v49, v18
	v_add_f32_e32 v210, v33, v210
	v_mov_b32_e32 v147, v18
	v_mov_b32_e32 v148, v210
	v_pk_mul_f32 v[12:13], v[12:13], v[12:13]
	v_pk_mul_f32 v[14:15], v[14:15], v[14:15]
	v_add_f32_e32 v12, v12, v13
	v_add_f32_e32 v12, v14, v12
	v_pk_mul_f32 v[8:9], v[8:9], v[8:9]
	v_add_f32_e32 v12, v15, v12
	v_add_f32_e32 v8, v8, v12
	v_pk_mul_f32 v[10:11], v[10:11], v[10:11]
	v_add_f32_e32 v8, v9, v8
	v_add_f32_e32 v8, v10, v8
	v_pk_mul_f32 v[4:5], v[4:5], v[4:5]
	v_add_f32_e32 v8, v11, v8
	v_add_f32_e32 v4, v4, v8
	v_pk_mul_f32 v[6:7], v[6:7], v[6:7]
	v_add_f32_e32 v4, v5, v4
	v_add_f32_e32 v4, v6, v4
	v_pk_mul_f32 v[0:1], v[0:1], v[0:1]
	v_add_f32_e32 v4, v7, v4
	v_add_f32_e32 v0, v0, v4
	v_pk_mul_f32 v[2:3], v[2:3], v[2:3]
	v_add_f32_e32 v0, v1, v0
	v_add_f32_e32 v0, v2, v0
	v_add_f32_e32 v0, v3, v0
	v_mov_b32_e32 v149, v0
	ds_bpermute_b32 v172, v16, v132
	ds_bpermute_b32 v173, v16, v133
	ds_bpermute_b32 v174, v16, v134
	ds_bpermute_b32 v175, v16, v135
	ds_bpermute_b32 v180, v16, v146
	ds_bpermute_b32 v181, v16, v147
	ds_bpermute_b32 v182, v16, v148
	ds_bpermute_b32 v183, v16, v149
	s_waitcnt lgkmcnt(0)
	v_add_f32_e32 v132, v132, v172
	v_add_f32_e32 v133, v133, v173
	v_add_f32_e32 v134, v134, v174
	v_add_f32_e32 v135, v135, v175
	v_add_f32_e32 v146, v146, v180
	v_add_f32_e32 v147, v147, v181
	v_add_f32_e32 v148, v148, v182
	v_add_f32_e32 v149, v149, v183
	ds_bpermute_b32 v172, v17, v132
	ds_bpermute_b32 v173, v17, v133
	ds_bpermute_b32 v174, v17, v134
	ds_bpermute_b32 v175, v17, v135
	ds_bpermute_b32 v180, v17, v146
	ds_bpermute_b32 v181, v17, v147
	ds_bpermute_b32 v182, v17, v148
	ds_bpermute_b32 v183, v17, v149
	s_and_saveexec_b64 s[52:53], s[42:43]
	s_cbranch_execz .LBB0_240
	s_waitcnt lgkmcnt(0)
	v_add_f32_e32 v132, v132, v172
	v_lshlrev_b64 v[18:19], 6, v[168:169]
	v_lshl_add_u64 v[18:19], s[50:51], 0, v[18:19]
	global_store_dword v[18:19], v132, off
	v_add_f32_e32 v133, v133, v173
	v_lshlrev_b64 v[18:19], 6, v[166:167]
	v_lshl_add_u64 v[18:19], s[50:51], 0, v[18:19]
	global_store_dword v[18:19], v133, off
	v_add_f32_e32 v134, v134, v174
	v_lshlrev_b64 v[18:19], 6, v[164:165]
	v_lshl_add_u64 v[18:19], s[50:51], 0, v[18:19]
	global_store_dword v[18:19], v134, off
	v_add_f32_e32 v135, v135, v175
	v_lshlrev_b64 v[18:19], 6, v[162:163]
	v_lshl_add_u64 v[18:19], s[50:51], 0, v[18:19]
	global_store_dword v[18:19], v135, off
	v_add_f32_e32 v146, v146, v180
	v_lshlrev_b64 v[18:19], 6, v[76:77]
	v_lshl_add_u64 v[18:19], s[50:51], 0, v[18:19]
	global_store_dword v[18:19], v146, off
	v_add_f32_e32 v147, v147, v181
	v_lshlrev_b64 v[18:19], 6, v[72:73]
	v_lshl_add_u64 v[18:19], s[50:51], 0, v[18:19]
	global_store_dword v[18:19], v147, off
	v_add_f32_e32 v148, v148, v182
	v_lshlrev_b64 v[18:19], 6, v[70:71]
	v_lshl_add_u64 v[18:19], s[50:51], 0, v[18:19]
	global_store_dword v[18:19], v148, off
	v_add_f32_e32 v149, v149, v183
	v_lshlrev_b64 v[18:19], 6, v[68:69]
	v_lshl_add_u64 v[18:19], s[50:51], 0, v[18:19]
	global_store_dword v[18:19], v149, off
	s_branch .LBB0_240

.Lm4bp_295:
	s_waitcnt lgkmcnt(0)
	s_mov_b32 s100, 0
	s_barrier
	v_mfma_f32_16x16x32_bf16 v[60:63], v[146:149], v[170:173], 0
	v_mfma_f32_16x16x32_bf16 v[56:59], v[162:165], v[170:173], 0
	v_mfma_f32_16x16x32_bf16 v[52:55], v[146:149], v[178:181], 0
	v_mfma_f32_16x16x32_bf16 v[48:51], v[162:165], v[178:181], 0
	v_mfma_f32_16x16x32_bf16 v[44:47], v[146:149], v[194:197], 0
	v_mfma_f32_16x16x32_bf16 v[40:43], v[162:165], v[194:197], 0
	v_mfma_f32_16x16x32_bf16 v[36:39], v[146:149], v[210:213], 0
	v_mfma_f32_16x16x32_bf16 v[32:35], v[162:165], v[210:213], 0
	v_mfma_f32_16x16x32_bf16 v[60:63], v[158:161], v[174:177], v[60:63]
	v_mfma_f32_16x16x32_bf16 v[56:59], v[166:169], v[174:177], v[56:59]
	v_mfma_f32_16x16x32_bf16 v[52:55], v[158:161], v[182:185], v[52:55]
	v_mfma_f32_16x16x32_bf16 v[48:51], v[166:169], v[182:185], v[48:51]
	v_mfma_f32_16x16x32_bf16 v[44:47], v[158:161], v[206:209], v[44:47]
	v_mfma_f32_16x16x32_bf16 v[40:43], v[166:169], v[206:209], v[40:43]
	v_mfma_f32_16x16x32_bf16 v[36:39], v[158:161], v[214:217], v[36:39]
	v_mfma_f32_16x16x32_bf16 v[32:35], v[166:169], v[214:217], v[32:35]
	v_mfma_f32_16x16x32_bf16 v[28:31], v[218:221], v[170:173], 0
	v_mfma_f32_16x16x32_bf16 v[24:27], v[226:229], v[170:173], 0
	v_mfma_f32_16x16x32_bf16 v[20:23], v[218:221], v[178:181], 0
	v_mfma_f32_16x16x32_bf16 v[16:19], v[226:229], v[178:181], 0
	v_mfma_f32_16x16x32_bf16 v[12:15], v[218:221], v[194:197], 0
	v_mfma_f32_16x16x32_bf16 v[8:11], v[226:229], v[194:197], 0
	v_mfma_f32_16x16x32_bf16 v[4:7], v[218:221], v[210:213], 0
	v_mfma_f32_16x16x32_bf16 v[0:3], v[226:229], v[210:213], 0
	v_mfma_f32_16x16x32_bf16 v[28:31], v[222:225], v[174:177], v[28:31]
	v_mfma_f32_16x16x32_bf16 v[24:27], v[230:233], v[174:177], v[24:27]
	v_mfma_f32_16x16x32_bf16 v[20:23], v[222:225], v[182:185], v[20:23]
	v_mfma_f32_16x16x32_bf16 v[16:19], v[230:233], v[182:185], v[16:19]
	v_mfma_f32_16x16x32_bf16 v[12:15], v[222:225], v[206:209], v[12:15]
	v_mfma_f32_16x16x32_bf16 v[8:11], v[230:233], v[206:209], v[8:11]
	v_mfma_f32_16x16x32_bf16 v[4:7], v[222:225], v[214:217], v[4:7]
	v_mfma_f32_16x16x32_bf16 v[0:3], v[230:233], v[214:217], v[0:3]
	s_barrier
	s_add_i32 s6, 0, 0x18000
	v_add_u32_e32 v166, s6, v154
	ds_read_b128 v[146:149], v166
	ds_read_b128 v[158:161], v166 offset:1024
	ds_read_b128 v[162:165], v166 offset:2048
	ds_read_b128 v[166:169], v166 offset:3072
	s_add_u32 s52, s52, 0x40000
	s_addc_u32 s53, s53, 0
	s_mov_b32 m0, s68
	v_lshl_add_u64 v[218:219], s[52:53], 0, v[128:129]
	ds_read_b128 v[170:173], v157 offset:32768
	ds_read_b128 v[174:177], v157 offset:33792
	ds_read_b128 v[178:181], v157 offset:34816
	ds_read_b128 v[182:185], v157 offset:35840
	ds_read_b128 v[194:197], v157 offset:36864
	ds_read_b128 v[206:209], v157 offset:37888
	ds_read_b128 v[210:213], v157 offset:38912
	ds_read_b128 v[214:217], v157 offset:39936
	global_load_lds_dwordx4 v[218:219], off
	v_lshl_add_u64 v[218:219], s[52:53], 0, v[130:131]
	s_mov_b32 m0, s69
	s_nop 0
	global_load_lds_dwordx4 v[218:219], off
	s_add_i32 s19, 0, 0x1c000
	v_add_u32_e32 v192, s19, v154
	ds_read_b128 v[218:221], v192
	ds_read_b128 v[222:225], v192 offset:1024
	ds_read_b128 v[226:229], v192 offset:2048
	ds_read_b128 v[230:233], v192 offset:3072
	s_waitcnt vmcnt(8)
	s_waitcnt lgkmcnt(0)
	s_barrier
	v_mfma_f32_16x16x32_bf16 v[124:127], v[146:149], v[170:173], v[124:127]
	v_mfma_f32_16x16x32_bf16 v[120:123], v[162:165], v[170:173], v[120:123]
	v_mfma_f32_16x16x32_bf16 v[116:119], v[146:149], v[178:181], v[116:119]
	v_mfma_f32_16x16x32_bf16 v[112:115], v[162:165], v[178:181], v[112:115]
	v_mfma_f32_16x16x32_bf16 v[108:111], v[146:149], v[194:197], v[108:111]
	v_mfma_f32_16x16x32_bf16 v[104:107], v[162:165], v[194:197], v[104:107]
	v_mfma_f32_16x16x32_bf16 v[100:103], v[146:149], v[210:213], v[100:103]
	v_mfma_f32_16x16x32_bf16 v[96:99], v[162:165], v[210:213], v[96:99]
	v_mfma_f32_16x16x32_bf16 v[124:127], v[158:161], v[174:177], v[124:127]
	v_mfma_f32_16x16x32_bf16 v[120:123], v[166:169], v[174:177], v[120:123]
	v_mfma_f32_16x16x32_bf16 v[116:119], v[158:161], v[182:185], v[116:119]
	v_mfma_f32_16x16x32_bf16 v[112:115], v[166:169], v[182:185], v[112:115]
	v_mfma_f32_16x16x32_bf16 v[108:111], v[158:161], v[206:209], v[108:111]
	v_mfma_f32_16x16x32_bf16 v[104:107], v[166:169], v[206:209], v[104:107]
	v_mfma_f32_16x16x32_bf16 v[100:103], v[158:161], v[214:217], v[100:103]
	v_mfma_f32_16x16x32_bf16 v[96:99], v[166:169], v[214:217], v[96:99]
	v_mfma_f32_16x16x32_bf16 v[92:95], v[218:221], v[170:173], v[92:95]
	v_mfma_f32_16x16x32_bf16 v[88:91], v[226:229], v[170:173], v[88:91]
	v_mfma_f32_16x16x32_bf16 v[84:87], v[218:221], v[178:181], v[84:87]
	v_mfma_f32_16x16x32_bf16 v[80:83], v[226:229], v[178:181], v[80:83]
	v_mfma_f32_16x16x32_bf16 v[76:79], v[218:221], v[194:197], v[76:79]
	v_mfma_f32_16x16x32_bf16 v[72:75], v[226:229], v[194:197], v[72:75]
	v_mfma_f32_16x16x32_bf16 v[68:71], v[218:221], v[210:213], v[68:71]
	v_mfma_f32_16x16x32_bf16 v[64:67], v[226:229], v[210:213], v[64:67]
	v_mfma_f32_16x16x32_bf16 v[92:95], v[222:225], v[174:177], v[92:95]
	v_mfma_f32_16x16x32_bf16 v[88:91], v[230:233], v[174:177], v[88:91]
	v_mfma_f32_16x16x32_bf16 v[84:87], v[222:225], v[182:185], v[84:87]
	v_mfma_f32_16x16x32_bf16 v[80:83], v[230:233], v[182:185], v[80:83]
	v_mfma_f32_16x16x32_bf16 v[76:79], v[222:225], v[206:209], v[76:79]
	v_mfma_f32_16x16x32_bf16 v[72:75], v[230:233], v[206:209], v[72:75]
	v_mfma_f32_16x16x32_bf16 v[68:71], v[222:225], v[214:217], v[68:71]
	v_mfma_f32_16x16x32_bf16 v[64:67], v[230:233], v[214:217], v[64:67]
	s_barrier
	s_add_i32 s6, s6, s57
	v_lshl_add_u64 v[234:235], v[234:235], 0, s[36:37]
	s_mov_b32 m0, s6
	s_nop 0
	global_load_lds_dwordx4 v[234:235], off
	v_lshl_add_u64 v[234:235], v[236:237], 0, s[36:37]
	s_add_i32 m0, s6, 0x2000
	s_nop 0
	global_load_lds_dwordx4 v[234:235], off
	s_mov_b32 m0, s70
	v_lshl_add_u64 v[234:235], v[238:239], 0, s[36:37]
	ds_read_b128 v[170:173], v157 offset:49152
	ds_read_b128 v[174:177], v157 offset:50176
	ds_read_b128 v[178:181], v157 offset:51200
	ds_read_b128 v[182:185], v157 offset:52224
	ds_read_b128 v[194:197], v157 offset:53248
	ds_read_b128 v[206:209], v157 offset:54272
	ds_read_b128 v[210:213], v157 offset:55296
	ds_read_b128 v[214:217], v157 offset:56320
	global_load_lds_dwordx4 v[234:235], off
	v_lshl_add_u64 v[234:235], v[240:241], 0, s[36:37]
	s_mov_b32 m0, s71
	s_nop 0
	global_load_lds_dwordx4 v[234:235], off
	s_add_u32 s50, s50, 0x40080
	s_addc_u32 s51, s51, 0
	s_add_i32 s6, s19, s57
	v_lshl_add_u64 v[250:251], s[50:51], 0, v[140:141]
	s_mov_b32 m0, s6
	s_nop 0
	global_load_lds_dwordx4 v[250:251], off
	v_lshl_add_u64 v[250:251], s[50:51], 0, v[132:133]
	s_add_i32 m0, s6, 0x2000
	s_nop 0
	global_load_lds_dwordx4 v[250:251], off
	s_add_i32 s75, s75, 2
	s_add_u32 s48, s48, 0x100
	s_addc_u32 s49, s49, 0
	s_cmp_gt_u32 s75, 13
	s_waitcnt vmcnt(8)
	s_waitcnt lgkmcnt(0)
	s_barrier
	v_mfma_f32_16x16x32_bf16 v[60:63], v[146:149], v[170:173], v[60:63]
	v_mfma_f32_16x16x32_bf16 v[56:59], v[162:165], v[170:173], v[56:59]
	v_mfma_f32_16x16x32_bf16 v[52:55], v[146:149], v[178:181], v[52:55]
	v_mfma_f32_16x16x32_bf16 v[48:51], v[162:165], v[178:181], v[48:51]
	v_mfma_f32_16x16x32_bf16 v[44:47], v[146:149], v[194:197], v[44:47]
	v_mfma_f32_16x16x32_bf16 v[40:43], v[162:165], v[194:197], v[40:43]
	v_mfma_f32_16x16x32_bf16 v[36:39], v[146:149], v[210:213], v[36:39]
	v_mfma_f32_16x16x32_bf16 v[32:35], v[162:165], v[210:213], v[32:35]
	v_mfma_f32_16x16x32_bf16 v[60:63], v[158:161], v[174:177], v[60:63]
	v_mfma_f32_16x16x32_bf16 v[56:59], v[166:169], v[174:177], v[56:59]
	v_mfma_f32_16x16x32_bf16 v[52:55], v[158:161], v[182:185], v[52:55]
	v_mfma_f32_16x16x32_bf16 v[48:51], v[166:169], v[182:185], v[48:51]
	v_mfma_f32_16x16x32_bf16 v[44:47], v[158:161], v[206:209], v[44:47]
	v_mfma_f32_16x16x32_bf16 v[40:43], v[166:169], v[206:209], v[40:43]
	v_mfma_f32_16x16x32_bf16 v[36:39], v[158:161], v[214:217], v[36:39]
	v_mfma_f32_16x16x32_bf16 v[32:35], v[166:169], v[214:217], v[32:35]
	v_mfma_f32_16x16x32_bf16 v[28:31], v[218:221], v[170:173], v[28:31]
	v_mfma_f32_16x16x32_bf16 v[24:27], v[226:229], v[170:173], v[24:27]
	v_mfma_f32_16x16x32_bf16 v[20:23], v[218:221], v[178:181], v[20:23]
	v_mfma_f32_16x16x32_bf16 v[16:19], v[226:229], v[178:181], v[16:19]
	v_mfma_f32_16x16x32_bf16 v[12:15], v[218:221], v[194:197], v[12:15]
	v_mfma_f32_16x16x32_bf16 v[8:11], v[226:229], v[194:197], v[8:11]
	v_mfma_f32_16x16x32_bf16 v[4:7], v[218:221], v[210:213], v[4:7]
	v_mfma_f32_16x16x32_bf16 v[0:3], v[226:229], v[210:213], v[0:3]
	v_mfma_f32_16x16x32_bf16 v[28:31], v[222:225], v[174:177], v[28:31]
	v_mfma_f32_16x16x32_bf16 v[24:27], v[230:233], v[174:177], v[24:27]
	v_mfma_f32_16x16x32_bf16 v[20:23], v[222:225], v[182:185], v[20:23]
	v_mfma_f32_16x16x32_bf16 v[16:19], v[230:233], v[182:185], v[16:19]
	v_mfma_f32_16x16x32_bf16 v[12:15], v[222:225], v[206:209], v[12:15]
	v_mfma_f32_16x16x32_bf16 v[8:11], v[230:233], v[206:209], v[8:11]
	v_mfma_f32_16x16x32_bf16 v[4:7], v[222:225], v[214:217], v[4:7]
	v_mfma_f32_16x16x32_bf16 v[0:3], v[230:233], v[214:217], v[0:3]
	s_barrier
.LBB0_295:
	s_add_u32 s6, s4, s48
	s_addc_u32 s19, s5, s49
	s_add_u32 s6, s6, 0x100
	s_addc_u32 s19, s19, 0
	s_add_u32 s23, s10, s48
	s_addc_u32 s50, s11, s49
	s_add_i32 s80, 0, 0x10000
	v_add_u32_e32 v166, s80, v154
	ds_read_b128 v[146:149], v166
	ds_read_b128 v[158:161], v166 offset:1024
	ds_read_b128 v[162:165], v166 offset:2048
	ds_read_b128 v[166:169], v166 offset:3072
	s_cmpk_eq_i32 s48, 0x700
	s_cselect_b32 s53, s12, s19
	s_cselect_b32 s52, s29, s6
	s_cselect_b32 s51, s31, s50
	s_cselect_b32 s50, s35, s23
	v_lshl_add_u64 v[218:219], v[150:151], 0, s[48:49]
	s_add_i32 m0, s58, 0xc000
	ds_read_b128 v[170:173], v157
	ds_read_b128 v[174:177], v157 offset:1024
	ds_read_b128 v[178:181], v157 offset:2048
	ds_read_b128 v[182:185], v157 offset:3072
	ds_read_b128 v[194:197], v157 offset:4096
	ds_read_b128 v[206:209], v157 offset:5120
	ds_read_b128 v[210:213], v157 offset:6144
	ds_read_b128 v[214:217], v157 offset:7168
	global_load_lds_dwordx4 v[218:219], off
	v_lshl_add_u64 v[218:219], v[152:153], 0, s[48:49]
	s_add_i32 m0, s58, 0xe000
	s_nop 0
	global_load_lds_dwordx4 v[218:219], off
	s_add_i32 s6, 0, 0x14000
	v_add_u32_e32 v192, s6, v154
	ds_read_b128 v[218:221], v192
	ds_read_b128 v[222:225], v192 offset:1024
	ds_read_b128 v[226:229], v192 offset:2048
	ds_read_b128 v[230:233], v192 offset:3072
	s_waitcnt vmcnt(8)
	s_waitcnt lgkmcnt(0)
	s_barrier
	v_mfma_f32_16x16x32_bf16 v[124:127], v[146:149], v[170:173], v[124:127]
	v_mfma_f32_16x16x32_bf16 v[120:123], v[162:165], v[170:173], v[120:123]
	v_mfma_f32_16x16x32_bf16 v[116:119], v[146:149], v[178:181], v[116:119]
	v_mfma_f32_16x16x32_bf16 v[112:115], v[162:165], v[178:181], v[112:115]
	v_mfma_f32_16x16x32_bf16 v[108:111], v[146:149], v[194:197], v[108:111]
	v_mfma_f32_16x16x32_bf16 v[104:107], v[162:165], v[194:197], v[104:107]
	v_mfma_f32_16x16x32_bf16 v[100:103], v[146:149], v[210:213], v[100:103]
	v_mfma_f32_16x16x32_bf16 v[96:99], v[162:165], v[210:213], v[96:99]
	v_mfma_f32_16x16x32_bf16 v[124:127], v[158:161], v[174:177], v[124:127]
	v_mfma_f32_16x16x32_bf16 v[120:123], v[166:169], v[174:177], v[120:123]
	v_mfma_f32_16x16x32_bf16 v[116:119], v[158:161], v[182:185], v[116:119]
	v_mfma_f32_16x16x32_bf16 v[112:115], v[166:169], v[182:185], v[112:115]
	v_mfma_f32_16x16x32_bf16 v[108:111], v[158:161], v[206:209], v[108:111]
	v_mfma_f32_16x16x32_bf16 v[104:107], v[166:169], v[206:209], v[104:107]
	v_mfma_f32_16x16x32_bf16 v[100:103], v[158:161], v[214:217], v[100:103]
	v_mfma_f32_16x16x32_bf16 v[96:99], v[166:169], v[214:217], v[96:99]
	v_mfma_f32_16x16x32_bf16 v[92:95], v[218:221], v[170:173], v[92:95]
	v_mfma_f32_16x16x32_bf16 v[88:91], v[226:229], v[170:173], v[88:91]
	v_mfma_f32_16x16x32_bf16 v[84:87], v[218:221], v[178:181], v[84:87]
	v_mfma_f32_16x16x32_bf16 v[80:83], v[226:229], v[178:181], v[80:83]
	v_mfma_f32_16x16x32_bf16 v[76:79], v[218:221], v[194:197], v[76:79]
	v_mfma_f32_16x16x32_bf16 v[72:75], v[226:229], v[194:197], v[72:75]
	v_mfma_f32_16x16x32_bf16 v[68:71], v[218:221], v[210:213], v[68:71]
	v_mfma_f32_16x16x32_bf16 v[64:67], v[226:229], v[210:213], v[64:67]
	v_mfma_f32_16x16x32_bf16 v[92:95], v[222:225], v[174:177], v[92:95]
	v_mfma_f32_16x16x32_bf16 v[88:91], v[230:233], v[174:177], v[88:91]
	v_mfma_f32_16x16x32_bf16 v[84:87], v[222:225], v[182:185], v[84:87]
	v_mfma_f32_16x16x32_bf16 v[80:83], v[230:233], v[182:185], v[80:83]
	v_mfma_f32_16x16x32_bf16 v[76:79], v[222:225], v[206:209], v[76:79]
	v_mfma_f32_16x16x32_bf16 v[72:75], v[230:233], v[206:209], v[72:75]
	v_mfma_f32_16x16x32_bf16 v[68:71], v[222:225], v[214:217], v[68:71]
	v_mfma_f32_16x16x32_bf16 v[64:67], v[230:233], v[214:217], v[64:67]
	s_barrier
	s_add_i32 s19, s80, s57
	v_lshl_add_u64 v[234:235], s[50:51], 0, v[140:141]
	s_mov_b32 m0, s19
	s_nop 0
	global_load_lds_dwordx4 v[234:235], off
	v_lshl_add_u64 v[236:237], s[50:51], 0, v[132:133]
	s_add_i32 m0, s19, 0x2000
	s_nop 0
	global_load_lds_dwordx4 v[236:237], off
	s_mov_b32 m0, s58
	v_lshl_add_u64 v[238:239], s[52:53], 0, v[128:129]
	ds_read_b128 v[170:173], v157 offset:16384
	ds_read_b128 v[174:177], v157 offset:17408
	ds_read_b128 v[178:181], v157 offset:18432
	ds_read_b128 v[182:185], v157 offset:19456
	ds_read_b128 v[194:197], v157 offset:20480
	ds_read_b128 v[206:209], v157 offset:21504
	ds_read_b128 v[210:213], v157 offset:22528
	ds_read_b128 v[214:217], v157 offset:23552
	global_load_lds_dwordx4 v[238:239], off
	v_lshl_add_u64 v[240:241], s[52:53], 0, v[130:131]
	s_mov_b32 m0, s59
	s_nop 0
	global_load_lds_dwordx4 v[240:241], off
	s_add_u32 s80, s50, 0x40000
	s_addc_u32 s81, s51, 0
	s_add_i32 s6, s6, s57
	v_lshl_add_u64 v[250:251], s[80:81], 0, v[140:141]
	s_mov_b32 m0, s6
	s_nop 0
	global_load_lds_dwordx4 v[250:251], off
	v_lshl_add_u64 v[250:251], s[80:81], 0, v[132:133]
	s_add_i32 m0, s6, 0x2000
	s_nop 0
	global_load_lds_dwordx4 v[250:251], off
	s_waitcnt vmcnt(8)
	s_waitcnt lgkmcnt(0)
	s_barrier
	v_mfma_f32_16x16x32_bf16 v[60:63], v[146:149], v[170:173], v[60:63]
	v_mfma_f32_16x16x32_bf16 v[56:59], v[162:165], v[170:173], v[56:59]
	v_mfma_f32_16x16x32_bf16 v[52:55], v[146:149], v[178:181], v[52:55]
	v_mfma_f32_16x16x32_bf16 v[48:51], v[162:165], v[178:181], v[48:51]
	v_mfma_f32_16x16x32_bf16 v[44:47], v[146:149], v[194:197], v[44:47]
	v_mfma_f32_16x16x32_bf16 v[40:43], v[162:165], v[194:197], v[40:43]
	v_mfma_f32_16x16x32_bf16 v[36:39], v[146:149], v[210:213], v[36:39]
	v_mfma_f32_16x16x32_bf16 v[32:35], v[162:165], v[210:213], v[32:35]
	v_mfma_f32_16x16x32_bf16 v[60:63], v[158:161], v[174:177], v[60:63]
	v_mfma_f32_16x16x32_bf16 v[56:59], v[166:169], v[174:177], v[56:59]
	v_mfma_f32_16x16x32_bf16 v[52:55], v[158:161], v[182:185], v[52:55]
	v_mfma_f32_16x16x32_bf16 v[48:51], v[166:169], v[182:185], v[48:51]
	v_mfma_f32_16x16x32_bf16 v[44:47], v[158:161], v[206:209], v[44:47]
	v_mfma_f32_16x16x32_bf16 v[40:43], v[166:169], v[206:209], v[40:43]
	v_mfma_f32_16x16x32_bf16 v[36:39], v[158:161], v[214:217], v[36:39]
	v_mfma_f32_16x16x32_bf16 v[32:35], v[166:169], v[214:217], v[32:35]
	v_mfma_f32_16x16x32_bf16 v[28:31], v[218:221], v[170:173], v[28:31]
	v_mfma_f32_16x16x32_bf16 v[24:27], v[226:229], v[170:173], v[24:27]
	v_mfma_f32_16x16x32_bf16 v[20:23], v[218:221], v[178:181], v[20:23]
	v_mfma_f32_16x16x32_bf16 v[16:19], v[226:229], v[178:181], v[16:19]
	v_mfma_f32_16x16x32_bf16 v[12:15], v[218:221], v[194:197], v[12:15]
	v_mfma_f32_16x16x32_bf16 v[8:11], v[226:229], v[194:197], v[8:11]
	v_mfma_f32_16x16x32_bf16 v[4:7], v[218:221], v[210:213], v[4:7]
	v_mfma_f32_16x16x32_bf16 v[0:3], v[226:229], v[210:213], v[0:3]
	v_mfma_f32_16x16x32_bf16 v[28:31], v[222:225], v[174:177], v[28:31]
	v_mfma_f32_16x16x32_bf16 v[24:27], v[230:233], v[174:177], v[24:27]
	v_mfma_f32_16x16x32_bf16 v[20:23], v[222:225], v[182:185], v[20:23]
	v_mfma_f32_16x16x32_bf16 v[16:19], v[230:233], v[182:185], v[16:19]
	v_mfma_f32_16x16x32_bf16 v[12:15], v[222:225], v[206:209], v[12:15]
	v_mfma_f32_16x16x32_bf16 v[8:11], v[230:233], v[206:209], v[8:11]
	v_mfma_f32_16x16x32_bf16 v[4:7], v[222:225], v[214:217], v[4:7]
	v_mfma_f32_16x16x32_bf16 v[0:3], v[230:233], v[214:217], v[0:3]
	s_barrier
	s_add_i32 s6, 0, 0x18000
	v_add_u32_e32 v166, s6, v154
	ds_read_b128 v[146:149], v166
	ds_read_b128 v[158:161], v166 offset:1024
	ds_read_b128 v[162:165], v166 offset:2048
	ds_read_b128 v[166:169], v166 offset:3072
	s_add_u32 s52, s52, 0x40000
	s_addc_u32 s53, s53, 0
	s_mov_b32 m0, s68
	v_lshl_add_u64 v[218:219], s[52:53], 0, v[128:129]
	ds_read_b128 v[170:173], v157 offset:32768
	ds_read_b128 v[174:177], v157 offset:33792
	ds_read_b128 v[178:181], v157 offset:34816
	ds_read_b128 v[182:185], v157 offset:35840
	ds_read_b128 v[194:197], v157 offset:36864
	ds_read_b128 v[206:209], v157 offset:37888
	ds_read_b128 v[210:213], v157 offset:38912
	ds_read_b128 v[214:217], v157 offset:39936
	global_load_lds_dwordx4 v[218:219], off
	v_lshl_add_u64 v[218:219], s[52:53], 0, v[130:131]
	s_mov_b32 m0, s69
	s_nop 0
	global_load_lds_dwordx4 v[218:219], off
	s_add_i32 s19, 0, 0x1c000
	v_add_u32_e32 v192, s19, v154
	ds_read_b128 v[218:221], v192
	ds_read_b128 v[222:225], v192 offset:1024
	ds_read_b128 v[226:229], v192 offset:2048
	ds_read_b128 v[230:233], v192 offset:3072
	s_waitcnt vmcnt(8)
	s_waitcnt lgkmcnt(0)
	s_barrier
	v_mfma_f32_16x16x32_bf16 v[124:127], v[146:149], v[170:173], v[124:127]
	v_mfma_f32_16x16x32_bf16 v[120:123], v[162:165], v[170:173], v[120:123]
	v_mfma_f32_16x16x32_bf16 v[116:119], v[146:149], v[178:181], v[116:119]
	v_mfma_f32_16x16x32_bf16 v[112:115], v[162:165], v[178:181], v[112:115]
	v_mfma_f32_16x16x32_bf16 v[108:111], v[146:149], v[194:197], v[108:111]
	v_mfma_f32_16x16x32_bf16 v[104:107], v[162:165], v[194:197], v[104:107]
	v_mfma_f32_16x16x32_bf16 v[100:103], v[146:149], v[210:213], v[100:103]
	v_mfma_f32_16x16x32_bf16 v[96:99], v[162:165], v[210:213], v[96:99]
	v_mfma_f32_16x16x32_bf16 v[124:127], v[158:161], v[174:177], v[124:127]
	v_mfma_f32_16x16x32_bf16 v[120:123], v[166:169], v[174:177], v[120:123]
	v_mfma_f32_16x16x32_bf16 v[116:119], v[158:161], v[182:185], v[116:119]
	v_mfma_f32_16x16x32_bf16 v[112:115], v[166:169], v[182:185], v[112:115]
	v_mfma_f32_16x16x32_bf16 v[108:111], v[158:161], v[206:209], v[108:111]
	v_mfma_f32_16x16x32_bf16 v[104:107], v[166:169], v[206:209], v[104:107]
	v_mfma_f32_16x16x32_bf16 v[100:103], v[158:161], v[214:217], v[100:103]
	v_mfma_f32_16x16x32_bf16 v[96:99], v[166:169], v[214:217], v[96:99]
	v_mfma_f32_16x16x32_bf16 v[92:95], v[218:221], v[170:173], v[92:95]
	v_mfma_f32_16x16x32_bf16 v[88:91], v[226:229], v[170:173], v[88:91]
	v_mfma_f32_16x16x32_bf16 v[84:87], v[218:221], v[178:181], v[84:87]
	v_mfma_f32_16x16x32_bf16 v[80:83], v[226:229], v[178:181], v[80:83]
	v_mfma_f32_16x16x32_bf16 v[76:79], v[218:221], v[194:197], v[76:79]
	v_mfma_f32_16x16x32_bf16 v[72:75], v[226:229], v[194:197], v[72:75]
	v_mfma_f32_16x16x32_bf16 v[68:71], v[218:221], v[210:213], v[68:71]
	v_mfma_f32_16x16x32_bf16 v[64:67], v[226:229], v[210:213], v[64:67]
	v_mfma_f32_16x16x32_bf16 v[92:95], v[222:225], v[174:177], v[92:95]
	v_mfma_f32_16x16x32_bf16 v[88:91], v[230:233], v[174:177], v[88:91]
	v_mfma_f32_16x16x32_bf16 v[84:87], v[222:225], v[182:185], v[84:87]
	v_mfma_f32_16x16x32_bf16 v[80:83], v[230:233], v[182:185], v[80:83]
	v_mfma_f32_16x16x32_bf16 v[76:79], v[222:225], v[206:209], v[76:79]
	v_mfma_f32_16x16x32_bf16 v[72:75], v[230:233], v[206:209], v[72:75]
	v_mfma_f32_16x16x32_bf16 v[68:71], v[222:225], v[214:217], v[68:71]
	v_mfma_f32_16x16x32_bf16 v[64:67], v[230:233], v[214:217], v[64:67]
	s_barrier
	s_add_i32 s6, s6, s57
	v_lshl_add_u64 v[234:235], v[234:235], 0, s[36:37]
	s_mov_b32 m0, s6
	s_nop 0
	global_load_lds_dwordx4 v[234:235], off
	v_lshl_add_u64 v[234:235], v[236:237], 0, s[36:37]
	s_add_i32 m0, s6, 0x2000
	s_nop 0
	global_load_lds_dwordx4 v[234:235], off
	s_mov_b32 m0, s70
	v_lshl_add_u64 v[234:235], v[238:239], 0, s[36:37]
	ds_read_b128 v[170:173], v157 offset:49152
	ds_read_b128 v[174:177], v157 offset:50176
	ds_read_b128 v[178:181], v157 offset:51200
	ds_read_b128 v[182:185], v157 offset:52224
	ds_read_b128 v[194:197], v157 offset:53248
	ds_read_b128 v[206:209], v157 offset:54272
	ds_read_b128 v[210:213], v157 offset:55296
	ds_read_b128 v[214:217], v157 offset:56320
	global_load_lds_dwordx4 v[234:235], off
	v_lshl_add_u64 v[234:235], v[240:241], 0, s[36:37]
	s_mov_b32 m0, s71
	s_nop 0
	global_load_lds_dwordx4 v[234:235], off
	s_add_u32 s50, s50, 0x40080
	s_addc_u32 s51, s51, 0
	s_add_i32 s6, s19, s57
	v_lshl_add_u64 v[250:251], s[50:51], 0, v[140:141]
	s_mov_b32 m0, s6
	s_nop 0
	global_load_lds_dwordx4 v[250:251], off
	v_lshl_add_u64 v[250:251], s[50:51], 0, v[132:133]
	s_add_i32 m0, s6, 0x2000
	s_nop 0
	global_load_lds_dwordx4 v[250:251], off
	s_add_i32 s75, s75, 2
	s_add_u32 s48, s48, 0x100
	s_addc_u32 s49, s49, 0
	s_cmp_gt_u32 s75, 13
	s_waitcnt vmcnt(8)
	s_waitcnt lgkmcnt(0)
	s_barrier
	v_mfma_f32_16x16x32_bf16 v[60:63], v[146:149], v[170:173], v[60:63]
	v_mfma_f32_16x16x32_bf16 v[56:59], v[162:165], v[170:173], v[56:59]
	v_mfma_f32_16x16x32_bf16 v[52:55], v[146:149], v[178:181], v[52:55]
	v_mfma_f32_16x16x32_bf16 v[48:51], v[162:165], v[178:181], v[48:51]
	v_mfma_f32_16x16x32_bf16 v[44:47], v[146:149], v[194:197], v[44:47]
	v_mfma_f32_16x16x32_bf16 v[40:43], v[162:165], v[194:197], v[40:43]
	v_mfma_f32_16x16x32_bf16 v[36:39], v[146:149], v[210:213], v[36:39]
	v_mfma_f32_16x16x32_bf16 v[32:35], v[162:165], v[210:213], v[32:35]
	v_mfma_f32_16x16x32_bf16 v[60:63], v[158:161], v[174:177], v[60:63]
	v_mfma_f32_16x16x32_bf16 v[56:59], v[166:169], v[174:177], v[56:59]
	v_mfma_f32_16x16x32_bf16 v[52:55], v[158:161], v[182:185], v[52:55]
	v_mfma_f32_16x16x32_bf16 v[48:51], v[166:169], v[182:185], v[48:51]
	v_mfma_f32_16x16x32_bf16 v[44:47], v[158:161], v[206:209], v[44:47]
	v_mfma_f32_16x16x32_bf16 v[40:43], v[166:169], v[206:209], v[40:43]
	v_mfma_f32_16x16x32_bf16 v[36:39], v[158:161], v[214:217], v[36:39]
	v_mfma_f32_16x16x32_bf16 v[32:35], v[166:169], v[214:217], v[32:35]
	v_mfma_f32_16x16x32_bf16 v[28:31], v[218:221], v[170:173], v[28:31]
	v_mfma_f32_16x16x32_bf16 v[24:27], v[226:229], v[170:173], v[24:27]
	v_mfma_f32_16x16x32_bf16 v[20:23], v[218:221], v[178:181], v[20:23]
	v_mfma_f32_16x16x32_bf16 v[16:19], v[226:229], v[178:181], v[16:19]
	v_mfma_f32_16x16x32_bf16 v[12:15], v[218:221], v[194:197], v[12:15]
	v_mfma_f32_16x16x32_bf16 v[8:11], v[226:229], v[194:197], v[8:11]
	v_mfma_f32_16x16x32_bf16 v[4:7], v[218:221], v[210:213], v[4:7]
	v_mfma_f32_16x16x32_bf16 v[0:3], v[226:229], v[210:213], v[0:3]
	v_mfma_f32_16x16x32_bf16 v[28:31], v[222:225], v[174:177], v[28:31]
	v_mfma_f32_16x16x32_bf16 v[24:27], v[230:233], v[174:177], v[24:27]
	v_mfma_f32_16x16x32_bf16 v[20:23], v[222:225], v[182:185], v[20:23]
	v_mfma_f32_16x16x32_bf16 v[16:19], v[230:233], v[182:185], v[16:19]
	v_mfma_f32_16x16x32_bf16 v[12:15], v[222:225], v[206:209], v[12:15]
	v_mfma_f32_16x16x32_bf16 v[8:11], v[230:233], v[206:209], v[8:11]
	v_mfma_f32_16x16x32_bf16 v[4:7], v[222:225], v[214:217], v[4:7]
	v_mfma_f32_16x16x32_bf16 v[0:3], v[230:233], v[214:217], v[0:3]
	s_barrier
	s_cbranch_scc0 .LBB0_295
	s_mov_b32 s100, 1
	s_add_u32 s48, s10, 0xffffff00
	v_lshl_add_u32 v166, s73, 10, v155
	s_addc_u32 s49, s11, -1
	s_ashr_i32 s29, s28, 31
	v_lshl_or_b32 v146, s72, 8, v156
	ds_read2_b32 v[158:159], v166 offset1:16
	s_lshl_b64 s[10:11], s[28:29], 8
	v_ashrrev_i32_e32 v147, 31, v146
	v_lshl_add_u64 v[148:149], s[10:11], 0, v[134:135]
	v_lshl_add_u64 v[146:147], v[146:147], 1, s[26:27]
	v_mad_u64_u32 v[150:151], s[10:11], v148, s13, v[146:147]
	v_mov_b32_e32 v146, v151
	v_mad_u64_u32 v[152:153], s[10:11], v149, s13, v[146:147]
	s_waitcnt lgkmcnt(0)
	v_pk_mul_f32 v[148:149], v[126:127], v[158:159] op_sel_hi:[1,0]
	v_pk_mul_f32 v[146:147], v[124:125], v[158:159] op_sel_hi:[1,0]
	v_pk_mul_f32 v[160:161], v[122:123], v[158:159] op_sel_hi:[1,0]
	v_pk_mul_f32 v[162:163], v[120:121], v[158:159] op_sel_hi:[1,0]
	v_mov_b32_e32 v151, v152
	v_cvt_pk_bf16_f32 v146, v146, v147
	v_cvt_pk_bf16_f32 v147, v148, v149
	v_cvt_pk_bf16_f32 v148, v162, v163
	v_cvt_pk_bf16_f32 v149, v160, v161
	global_store_dwordx4 v[150:151], v[146:149], off
	v_pk_mul_f32 v[160:161], v[90:91], v[158:159] op_sel_hi:[1,0]
	v_pk_mul_f32 v[162:163], v[88:89], v[158:159] op_sel_hi:[1,0]
	v_pk_mul_f32 v[148:149], v[94:95], v[158:159] op_sel_hi:[1,0]
	v_pk_mul_f32 v[146:147], v[92:93], v[158:159] op_sel_hi:[1,0]
	v_mov_b32_e32 v158, v159
	v_cvt_pk_bf16_f32 v146, v146, v147
	v_cvt_pk_bf16_f32 v147, v148, v149
	v_cvt_pk_bf16_f32 v148, v162, v163
	v_cvt_pk_bf16_f32 v149, v160, v161
	global_store_dwordx4 v[150:151], v[146:149], off offset:256
	v_pk_mul_f32 v[160:161], v[114:115], v[158:159] op_sel_hi:[1,0]
	s_mov_b32 s6, 0x1e000
	v_pk_mul_f32 v[148:149], v[118:119], v[158:159] op_sel_hi:[1,0]
	v_pk_mul_f32 v[146:147], v[116:117], v[158:159] op_sel_hi:[1,0]
	ds_read2_b32 v[164:165], v166 offset0:32 offset1:48
	v_pk_mul_f32 v[162:163], v[112:113], v[158:159] op_sel_hi:[1,0]
	v_cvt_pk_bf16_f32 v146, v146, v147
	v_cvt_pk_bf16_f32 v147, v148, v149
	v_cvt_pk_bf16_f32 v149, v160, v161
	v_add_co_u32_e32 v160, vcc, s6, v150
	v_cvt_pk_bf16_f32 v148, v162, v163
	s_nop 0
	v_addc_co_u32_e32 v161, vcc, 0, v152, vcc
	global_store_dwordx4 v[160:161], v[146:149], off
	v_pk_mul_f32 v[162:163], v[82:83], v[158:159] op_sel_hi:[1,0]
	s_mov_b32 s6, 0x3c000
	v_pk_mul_f32 v[148:149], v[86:87], v[158:159] op_sel_hi:[1,0]
	v_pk_mul_f32 v[146:147], v[84:85], v[158:159] op_sel_hi:[1,0]
	v_pk_mul_f32 v[158:159], v[80:81], v[158:159] op_sel_hi:[1,0]
	v_cvt_pk_bf16_f32 v146, v146, v147
	v_cvt_pk_bf16_f32 v147, v148, v149
	v_cvt_pk_bf16_f32 v148, v158, v159
	v_cvt_pk_bf16_f32 v149, v162, v163
	global_store_dwordx4 v[160:161], v[146:149], off offset:256
	s_waitcnt lgkmcnt(0)
	v_pk_mul_f32 v[158:159], v[106:107], v[164:165] op_sel_hi:[1,0]
	v_pk_mul_f32 v[160:161], v[104:105], v[164:165] op_sel_hi:[1,0]
	v_pk_mul_f32 v[148:149], v[110:111], v[164:165] op_sel_hi:[1,0]
	v_pk_mul_f32 v[146:147], v[108:109], v[164:165] op_sel_hi:[1,0]
	v_pk_mul_f32 v[162:163], v[72:73], v[164:165] op_sel_hi:[1,0]
	v_cvt_pk_bf16_f32 v146, v146, v147
	v_cvt_pk_bf16_f32 v147, v148, v149
	v_cvt_pk_bf16_f32 v149, v158, v159
	v_add_co_u32_e32 v158, vcc, s6, v150
	v_cvt_pk_bf16_f32 v148, v160, v161
	s_nop 0
	v_addc_co_u32_e32 v159, vcc, 0, v152, vcc
	global_store_dwordx4 v[158:159], v[146:149], off
	v_pk_mul_f32 v[160:161], v[74:75], v[164:165] op_sel_hi:[1,0]
	s_mov_b32 s6, 0x5a000
	v_pk_mul_f32 v[148:149], v[78:79], v[164:165] op_sel_hi:[1,0]
	v_pk_mul_f32 v[146:147], v[76:77], v[164:165] op_sel_hi:[1,0]
	s_nop 0
	v_cvt_pk_bf16_f32 v146, v146, v147
	v_cvt_pk_bf16_f32 v147, v148, v149
	v_cvt_pk_bf16_f32 v148, v162, v163
	v_cvt_pk_bf16_f32 v149, v160, v161
	global_store_dwordx4 v[158:159], v[146:149], off offset:256
	v_mov_b32_e32 v158, v165
	v_pk_mul_f32 v[160:161], v[98:99], v[158:159] op_sel_hi:[1,0]
	v_pk_mul_f32 v[148:149], v[102:103], v[158:159] op_sel_hi:[1,0]
	v_pk_mul_f32 v[146:147], v[100:101], v[158:159] op_sel_hi:[1,0]
	ds_read2_b32 v[164:165], v166 offset0:128 offset1:144
	v_pk_mul_f32 v[162:163], v[96:97], v[158:159] op_sel_hi:[1,0]
	v_cvt_pk_bf16_f32 v146, v146, v147
	v_cvt_pk_bf16_f32 v147, v148, v149
	v_cvt_pk_bf16_f32 v149, v160, v161
	v_add_co_u32_e32 v160, vcc, s6, v150
	v_cvt_pk_bf16_f32 v148, v162, v163
	s_nop 0
	v_addc_co_u32_e32 v161, vcc, 0, v152, vcc
	global_store_dwordx4 v[160:161], v[146:149], off
	v_pk_mul_f32 v[162:163], v[66:67], v[158:159] op_sel_hi:[1,0]
	s_mov_b32 s6, 0xf0000
	v_pk_mul_f32 v[148:149], v[70:71], v[158:159] op_sel_hi:[1,0]
	v_pk_mul_f32 v[146:147], v[68:69], v[158:159] op_sel_hi:[1,0]
	v_pk_mul_f32 v[158:159], v[64:65], v[158:159] op_sel_hi:[1,0]
	v_cvt_pk_bf16_f32 v146, v146, v147
	v_cvt_pk_bf16_f32 v147, v148, v149
	v_cvt_pk_bf16_f32 v148, v158, v159
	v_cvt_pk_bf16_f32 v149, v162, v163
	global_store_dwordx4 v[160:161], v[146:149], off offset:256
	s_waitcnt lgkmcnt(0)
	v_pk_mul_f32 v[158:159], v[58:59], v[164:165] op_sel_hi:[1,0]
	v_pk_mul_f32 v[160:161], v[56:57], v[164:165] op_sel_hi:[1,0]
	v_pk_mul_f32 v[148:149], v[62:63], v[164:165] op_sel_hi:[1,0]
	v_pk_mul_f32 v[146:147], v[60:61], v[164:165] op_sel_hi:[1,0]
	v_pk_mul_f32 v[162:163], v[24:25], v[164:165] op_sel_hi:[1,0]
	v_cvt_pk_bf16_f32 v146, v146, v147
	v_cvt_pk_bf16_f32 v147, v148, v149
	v_cvt_pk_bf16_f32 v149, v158, v159
	v_add_co_u32_e32 v158, vcc, s6, v150
	v_cvt_pk_bf16_f32 v148, v160, v161
	s_nop 0
	v_addc_co_u32_e32 v159, vcc, 0, v152, vcc
	global_store_dwordx4 v[158:159], v[146:149], off
	v_pk_mul_f32 v[160:161], v[26:27], v[164:165] op_sel_hi:[1,0]
	s_mov_b32 s6, 0x10e000
	v_pk_mul_f32 v[148:149], v[30:31], v[164:165] op_sel_hi:[1,0]
	v_pk_mul_f32 v[146:147], v[28:29], v[164:165] op_sel_hi:[1,0]
	s_nop 0
	v_cvt_pk_bf16_f32 v146, v146, v147
	v_cvt_pk_bf16_f32 v147, v148, v149
	v_cvt_pk_bf16_f32 v148, v162, v163
	v_cvt_pk_bf16_f32 v149, v160, v161
	global_store_dwordx4 v[158:159], v[146:149], off offset:256
	v_mov_b32_e32 v158, v165
	v_pk_mul_f32 v[160:161], v[50:51], v[158:159] op_sel_hi:[1,0]
	v_pk_mul_f32 v[148:149], v[54:55], v[158:159] op_sel_hi:[1,0]
	v_pk_mul_f32 v[146:147], v[52:53], v[158:159] op_sel_hi:[1,0]
	ds_read2_b32 v[164:165], v166 offset0:160 offset1:176
	v_pk_mul_f32 v[162:163], v[48:49], v[158:159] op_sel_hi:[1,0]
	v_cvt_pk_bf16_f32 v146, v146, v147
	v_cvt_pk_bf16_f32 v147, v148, v149
	v_cvt_pk_bf16_f32 v149, v160, v161
	v_add_co_u32_e32 v160, vcc, s6, v150
	v_cvt_pk_bf16_f32 v148, v162, v163
	s_nop 0
	v_addc_co_u32_e32 v161, vcc, 0, v152, vcc
	global_store_dwordx4 v[160:161], v[146:149], off
	v_pk_mul_f32 v[162:163], v[18:19], v[158:159] op_sel_hi:[1,0]
	s_mov_b32 s6, 0x12c000
	v_pk_mul_f32 v[148:149], v[22:23], v[158:159] op_sel_hi:[1,0]
	v_pk_mul_f32 v[146:147], v[20:21], v[158:159] op_sel_hi:[1,0]
	v_pk_mul_f32 v[158:159], v[16:17], v[158:159] op_sel_hi:[1,0]
	v_cvt_pk_bf16_f32 v146, v146, v147
	v_cvt_pk_bf16_f32 v147, v148, v149
	v_cvt_pk_bf16_f32 v148, v158, v159
	v_cvt_pk_bf16_f32 v149, v162, v163
	global_store_dwordx4 v[160:161], v[146:149], off offset:256
	s_waitcnt lgkmcnt(0)
	v_pk_mul_f32 v[158:159], v[42:43], v[164:165] op_sel_hi:[1,0]
	v_pk_mul_f32 v[160:161], v[40:41], v[164:165] op_sel_hi:[1,0]
	v_pk_mul_f32 v[148:149], v[46:47], v[164:165] op_sel_hi:[1,0]
	v_pk_mul_f32 v[146:147], v[44:45], v[164:165] op_sel_hi:[1,0]
	v_pk_mul_f32 v[162:163], v[8:9], v[164:165] op_sel_hi:[1,0]
	v_cvt_pk_bf16_f32 v146, v146, v147
	v_cvt_pk_bf16_f32 v147, v148, v149
	v_cvt_pk_bf16_f32 v149, v158, v159
	v_add_co_u32_e32 v158, vcc, s6, v150
	v_cvt_pk_bf16_f32 v148, v160, v161
	s_nop 0
	v_addc_co_u32_e32 v159, vcc, 0, v152, vcc
	global_store_dwordx4 v[158:159], v[146:149], off
	v_pk_mul_f32 v[160:161], v[10:11], v[164:165] op_sel_hi:[1,0]
	s_mov_b32 s6, 0x14a000
	v_pk_mul_f32 v[148:149], v[14:15], v[164:165] op_sel_hi:[1,0]
	v_pk_mul_f32 v[146:147], v[12:13], v[164:165] op_sel_hi:[1,0]
	v_add_co_u32_e32 v150, vcc, s6, v150
	v_cvt_pk_bf16_f32 v146, v146, v147
	v_cvt_pk_bf16_f32 v147, v148, v149
	v_cvt_pk_bf16_f32 v148, v162, v163
	v_cvt_pk_bf16_f32 v149, v160, v161
	global_store_dwordx4 v[158:159], v[146:149], off offset:256
	v_mov_b32_e32 v158, v165
	v_pk_mul_f32 v[160:161], v[34:35], v[158:159] op_sel_hi:[1,0]
	v_pk_mul_f32 v[148:149], v[38:39], v[158:159] op_sel_hi:[1,0]
	v_pk_mul_f32 v[146:147], v[36:37], v[158:159] op_sel_hi:[1,0]
	v_pk_mul_f32 v[162:163], v[32:33], v[158:159] op_sel_hi:[1,0]
	v_cvt_pk_bf16_f32 v146, v146, v147
	v_cvt_pk_bf16_f32 v147, v148, v149
	v_cvt_pk_bf16_f32 v148, v162, v163
	v_cvt_pk_bf16_f32 v149, v160, v161
	v_addc_co_u32_e32 v151, vcc, 0, v152, vcc
	global_store_dwordx4 v[150:151], v[146:149], off
	v_pk_mul_f32 v[152:153], v[2:3], v[158:159] op_sel_hi:[1,0]
	s_andn2_b64 vcc, exec, s[44:45]
	v_pk_mul_f32 v[148:149], v[6:7], v[158:159] op_sel_hi:[1,0]
	v_pk_mul_f32 v[146:147], v[4:5], v[158:159] op_sel_hi:[1,0]
	v_pk_mul_f32 v[158:159], v[0:1], v[158:159] op_sel_hi:[1,0]
	v_cvt_pk_bf16_f32 v146, v146, v147
	v_cvt_pk_bf16_f32 v147, v148, v149
	v_cvt_pk_bf16_f32 v148, v158, v159
	v_cvt_pk_bf16_f32 v149, v152, v153
	global_store_dwordx4 v[150:151], v[146:149], off offset:256
	s_cbranch_vccz .LBB0_291
	s_mov_b64 s[38:39], s[48:49]
	s_andn2_b64 vcc, exec, s[42:43]
	s_mov_b64 s[48:49], s[38:39]
	s_cbranch_vccnz .LBB0_292

.Lm4bp_315:
	s_waitcnt lgkmcnt(0)
	s_mov_b32 s100, 0
	s_barrier
	v_mfma_f32_16x16x32_bf16 v[60:63], v[146:149], v[170:173], 0
	v_mfma_f32_16x16x32_bf16 v[56:59], v[162:165], v[170:173], 0
	v_mfma_f32_16x16x32_bf16 v[52:55], v[146:149], v[178:181], 0
	v_mfma_f32_16x16x32_bf16 v[48:51], v[162:165], v[178:181], 0
	v_mfma_f32_16x16x32_bf16 v[44:47], v[146:149], v[194:197], 0
	v_mfma_f32_16x16x32_bf16 v[40:43], v[162:165], v[194:197], 0
	v_mfma_f32_16x16x32_bf16 v[36:39], v[146:149], v[210:213], 0
	v_mfma_f32_16x16x32_bf16 v[32:35], v[162:165], v[210:213], 0
	v_mfma_f32_16x16x32_bf16 v[60:63], v[158:161], v[174:177], v[60:63]
	v_mfma_f32_16x16x32_bf16 v[56:59], v[166:169], v[174:177], v[56:59]
	v_mfma_f32_16x16x32_bf16 v[52:55], v[158:161], v[182:185], v[52:55]
	v_mfma_f32_16x16x32_bf16 v[48:51], v[166:169], v[182:185], v[48:51]
	v_mfma_f32_16x16x32_bf16 v[44:47], v[158:161], v[206:209], v[44:47]
	v_mfma_f32_16x16x32_bf16 v[40:43], v[166:169], v[206:209], v[40:43]
	v_mfma_f32_16x16x32_bf16 v[36:39], v[158:161], v[214:217], v[36:39]
	v_mfma_f32_16x16x32_bf16 v[32:35], v[166:169], v[214:217], v[32:35]
	v_mfma_f32_16x16x32_bf16 v[28:31], v[218:221], v[170:173], 0
	v_mfma_f32_16x16x32_bf16 v[24:27], v[226:229], v[170:173], 0
	v_mfma_f32_16x16x32_bf16 v[20:23], v[218:221], v[178:181], 0
	v_mfma_f32_16x16x32_bf16 v[16:19], v[226:229], v[178:181], 0
	v_mfma_f32_16x16x32_bf16 v[12:15], v[218:221], v[194:197], 0
	v_mfma_f32_16x16x32_bf16 v[8:11], v[226:229], v[194:197], 0
	v_mfma_f32_16x16x32_bf16 v[4:7], v[218:221], v[210:213], 0
	v_mfma_f32_16x16x32_bf16 v[0:3], v[226:229], v[210:213], 0
	v_mfma_f32_16x16x32_bf16 v[28:31], v[222:225], v[174:177], v[28:31]
	v_mfma_f32_16x16x32_bf16 v[24:27], v[230:233], v[174:177], v[24:27]
	v_mfma_f32_16x16x32_bf16 v[20:23], v[222:225], v[182:185], v[20:23]
	v_mfma_f32_16x16x32_bf16 v[16:19], v[230:233], v[182:185], v[16:19]
	v_mfma_f32_16x16x32_bf16 v[12:15], v[222:225], v[206:209], v[12:15]
	v_mfma_f32_16x16x32_bf16 v[8:11], v[230:233], v[206:209], v[8:11]
	v_mfma_f32_16x16x32_bf16 v[4:7], v[222:225], v[214:217], v[4:7]
	v_mfma_f32_16x16x32_bf16 v[0:3], v[230:233], v[214:217], v[0:3]
	s_barrier
	s_add_i32 s6, 0, 0x18000
	v_add_u32_e32 v157, s6, v154
	ds_read_b128 v[146:149], v157
	ds_read_b128 v[158:161], v157 offset:1024
	ds_read_b128 v[162:165], v157 offset:2048
	ds_read_b128 v[166:169], v157 offset:3072
	s_add_u32 s52, s52, 0x40000
	s_addc_u32 s53, s53, 0
	s_mov_b32 m0, s68
	v_lshl_add_u64 v[218:219], s[52:53], 0, v[128:129]
	ds_read_b128 v[170:173], v156 offset:32768
	ds_read_b128 v[174:177], v156 offset:33792
	ds_read_b128 v[178:181], v156 offset:34816
	ds_read_b128 v[182:185], v156 offset:35840
	ds_read_b128 v[194:197], v156 offset:36864
	ds_read_b128 v[206:209], v156 offset:37888
	ds_read_b128 v[210:213], v156 offset:38912
	ds_read_b128 v[214:217], v156 offset:39936
	global_load_lds_dwordx4 v[218:219], off
	v_lshl_add_u64 v[218:219], s[52:53], 0, v[130:131]
	s_mov_b32 m0, s69
	s_nop 0
	global_load_lds_dwordx4 v[218:219], off
	s_add_i32 s19, 0, 0x1c000
	v_add_u32_e32 v157, s19, v154
	ds_read_b128 v[218:221], v157
	ds_read_b128 v[222:225], v157 offset:1024
	ds_read_b128 v[226:229], v157 offset:2048
	ds_read_b128 v[230:233], v157 offset:3072
	s_waitcnt vmcnt(8)
	s_waitcnt lgkmcnt(0)
	s_barrier
	v_mfma_f32_16x16x32_bf16 v[124:127], v[146:149], v[170:173], v[124:127]
	v_mfma_f32_16x16x32_bf16 v[120:123], v[162:165], v[170:173], v[120:123]
	v_mfma_f32_16x16x32_bf16 v[116:119], v[146:149], v[178:181], v[116:119]
	v_mfma_f32_16x16x32_bf16 v[112:115], v[162:165], v[178:181], v[112:115]
	v_mfma_f32_16x16x32_bf16 v[108:111], v[146:149], v[194:197], v[108:111]
	v_mfma_f32_16x16x32_bf16 v[104:107], v[162:165], v[194:197], v[104:107]
	v_mfma_f32_16x16x32_bf16 v[100:103], v[146:149], v[210:213], v[100:103]
	v_mfma_f32_16x16x32_bf16 v[96:99], v[162:165], v[210:213], v[96:99]
	v_mfma_f32_16x16x32_bf16 v[124:127], v[158:161], v[174:177], v[124:127]
	v_mfma_f32_16x16x32_bf16 v[120:123], v[166:169], v[174:177], v[120:123]
	v_mfma_f32_16x16x32_bf16 v[116:119], v[158:161], v[182:185], v[116:119]
	v_mfma_f32_16x16x32_bf16 v[112:115], v[166:169], v[182:185], v[112:115]
	v_mfma_f32_16x16x32_bf16 v[108:111], v[158:161], v[206:209], v[108:111]
	v_mfma_f32_16x16x32_bf16 v[104:107], v[166:169], v[206:209], v[104:107]
	v_mfma_f32_16x16x32_bf16 v[100:103], v[158:161], v[214:217], v[100:103]
	v_mfma_f32_16x16x32_bf16 v[96:99], v[166:169], v[214:217], v[96:99]
	v_mfma_f32_16x16x32_bf16 v[92:95], v[218:221], v[170:173], v[92:95]
	v_mfma_f32_16x16x32_bf16 v[88:91], v[226:229], v[170:173], v[88:91]
	v_mfma_f32_16x16x32_bf16 v[84:87], v[218:221], v[178:181], v[84:87]
	v_mfma_f32_16x16x32_bf16 v[80:83], v[226:229], v[178:181], v[80:83]
	v_mfma_f32_16x16x32_bf16 v[76:79], v[218:221], v[194:197], v[76:79]
	v_mfma_f32_16x16x32_bf16 v[72:75], v[226:229], v[194:197], v[72:75]
	v_mfma_f32_16x16x32_bf16 v[68:71], v[218:221], v[210:213], v[68:71]
	v_mfma_f32_16x16x32_bf16 v[64:67], v[226:229], v[210:213], v[64:67]
	v_mfma_f32_16x16x32_bf16 v[92:95], v[222:225], v[174:177], v[92:95]
	v_mfma_f32_16x16x32_bf16 v[88:91], v[230:233], v[174:177], v[88:91]
	v_mfma_f32_16x16x32_bf16 v[84:87], v[222:225], v[182:185], v[84:87]
	v_mfma_f32_16x16x32_bf16 v[80:83], v[230:233], v[182:185], v[80:83]
	v_mfma_f32_16x16x32_bf16 v[76:79], v[222:225], v[206:209], v[76:79]
	v_mfma_f32_16x16x32_bf16 v[72:75], v[230:233], v[206:209], v[72:75]
	v_mfma_f32_16x16x32_bf16 v[68:71], v[222:225], v[214:217], v[68:71]
	v_mfma_f32_16x16x32_bf16 v[64:67], v[230:233], v[214:217], v[64:67]
	s_barrier
	s_add_i32 s6, s6, s57
	v_lshl_add_u64 v[234:235], v[234:235], 0, s[36:37]
	s_mov_b32 m0, s6
	s_nop 0
	global_load_lds_dwordx4 v[234:235], off
	v_lshl_add_u64 v[234:235], v[236:237], 0, s[36:37]
	s_add_i32 m0, s6, 0x2000
	s_nop 0
	global_load_lds_dwordx4 v[234:235], off
	s_mov_b32 m0, s71
	v_lshl_add_u64 v[234:235], v[238:239], 0, s[36:37]
	ds_read_b128 v[170:173], v156 offset:49152
	ds_read_b128 v[174:177], v156 offset:50176
	ds_read_b128 v[178:181], v156 offset:51200
	ds_read_b128 v[182:185], v156 offset:52224
	ds_read_b128 v[194:197], v156 offset:53248
	ds_read_b128 v[206:209], v156 offset:54272
	ds_read_b128 v[210:213], v156 offset:55296
	ds_read_b128 v[214:217], v156 offset:56320
	global_load_lds_dwordx4 v[234:235], off
	v_lshl_add_u64 v[234:235], v[240:241], 0, s[36:37]
	s_mov_b32 m0, s72
	s_nop 0
	global_load_lds_dwordx4 v[234:235], off
	s_add_u32 s50, s50, 0x40080
	s_addc_u32 s51, s51, 0
	s_add_i32 s6, s19, s57
	v_lshl_add_u64 v[250:251], s[50:51], 0, v[140:141]
	s_mov_b32 m0, s6
	s_nop 0
	global_load_lds_dwordx4 v[250:251], off
	v_lshl_add_u64 v[250:251], s[50:51], 0, v[132:133]
	s_add_i32 m0, s6, 0x2000
	s_nop 0
	global_load_lds_dwordx4 v[250:251], off
	s_add_i32 s75, s75, 2
	s_add_u32 s48, s48, 0x100
	s_addc_u32 s49, s49, 0
	s_cmp_gt_u32 s75, 13
	s_waitcnt vmcnt(8)
	s_waitcnt lgkmcnt(0)
	s_barrier
	v_mfma_f32_16x16x32_bf16 v[60:63], v[146:149], v[170:173], v[60:63]
	v_mfma_f32_16x16x32_bf16 v[56:59], v[162:165], v[170:173], v[56:59]
	v_mfma_f32_16x16x32_bf16 v[52:55], v[146:149], v[178:181], v[52:55]
	v_mfma_f32_16x16x32_bf16 v[48:51], v[162:165], v[178:181], v[48:51]
	v_mfma_f32_16x16x32_bf16 v[44:47], v[146:149], v[194:197], v[44:47]
	v_mfma_f32_16x16x32_bf16 v[40:43], v[162:165], v[194:197], v[40:43]
	v_mfma_f32_16x16x32_bf16 v[36:39], v[146:149], v[210:213], v[36:39]
	v_mfma_f32_16x16x32_bf16 v[32:35], v[162:165], v[210:213], v[32:35]
	v_mfma_f32_16x16x32_bf16 v[60:63], v[158:161], v[174:177], v[60:63]
	v_mfma_f32_16x16x32_bf16 v[56:59], v[166:169], v[174:177], v[56:59]
	v_mfma_f32_16x16x32_bf16 v[52:55], v[158:161], v[182:185], v[52:55]
	v_mfma_f32_16x16x32_bf16 v[48:51], v[166:169], v[182:185], v[48:51]
	v_mfma_f32_16x16x32_bf16 v[44:47], v[158:161], v[206:209], v[44:47]
	v_mfma_f32_16x16x32_bf16 v[40:43], v[166:169], v[206:209], v[40:43]
	v_mfma_f32_16x16x32_bf16 v[36:39], v[158:161], v[214:217], v[36:39]
	v_mfma_f32_16x16x32_bf16 v[32:35], v[166:169], v[214:217], v[32:35]
	v_mfma_f32_16x16x32_bf16 v[28:31], v[218:221], v[170:173], v[28:31]
	v_mfma_f32_16x16x32_bf16 v[24:27], v[226:229], v[170:173], v[24:27]
	v_mfma_f32_16x16x32_bf16 v[20:23], v[218:221], v[178:181], v[20:23]
	v_mfma_f32_16x16x32_bf16 v[16:19], v[226:229], v[178:181], v[16:19]
	v_mfma_f32_16x16x32_bf16 v[12:15], v[218:221], v[194:197], v[12:15]
	v_mfma_f32_16x16x32_bf16 v[8:11], v[226:229], v[194:197], v[8:11]
	v_mfma_f32_16x16x32_bf16 v[4:7], v[218:221], v[210:213], v[4:7]
	v_mfma_f32_16x16x32_bf16 v[0:3], v[226:229], v[210:213], v[0:3]
	v_mfma_f32_16x16x32_bf16 v[28:31], v[222:225], v[174:177], v[28:31]
	v_mfma_f32_16x16x32_bf16 v[24:27], v[230:233], v[174:177], v[24:27]
	v_mfma_f32_16x16x32_bf16 v[20:23], v[222:225], v[182:185], v[20:23]
	v_mfma_f32_16x16x32_bf16 v[16:19], v[230:233], v[182:185], v[16:19]
	v_mfma_f32_16x16x32_bf16 v[12:15], v[222:225], v[206:209], v[12:15]
	v_mfma_f32_16x16x32_bf16 v[8:11], v[230:233], v[206:209], v[8:11]
	v_mfma_f32_16x16x32_bf16 v[4:7], v[222:225], v[214:217], v[4:7]
	v_mfma_f32_16x16x32_bf16 v[0:3], v[230:233], v[214:217], v[0:3]
	s_barrier
.LBB0_315:
	s_add_u32 s6, s4, s48
	s_addc_u32 s19, s5, s49
	s_add_u32 s6, s6, 0x100
	s_addc_u32 s19, s19, 0
	s_add_u32 s23, s11, s48
	s_addc_u32 s50, s12, s49
	s_add_i32 s80, 0, 0x10000
	v_add_u32_e32 v157, s80, v154
	ds_read_b128 v[146:149], v157
	ds_read_b128 v[158:161], v157 offset:1024
	ds_read_b128 v[162:165], v157 offset:2048
	ds_read_b128 v[166:169], v157 offset:3072
	s_cmpk_eq_i32 s48, 0x700
	s_cselect_b32 s53, s29, s19
	s_cselect_b32 s52, s31, s6
	s_cselect_b32 s51, s35, s50
	s_cselect_b32 s50, s74, s23
	v_lshl_add_u64 v[218:219], v[150:151], 0, s[48:49]
	s_add_i32 m0, s58, 0xc000
	ds_read_b128 v[170:173], v156
	ds_read_b128 v[174:177], v156 offset:1024
	ds_read_b128 v[178:181], v156 offset:2048
	ds_read_b128 v[182:185], v156 offset:3072
	ds_read_b128 v[194:197], v156 offset:4096
	ds_read_b128 v[206:209], v156 offset:5120
	ds_read_b128 v[210:213], v156 offset:6144
	ds_read_b128 v[214:217], v156 offset:7168
	global_load_lds_dwordx4 v[218:219], off
	v_lshl_add_u64 v[218:219], v[152:153], 0, s[48:49]
	s_add_i32 m0, s58, 0xe000
	s_nop 0
	global_load_lds_dwordx4 v[218:219], off
	s_add_i32 s6, 0, 0x14000
	v_add_u32_e32 v157, s6, v154
	ds_read_b128 v[218:221], v157
	ds_read_b128 v[222:225], v157 offset:1024
	ds_read_b128 v[226:229], v157 offset:2048
	ds_read_b128 v[230:233], v157 offset:3072
	s_waitcnt vmcnt(8)
	s_waitcnt lgkmcnt(0)
	s_barrier
	v_mfma_f32_16x16x32_bf16 v[124:127], v[146:149], v[170:173], v[124:127]
	v_mfma_f32_16x16x32_bf16 v[120:123], v[162:165], v[170:173], v[120:123]
	v_mfma_f32_16x16x32_bf16 v[116:119], v[146:149], v[178:181], v[116:119]
	v_mfma_f32_16x16x32_bf16 v[112:115], v[162:165], v[178:181], v[112:115]
	v_mfma_f32_16x16x32_bf16 v[108:111], v[146:149], v[194:197], v[108:111]
	v_mfma_f32_16x16x32_bf16 v[104:107], v[162:165], v[194:197], v[104:107]
	v_mfma_f32_16x16x32_bf16 v[100:103], v[146:149], v[210:213], v[100:103]
	v_mfma_f32_16x16x32_bf16 v[96:99], v[162:165], v[210:213], v[96:99]
	v_mfma_f32_16x16x32_bf16 v[124:127], v[158:161], v[174:177], v[124:127]
	v_mfma_f32_16x16x32_bf16 v[120:123], v[166:169], v[174:177], v[120:123]
	v_mfma_f32_16x16x32_bf16 v[116:119], v[158:161], v[182:185], v[116:119]
	v_mfma_f32_16x16x32_bf16 v[112:115], v[166:169], v[182:185], v[112:115]
	v_mfma_f32_16x16x32_bf16 v[108:111], v[158:161], v[206:209], v[108:111]
	v_mfma_f32_16x16x32_bf16 v[104:107], v[166:169], v[206:209], v[104:107]
	v_mfma_f32_16x16x32_bf16 v[100:103], v[158:161], v[214:217], v[100:103]
	v_mfma_f32_16x16x32_bf16 v[96:99], v[166:169], v[214:217], v[96:99]
	v_mfma_f32_16x16x32_bf16 v[92:95], v[218:221], v[170:173], v[92:95]
	v_mfma_f32_16x16x32_bf16 v[88:91], v[226:229], v[170:173], v[88:91]
	v_mfma_f32_16x16x32_bf16 v[84:87], v[218:221], v[178:181], v[84:87]
	v_mfma_f32_16x16x32_bf16 v[80:83], v[226:229], v[178:181], v[80:83]
	v_mfma_f32_16x16x32_bf16 v[76:79], v[218:221], v[194:197], v[76:79]
	v_mfma_f32_16x16x32_bf16 v[72:75], v[226:229], v[194:197], v[72:75]
	v_mfma_f32_16x16x32_bf16 v[68:71], v[218:221], v[210:213], v[68:71]
	v_mfma_f32_16x16x32_bf16 v[64:67], v[226:229], v[210:213], v[64:67]
	v_mfma_f32_16x16x32_bf16 v[92:95], v[222:225], v[174:177], v[92:95]
	v_mfma_f32_16x16x32_bf16 v[88:91], v[230:233], v[174:177], v[88:91]
	v_mfma_f32_16x16x32_bf16 v[84:87], v[222:225], v[182:185], v[84:87]
	v_mfma_f32_16x16x32_bf16 v[80:83], v[230:233], v[182:185], v[80:83]
	v_mfma_f32_16x16x32_bf16 v[76:79], v[222:225], v[206:209], v[76:79]
	v_mfma_f32_16x16x32_bf16 v[72:75], v[230:233], v[206:209], v[72:75]
	v_mfma_f32_16x16x32_bf16 v[68:71], v[222:225], v[214:217], v[68:71]
	v_mfma_f32_16x16x32_bf16 v[64:67], v[230:233], v[214:217], v[64:67]
	s_barrier
	s_add_i32 s19, s80, s57
	v_lshl_add_u64 v[234:235], s[50:51], 0, v[140:141]
	s_mov_b32 m0, s19
	s_nop 0
	global_load_lds_dwordx4 v[234:235], off
	v_lshl_add_u64 v[236:237], s[50:51], 0, v[132:133]
	s_add_i32 m0, s19, 0x2000
	s_nop 0
	global_load_lds_dwordx4 v[236:237], off
	s_mov_b32 m0, s58
	v_lshl_add_u64 v[238:239], s[52:53], 0, v[128:129]
	ds_read_b128 v[170:173], v156 offset:16384
	ds_read_b128 v[174:177], v156 offset:17408
	ds_read_b128 v[178:181], v156 offset:18432
	ds_read_b128 v[182:185], v156 offset:19456
	ds_read_b128 v[194:197], v156 offset:20480
	ds_read_b128 v[206:209], v156 offset:21504
	ds_read_b128 v[210:213], v156 offset:22528
	ds_read_b128 v[214:217], v156 offset:23552
	global_load_lds_dwordx4 v[238:239], off
	v_lshl_add_u64 v[240:241], s[52:53], 0, v[130:131]
	s_mov_b32 m0, s59
	s_nop 0
	global_load_lds_dwordx4 v[240:241], off
	s_add_u32 s80, s50, 0x40000
	s_addc_u32 s81, s51, 0
	s_add_i32 s6, s6, s57
	v_lshl_add_u64 v[250:251], s[80:81], 0, v[140:141]
	s_mov_b32 m0, s6
	s_nop 0
	global_load_lds_dwordx4 v[250:251], off
	v_lshl_add_u64 v[250:251], s[80:81], 0, v[132:133]
	s_add_i32 m0, s6, 0x2000
	s_nop 0
	global_load_lds_dwordx4 v[250:251], off
	s_waitcnt vmcnt(8)
	s_waitcnt lgkmcnt(0)
	s_barrier
	v_mfma_f32_16x16x32_bf16 v[60:63], v[146:149], v[170:173], v[60:63]
	v_mfma_f32_16x16x32_bf16 v[56:59], v[162:165], v[170:173], v[56:59]
	v_mfma_f32_16x16x32_bf16 v[52:55], v[146:149], v[178:181], v[52:55]
	v_mfma_f32_16x16x32_bf16 v[48:51], v[162:165], v[178:181], v[48:51]
	v_mfma_f32_16x16x32_bf16 v[44:47], v[146:149], v[194:197], v[44:47]
	v_mfma_f32_16x16x32_bf16 v[40:43], v[162:165], v[194:197], v[40:43]
	v_mfma_f32_16x16x32_bf16 v[36:39], v[146:149], v[210:213], v[36:39]
	v_mfma_f32_16x16x32_bf16 v[32:35], v[162:165], v[210:213], v[32:35]
	v_mfma_f32_16x16x32_bf16 v[60:63], v[158:161], v[174:177], v[60:63]
	v_mfma_f32_16x16x32_bf16 v[56:59], v[166:169], v[174:177], v[56:59]
	v_mfma_f32_16x16x32_bf16 v[52:55], v[158:161], v[182:185], v[52:55]
	v_mfma_f32_16x16x32_bf16 v[48:51], v[166:169], v[182:185], v[48:51]
	v_mfma_f32_16x16x32_bf16 v[44:47], v[158:161], v[206:209], v[44:47]
	v_mfma_f32_16x16x32_bf16 v[40:43], v[166:169], v[206:209], v[40:43]
	v_mfma_f32_16x16x32_bf16 v[36:39], v[158:161], v[214:217], v[36:39]
	v_mfma_f32_16x16x32_bf16 v[32:35], v[166:169], v[214:217], v[32:35]
	v_mfma_f32_16x16x32_bf16 v[28:31], v[218:221], v[170:173], v[28:31]
	v_mfma_f32_16x16x32_bf16 v[24:27], v[226:229], v[170:173], v[24:27]
	v_mfma_f32_16x16x32_bf16 v[20:23], v[218:221], v[178:181], v[20:23]
	v_mfma_f32_16x16x32_bf16 v[16:19], v[226:229], v[178:181], v[16:19]
	v_mfma_f32_16x16x32_bf16 v[12:15], v[218:221], v[194:197], v[12:15]
	v_mfma_f32_16x16x32_bf16 v[8:11], v[226:229], v[194:197], v[8:11]
	v_mfma_f32_16x16x32_bf16 v[4:7], v[218:221], v[210:213], v[4:7]
	v_mfma_f32_16x16x32_bf16 v[0:3], v[226:229], v[210:213], v[0:3]
	v_mfma_f32_16x16x32_bf16 v[28:31], v[222:225], v[174:177], v[28:31]
	v_mfma_f32_16x16x32_bf16 v[24:27], v[230:233], v[174:177], v[24:27]
	v_mfma_f32_16x16x32_bf16 v[20:23], v[222:225], v[182:185], v[20:23]
	v_mfma_f32_16x16x32_bf16 v[16:19], v[230:233], v[182:185], v[16:19]
	v_mfma_f32_16x16x32_bf16 v[12:15], v[222:225], v[206:209], v[12:15]
	v_mfma_f32_16x16x32_bf16 v[8:11], v[230:233], v[206:209], v[8:11]
	v_mfma_f32_16x16x32_bf16 v[4:7], v[222:225], v[214:217], v[4:7]
	v_mfma_f32_16x16x32_bf16 v[0:3], v[230:233], v[214:217], v[0:3]
	s_barrier
	s_add_i32 s6, 0, 0x18000
	v_add_u32_e32 v157, s6, v154
	ds_read_b128 v[146:149], v157
	ds_read_b128 v[158:161], v157 offset:1024
	ds_read_b128 v[162:165], v157 offset:2048
	ds_read_b128 v[166:169], v157 offset:3072
	s_add_u32 s52, s52, 0x40000
	s_addc_u32 s53, s53, 0
	s_mov_b32 m0, s68
	v_lshl_add_u64 v[218:219], s[52:53], 0, v[128:129]
	ds_read_b128 v[170:173], v156 offset:32768
	ds_read_b128 v[174:177], v156 offset:33792
	ds_read_b128 v[178:181], v156 offset:34816
	ds_read_b128 v[182:185], v156 offset:35840
	ds_read_b128 v[194:197], v156 offset:36864
	ds_read_b128 v[206:209], v156 offset:37888
	ds_read_b128 v[210:213], v156 offset:38912
	ds_read_b128 v[214:217], v156 offset:39936
	global_load_lds_dwordx4 v[218:219], off
	v_lshl_add_u64 v[218:219], s[52:53], 0, v[130:131]
	s_mov_b32 m0, s69
	s_nop 0
	global_load_lds_dwordx4 v[218:219], off
	s_add_i32 s19, 0, 0x1c000
	v_add_u32_e32 v157, s19, v154
	ds_read_b128 v[218:221], v157
	ds_read_b128 v[222:225], v157 offset:1024
	ds_read_b128 v[226:229], v157 offset:2048
	ds_read_b128 v[230:233], v157 offset:3072
	s_waitcnt vmcnt(8)
	s_waitcnt lgkmcnt(0)
	s_barrier
	v_mfma_f32_16x16x32_bf16 v[124:127], v[146:149], v[170:173], v[124:127]
	v_mfma_f32_16x16x32_bf16 v[120:123], v[162:165], v[170:173], v[120:123]
	v_mfma_f32_16x16x32_bf16 v[116:119], v[146:149], v[178:181], v[116:119]
	v_mfma_f32_16x16x32_bf16 v[112:115], v[162:165], v[178:181], v[112:115]
	v_mfma_f32_16x16x32_bf16 v[108:111], v[146:149], v[194:197], v[108:111]
	v_mfma_f32_16x16x32_bf16 v[104:107], v[162:165], v[194:197], v[104:107]
	v_mfma_f32_16x16x32_bf16 v[100:103], v[146:149], v[210:213], v[100:103]
	v_mfma_f32_16x16x32_bf16 v[96:99], v[162:165], v[210:213], v[96:99]
	v_mfma_f32_16x16x32_bf16 v[124:127], v[158:161], v[174:177], v[124:127]
	v_mfma_f32_16x16x32_bf16 v[120:123], v[166:169], v[174:177], v[120:123]
	v_mfma_f32_16x16x32_bf16 v[116:119], v[158:161], v[182:185], v[116:119]
	v_mfma_f32_16x16x32_bf16 v[112:115], v[166:169], v[182:185], v[112:115]
	v_mfma_f32_16x16x32_bf16 v[108:111], v[158:161], v[206:209], v[108:111]
	v_mfma_f32_16x16x32_bf16 v[104:107], v[166:169], v[206:209], v[104:107]
	v_mfma_f32_16x16x32_bf16 v[100:103], v[158:161], v[214:217], v[100:103]
	v_mfma_f32_16x16x32_bf16 v[96:99], v[166:169], v[214:217], v[96:99]
	v_mfma_f32_16x16x32_bf16 v[92:95], v[218:221], v[170:173], v[92:95]
	v_mfma_f32_16x16x32_bf16 v[88:91], v[226:229], v[170:173], v[88:91]
	v_mfma_f32_16x16x32_bf16 v[84:87], v[218:221], v[178:181], v[84:87]
	v_mfma_f32_16x16x32_bf16 v[80:83], v[226:229], v[178:181], v[80:83]
	v_mfma_f32_16x16x32_bf16 v[76:79], v[218:221], v[194:197], v[76:79]
	v_mfma_f32_16x16x32_bf16 v[72:75], v[226:229], v[194:197], v[72:75]
	v_mfma_f32_16x16x32_bf16 v[68:71], v[218:221], v[210:213], v[68:71]
	v_mfma_f32_16x16x32_bf16 v[64:67], v[226:229], v[210:213], v[64:67]
	v_mfma_f32_16x16x32_bf16 v[92:95], v[222:225], v[174:177], v[92:95]
	v_mfma_f32_16x16x32_bf16 v[88:91], v[230:233], v[174:177], v[88:91]
	v_mfma_f32_16x16x32_bf16 v[84:87], v[222:225], v[182:185], v[84:87]
	v_mfma_f32_16x16x32_bf16 v[80:83], v[230:233], v[182:185], v[80:83]
	v_mfma_f32_16x16x32_bf16 v[76:79], v[222:225], v[206:209], v[76:79]
	v_mfma_f32_16x16x32_bf16 v[72:75], v[230:233], v[206:209], v[72:75]
	v_mfma_f32_16x16x32_bf16 v[68:71], v[222:225], v[214:217], v[68:71]
	v_mfma_f32_16x16x32_bf16 v[64:67], v[230:233], v[214:217], v[64:67]
	s_barrier
	s_add_i32 s6, s6, s57
	v_lshl_add_u64 v[234:235], v[234:235], 0, s[36:37]
	s_mov_b32 m0, s6
	s_nop 0
	global_load_lds_dwordx4 v[234:235], off
	v_lshl_add_u64 v[234:235], v[236:237], 0, s[36:37]
	s_add_i32 m0, s6, 0x2000
	s_nop 0
	global_load_lds_dwordx4 v[234:235], off
	s_mov_b32 m0, s71
	v_lshl_add_u64 v[234:235], v[238:239], 0, s[36:37]
	ds_read_b128 v[170:173], v156 offset:49152
	ds_read_b128 v[174:177], v156 offset:50176
	ds_read_b128 v[178:181], v156 offset:51200
	ds_read_b128 v[182:185], v156 offset:52224
	ds_read_b128 v[194:197], v156 offset:53248
	ds_read_b128 v[206:209], v156 offset:54272
	ds_read_b128 v[210:213], v156 offset:55296
	ds_read_b128 v[214:217], v156 offset:56320
	global_load_lds_dwordx4 v[234:235], off
	v_lshl_add_u64 v[234:235], v[240:241], 0, s[36:37]
	s_mov_b32 m0, s72
	s_nop 0
	global_load_lds_dwordx4 v[234:235], off
	s_add_u32 s50, s50, 0x40080
	s_addc_u32 s51, s51, 0
	s_add_i32 s6, s19, s57
	v_lshl_add_u64 v[250:251], s[50:51], 0, v[140:141]
	s_mov_b32 m0, s6
	s_nop 0
	global_load_lds_dwordx4 v[250:251], off
	v_lshl_add_u64 v[250:251], s[50:51], 0, v[132:133]
	s_add_i32 m0, s6, 0x2000
	s_nop 0
	global_load_lds_dwordx4 v[250:251], off
	s_add_i32 s75, s75, 2
	s_add_u32 s48, s48, 0x100
	s_addc_u32 s49, s49, 0
	s_cmp_gt_u32 s75, 13
	s_waitcnt vmcnt(8)
	s_waitcnt lgkmcnt(0)
	s_barrier
	v_mfma_f32_16x16x32_bf16 v[60:63], v[146:149], v[170:173], v[60:63]
	v_mfma_f32_16x16x32_bf16 v[56:59], v[162:165], v[170:173], v[56:59]
	v_mfma_f32_16x16x32_bf16 v[52:55], v[146:149], v[178:181], v[52:55]
	v_mfma_f32_16x16x32_bf16 v[48:51], v[162:165], v[178:181], v[48:51]
	v_mfma_f32_16x16x32_bf16 v[44:47], v[146:149], v[194:197], v[44:47]
	v_mfma_f32_16x16x32_bf16 v[40:43], v[162:165], v[194:197], v[40:43]
	v_mfma_f32_16x16x32_bf16 v[36:39], v[146:149], v[210:213], v[36:39]
	v_mfma_f32_16x16x32_bf16 v[32:35], v[162:165], v[210:213], v[32:35]
	v_mfma_f32_16x16x32_bf16 v[60:63], v[158:161], v[174:177], v[60:63]
	v_mfma_f32_16x16x32_bf16 v[56:59], v[166:169], v[174:177], v[56:59]
	v_mfma_f32_16x16x32_bf16 v[52:55], v[158:161], v[182:185], v[52:55]
	v_mfma_f32_16x16x32_bf16 v[48:51], v[166:169], v[182:185], v[48:51]
	v_mfma_f32_16x16x32_bf16 v[44:47], v[158:161], v[206:209], v[44:47]
	v_mfma_f32_16x16x32_bf16 v[40:43], v[166:169], v[206:209], v[40:43]
	v_mfma_f32_16x16x32_bf16 v[36:39], v[158:161], v[214:217], v[36:39]
	v_mfma_f32_16x16x32_bf16 v[32:35], v[166:169], v[214:217], v[32:35]
	v_mfma_f32_16x16x32_bf16 v[28:31], v[218:221], v[170:173], v[28:31]
	v_mfma_f32_16x16x32_bf16 v[24:27], v[226:229], v[170:173], v[24:27]
	v_mfma_f32_16x16x32_bf16 v[20:23], v[218:221], v[178:181], v[20:23]
	v_mfma_f32_16x16x32_bf16 v[16:19], v[226:229], v[178:181], v[16:19]
	v_mfma_f32_16x16x32_bf16 v[12:15], v[218:221], v[194:197], v[12:15]
	v_mfma_f32_16x16x32_bf16 v[8:11], v[226:229], v[194:197], v[8:11]
	v_mfma_f32_16x16x32_bf16 v[4:7], v[218:221], v[210:213], v[4:7]
	v_mfma_f32_16x16x32_bf16 v[0:3], v[226:229], v[210:213], v[0:3]
	v_mfma_f32_16x16x32_bf16 v[28:31], v[222:225], v[174:177], v[28:31]
	v_mfma_f32_16x16x32_bf16 v[24:27], v[230:233], v[174:177], v[24:27]
	v_mfma_f32_16x16x32_bf16 v[20:23], v[222:225], v[182:185], v[20:23]
	v_mfma_f32_16x16x32_bf16 v[16:19], v[230:233], v[182:185], v[16:19]
	v_mfma_f32_16x16x32_bf16 v[12:15], v[222:225], v[206:209], v[12:15]
	v_mfma_f32_16x16x32_bf16 v[8:11], v[230:233], v[206:209], v[8:11]
	v_mfma_f32_16x16x32_bf16 v[4:7], v[222:225], v[214:217], v[4:7]
	v_mfma_f32_16x16x32_bf16 v[0:3], v[230:233], v[214:217], v[0:3]
	s_barrier
	s_cbranch_scc0 .LBB0_315
	s_mov_b32 s100, 1
	s_add_u32 s48, s11, 0xffffff00
	v_lshl_or_b32 v146, s70, 8, v155
	s_addc_u32 s49, s12, -1
	s_ashr_i32 s29, s28, 31
	v_ashrrev_i32_e32 v147, 31, v146
	v_lshl_add_u64 v[146:147], v[146:147], 1, s[26:27]
	s_lshl_b64 s[50:51], s[28:29], 20
	v_lshl_add_u64 v[146:147], v[146:147], 0, s[50:51]
	v_lshl_add_u64 v[150:151], v[146:147], 0, v[134:135]
	v_cvt_pk_bf16_f32 v146, v124, v125
	v_cvt_pk_bf16_f32 v147, v126, v127
	v_cvt_pk_bf16_f32 v148, v120, v121
	v_cvt_pk_bf16_f32 v149, v122, v123
	global_store_dwordx4 v[150:151], v[146:149], off
	v_add_co_u32_e32 v152, vcc, s66, v150
	s_nop 0
	v_cvt_pk_bf16_f32 v146, v92, v93
	v_cvt_pk_bf16_f32 v147, v94, v95
	v_cvt_pk_bf16_f32 v148, v88, v89
	v_cvt_pk_bf16_f32 v149, v90, v91
	global_store_dwordx4 v[150:151], v[146:149], off offset:256
	v_addc_co_u32_e32 v153, vcc, 0, v151, vcc
	s_nop 0
	v_cvt_pk_bf16_f32 v146, v116, v117
	v_cvt_pk_bf16_f32 v147, v118, v119
	v_cvt_pk_bf16_f32 v148, v112, v113
	v_cvt_pk_bf16_f32 v149, v114, v115
	global_store_dwordx4 v[152:153], v[146:149], off
	s_mov_b32 s6, 0x20000
	s_nop 0
	v_cvt_pk_bf16_f32 v146, v84, v85
	v_cvt_pk_bf16_f32 v147, v86, v87
	v_cvt_pk_bf16_f32 v148, v80, v81
	v_cvt_pk_bf16_f32 v149, v82, v83
	global_store_dwordx4 v[152:153], v[146:149], off offset:256
	v_add_co_u32_e32 v152, vcc, s6, v150
	s_nop 0
	v_cvt_pk_bf16_f32 v146, v108, v109
	v_cvt_pk_bf16_f32 v147, v110, v111
	v_cvt_pk_bf16_f32 v148, v104, v105
	v_cvt_pk_bf16_f32 v149, v106, v107
	v_addc_co_u32_e32 v153, vcc, 0, v151, vcc
	global_store_dwordx4 v[152:153], v[146:149], off
	s_mov_b32 s6, 0x30000
	s_nop 0
	v_cvt_pk_bf16_f32 v146, v76, v77
	v_cvt_pk_bf16_f32 v147, v78, v79
	v_cvt_pk_bf16_f32 v148, v72, v73
	v_cvt_pk_bf16_f32 v149, v74, v75
	global_store_dwordx4 v[152:153], v[146:149], off offset:256
	v_add_co_u32_e32 v152, vcc, s6, v150
	s_nop 0
	v_cvt_pk_bf16_f32 v146, v100, v101
	v_cvt_pk_bf16_f32 v147, v102, v103
	v_cvt_pk_bf16_f32 v148, v96, v97
	v_cvt_pk_bf16_f32 v149, v98, v99
	v_addc_co_u32_e32 v153, vcc, 0, v151, vcc
	global_store_dwordx4 v[152:153], v[146:149], off
	s_mov_b32 s6, 0x80000
	s_nop 0
	v_cvt_pk_bf16_f32 v146, v68, v69
	v_cvt_pk_bf16_f32 v147, v70, v71
	v_cvt_pk_bf16_f32 v148, v64, v65
	v_cvt_pk_bf16_f32 v149, v66, v67
	global_store_dwordx4 v[152:153], v[146:149], off offset:256
	v_add_co_u32_e32 v152, vcc, s6, v150
	s_nop 0
	v_cvt_pk_bf16_f32 v146, v60, v61
	v_cvt_pk_bf16_f32 v147, v62, v63
	v_cvt_pk_bf16_f32 v148, v56, v57
	v_cvt_pk_bf16_f32 v149, v58, v59
	v_addc_co_u32_e32 v153, vcc, 0, v151, vcc
	global_store_dwordx4 v[152:153], v[146:149], off
	s_mov_b32 s6, 0x90000
	s_nop 0
	v_cvt_pk_bf16_f32 v146, v28, v29
	v_cvt_pk_bf16_f32 v147, v30, v31
	v_cvt_pk_bf16_f32 v148, v24, v25
	v_cvt_pk_bf16_f32 v149, v26, v27
	global_store_dwordx4 v[152:153], v[146:149], off offset:256
	v_add_co_u32_e32 v152, vcc, s6, v150
	s_nop 0
	v_cvt_pk_bf16_f32 v146, v52, v53
	v_cvt_pk_bf16_f32 v147, v54, v55
	v_cvt_pk_bf16_f32 v148, v48, v49
	v_cvt_pk_bf16_f32 v149, v50, v51
	v_addc_co_u32_e32 v153, vcc, 0, v151, vcc
	global_store_dwordx4 v[152:153], v[146:149], off
	s_mov_b32 s6, 0xa0000
	s_nop 0
	v_cvt_pk_bf16_f32 v146, v20, v21
	v_cvt_pk_bf16_f32 v147, v22, v23
	v_cvt_pk_bf16_f32 v148, v16, v17
	v_cvt_pk_bf16_f32 v149, v18, v19
	global_store_dwordx4 v[152:153], v[146:149], off offset:256
	v_add_co_u32_e32 v152, vcc, s6, v150
	s_nop 0
	v_cvt_pk_bf16_f32 v146, v44, v45
	v_cvt_pk_bf16_f32 v147, v46, v47
	v_cvt_pk_bf16_f32 v148, v40, v41
	v_cvt_pk_bf16_f32 v149, v42, v43
	v_addc_co_u32_e32 v153, vcc, 0, v151, vcc
	s_mov_b32 s6, 0xb0000
	global_store_dwordx4 v[152:153], v[146:149], off
	v_add_co_u32_e32 v150, vcc, s6, v150
	s_nop 0
	v_cvt_pk_bf16_f32 v146, v12, v13
	v_cvt_pk_bf16_f32 v147, v14, v15
	v_cvt_pk_bf16_f32 v148, v8, v9
	v_cvt_pk_bf16_f32 v149, v10, v11
	global_store_dwordx4 v[152:153], v[146:149], off offset:256
	v_addc_co_u32_e32 v151, vcc, 0, v151, vcc
	s_nop 0
	v_cvt_pk_bf16_f32 v146, v36, v37
	v_cvt_pk_bf16_f32 v147, v38, v39
	v_cvt_pk_bf16_f32 v148, v32, v33
	v_cvt_pk_bf16_f32 v149, v34, v35
	global_store_dwordx4 v[150:151], v[146:149], off
	s_andn2_b64 vcc, exec, s[44:45]
	s_nop 0
	v_cvt_pk_bf16_f32 v146, v4, v5
	v_cvt_pk_bf16_f32 v147, v6, v7
	v_cvt_pk_bf16_f32 v148, v0, v1
	v_cvt_pk_bf16_f32 v149, v2, v3
	global_store_dwordx4 v[150:151], v[146:149], off offset:256
	s_cbranch_vccz .LBB0_307
	s_mov_b64 s[42:43], s[48:49]
	s_andn2_b64 vcc, exec, s[38:39]
	s_mov_b64 s[48:49], s[42:43]
	s_cbranch_vccnz .LBB0_308

.Lm4bp_341:
	s_waitcnt lgkmcnt(0)
	s_mov_b32 s100, 0
	s_barrier
	v_mfma_f32_16x16x32_bf16 v[60:63], v[128:131], v[162:165], 0
	v_mfma_f32_16x16x32_bf16 v[56:59], v[136:139], v[162:165], 0
	v_mfma_f32_16x16x32_bf16 v[48:51], v[128:131], v[170:173], 0
	v_mfma_f32_16x16x32_bf16 v[40:43], v[136:139], v[170:173], 0
	v_mfma_f32_16x16x32_bf16 v[32:35], v[128:131], v[178:181], 0
	v_mfma_f32_16x16x32_bf16 v[24:27], v[136:139], v[178:181], 0
	v_mfma_f32_16x16x32_bf16 v[16:19], v[128:131], v[194:197], 0
	v_mfma_f32_16x16x32_bf16 v[8:11], v[136:139], v[194:197], 0
	v_mfma_f32_16x16x32_bf16 v[60:63], v[132:135], v[166:169], v[60:63]
	v_mfma_f32_16x16x32_bf16 v[56:59], v[146:149], v[166:169], v[56:59]
	v_mfma_f32_16x16x32_bf16 v[48:51], v[132:135], v[174:177], v[48:51]
	v_mfma_f32_16x16x32_bf16 v[40:43], v[146:149], v[174:177], v[40:43]
	v_mfma_f32_16x16x32_bf16 v[32:35], v[132:135], v[182:185], v[32:35]
	v_mfma_f32_16x16x32_bf16 v[24:27], v[146:149], v[182:185], v[24:27]
	v_mfma_f32_16x16x32_bf16 v[16:19], v[132:135], v[210:213], v[16:19]
	v_mfma_f32_16x16x32_bf16 v[8:11], v[146:149], v[210:213], v[8:11]
	v_mfma_f32_16x16x32_bf16 v[52:55], v[214:217], v[162:165], 0
	v_mfma_f32_16x16x32_bf16 v[44:47], v[222:225], v[162:165], 0
	v_mfma_f32_16x16x32_bf16 v[36:39], v[214:217], v[170:173], 0
	v_mfma_f32_16x16x32_bf16 v[28:31], v[222:225], v[170:173], 0
	v_mfma_f32_16x16x32_bf16 v[20:23], v[214:217], v[178:181], 0
	v_mfma_f32_16x16x32_bf16 v[12:15], v[222:225], v[178:181], 0
	v_mfma_f32_16x16x32_bf16 v[4:7], v[214:217], v[194:197], 0
	v_mfma_f32_16x16x32_bf16 v[0:3], v[222:225], v[194:197], 0
	v_mfma_f32_16x16x32_bf16 v[52:55], v[218:221], v[166:169], v[52:55]
	v_mfma_f32_16x16x32_bf16 v[44:47], v[226:229], v[166:169], v[44:47]
	v_mfma_f32_16x16x32_bf16 v[36:39], v[218:221], v[174:177], v[36:39]
	v_mfma_f32_16x16x32_bf16 v[28:31], v[226:229], v[174:177], v[28:31]
	v_mfma_f32_16x16x32_bf16 v[20:23], v[218:221], v[182:185], v[20:23]
	v_mfma_f32_16x16x32_bf16 v[12:15], v[226:229], v[182:185], v[12:15]
	v_mfma_f32_16x16x32_bf16 v[4:7], v[218:221], v[210:213], v[4:7]
	v_mfma_f32_16x16x32_bf16 v[0:3], v[226:229], v[210:213], v[0:3]
	s_barrier
	s_add_i32 s6, 0, 0x18000
	v_add_u32_e32 v146, s6, v206
	ds_read_b128 v[128:131], v146
	ds_read_b128 v[132:135], v146 offset:1024
	ds_read_b128 v[136:139], v146 offset:2048
	ds_read_b128 v[146:149], v146 offset:3072
	s_add_u32 s50, s52, 0xb0000
	s_addc_u32 s51, s53, 0
	s_mov_b32 m0, s68
	v_lshl_add_u64 v[214:215], s[50:51], 0, v[154:155]
	ds_read_b128 v[162:165], v208 offset:32768
	ds_read_b128 v[166:169], v208 offset:33792
	ds_read_b128 v[170:173], v208 offset:34816
	ds_read_b128 v[174:177], v208 offset:35840
	ds_read_b128 v[178:181], v208 offset:36864
	ds_read_b128 v[182:185], v208 offset:37888
	ds_read_b128 v[194:197], v208 offset:38912
	ds_read_b128 v[210:213], v208 offset:39936
	global_load_lds_dwordx4 v[214:215], off
	v_lshl_add_u64 v[214:215], s[50:51], 0, v[152:153]
	s_mov_b32 m0, s69
	s_nop 0
	global_load_lds_dwordx4 v[214:215], off
	s_add_i32 s19, 0, 0x1c000
	v_add_u32_e32 v192, s19, v206
	ds_read_b128 v[214:217], v192
	ds_read_b128 v[218:221], v192 offset:1024
	ds_read_b128 v[222:225], v192 offset:2048
	ds_read_b128 v[226:229], v192 offset:3072
	s_waitcnt vmcnt(8)
	s_waitcnt lgkmcnt(0)
	s_barrier
	v_mfma_f32_16x16x32_bf16 v[124:127], v[128:131], v[162:165], v[124:127]
	v_mfma_f32_16x16x32_bf16 v[120:123], v[136:139], v[162:165], v[120:123]
	v_mfma_f32_16x16x32_bf16 v[108:111], v[128:131], v[170:173], v[108:111]
	v_mfma_f32_16x16x32_bf16 v[104:107], v[136:139], v[170:173], v[104:107]
	v_mfma_f32_16x16x32_bf16 v[96:99], v[128:131], v[178:181], v[96:99]
	v_mfma_f32_16x16x32_bf16 v[88:91], v[136:139], v[178:181], v[88:91]
	v_mfma_f32_16x16x32_bf16 v[84:87], v[128:131], v[194:197], v[84:87]
	v_mfma_f32_16x16x32_bf16 v[80:83], v[136:139], v[194:197], v[80:83]
	v_mfma_f32_16x16x32_bf16 v[124:127], v[132:135], v[166:169], v[124:127]
	v_mfma_f32_16x16x32_bf16 v[120:123], v[146:149], v[166:169], v[120:123]
	v_mfma_f32_16x16x32_bf16 v[108:111], v[132:135], v[174:177], v[108:111]
	v_mfma_f32_16x16x32_bf16 v[104:107], v[146:149], v[174:177], v[104:107]
	v_mfma_f32_16x16x32_bf16 v[96:99], v[132:135], v[182:185], v[96:99]
	v_mfma_f32_16x16x32_bf16 v[88:91], v[146:149], v[182:185], v[88:91]
	v_mfma_f32_16x16x32_bf16 v[84:87], v[132:135], v[210:213], v[84:87]
	v_mfma_f32_16x16x32_bf16 v[80:83], v[146:149], v[210:213], v[80:83]
	v_mfma_f32_16x16x32_bf16 v[116:119], v[214:217], v[162:165], v[116:119]
	v_mfma_f32_16x16x32_bf16 v[112:115], v[222:225], v[162:165], v[112:115]
	v_mfma_f32_16x16x32_bf16 v[100:103], v[214:217], v[170:173], v[100:103]
	v_mfma_f32_16x16x32_bf16 v[92:95], v[222:225], v[170:173], v[92:95]
	v_mfma_f32_16x16x32_bf16 v[76:79], v[214:217], v[178:181], v[76:79]
	v_mfma_f32_16x16x32_bf16 v[72:75], v[222:225], v[178:181], v[72:75]
	v_mfma_f32_16x16x32_bf16 v[68:71], v[214:217], v[194:197], v[68:71]
	v_mfma_f32_16x16x32_bf16 v[64:67], v[222:225], v[194:197], v[64:67]
	v_mfma_f32_16x16x32_bf16 v[116:119], v[218:221], v[166:169], v[116:119]
	v_mfma_f32_16x16x32_bf16 v[112:115], v[226:229], v[166:169], v[112:115]
	v_mfma_f32_16x16x32_bf16 v[100:103], v[218:221], v[174:177], v[100:103]
	v_mfma_f32_16x16x32_bf16 v[92:95], v[226:229], v[174:177], v[92:95]
	v_mfma_f32_16x16x32_bf16 v[76:79], v[218:221], v[182:185], v[76:79]
	v_mfma_f32_16x16x32_bf16 v[72:75], v[226:229], v[182:185], v[72:75]
	v_mfma_f32_16x16x32_bf16 v[68:71], v[218:221], v[210:213], v[68:71]
	v_mfma_f32_16x16x32_bf16 v[64:67], v[226:229], v[210:213], v[64:67]
	s_barrier
	s_add_i32 s6, s6, s57
	v_lshl_add_u64 v[230:231], v[230:231], 0, s[36:37]
	s_mov_b32 m0, s6
	s_nop 0
	global_load_lds_dwordx4 v[230:231], off
	v_lshl_add_u64 v[230:231], v[232:233], 0, s[36:37]
	s_add_i32 m0, s6, 0x2000
	s_nop 0
	global_load_lds_dwordx4 v[230:231], off
	s_mov_b32 m0, s70
	v_lshl_add_u64 v[230:231], v[234:235], 0, s[36:37]
	ds_read_b128 v[162:165], v208 offset:49152
	ds_read_b128 v[166:169], v208 offset:50176
	ds_read_b128 v[170:173], v208 offset:51200
	ds_read_b128 v[174:177], v208 offset:52224
	ds_read_b128 v[178:181], v208 offset:53248
	ds_read_b128 v[182:185], v208 offset:54272
	ds_read_b128 v[194:197], v208 offset:55296
	ds_read_b128 v[210:213], v208 offset:56320
	global_load_lds_dwordx4 v[230:231], off
	v_lshl_add_u64 v[230:231], v[236:237], 0, s[36:37]
	s_mov_b32 m0, s71
	s_nop 0
	global_load_lds_dwordx4 v[230:231], off
	s_add_u32 s48, s48, 0xb0080
	s_addc_u32 s49, s49, 0
	s_add_i32 s6, s19, s57
	v_lshl_add_u64 v[250:251], s[48:49], 0, v[140:141]
	s_mov_b32 m0, s6
	s_nop 0
	global_load_lds_dwordx4 v[250:251], off
	v_lshl_add_u64 v[250:251], s[48:49], 0, v[150:151]
	s_add_i32 m0, s6, 0x2000
	s_nop 0
	global_load_lds_dwordx4 v[250:251], off
	s_add_i32 s12, s12, 2
	s_add_u32 s10, s10, 0x100
	s_addc_u32 s11, s11, 0
	s_cmp_gt_u32 s12, 41
	s_mov_b64 s[50:51], s[46:47]
	s_waitcnt vmcnt(8)
	s_waitcnt lgkmcnt(0)
	s_barrier
	v_mfma_f32_16x16x32_bf16 v[60:63], v[128:131], v[162:165], v[60:63]
	v_mfma_f32_16x16x32_bf16 v[56:59], v[136:139], v[162:165], v[56:59]
	v_mfma_f32_16x16x32_bf16 v[48:51], v[128:131], v[170:173], v[48:51]
	v_mfma_f32_16x16x32_bf16 v[40:43], v[136:139], v[170:173], v[40:43]
	v_mfma_f32_16x16x32_bf16 v[32:35], v[128:131], v[178:181], v[32:35]
	v_mfma_f32_16x16x32_bf16 v[24:27], v[136:139], v[178:181], v[24:27]
	v_mfma_f32_16x16x32_bf16 v[16:19], v[128:131], v[194:197], v[16:19]
	v_mfma_f32_16x16x32_bf16 v[8:11], v[136:139], v[194:197], v[8:11]
	v_mfma_f32_16x16x32_bf16 v[60:63], v[132:135], v[166:169], v[60:63]
	v_mfma_f32_16x16x32_bf16 v[56:59], v[146:149], v[166:169], v[56:59]
	v_mfma_f32_16x16x32_bf16 v[48:51], v[132:135], v[174:177], v[48:51]
	v_mfma_f32_16x16x32_bf16 v[40:43], v[146:149], v[174:177], v[40:43]
	v_mfma_f32_16x16x32_bf16 v[32:35], v[132:135], v[182:185], v[32:35]
	v_mfma_f32_16x16x32_bf16 v[24:27], v[146:149], v[182:185], v[24:27]
	v_mfma_f32_16x16x32_bf16 v[16:19], v[132:135], v[210:213], v[16:19]
	v_mfma_f32_16x16x32_bf16 v[8:11], v[146:149], v[210:213], v[8:11]
	v_mfma_f32_16x16x32_bf16 v[52:55], v[214:217], v[162:165], v[52:55]
	v_mfma_f32_16x16x32_bf16 v[44:47], v[222:225], v[162:165], v[44:47]
	v_mfma_f32_16x16x32_bf16 v[36:39], v[214:217], v[170:173], v[36:39]
	v_mfma_f32_16x16x32_bf16 v[28:31], v[222:225], v[170:173], v[28:31]
	v_mfma_f32_16x16x32_bf16 v[20:23], v[214:217], v[178:181], v[20:23]
	v_mfma_f32_16x16x32_bf16 v[12:15], v[222:225], v[178:181], v[12:15]
	v_mfma_f32_16x16x32_bf16 v[4:7], v[214:217], v[194:197], v[4:7]
	v_mfma_f32_16x16x32_bf16 v[0:3], v[222:225], v[194:197], v[0:3]
	v_mfma_f32_16x16x32_bf16 v[52:55], v[218:221], v[166:169], v[52:55]
	v_mfma_f32_16x16x32_bf16 v[44:47], v[226:229], v[166:169], v[44:47]
	v_mfma_f32_16x16x32_bf16 v[36:39], v[218:221], v[174:177], v[36:39]
	v_mfma_f32_16x16x32_bf16 v[28:31], v[226:229], v[174:177], v[28:31]
	v_mfma_f32_16x16x32_bf16 v[20:23], v[218:221], v[182:185], v[20:23]
	v_mfma_f32_16x16x32_bf16 v[12:15], v[226:229], v[182:185], v[12:15]
	v_mfma_f32_16x16x32_bf16 v[4:7], v[218:221], v[210:213], v[4:7]
	v_mfma_f32_16x16x32_bf16 v[0:3], v[226:229], v[210:213], v[0:3]
	s_barrier
.LBB0_341:
	s_add_u32 s46, s50, 0x100
	s_addc_u32 s47, s51, 0
	s_add_i32 s6, 0, 0x10000
	v_add_u32_e32 v146, s6, v206
	ds_read_b128 v[128:131], v146
	ds_read_b128 v[132:135], v146 offset:1024
	ds_read_b128 v[136:139], v146 offset:2048
	ds_read_b128 v[146:149], v146 offset:3072
	s_cmp_eq_u32 s12, 40
	s_cselect_b32 s53, s31, s47
	s_cselect_b32 s52, s30, s46
	s_cselect_b32 s49, s35, s11
	s_cselect_b32 s48, s34, s10
	v_lshl_add_u64 v[214:215], s[50:51], 0, v[158:159]
	s_add_i32 m0, s58, 0xc000
	ds_read_b128 v[162:165], v208
	ds_read_b128 v[166:169], v208 offset:1024
	ds_read_b128 v[170:173], v208 offset:2048
	ds_read_b128 v[174:177], v208 offset:3072
	ds_read_b128 v[178:181], v208 offset:4096
	ds_read_b128 v[182:185], v208 offset:5120
	ds_read_b128 v[194:197], v208 offset:6144
	ds_read_b128 v[210:213], v208 offset:7168
	global_load_lds_dwordx4 v[214:215], off
	v_lshl_add_u64 v[214:215], s[50:51], 0, v[160:161]
	s_add_i32 m0, s58, 0xe000
	s_nop 0
	global_load_lds_dwordx4 v[214:215], off
	s_add_i32 s19, 0, 0x14000
	v_add_u32_e32 v192, s19, v206
	ds_read_b128 v[214:217], v192
	ds_read_b128 v[218:221], v192 offset:1024
	ds_read_b128 v[222:225], v192 offset:2048
	ds_read_b128 v[226:229], v192 offset:3072
	s_waitcnt vmcnt(8)
	s_waitcnt lgkmcnt(0)
	s_barrier
	v_mfma_f32_16x16x32_bf16 v[124:127], v[128:131], v[162:165], v[124:127]
	v_mfma_f32_16x16x32_bf16 v[120:123], v[136:139], v[162:165], v[120:123]
	v_mfma_f32_16x16x32_bf16 v[108:111], v[128:131], v[170:173], v[108:111]
	v_mfma_f32_16x16x32_bf16 v[104:107], v[136:139], v[170:173], v[104:107]
	v_mfma_f32_16x16x32_bf16 v[96:99], v[128:131], v[178:181], v[96:99]
	v_mfma_f32_16x16x32_bf16 v[88:91], v[136:139], v[178:181], v[88:91]
	v_mfma_f32_16x16x32_bf16 v[84:87], v[128:131], v[194:197], v[84:87]
	v_mfma_f32_16x16x32_bf16 v[80:83], v[136:139], v[194:197], v[80:83]
	v_mfma_f32_16x16x32_bf16 v[124:127], v[132:135], v[166:169], v[124:127]
	v_mfma_f32_16x16x32_bf16 v[120:123], v[146:149], v[166:169], v[120:123]
	v_mfma_f32_16x16x32_bf16 v[108:111], v[132:135], v[174:177], v[108:111]
	v_mfma_f32_16x16x32_bf16 v[104:107], v[146:149], v[174:177], v[104:107]
	v_mfma_f32_16x16x32_bf16 v[96:99], v[132:135], v[182:185], v[96:99]
	v_mfma_f32_16x16x32_bf16 v[88:91], v[146:149], v[182:185], v[88:91]
	v_mfma_f32_16x16x32_bf16 v[84:87], v[132:135], v[210:213], v[84:87]
	v_mfma_f32_16x16x32_bf16 v[80:83], v[146:149], v[210:213], v[80:83]
	v_mfma_f32_16x16x32_bf16 v[116:119], v[214:217], v[162:165], v[116:119]
	v_mfma_f32_16x16x32_bf16 v[112:115], v[222:225], v[162:165], v[112:115]
	v_mfma_f32_16x16x32_bf16 v[100:103], v[214:217], v[170:173], v[100:103]
	v_mfma_f32_16x16x32_bf16 v[92:95], v[222:225], v[170:173], v[92:95]
	v_mfma_f32_16x16x32_bf16 v[76:79], v[214:217], v[178:181], v[76:79]
	v_mfma_f32_16x16x32_bf16 v[72:75], v[222:225], v[178:181], v[72:75]
	v_mfma_f32_16x16x32_bf16 v[68:71], v[214:217], v[194:197], v[68:71]
	v_mfma_f32_16x16x32_bf16 v[64:67], v[222:225], v[194:197], v[64:67]
	v_mfma_f32_16x16x32_bf16 v[116:119], v[218:221], v[166:169], v[116:119]
	v_mfma_f32_16x16x32_bf16 v[112:115], v[226:229], v[166:169], v[112:115]
	v_mfma_f32_16x16x32_bf16 v[100:103], v[218:221], v[174:177], v[100:103]
	v_mfma_f32_16x16x32_bf16 v[92:95], v[226:229], v[174:177], v[92:95]
	v_mfma_f32_16x16x32_bf16 v[76:79], v[218:221], v[182:185], v[76:79]
	v_mfma_f32_16x16x32_bf16 v[72:75], v[226:229], v[182:185], v[72:75]
	v_mfma_f32_16x16x32_bf16 v[68:71], v[218:221], v[210:213], v[68:71]
	v_mfma_f32_16x16x32_bf16 v[64:67], v[226:229], v[210:213], v[64:67]
	s_barrier
	s_add_i32 s6, s6, s57
	v_lshl_add_u64 v[230:231], s[48:49], 0, v[140:141]
	s_mov_b32 m0, s6
	s_nop 0
	global_load_lds_dwordx4 v[230:231], off
	v_lshl_add_u64 v[232:233], s[48:49], 0, v[150:151]
	s_add_i32 m0, s6, 0x2000
	s_nop 0
	global_load_lds_dwordx4 v[232:233], off
	s_mov_b32 m0, s58
	v_lshl_add_u64 v[234:235], s[52:53], 0, v[154:155]
	ds_read_b128 v[162:165], v208 offset:16384
	ds_read_b128 v[166:169], v208 offset:17408
	ds_read_b128 v[170:173], v208 offset:18432
	ds_read_b128 v[174:177], v208 offset:19456
	ds_read_b128 v[178:181], v208 offset:20480
	ds_read_b128 v[182:185], v208 offset:21504
	ds_read_b128 v[194:197], v208 offset:22528
	ds_read_b128 v[210:213], v208 offset:23552
	global_load_lds_dwordx4 v[234:235], off
	v_lshl_add_u64 v[236:237], s[52:53], 0, v[152:153]
	s_mov_b32 m0, s59
	s_nop 0
	global_load_lds_dwordx4 v[236:237], off
	s_add_u32 s50, s48, 0xb0000
	s_addc_u32 s51, s49, 0
	s_add_i32 s6, s19, s57
	v_lshl_add_u64 v[250:251], s[50:51], 0, v[140:141]
	s_mov_b32 m0, s6
	s_nop 0
	global_load_lds_dwordx4 v[250:251], off
	v_lshl_add_u64 v[250:251], s[50:51], 0, v[150:151]
	s_add_i32 m0, s6, 0x2000
	s_nop 0
	global_load_lds_dwordx4 v[250:251], off
	s_waitcnt vmcnt(8)
	s_waitcnt lgkmcnt(0)
	s_barrier
	v_mfma_f32_16x16x32_bf16 v[60:63], v[128:131], v[162:165], v[60:63]
	v_mfma_f32_16x16x32_bf16 v[56:59], v[136:139], v[162:165], v[56:59]
	v_mfma_f32_16x16x32_bf16 v[48:51], v[128:131], v[170:173], v[48:51]
	v_mfma_f32_16x16x32_bf16 v[40:43], v[136:139], v[170:173], v[40:43]
	v_mfma_f32_16x16x32_bf16 v[32:35], v[128:131], v[178:181], v[32:35]
	v_mfma_f32_16x16x32_bf16 v[24:27], v[136:139], v[178:181], v[24:27]
	v_mfma_f32_16x16x32_bf16 v[16:19], v[128:131], v[194:197], v[16:19]
	v_mfma_f32_16x16x32_bf16 v[8:11], v[136:139], v[194:197], v[8:11]
	v_mfma_f32_16x16x32_bf16 v[60:63], v[132:135], v[166:169], v[60:63]
	v_mfma_f32_16x16x32_bf16 v[56:59], v[146:149], v[166:169], v[56:59]
	v_mfma_f32_16x16x32_bf16 v[48:51], v[132:135], v[174:177], v[48:51]
	v_mfma_f32_16x16x32_bf16 v[40:43], v[146:149], v[174:177], v[40:43]
	v_mfma_f32_16x16x32_bf16 v[32:35], v[132:135], v[182:185], v[32:35]
	v_mfma_f32_16x16x32_bf16 v[24:27], v[146:149], v[182:185], v[24:27]
	v_mfma_f32_16x16x32_bf16 v[16:19], v[132:135], v[210:213], v[16:19]
	v_mfma_f32_16x16x32_bf16 v[8:11], v[146:149], v[210:213], v[8:11]
	v_mfma_f32_16x16x32_bf16 v[52:55], v[214:217], v[162:165], v[52:55]
	v_mfma_f32_16x16x32_bf16 v[44:47], v[222:225], v[162:165], v[44:47]
	v_mfma_f32_16x16x32_bf16 v[36:39], v[214:217], v[170:173], v[36:39]
	v_mfma_f32_16x16x32_bf16 v[28:31], v[222:225], v[170:173], v[28:31]
	v_mfma_f32_16x16x32_bf16 v[20:23], v[214:217], v[178:181], v[20:23]
	v_mfma_f32_16x16x32_bf16 v[12:15], v[222:225], v[178:181], v[12:15]
	v_mfma_f32_16x16x32_bf16 v[4:7], v[214:217], v[194:197], v[4:7]
	v_mfma_f32_16x16x32_bf16 v[0:3], v[222:225], v[194:197], v[0:3]
	v_mfma_f32_16x16x32_bf16 v[52:55], v[218:221], v[166:169], v[52:55]
	v_mfma_f32_16x16x32_bf16 v[44:47], v[226:229], v[166:169], v[44:47]
	v_mfma_f32_16x16x32_bf16 v[36:39], v[218:221], v[174:177], v[36:39]
	v_mfma_f32_16x16x32_bf16 v[28:31], v[226:229], v[174:177], v[28:31]
	v_mfma_f32_16x16x32_bf16 v[20:23], v[218:221], v[182:185], v[20:23]
	v_mfma_f32_16x16x32_bf16 v[12:15], v[226:229], v[182:185], v[12:15]
	v_mfma_f32_16x16x32_bf16 v[4:7], v[218:221], v[210:213], v[4:7]
	v_mfma_f32_16x16x32_bf16 v[0:3], v[226:229], v[210:213], v[0:3]
	s_barrier
	s_add_i32 s6, 0, 0x18000
	v_add_u32_e32 v146, s6, v206
	ds_read_b128 v[128:131], v146
	ds_read_b128 v[132:135], v146 offset:1024
	ds_read_b128 v[136:139], v146 offset:2048
	ds_read_b128 v[146:149], v146 offset:3072
	s_add_u32 s50, s52, 0xb0000
	s_addc_u32 s51, s53, 0
	s_mov_b32 m0, s68
	v_lshl_add_u64 v[214:215], s[50:51], 0, v[154:155]
	ds_read_b128 v[162:165], v208 offset:32768
	ds_read_b128 v[166:169], v208 offset:33792
	ds_read_b128 v[170:173], v208 offset:34816
	ds_read_b128 v[174:177], v208 offset:35840
	ds_read_b128 v[178:181], v208 offset:36864
	ds_read_b128 v[182:185], v208 offset:37888
	ds_read_b128 v[194:197], v208 offset:38912
	ds_read_b128 v[210:213], v208 offset:39936
	global_load_lds_dwordx4 v[214:215], off
	v_lshl_add_u64 v[214:215], s[50:51], 0, v[152:153]
	s_mov_b32 m0, s69
	s_nop 0
	global_load_lds_dwordx4 v[214:215], off
	s_add_i32 s19, 0, 0x1c000
	v_add_u32_e32 v192, s19, v206
	ds_read_b128 v[214:217], v192
	ds_read_b128 v[218:221], v192 offset:1024
	ds_read_b128 v[222:225], v192 offset:2048
	ds_read_b128 v[226:229], v192 offset:3072
	s_waitcnt vmcnt(8)
	s_waitcnt lgkmcnt(0)
	s_barrier
	v_mfma_f32_16x16x32_bf16 v[124:127], v[128:131], v[162:165], v[124:127]
	v_mfma_f32_16x16x32_bf16 v[120:123], v[136:139], v[162:165], v[120:123]
	v_mfma_f32_16x16x32_bf16 v[108:111], v[128:131], v[170:173], v[108:111]
	v_mfma_f32_16x16x32_bf16 v[104:107], v[136:139], v[170:173], v[104:107]
	v_mfma_f32_16x16x32_bf16 v[96:99], v[128:131], v[178:181], v[96:99]
	v_mfma_f32_16x16x32_bf16 v[88:91], v[136:139], v[178:181], v[88:91]
	v_mfma_f32_16x16x32_bf16 v[84:87], v[128:131], v[194:197], v[84:87]
	v_mfma_f32_16x16x32_bf16 v[80:83], v[136:139], v[194:197], v[80:83]
	v_mfma_f32_16x16x32_bf16 v[124:127], v[132:135], v[166:169], v[124:127]
	v_mfma_f32_16x16x32_bf16 v[120:123], v[146:149], v[166:169], v[120:123]
	v_mfma_f32_16x16x32_bf16 v[108:111], v[132:135], v[174:177], v[108:111]
	v_mfma_f32_16x16x32_bf16 v[104:107], v[146:149], v[174:177], v[104:107]
	v_mfma_f32_16x16x32_bf16 v[96:99], v[132:135], v[182:185], v[96:99]
	v_mfma_f32_16x16x32_bf16 v[88:91], v[146:149], v[182:185], v[88:91]
	v_mfma_f32_16x16x32_bf16 v[84:87], v[132:135], v[210:213], v[84:87]
	v_mfma_f32_16x16x32_bf16 v[80:83], v[146:149], v[210:213], v[80:83]
	v_mfma_f32_16x16x32_bf16 v[116:119], v[214:217], v[162:165], v[116:119]
	v_mfma_f32_16x16x32_bf16 v[112:115], v[222:225], v[162:165], v[112:115]
	v_mfma_f32_16x16x32_bf16 v[100:103], v[214:217], v[170:173], v[100:103]
	v_mfma_f32_16x16x32_bf16 v[92:95], v[222:225], v[170:173], v[92:95]
	v_mfma_f32_16x16x32_bf16 v[76:79], v[214:217], v[178:181], v[76:79]
	v_mfma_f32_16x16x32_bf16 v[72:75], v[222:225], v[178:181], v[72:75]
	v_mfma_f32_16x16x32_bf16 v[68:71], v[214:217], v[194:197], v[68:71]
	v_mfma_f32_16x16x32_bf16 v[64:67], v[222:225], v[194:197], v[64:67]
	v_mfma_f32_16x16x32_bf16 v[116:119], v[218:221], v[166:169], v[116:119]
	v_mfma_f32_16x16x32_bf16 v[112:115], v[226:229], v[166:169], v[112:115]
	v_mfma_f32_16x16x32_bf16 v[100:103], v[218:221], v[174:177], v[100:103]
	v_mfma_f32_16x16x32_bf16 v[92:95], v[226:229], v[174:177], v[92:95]
	v_mfma_f32_16x16x32_bf16 v[76:79], v[218:221], v[182:185], v[76:79]
	v_mfma_f32_16x16x32_bf16 v[72:75], v[226:229], v[182:185], v[72:75]
	v_mfma_f32_16x16x32_bf16 v[68:71], v[218:221], v[210:213], v[68:71]
	v_mfma_f32_16x16x32_bf16 v[64:67], v[226:229], v[210:213], v[64:67]
	s_barrier
	s_add_i32 s6, s6, s57
	v_lshl_add_u64 v[230:231], v[230:231], 0, s[36:37]
	s_mov_b32 m0, s6
	s_nop 0
	global_load_lds_dwordx4 v[230:231], off
	v_lshl_add_u64 v[230:231], v[232:233], 0, s[36:37]
	s_add_i32 m0, s6, 0x2000
	s_nop 0
	global_load_lds_dwordx4 v[230:231], off
	s_mov_b32 m0, s70
	v_lshl_add_u64 v[230:231], v[234:235], 0, s[36:37]
	ds_read_b128 v[162:165], v208 offset:49152
	ds_read_b128 v[166:169], v208 offset:50176
	ds_read_b128 v[170:173], v208 offset:51200
	ds_read_b128 v[174:177], v208 offset:52224
	ds_read_b128 v[178:181], v208 offset:53248
	ds_read_b128 v[182:185], v208 offset:54272
	ds_read_b128 v[194:197], v208 offset:55296
	ds_read_b128 v[210:213], v208 offset:56320
	global_load_lds_dwordx4 v[230:231], off
	v_lshl_add_u64 v[230:231], v[236:237], 0, s[36:37]
	s_mov_b32 m0, s71
	s_nop 0
	global_load_lds_dwordx4 v[230:231], off
	s_add_u32 s48, s48, 0xb0080
	s_addc_u32 s49, s49, 0
	s_add_i32 s6, s19, s57
	v_lshl_add_u64 v[250:251], s[48:49], 0, v[140:141]
	s_mov_b32 m0, s6
	s_nop 0
	global_load_lds_dwordx4 v[250:251], off
	v_lshl_add_u64 v[250:251], s[48:49], 0, v[150:151]
	s_add_i32 m0, s6, 0x2000
	s_nop 0
	global_load_lds_dwordx4 v[250:251], off
	s_add_i32 s12, s12, 2
	s_add_u32 s10, s10, 0x100
	s_addc_u32 s11, s11, 0
	s_cmp_gt_u32 s12, 41
	s_mov_b64 s[50:51], s[46:47]
	s_waitcnt vmcnt(8)
	s_waitcnt lgkmcnt(0)
	s_barrier
	v_mfma_f32_16x16x32_bf16 v[60:63], v[128:131], v[162:165], v[60:63]
	v_mfma_f32_16x16x32_bf16 v[56:59], v[136:139], v[162:165], v[56:59]
	v_mfma_f32_16x16x32_bf16 v[48:51], v[128:131], v[170:173], v[48:51]
	v_mfma_f32_16x16x32_bf16 v[40:43], v[136:139], v[170:173], v[40:43]
	v_mfma_f32_16x16x32_bf16 v[32:35], v[128:131], v[178:181], v[32:35]
	v_mfma_f32_16x16x32_bf16 v[24:27], v[136:139], v[178:181], v[24:27]
	v_mfma_f32_16x16x32_bf16 v[16:19], v[128:131], v[194:197], v[16:19]
	v_mfma_f32_16x16x32_bf16 v[8:11], v[136:139], v[194:197], v[8:11]
	v_mfma_f32_16x16x32_bf16 v[60:63], v[132:135], v[166:169], v[60:63]
	v_mfma_f32_16x16x32_bf16 v[56:59], v[146:149], v[166:169], v[56:59]
	v_mfma_f32_16x16x32_bf16 v[48:51], v[132:135], v[174:177], v[48:51]
	v_mfma_f32_16x16x32_bf16 v[40:43], v[146:149], v[174:177], v[40:43]
	v_mfma_f32_16x16x32_bf16 v[32:35], v[132:135], v[182:185], v[32:35]
	v_mfma_f32_16x16x32_bf16 v[24:27], v[146:149], v[182:185], v[24:27]
	v_mfma_f32_16x16x32_bf16 v[16:19], v[132:135], v[210:213], v[16:19]
	v_mfma_f32_16x16x32_bf16 v[8:11], v[146:149], v[210:213], v[8:11]
	v_mfma_f32_16x16x32_bf16 v[52:55], v[214:217], v[162:165], v[52:55]
	v_mfma_f32_16x16x32_bf16 v[44:47], v[222:225], v[162:165], v[44:47]
	v_mfma_f32_16x16x32_bf16 v[36:39], v[214:217], v[170:173], v[36:39]
	v_mfma_f32_16x16x32_bf16 v[28:31], v[222:225], v[170:173], v[28:31]
	v_mfma_f32_16x16x32_bf16 v[20:23], v[214:217], v[178:181], v[20:23]
	v_mfma_f32_16x16x32_bf16 v[12:15], v[222:225], v[178:181], v[12:15]
	v_mfma_f32_16x16x32_bf16 v[4:7], v[214:217], v[194:197], v[4:7]
	v_mfma_f32_16x16x32_bf16 v[0:3], v[222:225], v[194:197], v[0:3]
	v_mfma_f32_16x16x32_bf16 v[52:55], v[218:221], v[166:169], v[52:55]
	v_mfma_f32_16x16x32_bf16 v[44:47], v[226:229], v[166:169], v[44:47]
	v_mfma_f32_16x16x32_bf16 v[36:39], v[218:221], v[174:177], v[36:39]
	v_mfma_f32_16x16x32_bf16 v[28:31], v[226:229], v[174:177], v[28:31]
	v_mfma_f32_16x16x32_bf16 v[20:23], v[218:221], v[182:185], v[20:23]
	v_mfma_f32_16x16x32_bf16 v[12:15], v[226:229], v[182:185], v[12:15]
	v_mfma_f32_16x16x32_bf16 v[4:7], v[218:221], v[210:213], v[4:7]
	v_mfma_f32_16x16x32_bf16 v[0:3], v[226:229], v[210:213], v[0:3]
	s_barrier
	s_cbranch_scc0 .LBB0_341
	s_mov_b32 s100, 1
	s_ashr_i32 s39, s38, 31
	v_lshl_or_b32 v128, s81, 8, v207
	s_lshl_b64 s[10:11], s[38:39], 8
	v_ashrrev_i32_e32 v129, 31, v128
	v_lshl_add_u64 v[168:169], s[10:11], 0, v[156:157]
	v_lshlrev_b64 v[170:171], 1, v[128:129]
	v_lshl_add_u64 v[174:175], s[26:27], 0, v[170:171]
	v_lshlrev_b64 v[172:173], 11, v[168:169]
	v_lshl_add_u64 v[128:129], v[174:175], 0, v[172:173]
	global_load_dwordx4 v[182:185], v[128:129], off
	global_load_dwordx4 v[210:213], v[128:129], off offset:256
	v_or_b32_e32 v166, 16, v168
	v_mov_b32_e32 v167, v169
	v_lshlrev_b64 v[176:177], 11, v[166:167]
	v_lshl_add_u64 v[128:129], v[174:175], 0, v[176:177]
	global_load_dwordx4 v[214:217], v[128:129], off
	global_load_dwordx4 v[218:221], v[128:129], off offset:256
	v_or_b32_e32 v164, 32, v168
	v_mov_b32_e32 v165, v169
	v_or_b32_e32 v162, 48, v168
	v_mov_b32_e32 v163, v169
	v_lshlrev_b64 v[180:181], 11, v[164:165]
	v_lshlrev_b64 v[178:179], 11, v[162:163]
	v_lshl_add_u64 v[128:129], v[174:175], 0, v[180:181]
	v_lshl_add_u64 v[130:131], v[174:175], 0, v[178:179]
	global_load_dwordx4 v[222:225], v[128:129], off
	global_load_dwordx4 v[136:139], v[128:129], off offset:256
	global_load_dwordx4 v[132:135], v[130:131], off
	s_nop 0
	global_load_dwordx4 v[128:131], v[130:131], off offset:256
	s_mov_b64 s[10:11], 0x90
	v_lshl_add_u64 v[172:173], s[28:29], 0, v[172:173]
	v_lshl_add_u64 v[172:173], v[172:173], 0, v[170:171]
	s_waitcnt vmcnt(0)
	v_lshlrev_b32_e32 v146, 16, v182
	v_and_b32_e32 v147, 0xffff0000, v182
	v_lshlrev_b32_e32 v148, 16, v184
	v_and_b32_e32 v149, 0xffff0000, v184
	v_lshlrev_b32_e32 v182, 16, v183
	v_and_b32_e32 v183, 0xffff0000, v183
	v_lshlrev_b32_e32 v194, 16, v210
	v_and_b32_e32 v195, 0xffff0000, v210
	v_lshlrev_b32_e32 v196, 16, v212
	v_and_b32_e32 v197, 0xffff0000, v212
	v_lshlrev_b32_e32 v210, 16, v211
	v_and_b32_e32 v211, 0xffff0000, v211
	v_lshlrev_b32_e32 v212, 16, v213
	v_and_b32_e32 v213, 0xffff0000, v213
	v_pk_fma_f32 v[124:125], v[124:125], 0.5, v[146:147] op_sel_hi:[1,0,1]
	v_pk_fma_f32 v[120:121], v[120:121], 0.5, v[148:149] op_sel_hi:[1,0,1]
	v_pk_fma_f32 v[126:127], v[126:127], 0.5, v[182:183] op_sel_hi:[1,0,1]
	v_pk_fma_f32 v[116:117], v[116:117], 0.5, v[194:195] op_sel_hi:[1,0,1]
	v_pk_fma_f32 v[146:147], v[112:113], 0.5, v[196:197] op_sel_hi:[1,0,1]
	v_pk_fma_f32 v[118:119], v[118:119], 0.5, v[210:211] op_sel_hi:[1,0,1]
	v_pk_fma_f32 v[148:149], v[114:115], 0.5, v[212:213] op_sel_hi:[1,0,1]
	v_pk_mul_f32 v[212:213], v[124:125], v[124:125]
	v_lshlrev_b32_e32 v182, 16, v214
	v_and_b32_e32 v183, 0xffff0000, v214
	v_lshlrev_b32_e32 v194, 16, v215
	v_and_b32_e32 v195, 0xffff0000, v215
	v_pk_mul_f32 v[214:215], v[126:127], v[126:127]
	v_cvt_pk_bf16_f32 v112, v124, v125
	v_cvt_pk_bf16_f32 v113, v126, v127
	v_pk_mul_f32 v[124:125], v[116:117], v[116:117]
	v_pk_mul_f32 v[126:127], v[118:119], v[118:119]
	v_pk_mul_f32 v[228:229], v[146:147], v[146:147]
	v_cvt_pk_bf16_f32 v116, v116, v117
	v_cvt_pk_bf16_f32 v117, v118, v119
	v_cvt_pk_bf16_f32 v118, v146, v147
	v_add_f32_e32 v146, v212, v213
	v_lshlrev_b32_e32 v184, 16, v185
	v_and_b32_e32 v185, 0xffff0000, v185
	v_add_f32_e32 v146, v214, v146
	v_pk_fma_f32 v[122:123], v[122:123], 0.5, v[184:185] op_sel_hi:[1,0,1]
	v_lshlrev_b32_e32 v184, 16, v216
	v_and_b32_e32 v185, 0xffff0000, v216
	v_lshlrev_b32_e32 v196, 16, v217
	v_and_b32_e32 v197, 0xffff0000, v217
	v_pk_mul_f32 v[216:217], v[120:121], v[120:121]
	v_add_f32_e32 v146, v215, v146
	v_add_f32_e32 v146, v216, v146
	v_pk_mul_f32 v[226:227], v[122:123], v[122:123]
	v_add_f32_e32 v146, v217, v146
	v_add_f32_e32 v146, v226, v146
	v_add_f32_e32 v146, v227, v146
	v_add_f32_e32 v124, v124, v146
	v_add_f32_e32 v124, v125, v124
	v_add_f32_e32 v124, v126, v124
	v_add_f32_e32 v124, v127, v124
	v_add_f32_e32 v124, v228, v124
	v_pk_mul_f32 v[230:231], v[148:149], v[148:149]
	v_add_f32_e32 v124, v229, v124
	v_add_f32_e32 v124, v230, v124
	v_add_f32_e32 v209, v231, v124
	v_lshlrev_b32_e32 v124, 16, v220
	v_and_b32_e32 v125, 0xffff0000, v220
	v_pk_fma_f32 v[124:125], v[92:93], 0.5, v[124:125] op_sel_hi:[1,0,1]
	v_lshlrev_b32_e32 v92, 16, v219
	v_and_b32_e32 v93, 0xffff0000, v219
	v_pk_fma_f32 v[102:103], v[102:103], 0.5, v[92:93] op_sel_hi:[1,0,1]
	v_lshlrev_b32_e32 v92, 16, v221
	v_and_b32_e32 v93, 0xffff0000, v221
	v_pk_fma_f32 v[126:127], v[94:95], 0.5, v[92:93] op_sel_hi:[1,0,1]
	v_lshlrev_b32_e32 v92, 16, v222
	v_and_b32_e32 v93, 0xffff0000, v222
	v_pk_fma_f32 v[92:93], v[96:97], 0.5, v[92:93] op_sel_hi:[1,0,1]
	v_lshlrev_b32_e32 v96, 16, v225
	v_and_b32_e32 v97, 0xffff0000, v225
	v_lshlrev_b32_e32 v94, 16, v224
	v_and_b32_e32 v95, 0xffff0000, v224
	v_pk_fma_f32 v[90:91], v[90:91], 0.5, v[96:97] op_sel_hi:[1,0,1]
	v_lshlrev_b32_e32 v96, 16, v136
	v_and_b32_e32 v97, 0xffff0000, v136
	v_pk_fma_f32 v[88:89], v[88:89], 0.5, v[94:95] op_sel_hi:[1,0,1]
	v_lshlrev_b32_e32 v94, 16, v223
	v_and_b32_e32 v95, 0xffff0000, v223
	v_pk_fma_f32 v[96:97], v[76:77], 0.5, v[96:97] op_sel_hi:[1,0,1]
	v_lshl_add_u64 v[76:77], v[168:169], 0, s[36:37]
	v_cvt_pk_bf16_f32 v114, v120, v121
	v_pk_fma_f32 v[120:121], v[108:109], 0.5, v[182:183] op_sel_hi:[1,0,1]
	v_pk_fma_f32 v[94:95], v[98:99], 0.5, v[94:95] op_sel_hi:[1,0,1]
	v_lshlrev_b64 v[182:183], 11, v[76:77]
	v_lshlrev_b32_e32 v98, 16, v138
	v_and_b32_e32 v99, 0xffff0000, v138
	v_lshl_add_u64 v[146:147], v[174:175], 0, v[182:183]
	v_pk_fma_f32 v[98:99], v[72:73], 0.5, v[98:99] op_sel_hi:[1,0,1]
	v_lshlrev_b32_e32 v72, 16, v137
	v_and_b32_e32 v73, 0xffff0000, v137
	v_lshlrev_b32_e32 v210, 16, v218
	v_and_b32_e32 v211, 0xffff0000, v218
	global_load_dwordx4 v[218:221], v[146:147], off
	global_load_dwordx4 v[226:229], v[146:147], off offset:256
	v_pk_fma_f32 v[136:137], v[78:79], 0.5, v[72:73] op_sel_hi:[1,0,1]
	v_lshlrev_b32_e32 v72, 16, v139
	v_and_b32_e32 v73, 0xffff0000, v139
	v_pk_fma_f32 v[138:139], v[74:75], 0.5, v[72:73] op_sel_hi:[1,0,1]
	v_lshlrev_b32_e32 v72, 16, v132
	v_and_b32_e32 v73, 0xffff0000, v132
	v_pk_fma_f32 v[74:75], v[84:85], 0.5, v[72:73] op_sel_hi:[1,0,1]
	v_lshlrev_b32_e32 v72, 16, v134
	v_and_b32_e32 v73, 0xffff0000, v134
	v_pk_fma_f32 v[78:79], v[80:81], 0.5, v[72:73] op_sel_hi:[1,0,1]
	v_lshlrev_b32_e32 v72, 16, v133
	v_and_b32_e32 v73, 0xffff0000, v133
	v_pk_fma_f32 v[80:81], v[86:87], 0.5, v[72:73] op_sel_hi:[1,0,1]
	v_lshlrev_b32_e32 v72, 16, v135
	v_and_b32_e32 v73, 0xffff0000, v135
	v_pk_fma_f32 v[82:83], v[82:83], 0.5, v[72:73] op_sel_hi:[1,0,1]
	v_lshl_add_u64 v[72:73], v[168:169], 0, s[10:11]
	v_lshlrev_b64 v[132:133], 11, v[72:73]
	v_lshl_add_u64 v[134:135], v[174:175], 0, v[132:133]
	global_load_dwordx4 v[234:237], v[134:135], off
	global_load_dwordx4 v[242:245], v[134:135], off offset:256
	v_lshlrev_b32_e32 v84, 16, v128
	v_and_b32_e32 v85, 0xffff0000, v128
	v_pk_fma_f32 v[84:85], v[68:69], 0.5, v[84:85] op_sel_hi:[1,0,1]
	v_lshlrev_b32_e32 v68, 16, v130
	v_and_b32_e32 v69, 0xffff0000, v130
	v_pk_fma_f32 v[86:87], v[64:65], 0.5, v[68:69] op_sel_hi:[1,0,1]
	v_lshlrev_b32_e32 v64, 16, v129
	v_and_b32_e32 v65, 0xffff0000, v129
	s_mov_b64 s[10:11], 0xa0
	v_pk_fma_f32 v[128:129], v[70:71], 0.5, v[64:65] op_sel_hi:[1,0,1]
	v_lshl_add_u64 v[70:71], v[168:169], 0, s[10:11]
	v_lshlrev_b32_e32 v64, 16, v131
	v_and_b32_e32 v65, 0xffff0000, v131
	v_lshlrev_b64 v[134:135], 11, v[70:71]
	v_pk_fma_f32 v[130:131], v[66:67], 0.5, v[64:65] op_sel_hi:[1,0,1]
	v_lshl_add_u64 v[64:65], v[174:175], 0, v[134:135]
	v_cvt_pk_bf16_f32 v115, v122, v123
	v_pk_fma_f32 v[122:123], v[110:111], 0.5, v[194:195] op_sel_hi:[1,0,1]
	v_pk_fma_f32 v[110:111], v[106:107], 0.5, v[196:197] op_sel_hi:[1,0,1]
	global_load_dwordx4 v[246:249], v[64:65], off
	global_load_dwordx4 v[194:197], v[64:65], off offset:256
	s_mov_b64 s[10:11], 0xb0
	v_lshl_add_u64 v[68:69], v[168:169], 0, s[10:11]
	v_pk_fma_f32 v[108:109], v[104:105], 0.5, v[184:185] op_sel_hi:[1,0,1]
	v_lshlrev_b64 v[184:185], 11, v[68:69]
	v_lshl_add_u64 v[64:65], v[174:175], 0, v[184:185]
	v_cvt_pk_bf16_f32 v119, v148, v149
	global_load_dwordx4 v[146:149], v[64:65], off
	s_nop 0
	global_load_dwordx4 v[64:67], v[64:65], off offset:256
	global_store_dwordx4 v[172:173], v[112:115], off
	global_store_dwordx4 v[172:173], v[116:119], off offset:256
	v_cvt_pk_bf16_f32 v104, v120, v121
	v_lshl_add_u64 v[112:113], s[28:29], 0, v[176:177]
	v_cvt_pk_bf16_f32 v105, v122, v123
	v_cvt_pk_bf16_f32 v106, v108, v109
	v_cvt_pk_bf16_f32 v107, v110, v111
	v_pk_fma_f32 v[100:101], v[100:101], 0.5, v[210:211] op_sel_hi:[1,0,1]
	v_lshl_add_u64 v[112:113], v[112:113], 0, v[170:171]
	v_cvt_pk_bf16_f32 v210, v100, v101
	v_cvt_pk_bf16_f32 v211, v102, v103
	v_cvt_pk_bf16_f32 v212, v124, v125
	v_cvt_pk_bf16_f32 v213, v126, v127
	global_store_dwordx4 v[112:113], v[104:107], off
	global_store_dwordx4 v[112:113], v[210:213], off offset:256
	v_cvt_pk_bf16_f32 v214, v92, v93
	v_lshl_add_u64 v[104:105], s[28:29], 0, v[180:181]
	v_cvt_pk_bf16_f32 v215, v94, v95
	v_cvt_pk_bf16_f32 v216, v88, v89
	v_cvt_pk_bf16_f32 v217, v90, v91
	v_lshl_add_u64 v[104:105], v[104:105], 0, v[170:171]
	v_cvt_pk_bf16_f32 v222, v96, v97
	v_cvt_pk_bf16_f32 v223, v136, v137
	v_cvt_pk_bf16_f32 v224, v98, v99
	v_cvt_pk_bf16_f32 v225, v138, v139
	global_store_dwordx4 v[104:105], v[214:217], off
	global_store_dwordx4 v[104:105], v[222:225], off offset:256
	v_lshl_add_u64 v[104:105], s[28:29], 0, v[178:179]
	v_cvt_pk_bf16_f32 v230, v74, v75
	v_cvt_pk_bf16_f32 v231, v80, v81
	v_cvt_pk_bf16_f32 v232, v78, v79
	v_cvt_pk_bf16_f32 v233, v82, v83
	v_lshl_add_u64 v[104:105], v[104:105], 0, v[170:171]
	v_cvt_pk_bf16_f32 v238, v84, v85
	v_cvt_pk_bf16_f32 v239, v128, v129
	v_cvt_pk_bf16_f32 v240, v86, v87
	v_cvt_pk_bf16_f32 v241, v130, v131
	global_store_dwordx4 v[104:105], v[230:233], off
	global_store_dwordx4 v[104:105], v[238:241], off offset:256
	s_waitcnt vmcnt(8)
	v_lshlrev_b32_e32 v104, 16, v218
	v_and_b32_e32 v105, 0xffff0000, v218
	v_pk_fma_f32 v[60:61], v[60:61], 0.5, v[104:105] op_sel_hi:[1,0,1]
	v_lshlrev_b32_e32 v104, 16, v220
	v_and_b32_e32 v105, 0xffff0000, v220
	v_pk_fma_f32 v[56:57], v[56:57], 0.5, v[104:105] op_sel_hi:[1,0,1]
	v_lshlrev_b32_e32 v104, 16, v219
	v_and_b32_e32 v105, 0xffff0000, v219
	v_pk_fma_f32 v[62:63], v[62:63], 0.5, v[104:105] op_sel_hi:[1,0,1]
	v_lshlrev_b32_e32 v104, 16, v221
	v_and_b32_e32 v105, 0xffff0000, v221
	v_pk_fma_f32 v[58:59], v[58:59], 0.5, v[104:105] op_sel_hi:[1,0,1]
	v_lshlrev_b32_e32 v104, 16, v226
	v_and_b32_e32 v105, 0xffff0000, v226
	v_pk_fma_f32 v[52:53], v[52:53], 0.5, v[104:105] op_sel_hi:[1,0,1]
	v_lshlrev_b32_e32 v104, 16, v228
	v_and_b32_e32 v105, 0xffff0000, v228
	v_pk_fma_f32 v[104:105], v[44:45], 0.5, v[104:105] op_sel_hi:[1,0,1]
	v_lshlrev_b32_e32 v44, 16, v227
	v_and_b32_e32 v45, 0xffff0000, v227
	v_pk_fma_f32 v[54:55], v[54:55], 0.5, v[44:45] op_sel_hi:[1,0,1]
	v_lshlrev_b32_e32 v44, 16, v229
	v_and_b32_e32 v45, 0xffff0000, v229
	v_pk_fma_f32 v[106:107], v[46:47], 0.5, v[44:45] op_sel_hi:[1,0,1]
	v_lshlrev_b32_e32 v44, 16, v234
	v_and_b32_e32 v45, 0xffff0000, v234
	v_pk_fma_f32 v[44:45], v[48:49], 0.5, v[44:45] op_sel_hi:[1,0,1]
	v_lshlrev_b32_e32 v48, 16, v237
	v_and_b32_e32 v49, 0xffff0000, v237
	v_pk_fma_f32 v[42:43], v[42:43], 0.5, v[48:49] op_sel_hi:[1,0,1]
	v_lshlrev_b32_e32 v48, 16, v242
	v_and_b32_e32 v49, 0xffff0000, v242
	v_pk_fma_f32 v[36:37], v[36:37], 0.5, v[48:49] op_sel_hi:[1,0,1]
	v_lshlrev_b32_e32 v48, 16, v244
	v_and_b32_e32 v49, 0xffff0000, v244
	v_lshlrev_b32_e32 v46, 16, v236
	v_and_b32_e32 v47, 0xffff0000, v236
	v_pk_fma_f32 v[48:49], v[28:29], 0.5, v[48:49] op_sel_hi:[1,0,1]
	v_lshlrev_b32_e32 v28, 16, v243
	v_and_b32_e32 v29, 0xffff0000, v243
	v_pk_fma_f32 v[40:41], v[40:41], 0.5, v[46:47] op_sel_hi:[1,0,1]
	v_lshlrev_b32_e32 v46, 16, v235
	v_and_b32_e32 v47, 0xffff0000, v235
	v_pk_fma_f32 v[38:39], v[38:39], 0.5, v[28:29] op_sel_hi:[1,0,1]
	v_lshlrev_b32_e32 v28, 16, v245
	v_and_b32_e32 v29, 0xffff0000, v245
	v_pk_fma_f32 v[46:47], v[50:51], 0.5, v[46:47] op_sel_hi:[1,0,1]
	v_pk_fma_f32 v[50:51], v[30:31], 0.5, v[28:29] op_sel_hi:[1,0,1]
	v_lshlrev_b32_e32 v28, 16, v246
	v_and_b32_e32 v29, 0xffff0000, v246
	v_pk_fma_f32 v[28:29], v[32:33], 0.5, v[28:29] op_sel_hi:[1,0,1]
	v_lshlrev_b32_e32 v32, 16, v249
	v_and_b32_e32 v33, 0xffff0000, v249
	v_pk_fma_f32 v[26:27], v[26:27], 0.5, v[32:33] op_sel_hi:[1,0,1]
	v_lshlrev_b32_e32 v32, 16, v194
	v_and_b32_e32 v33, 0xffff0000, v194
	v_pk_fma_f32 v[20:21], v[20:21], 0.5, v[32:33] op_sel_hi:[1,0,1]
	v_lshlrev_b32_e32 v32, 16, v196
	v_and_b32_e32 v33, 0xffff0000, v196
	v_lshlrev_b32_e32 v30, 16, v248
	v_and_b32_e32 v31, 0xffff0000, v248
	v_pk_fma_f32 v[32:33], v[12:13], 0.5, v[32:33] op_sel_hi:[1,0,1]
	v_lshlrev_b32_e32 v12, 16, v195
	v_and_b32_e32 v13, 0xffff0000, v195
	v_pk_fma_f32 v[24:25], v[24:25], 0.5, v[30:31] op_sel_hi:[1,0,1]
	v_lshlrev_b32_e32 v30, 16, v247
	v_and_b32_e32 v31, 0xffff0000, v247
	v_pk_fma_f32 v[22:23], v[22:23], 0.5, v[12:13] op_sel_hi:[1,0,1]
	v_lshlrev_b32_e32 v12, 16, v197
	v_and_b32_e32 v13, 0xffff0000, v197
	v_pk_fma_f32 v[30:31], v[34:35], 0.5, v[30:31] op_sel_hi:[1,0,1]
	v_pk_fma_f32 v[34:35], v[14:15], 0.5, v[12:13] op_sel_hi:[1,0,1]
	v_lshlrev_b32_e32 v14, 16, v148
	v_and_b32_e32 v15, 0xffff0000, v148
	v_lshlrev_b32_e32 v12, 16, v146
	v_and_b32_e32 v13, 0xffff0000, v146
	v_pk_fma_f32 v[8:9], v[8:9], 0.5, v[14:15] op_sel_hi:[1,0,1]
	v_lshlrev_b32_e32 v14, 16, v147
	v_and_b32_e32 v15, 0xffff0000, v147
	v_lshlrev_b32_e32 v146, 16, v64
	v_and_b32_e32 v147, 0xffff0000, v64
	v_pk_fma_f32 v[4:5], v[4:5], 0.5, v[146:147] op_sel_hi:[1,0,1]
	v_lshlrev_b32_e32 v146, 16, v66
	v_and_b32_e32 v147, 0xffff0000, v66
	v_pk_fma_f32 v[0:1], v[0:1], 0.5, v[146:147] op_sel_hi:[1,0,1]
	v_lshl_add_u64 v[146:147], s[28:29], 0, v[182:183]
	v_cvt_pk_bf16_f32 v112, v60, v61
	v_cvt_pk_bf16_f32 v113, v62, v63
	v_cvt_pk_bf16_f32 v114, v56, v57
	v_cvt_pk_bf16_f32 v115, v58, v59
	v_lshl_add_u64 v[146:147], v[146:147], 0, v[170:171]
	v_cvt_pk_bf16_f32 v116, v52, v53
	v_cvt_pk_bf16_f32 v117, v54, v55
	v_cvt_pk_bf16_f32 v118, v104, v105
	v_cvt_pk_bf16_f32 v119, v106, v107
	global_store_dwordx4 v[146:147], v[112:115], off
	global_store_dwordx4 v[146:147], v[116:119], off offset:256
	v_cvt_pk_bf16_f32 v172, v44, v45
	v_lshl_add_u64 v[112:113], s[28:29], 0, v[132:133]
	v_cvt_pk_bf16_f32 v173, v46, v47
	v_cvt_pk_bf16_f32 v174, v40, v41
	v_cvt_pk_bf16_f32 v175, v42, v43
	v_lshl_add_u64 v[112:113], v[112:113], 0, v[170:171]
	v_cvt_pk_bf16_f32 v176, v36, v37
	v_cvt_pk_bf16_f32 v177, v38, v39
	v_cvt_pk_bf16_f32 v178, v48, v49
	v_cvt_pk_bf16_f32 v179, v50, v51
	global_store_dwordx4 v[112:113], v[172:175], off
	global_store_dwordx4 v[112:113], v[176:179], off offset:256
	v_lshl_add_u64 v[112:113], s[28:29], 0, v[134:135]
	v_cvt_pk_bf16_f32 v210, v28, v29
	v_cvt_pk_bf16_f32 v211, v30, v31
	v_cvt_pk_bf16_f32 v212, v24, v25
	v_cvt_pk_bf16_f32 v213, v26, v27
	v_pk_fma_f32 v[12:13], v[16:17], 0.5, v[12:13] op_sel_hi:[1,0,1]
	v_lshlrev_b32_e32 v16, 16, v149
	v_and_b32_e32 v17, 0xffff0000, v149
	v_lshlrev_b32_e32 v64, 16, v65
	v_and_b32_e32 v65, 0xffff0000, v65
	v_lshl_add_u64 v[112:113], v[112:113], 0, v[170:171]
	v_cvt_pk_bf16_f32 v194, v20, v21
	v_cvt_pk_bf16_f32 v195, v22, v23
	v_cvt_pk_bf16_f32 v196, v32, v33
	v_cvt_pk_bf16_f32 v197, v34, v35
	v_pk_fma_f32 v[14:15], v[18:19], 0.5, v[14:15] op_sel_hi:[1,0,1]
	v_pk_fma_f32 v[10:11], v[10:11], 0.5, v[16:17] op_sel_hi:[1,0,1]
	v_pk_fma_f32 v[6:7], v[6:7], 0.5, v[64:65] op_sel_hi:[1,0,1]
	v_lshlrev_b32_e32 v64, 16, v67
	v_and_b32_e32 v65, 0xffff0000, v67
	global_store_dwordx4 v[112:113], v[210:213], off
	global_store_dwordx4 v[112:113], v[194:197], off offset:256
	v_lshl_add_u64 v[112:113], s[28:29], 0, v[184:185]
	v_cvt_pk_bf16_f32 v16, v12, v13
	v_cvt_pk_bf16_f32 v17, v14, v15
	v_cvt_pk_bf16_f32 v18, v8, v9
	v_cvt_pk_bf16_f32 v19, v10, v11
	v_pk_fma_f32 v[2:3], v[2:3], 0.5, v[64:65] op_sel_hi:[1,0,1]
	v_lshl_add_u64 v[112:113], v[112:113], 0, v[170:171]
	v_cvt_pk_bf16_f32 v64, v4, v5
	v_cvt_pk_bf16_f32 v65, v6, v7
	v_cvt_pk_bf16_f32 v66, v0, v1
	v_cvt_pk_bf16_f32 v67, v2, v3
	global_store_dwordx4 v[112:113], v[16:19], off
	global_store_dwordx4 v[112:113], v[64:67], off offset:256
	s_lshl_b32 s10, s81, 2
	v_and_b32_e32 v17, 64, v188
	v_xor_b32_e32 v16, 16, v188
	v_add_u32_e32 v17, 64, v17
	v_cmp_lt_i32_e32 vcc, v16, v17
	v_xor_b32_e32 v18, 32, v188
	s_ashr_i32 s11, s10, 31
	v_cndmask_b32_e32 v16, v188, v16, vcc
	v_lshlrev_b32_e32 v16, 2, v16
	v_mov_b32_e32 v132, v209
	v_cmp_lt_i32_e32 vcc, v18, v17
	s_lshl_b64 s[10:11], s[10:11], 2
	s_add_u32 s38, s73, s10
	v_cndmask_b32_e32 v17, v188, v18, vcc
	v_lshlrev_b32_e32 v17, 2, v17
	s_addc_u32 s39, s74, s11
	v_pk_mul_f32 v[18:19], v[120:121], v[120:121]
	v_pk_mul_f32 v[64:65], v[122:123], v[122:123]
	v_add_f32_e32 v18, v18, v19
	v_add_f32_e32 v18, v64, v18
	v_pk_mul_f32 v[66:67], v[108:109], v[108:109]
	v_add_f32_e32 v18, v65, v18
	v_add_f32_e32 v18, v66, v18
	v_pk_mul_f32 v[108:109], v[110:111], v[110:111]
	v_add_f32_e32 v18, v67, v18
	v_add_f32_e32 v18, v108, v18
	v_pk_mul_f32 v[100:101], v[100:101], v[100:101]
	v_add_f32_e32 v18, v109, v18
	v_add_f32_e32 v18, v100, v18
	v_pk_mul_f32 v[102:103], v[102:103], v[102:103]
	v_add_f32_e32 v18, v101, v18
	v_add_f32_e32 v18, v102, v18
	v_pk_mul_f32 v[110:111], v[124:125], v[124:125]
	v_add_f32_e32 v18, v103, v18
	v_add_f32_e32 v18, v110, v18
	v_pk_mul_f32 v[112:113], v[126:127], v[126:127]
	v_add_f32_e32 v18, v111, v18
	v_add_f32_e32 v18, v112, v18
	v_add_f32_e32 v18, v113, v18
	v_mov_b32_e32 v133, v18
	v_pk_mul_f32 v[18:19], v[92:93], v[92:93]
	v_pk_mul_f32 v[64:65], v[94:95], v[94:95]
	v_add_f32_e32 v18, v18, v19
	v_add_f32_e32 v18, v64, v18
	v_pk_mul_f32 v[66:67], v[88:89], v[88:89]
	v_add_f32_e32 v18, v65, v18
	v_add_f32_e32 v18, v66, v18
	v_pk_mul_f32 v[88:89], v[90:91], v[90:91]
	v_add_f32_e32 v18, v67, v18
	v_add_f32_e32 v18, v88, v18
	v_pk_mul_f32 v[90:91], v[96:97], v[96:97]
	v_add_f32_e32 v18, v89, v18
	v_add_f32_e32 v18, v90, v18
	v_pk_mul_f32 v[92:93], v[136:137], v[136:137]
	v_add_f32_e32 v18, v91, v18
	v_add_f32_e32 v18, v92, v18
	v_pk_mul_f32 v[94:95], v[98:99], v[98:99]
	v_add_f32_e32 v18, v93, v18
	v_add_f32_e32 v18, v94, v18
	v_pk_mul_f32 v[96:97], v[138:139], v[138:139]
	v_add_f32_e32 v18, v95, v18
	v_add_f32_e32 v18, v96, v18
	v_add_f32_e32 v18, v97, v18
	v_mov_b32_e32 v134, v18
	v_pk_mul_f32 v[18:19], v[74:75], v[74:75]
	v_pk_mul_f32 v[180:181], v[60:61], v[60:61]
	v_pk_mul_f32 v[64:65], v[80:81], v[80:81]
	v_pk_mul_f32 v[60:61], v[62:63], v[62:63]
	v_add_f32_e32 v18, v18, v19
	v_add_f32_e32 v180, v180, v181
	v_add_f32_e32 v18, v64, v18
	v_add_f32_e32 v180, v60, v180
	v_pk_mul_f32 v[66:67], v[78:79], v[78:79]
	v_pk_mul_f32 v[56:57], v[56:57], v[56:57]
	v_add_f32_e32 v18, v65, v18
	v_add_f32_e32 v180, v61, v180
	v_add_f32_e32 v18, v66, v18
	v_add_f32_e32 v180, v56, v180
	v_pk_mul_f32 v[74:75], v[82:83], v[82:83]
	v_pk_mul_f32 v[58:59], v[58:59], v[58:59]
	v_add_f32_e32 v18, v67, v18
	v_add_f32_e32 v180, v57, v180
	v_add_f32_e32 v18, v74, v18
	v_add_f32_e32 v180, v58, v180
	v_pk_mul_f32 v[78:79], v[84:85], v[84:85]
	v_pk_mul_f32 v[52:53], v[52:53], v[52:53]
	v_add_f32_e32 v18, v75, v18
	v_add_f32_e32 v180, v59, v180
	v_add_f32_e32 v18, v78, v18
	v_add_f32_e32 v180, v52, v180
	v_pk_mul_f32 v[80:81], v[128:129], v[128:129]
	v_pk_mul_f32 v[54:55], v[54:55], v[54:55]
	v_add_f32_e32 v18, v79, v18
	v_add_f32_e32 v180, v53, v180
	v_add_f32_e32 v18, v80, v18
	v_add_f32_e32 v180, v54, v180
	v_pk_mul_f32 v[82:83], v[86:87], v[86:87]
	v_pk_mul_f32 v[62:63], v[104:105], v[104:105]
	v_add_f32_e32 v18, v81, v18
	v_add_f32_e32 v180, v55, v180
	v_add_f32_e32 v18, v82, v18
	v_add_f32_e32 v180, v62, v180
	v_pk_mul_f32 v[84:85], v[130:131], v[130:131]
	v_pk_mul_f32 v[182:183], v[106:107], v[106:107]
	v_add_f32_e32 v18, v83, v18
	v_add_f32_e32 v180, v63, v180
	v_add_f32_e32 v18, v84, v18
	v_add_f32_e32 v180, v182, v180
	v_add_f32_e32 v18, v85, v18
	v_add_f32_e32 v180, v183, v180
	v_mov_b32_e32 v135, v18
	v_mov_b32_e32 v146, v180
	v_pk_mul_f32 v[18:19], v[44:45], v[44:45]
	v_pk_mul_f32 v[180:181], v[28:29], v[28:29]
	v_pk_mul_f32 v[44:45], v[46:47], v[46:47]
	v_pk_mul_f32 v[28:29], v[30:31], v[30:31]
	v_add_f32_e32 v18, v18, v19
	v_add_f32_e32 v180, v180, v181
	v_add_f32_e32 v18, v44, v18
	v_add_f32_e32 v180, v28, v180
	v_pk_mul_f32 v[40:41], v[40:41], v[40:41]
	v_pk_mul_f32 v[24:25], v[24:25], v[24:25]
	v_add_f32_e32 v18, v45, v18
	v_add_f32_e32 v180, v29, v180
	v_add_f32_e32 v18, v40, v18
	v_add_f32_e32 v180, v24, v180
	v_pk_mul_f32 v[42:43], v[42:43], v[42:43]
	v_pk_mul_f32 v[26:27], v[26:27], v[26:27]
	v_add_f32_e32 v18, v41, v18
	v_add_f32_e32 v180, v25, v180
	v_add_f32_e32 v18, v42, v18
	v_add_f32_e32 v180, v26, v180
	v_pk_mul_f32 v[36:37], v[36:37], v[36:37]
	v_pk_mul_f32 v[20:21], v[20:21], v[20:21]
	v_add_f32_e32 v18, v43, v18
	v_add_f32_e32 v180, v27, v180
	v_add_f32_e32 v18, v36, v18
	v_add_f32_e32 v180, v20, v180
	v_pk_mul_f32 v[38:39], v[38:39], v[38:39]
	v_pk_mul_f32 v[22:23], v[22:23], v[22:23]
	v_add_f32_e32 v18, v37, v18
	v_add_f32_e32 v180, v21, v180
	v_add_f32_e32 v18, v38, v18
	v_add_f32_e32 v180, v22, v180
	v_pk_mul_f32 v[46:47], v[48:49], v[48:49]
	v_pk_mul_f32 v[30:31], v[32:33], v[32:33]
	v_add_f32_e32 v18, v39, v18
	v_add_f32_e32 v180, v23, v180
	v_add_f32_e32 v18, v46, v18
	v_add_f32_e32 v180, v30, v180
	v_pk_mul_f32 v[48:49], v[50:51], v[50:51]
	v_pk_mul_f32 v[32:33], v[34:35], v[34:35]
	v_add_f32_e32 v18, v47, v18
	v_add_f32_e32 v180, v31, v180
	v_add_f32_e32 v18, v48, v18
	v_add_f32_e32 v180, v32, v180
	v_add_f32_e32 v18, v49, v18
	v_add_f32_e32 v180, v33, v180
	v_mov_b32_e32 v147, v18
	v_mov_b32_e32 v148, v180
	v_pk_mul_f32 v[12:13], v[12:13], v[12:13]
	v_pk_mul_f32 v[14:15], v[14:15], v[14:15]
	v_add_f32_e32 v12, v12, v13
	v_add_f32_e32 v12, v14, v12
	v_pk_mul_f32 v[8:9], v[8:9], v[8:9]
	v_add_f32_e32 v12, v15, v12
	v_add_f32_e32 v8, v8, v12
	v_pk_mul_f32 v[10:11], v[10:11], v[10:11]
	v_add_f32_e32 v8, v9, v8
	v_add_f32_e32 v8, v10, v8
	v_pk_mul_f32 v[4:5], v[4:5], v[4:5]
	v_add_f32_e32 v8, v11, v8
	v_add_f32_e32 v4, v4, v8
	v_pk_mul_f32 v[6:7], v[6:7], v[6:7]
	v_add_f32_e32 v4, v5, v4
	v_add_f32_e32 v4, v6, v4
	v_pk_mul_f32 v[0:1], v[0:1], v[0:1]
	v_add_f32_e32 v4, v7, v4
	v_add_f32_e32 v0, v0, v4
	v_pk_mul_f32 v[2:3], v[2:3], v[2:3]
	v_add_f32_e32 v0, v1, v0
	v_add_f32_e32 v0, v2, v0
	v_add_f32_e32 v0, v3, v0
	v_mov_b32_e32 v149, v0
	ds_bpermute_b32 v172, v16, v132
	ds_bpermute_b32 v173, v16, v133
	ds_bpermute_b32 v174, v16, v134
	ds_bpermute_b32 v175, v16, v135
	ds_bpermute_b32 v176, v16, v146
	ds_bpermute_b32 v177, v16, v147
	ds_bpermute_b32 v178, v16, v148
	ds_bpermute_b32 v179, v16, v149
	s_waitcnt lgkmcnt(0)
	v_add_f32_e32 v132, v132, v172
	v_add_f32_e32 v133, v133, v173
	v_add_f32_e32 v134, v134, v174
	v_add_f32_e32 v135, v135, v175
	v_add_f32_e32 v146, v146, v176
	v_add_f32_e32 v147, v147, v177
	v_add_f32_e32 v148, v148, v178
	v_add_f32_e32 v149, v149, v179
	ds_bpermute_b32 v172, v17, v132
	ds_bpermute_b32 v173, v17, v133
	ds_bpermute_b32 v174, v17, v134
	ds_bpermute_b32 v175, v17, v135
	ds_bpermute_b32 v176, v17, v146
	ds_bpermute_b32 v177, v17, v147
	ds_bpermute_b32 v178, v17, v148
	ds_bpermute_b32 v179, v17, v149
	s_and_saveexec_b64 s[46:47], s[42:43]
	s_cbranch_execz .LBB0_329
	s_waitcnt lgkmcnt(0)
	v_add_f32_e32 v132, v132, v172
	v_lshlrev_b64 v[18:19], 6, v[168:169]
	v_lshl_add_u64 v[18:19], s[38:39], 0, v[18:19]
	global_store_dword v[18:19], v132, off
	v_add_f32_e32 v133, v133, v173
	v_lshlrev_b64 v[18:19], 6, v[166:167]
	v_lshl_add_u64 v[18:19], s[38:39], 0, v[18:19]
	global_store_dword v[18:19], v133, off
	v_add_f32_e32 v134, v134, v174
	v_lshlrev_b64 v[18:19], 6, v[164:165]
	v_lshl_add_u64 v[18:19], s[38:39], 0, v[18:19]
	global_store_dword v[18:19], v134, off
	v_add_f32_e32 v135, v135, v175
	v_lshlrev_b64 v[18:19], 6, v[162:163]
	v_lshl_add_u64 v[18:19], s[38:39], 0, v[18:19]
	global_store_dword v[18:19], v135, off
	v_add_f32_e32 v146, v146, v176
	v_lshlrev_b64 v[18:19], 6, v[76:77]
	v_lshl_add_u64 v[18:19], s[38:39], 0, v[18:19]
	global_store_dword v[18:19], v146, off
	v_add_f32_e32 v147, v147, v177
	v_lshlrev_b64 v[18:19], 6, v[72:73]
	v_lshl_add_u64 v[18:19], s[38:39], 0, v[18:19]
	global_store_dword v[18:19], v147, off
	v_add_f32_e32 v148, v148, v178
	v_lshlrev_b64 v[18:19], 6, v[70:71]
	v_lshl_add_u64 v[18:19], s[38:39], 0, v[18:19]
	global_store_dword v[18:19], v148, off
	v_add_f32_e32 v149, v149, v179
	v_lshlrev_b64 v[18:19], 6, v[68:69]
	v_lshl_add_u64 v[18:19], s[38:39], 0, v[18:19]
	global_store_dword v[18:19], v149, off
	s_branch .LBB0_329

.Lm4bp_386:
	s_waitcnt lgkmcnt(0)
	s_mov_b32 s100, 0
	s_barrier
	v_mfma_f32_16x16x32_bf16 v[60:63], v[158:161], v[174:177], 0
	v_mfma_f32_16x16x32_bf16 v[56:59], v[166:169], v[174:177], 0
	v_mfma_f32_16x16x32_bf16 v[52:55], v[158:161], v[182:185], 0
	v_mfma_f32_16x16x32_bf16 v[48:51], v[166:169], v[182:185], 0
	v_mfma_f32_16x16x32_bf16 v[44:47], v[158:161], v[210:213], 0
	v_mfma_f32_16x16x32_bf16 v[40:43], v[166:169], v[210:213], 0
	v_mfma_f32_16x16x32_bf16 v[36:39], v[158:161], v[218:221], 0
	v_mfma_f32_16x16x32_bf16 v[32:35], v[166:169], v[218:221], 0
	v_mfma_f32_16x16x32_bf16 v[60:63], v[162:165], v[178:181], v[60:63]
	v_mfma_f32_16x16x32_bf16 v[56:59], v[170:173], v[178:181], v[56:59]
	v_mfma_f32_16x16x32_bf16 v[52:55], v[162:165], v[206:209], v[52:55]
	v_mfma_f32_16x16x32_bf16 v[48:51], v[170:173], v[206:209], v[48:51]
	v_mfma_f32_16x16x32_bf16 v[44:47], v[162:165], v[214:217], v[44:47]
	v_mfma_f32_16x16x32_bf16 v[40:43], v[170:173], v[214:217], v[40:43]
	v_mfma_f32_16x16x32_bf16 v[36:39], v[162:165], v[222:225], v[36:39]
	v_mfma_f32_16x16x32_bf16 v[32:35], v[170:173], v[222:225], v[32:35]
	v_mfma_f32_16x16x32_bf16 v[28:31], v[226:229], v[174:177], 0
	v_mfma_f32_16x16x32_bf16 v[24:27], v[234:237], v[174:177], 0
	v_mfma_f32_16x16x32_bf16 v[20:23], v[226:229], v[182:185], 0
	v_mfma_f32_16x16x32_bf16 v[16:19], v[234:237], v[182:185], 0
	v_mfma_f32_16x16x32_bf16 v[12:15], v[226:229], v[210:213], 0
	v_mfma_f32_16x16x32_bf16 v[8:11], v[234:237], v[210:213], 0
	v_mfma_f32_16x16x32_bf16 v[4:7], v[226:229], v[218:221], 0
	v_mfma_f32_16x16x32_bf16 v[0:3], v[234:237], v[218:221], 0
	v_mfma_f32_16x16x32_bf16 v[28:31], v[230:233], v[178:181], v[28:31]
	v_mfma_f32_16x16x32_bf16 v[24:27], v[238:241], v[178:181], v[24:27]
	v_mfma_f32_16x16x32_bf16 v[20:23], v[230:233], v[206:209], v[20:23]
	v_mfma_f32_16x16x32_bf16 v[16:19], v[238:241], v[206:209], v[16:19]
	v_mfma_f32_16x16x32_bf16 v[12:15], v[230:233], v[214:217], v[12:15]
	v_mfma_f32_16x16x32_bf16 v[8:11], v[238:241], v[214:217], v[8:11]
	v_mfma_f32_16x16x32_bf16 v[4:7], v[230:233], v[222:225], v[4:7]
	v_mfma_f32_16x16x32_bf16 v[0:3], v[238:241], v[222:225], v[0:3]
	s_barrier
	s_add_i32 s6, 0, 0x18000
	v_add_u32_e32 v170, s6, v154
	ds_read_b128 v[158:161], v170
	ds_read_b128 v[162:165], v170 offset:1024
	ds_read_b128 v[166:169], v170 offset:2048
	ds_read_b128 v[170:173], v170 offset:3072
	s_add_u32 s58, s58, 0x40000
	s_addc_u32 s59, s59, 0
	s_mov_b32 m0, s70
	v_lshl_add_u64 v[226:227], s[58:59], 0, v[128:129]
	ds_read_b128 v[174:177], v157 offset:32768
	ds_read_b128 v[178:181], v157 offset:33792
	ds_read_b128 v[182:185], v157 offset:34816
	ds_read_b128 v[206:209], v157 offset:35840
	ds_read_b128 v[210:213], v157 offset:36864
	ds_read_b128 v[214:217], v157 offset:37888
	ds_read_b128 v[218:221], v157 offset:38912
	ds_read_b128 v[222:225], v157 offset:39936
	global_load_lds_dwordx4 v[226:227], off
	v_lshl_add_u64 v[226:227], s[58:59], 0, v[130:131]
	s_mov_b32 m0, s71
	s_nop 0
	global_load_lds_dwordx4 v[226:227], off
	s_add_i32 s19, 0, 0x1c000
	v_add_u32_e32 v192, s19, v154
	ds_read_b128 v[226:229], v192
	ds_read_b128 v[230:233], v192 offset:1024
	ds_read_b128 v[234:237], v192 offset:2048
	ds_read_b128 v[238:241], v192 offset:3072
	s_waitcnt vmcnt(8)
	s_waitcnt lgkmcnt(0)
	s_barrier
	v_mfma_f32_16x16x32_bf16 v[124:127], v[158:161], v[174:177], v[124:127]
	v_mfma_f32_16x16x32_bf16 v[120:123], v[166:169], v[174:177], v[120:123]
	v_mfma_f32_16x16x32_bf16 v[116:119], v[158:161], v[182:185], v[116:119]
	v_mfma_f32_16x16x32_bf16 v[112:115], v[166:169], v[182:185], v[112:115]
	v_mfma_f32_16x16x32_bf16 v[108:111], v[158:161], v[210:213], v[108:111]
	v_mfma_f32_16x16x32_bf16 v[104:107], v[166:169], v[210:213], v[104:107]
	v_mfma_f32_16x16x32_bf16 v[100:103], v[158:161], v[218:221], v[100:103]
	v_mfma_f32_16x16x32_bf16 v[96:99], v[166:169], v[218:221], v[96:99]
	v_mfma_f32_16x16x32_bf16 v[124:127], v[162:165], v[178:181], v[124:127]
	v_mfma_f32_16x16x32_bf16 v[120:123], v[170:173], v[178:181], v[120:123]
	v_mfma_f32_16x16x32_bf16 v[116:119], v[162:165], v[206:209], v[116:119]
	v_mfma_f32_16x16x32_bf16 v[112:115], v[170:173], v[206:209], v[112:115]
	v_mfma_f32_16x16x32_bf16 v[108:111], v[162:165], v[214:217], v[108:111]
	v_mfma_f32_16x16x32_bf16 v[104:107], v[170:173], v[214:217], v[104:107]
	v_mfma_f32_16x16x32_bf16 v[100:103], v[162:165], v[222:225], v[100:103]
	v_mfma_f32_16x16x32_bf16 v[96:99], v[170:173], v[222:225], v[96:99]
	v_mfma_f32_16x16x32_bf16 v[92:95], v[226:229], v[174:177], v[92:95]
	v_mfma_f32_16x16x32_bf16 v[88:91], v[234:237], v[174:177], v[88:91]
	v_mfma_f32_16x16x32_bf16 v[84:87], v[226:229], v[182:185], v[84:87]
	v_mfma_f32_16x16x32_bf16 v[80:83], v[234:237], v[182:185], v[80:83]
	v_mfma_f32_16x16x32_bf16 v[76:79], v[226:229], v[210:213], v[76:79]
	v_mfma_f32_16x16x32_bf16 v[72:75], v[234:237], v[210:213], v[72:75]
	v_mfma_f32_16x16x32_bf16 v[68:71], v[226:229], v[218:221], v[68:71]
	v_mfma_f32_16x16x32_bf16 v[64:67], v[234:237], v[218:221], v[64:67]
	v_mfma_f32_16x16x32_bf16 v[92:95], v[230:233], v[178:181], v[92:95]
	v_mfma_f32_16x16x32_bf16 v[88:91], v[238:241], v[178:181], v[88:91]
	v_mfma_f32_16x16x32_bf16 v[84:87], v[230:233], v[206:209], v[84:87]
	v_mfma_f32_16x16x32_bf16 v[80:83], v[238:241], v[206:209], v[80:83]
	v_mfma_f32_16x16x32_bf16 v[76:79], v[230:233], v[214:217], v[76:79]
	v_mfma_f32_16x16x32_bf16 v[72:75], v[238:241], v[214:217], v[72:75]
	v_mfma_f32_16x16x32_bf16 v[68:71], v[230:233], v[222:225], v[68:71]
	v_mfma_f32_16x16x32_bf16 v[64:67], v[238:241], v[222:225], v[64:67]
	s_barrier
	s_add_i32 s6, s6, s57
	v_lshl_add_u64 v[146:147], v[146:147], 0, s[36:37]
	s_mov_b32 m0, s6
	s_nop 0
	global_load_lds_dwordx4 v[146:147], off
	v_lshl_add_u64 v[146:147], v[148:149], 0, s[36:37]
	s_add_i32 m0, s6, 0x2000
	s_nop 0
	global_load_lds_dwordx4 v[146:147], off
	s_mov_b32 m0, s72
	v_lshl_add_u64 v[146:147], v[194:195], 0, s[36:37]
	ds_read_b128 v[174:177], v157 offset:49152
	ds_read_b128 v[178:181], v157 offset:50176
	ds_read_b128 v[182:185], v157 offset:51200
	ds_read_b128 v[206:209], v157 offset:52224
	ds_read_b128 v[210:213], v157 offset:53248
	ds_read_b128 v[214:217], v157 offset:54272
	ds_read_b128 v[218:221], v157 offset:55296
	ds_read_b128 v[222:225], v157 offset:56320
	global_load_lds_dwordx4 v[146:147], off
	v_lshl_add_u64 v[146:147], v[196:197], 0, s[36:37]
	s_mov_b32 m0, s73
	s_nop 0
	global_load_lds_dwordx4 v[146:147], off
	s_add_u32 s54, s54, 0x40080
	s_addc_u32 s55, s55, 0
	s_add_i32 s6, s19, s57
	v_lshl_add_u64 v[146:147], s[54:55], 0, v[140:141]
	s_mov_b32 m0, s6
	s_nop 0
	global_load_lds_dwordx4 v[146:147], off
	v_lshl_add_u64 v[146:147], s[54:55], 0, v[132:133]
	s_add_i32 m0, s6, 0x2000
	s_nop 0
	global_load_lds_dwordx4 v[146:147], off
	s_add_i32 s81, s81, 2
	s_add_u32 s52, s52, 0x100
	s_addc_u32 s53, s53, 0
	s_cmp_gt_u32 s81, 13
	s_waitcnt vmcnt(8)
	s_waitcnt lgkmcnt(0)
	s_barrier
	v_mfma_f32_16x16x32_bf16 v[60:63], v[158:161], v[174:177], v[60:63]
	v_mfma_f32_16x16x32_bf16 v[56:59], v[166:169], v[174:177], v[56:59]
	v_mfma_f32_16x16x32_bf16 v[52:55], v[158:161], v[182:185], v[52:55]
	v_mfma_f32_16x16x32_bf16 v[48:51], v[166:169], v[182:185], v[48:51]
	v_mfma_f32_16x16x32_bf16 v[44:47], v[158:161], v[210:213], v[44:47]
	v_mfma_f32_16x16x32_bf16 v[40:43], v[166:169], v[210:213], v[40:43]
	v_mfma_f32_16x16x32_bf16 v[36:39], v[158:161], v[218:221], v[36:39]
	v_mfma_f32_16x16x32_bf16 v[32:35], v[166:169], v[218:221], v[32:35]
	v_mfma_f32_16x16x32_bf16 v[60:63], v[162:165], v[178:181], v[60:63]
	v_mfma_f32_16x16x32_bf16 v[56:59], v[170:173], v[178:181], v[56:59]
	v_mfma_f32_16x16x32_bf16 v[52:55], v[162:165], v[206:209], v[52:55]
	v_mfma_f32_16x16x32_bf16 v[48:51], v[170:173], v[206:209], v[48:51]
	v_mfma_f32_16x16x32_bf16 v[44:47], v[162:165], v[214:217], v[44:47]
	v_mfma_f32_16x16x32_bf16 v[40:43], v[170:173], v[214:217], v[40:43]
	v_mfma_f32_16x16x32_bf16 v[36:39], v[162:165], v[222:225], v[36:39]
	v_mfma_f32_16x16x32_bf16 v[32:35], v[170:173], v[222:225], v[32:35]
	v_mfma_f32_16x16x32_bf16 v[28:31], v[226:229], v[174:177], v[28:31]
	v_mfma_f32_16x16x32_bf16 v[24:27], v[234:237], v[174:177], v[24:27]
	v_mfma_f32_16x16x32_bf16 v[20:23], v[226:229], v[182:185], v[20:23]
	v_mfma_f32_16x16x32_bf16 v[16:19], v[234:237], v[182:185], v[16:19]
	v_mfma_f32_16x16x32_bf16 v[12:15], v[226:229], v[210:213], v[12:15]
	v_mfma_f32_16x16x32_bf16 v[8:11], v[234:237], v[210:213], v[8:11]
	v_mfma_f32_16x16x32_bf16 v[4:7], v[226:229], v[218:221], v[4:7]
	v_mfma_f32_16x16x32_bf16 v[0:3], v[234:237], v[218:221], v[0:3]
	v_mfma_f32_16x16x32_bf16 v[28:31], v[230:233], v[178:181], v[28:31]
	v_mfma_f32_16x16x32_bf16 v[24:27], v[238:241], v[178:181], v[24:27]
	v_mfma_f32_16x16x32_bf16 v[20:23], v[230:233], v[206:209], v[20:23]
	v_mfma_f32_16x16x32_bf16 v[16:19], v[238:241], v[206:209], v[16:19]
	v_mfma_f32_16x16x32_bf16 v[12:15], v[230:233], v[214:217], v[12:15]
	v_mfma_f32_16x16x32_bf16 v[8:11], v[238:241], v[214:217], v[8:11]
	v_mfma_f32_16x16x32_bf16 v[4:7], v[230:233], v[222:225], v[4:7]
	v_mfma_f32_16x16x32_bf16 v[0:3], v[238:241], v[222:225], v[0:3]
	s_barrier
.LBB0_386:
	s_add_u32 s6, s28, s52
	s_addc_u32 s19, s29, s53
	s_add_u32 s6, s6, 0x100
	s_addc_u32 s19, s19, 0
	s_add_u32 s23, s10, s52
	s_addc_u32 s54, s11, s53
	s_add_i32 s82, 0, 0x10000
	v_add_u32_e32 v146, s82, v154
	ds_read_b128 v[158:161], v146
	ds_read_b128 v[162:165], v146 offset:1024
	ds_read_b128 v[166:169], v146 offset:2048
	ds_read_b128 v[170:173], v146 offset:3072
	s_cmpk_eq_i32 s52, 0x700
	s_cselect_b32 s59, s12, s19
	s_cselect_b32 s58, s35, s6
	s_cselect_b32 s55, s39, s54
	s_cselect_b32 s54, s47, s23
	v_lshl_add_u64 v[146:147], v[150:151], 0, s[52:53]
	s_add_i32 m0, s68, 0xc000
	ds_read_b128 v[174:177], v157
	ds_read_b128 v[178:181], v157 offset:1024
	ds_read_b128 v[182:185], v157 offset:2048
	ds_read_b128 v[206:209], v157 offset:3072
	ds_read_b128 v[210:213], v157 offset:4096
	ds_read_b128 v[214:217], v157 offset:5120
	ds_read_b128 v[218:221], v157 offset:6144
	ds_read_b128 v[222:225], v157 offset:7168
	global_load_lds_dwordx4 v[146:147], off
	v_lshl_add_u64 v[146:147], v[152:153], 0, s[52:53]
	s_add_i32 m0, s68, 0xe000
	s_nop 0
	global_load_lds_dwordx4 v[146:147], off
	s_add_i32 s6, 0, 0x14000
	v_add_u32_e32 v146, s6, v154
	ds_read_b128 v[226:229], v146
	ds_read_b128 v[230:233], v146 offset:1024
	ds_read_b128 v[234:237], v146 offset:2048
	ds_read_b128 v[238:241], v146 offset:3072
	s_waitcnt vmcnt(8)
	s_waitcnt lgkmcnt(0)
	s_barrier
	v_mfma_f32_16x16x32_bf16 v[124:127], v[158:161], v[174:177], v[124:127]
	v_mfma_f32_16x16x32_bf16 v[120:123], v[166:169], v[174:177], v[120:123]
	v_mfma_f32_16x16x32_bf16 v[116:119], v[158:161], v[182:185], v[116:119]
	v_mfma_f32_16x16x32_bf16 v[112:115], v[166:169], v[182:185], v[112:115]
	v_mfma_f32_16x16x32_bf16 v[108:111], v[158:161], v[210:213], v[108:111]
	v_mfma_f32_16x16x32_bf16 v[104:107], v[166:169], v[210:213], v[104:107]
	v_mfma_f32_16x16x32_bf16 v[100:103], v[158:161], v[218:221], v[100:103]
	v_mfma_f32_16x16x32_bf16 v[96:99], v[166:169], v[218:221], v[96:99]
	v_mfma_f32_16x16x32_bf16 v[124:127], v[162:165], v[178:181], v[124:127]
	v_mfma_f32_16x16x32_bf16 v[120:123], v[170:173], v[178:181], v[120:123]
	v_mfma_f32_16x16x32_bf16 v[116:119], v[162:165], v[206:209], v[116:119]
	v_mfma_f32_16x16x32_bf16 v[112:115], v[170:173], v[206:209], v[112:115]
	v_mfma_f32_16x16x32_bf16 v[108:111], v[162:165], v[214:217], v[108:111]
	v_mfma_f32_16x16x32_bf16 v[104:107], v[170:173], v[214:217], v[104:107]
	v_mfma_f32_16x16x32_bf16 v[100:103], v[162:165], v[222:225], v[100:103]
	v_mfma_f32_16x16x32_bf16 v[96:99], v[170:173], v[222:225], v[96:99]
	v_mfma_f32_16x16x32_bf16 v[92:95], v[226:229], v[174:177], v[92:95]
	v_mfma_f32_16x16x32_bf16 v[88:91], v[234:237], v[174:177], v[88:91]
	v_mfma_f32_16x16x32_bf16 v[84:87], v[226:229], v[182:185], v[84:87]
	v_mfma_f32_16x16x32_bf16 v[80:83], v[234:237], v[182:185], v[80:83]
	v_mfma_f32_16x16x32_bf16 v[76:79], v[226:229], v[210:213], v[76:79]
	v_mfma_f32_16x16x32_bf16 v[72:75], v[234:237], v[210:213], v[72:75]
	v_mfma_f32_16x16x32_bf16 v[68:71], v[226:229], v[218:221], v[68:71]
	v_mfma_f32_16x16x32_bf16 v[64:67], v[234:237], v[218:221], v[64:67]
	v_mfma_f32_16x16x32_bf16 v[92:95], v[230:233], v[178:181], v[92:95]
	v_mfma_f32_16x16x32_bf16 v[88:91], v[238:241], v[178:181], v[88:91]
	v_mfma_f32_16x16x32_bf16 v[84:87], v[230:233], v[206:209], v[84:87]
	v_mfma_f32_16x16x32_bf16 v[80:83], v[238:241], v[206:209], v[80:83]
	v_mfma_f32_16x16x32_bf16 v[76:79], v[230:233], v[214:217], v[76:79]
	v_mfma_f32_16x16x32_bf16 v[72:75], v[238:241], v[214:217], v[72:75]
	v_mfma_f32_16x16x32_bf16 v[68:71], v[230:233], v[222:225], v[68:71]
	v_mfma_f32_16x16x32_bf16 v[64:67], v[238:241], v[222:225], v[64:67]
	s_barrier
	s_add_i32 s19, s82, s57
	v_lshl_add_u64 v[146:147], s[54:55], 0, v[140:141]
	s_mov_b32 m0, s19
	v_lshl_add_u64 v[148:149], s[54:55], 0, v[132:133]
	global_load_lds_dwordx4 v[146:147], off
	s_add_i32 m0, s19, 0x2000
	s_nop 0
	global_load_lds_dwordx4 v[148:149], off
	s_mov_b32 m0, s68
	v_lshl_add_u64 v[194:195], s[58:59], 0, v[128:129]
	ds_read_b128 v[174:177], v157 offset:16384
	ds_read_b128 v[178:181], v157 offset:17408
	ds_read_b128 v[182:185], v157 offset:18432
	ds_read_b128 v[206:209], v157 offset:19456
	ds_read_b128 v[210:213], v157 offset:20480
	ds_read_b128 v[214:217], v157 offset:21504
	ds_read_b128 v[218:221], v157 offset:22528
	ds_read_b128 v[222:225], v157 offset:23552
	global_load_lds_dwordx4 v[194:195], off
	v_lshl_add_u64 v[196:197], s[58:59], 0, v[130:131]
	s_mov_b32 m0, s69
	s_nop 0
	global_load_lds_dwordx4 v[196:197], off
	s_add_u32 s82, s54, 0x40000
	s_addc_u32 s83, s55, 0
	s_add_i32 s6, s6, s57
	v_lshl_add_u64 v[250:251], s[82:83], 0, v[140:141]
	s_mov_b32 m0, s6
	s_nop 0
	global_load_lds_dwordx4 v[250:251], off
	v_lshl_add_u64 v[250:251], s[82:83], 0, v[132:133]
	s_add_i32 m0, s6, 0x2000
	s_nop 0
	global_load_lds_dwordx4 v[250:251], off
	s_waitcnt vmcnt(8)
	s_waitcnt lgkmcnt(0)
	s_barrier
	v_mfma_f32_16x16x32_bf16 v[60:63], v[158:161], v[174:177], v[60:63]
	v_mfma_f32_16x16x32_bf16 v[56:59], v[166:169], v[174:177], v[56:59]
	v_mfma_f32_16x16x32_bf16 v[52:55], v[158:161], v[182:185], v[52:55]
	v_mfma_f32_16x16x32_bf16 v[48:51], v[166:169], v[182:185], v[48:51]
	v_mfma_f32_16x16x32_bf16 v[44:47], v[158:161], v[210:213], v[44:47]
	v_mfma_f32_16x16x32_bf16 v[40:43], v[166:169], v[210:213], v[40:43]
	v_mfma_f32_16x16x32_bf16 v[36:39], v[158:161], v[218:221], v[36:39]
	v_mfma_f32_16x16x32_bf16 v[32:35], v[166:169], v[218:221], v[32:35]
	v_mfma_f32_16x16x32_bf16 v[60:63], v[162:165], v[178:181], v[60:63]
	v_mfma_f32_16x16x32_bf16 v[56:59], v[170:173], v[178:181], v[56:59]
	v_mfma_f32_16x16x32_bf16 v[52:55], v[162:165], v[206:209], v[52:55]
	v_mfma_f32_16x16x32_bf16 v[48:51], v[170:173], v[206:209], v[48:51]
	v_mfma_f32_16x16x32_bf16 v[44:47], v[162:165], v[214:217], v[44:47]
	v_mfma_f32_16x16x32_bf16 v[40:43], v[170:173], v[214:217], v[40:43]
	v_mfma_f32_16x16x32_bf16 v[36:39], v[162:165], v[222:225], v[36:39]
	v_mfma_f32_16x16x32_bf16 v[32:35], v[170:173], v[222:225], v[32:35]
	v_mfma_f32_16x16x32_bf16 v[28:31], v[226:229], v[174:177], v[28:31]
	v_mfma_f32_16x16x32_bf16 v[24:27], v[234:237], v[174:177], v[24:27]
	v_mfma_f32_16x16x32_bf16 v[20:23], v[226:229], v[182:185], v[20:23]
	v_mfma_f32_16x16x32_bf16 v[16:19], v[234:237], v[182:185], v[16:19]
	v_mfma_f32_16x16x32_bf16 v[12:15], v[226:229], v[210:213], v[12:15]
	v_mfma_f32_16x16x32_bf16 v[8:11], v[234:237], v[210:213], v[8:11]
	v_mfma_f32_16x16x32_bf16 v[4:7], v[226:229], v[218:221], v[4:7]
	v_mfma_f32_16x16x32_bf16 v[0:3], v[234:237], v[218:221], v[0:3]
	v_mfma_f32_16x16x32_bf16 v[28:31], v[230:233], v[178:181], v[28:31]
	v_mfma_f32_16x16x32_bf16 v[24:27], v[238:241], v[178:181], v[24:27]
	v_mfma_f32_16x16x32_bf16 v[20:23], v[230:233], v[206:209], v[20:23]
	v_mfma_f32_16x16x32_bf16 v[16:19], v[238:241], v[206:209], v[16:19]
	v_mfma_f32_16x16x32_bf16 v[12:15], v[230:233], v[214:217], v[12:15]
	v_mfma_f32_16x16x32_bf16 v[8:11], v[238:241], v[214:217], v[8:11]
	v_mfma_f32_16x16x32_bf16 v[4:7], v[230:233], v[222:225], v[4:7]
	v_mfma_f32_16x16x32_bf16 v[0:3], v[238:241], v[222:225], v[0:3]
	s_barrier
	s_add_i32 s6, 0, 0x18000
	v_add_u32_e32 v170, s6, v154
	ds_read_b128 v[158:161], v170
	ds_read_b128 v[162:165], v170 offset:1024
	ds_read_b128 v[166:169], v170 offset:2048
	ds_read_b128 v[170:173], v170 offset:3072
	s_add_u32 s58, s58, 0x40000
	s_addc_u32 s59, s59, 0
	s_mov_b32 m0, s70
	v_lshl_add_u64 v[226:227], s[58:59], 0, v[128:129]
	ds_read_b128 v[174:177], v157 offset:32768
	ds_read_b128 v[178:181], v157 offset:33792
	ds_read_b128 v[182:185], v157 offset:34816
	ds_read_b128 v[206:209], v157 offset:35840
	ds_read_b128 v[210:213], v157 offset:36864
	ds_read_b128 v[214:217], v157 offset:37888
	ds_read_b128 v[218:221], v157 offset:38912
	ds_read_b128 v[222:225], v157 offset:39936
	global_load_lds_dwordx4 v[226:227], off
	v_lshl_add_u64 v[226:227], s[58:59], 0, v[130:131]
	s_mov_b32 m0, s71
	s_nop 0
	global_load_lds_dwordx4 v[226:227], off
	s_add_i32 s19, 0, 0x1c000
	v_add_u32_e32 v192, s19, v154
	ds_read_b128 v[226:229], v192
	ds_read_b128 v[230:233], v192 offset:1024
	ds_read_b128 v[234:237], v192 offset:2048
	ds_read_b128 v[238:241], v192 offset:3072
	s_waitcnt vmcnt(8)
	s_waitcnt lgkmcnt(0)
	s_barrier
	v_mfma_f32_16x16x32_bf16 v[124:127], v[158:161], v[174:177], v[124:127]
	v_mfma_f32_16x16x32_bf16 v[120:123], v[166:169], v[174:177], v[120:123]
	v_mfma_f32_16x16x32_bf16 v[116:119], v[158:161], v[182:185], v[116:119]
	v_mfma_f32_16x16x32_bf16 v[112:115], v[166:169], v[182:185], v[112:115]
	v_mfma_f32_16x16x32_bf16 v[108:111], v[158:161], v[210:213], v[108:111]
	v_mfma_f32_16x16x32_bf16 v[104:107], v[166:169], v[210:213], v[104:107]
	v_mfma_f32_16x16x32_bf16 v[100:103], v[158:161], v[218:221], v[100:103]
	v_mfma_f32_16x16x32_bf16 v[96:99], v[166:169], v[218:221], v[96:99]
	v_mfma_f32_16x16x32_bf16 v[124:127], v[162:165], v[178:181], v[124:127]
	v_mfma_f32_16x16x32_bf16 v[120:123], v[170:173], v[178:181], v[120:123]
	v_mfma_f32_16x16x32_bf16 v[116:119], v[162:165], v[206:209], v[116:119]
	v_mfma_f32_16x16x32_bf16 v[112:115], v[170:173], v[206:209], v[112:115]
	v_mfma_f32_16x16x32_bf16 v[108:111], v[162:165], v[214:217], v[108:111]
	v_mfma_f32_16x16x32_bf16 v[104:107], v[170:173], v[214:217], v[104:107]
	v_mfma_f32_16x16x32_bf16 v[100:103], v[162:165], v[222:225], v[100:103]
	v_mfma_f32_16x16x32_bf16 v[96:99], v[170:173], v[222:225], v[96:99]
	v_mfma_f32_16x16x32_bf16 v[92:95], v[226:229], v[174:177], v[92:95]
	v_mfma_f32_16x16x32_bf16 v[88:91], v[234:237], v[174:177], v[88:91]
	v_mfma_f32_16x16x32_bf16 v[84:87], v[226:229], v[182:185], v[84:87]
	v_mfma_f32_16x16x32_bf16 v[80:83], v[234:237], v[182:185], v[80:83]
	v_mfma_f32_16x16x32_bf16 v[76:79], v[226:229], v[210:213], v[76:79]
	v_mfma_f32_16x16x32_bf16 v[72:75], v[234:237], v[210:213], v[72:75]
	v_mfma_f32_16x16x32_bf16 v[68:71], v[226:229], v[218:221], v[68:71]
	v_mfma_f32_16x16x32_bf16 v[64:67], v[234:237], v[218:221], v[64:67]
	v_mfma_f32_16x16x32_bf16 v[92:95], v[230:233], v[178:181], v[92:95]
	v_mfma_f32_16x16x32_bf16 v[88:91], v[238:241], v[178:181], v[88:91]
	v_mfma_f32_16x16x32_bf16 v[84:87], v[230:233], v[206:209], v[84:87]
	v_mfma_f32_16x16x32_bf16 v[80:83], v[238:241], v[206:209], v[80:83]
	v_mfma_f32_16x16x32_bf16 v[76:79], v[230:233], v[214:217], v[76:79]
	v_mfma_f32_16x16x32_bf16 v[72:75], v[238:241], v[214:217], v[72:75]
	v_mfma_f32_16x16x32_bf16 v[68:71], v[230:233], v[222:225], v[68:71]
	v_mfma_f32_16x16x32_bf16 v[64:67], v[238:241], v[222:225], v[64:67]
	s_barrier
	s_add_i32 s6, s6, s57
	v_lshl_add_u64 v[146:147], v[146:147], 0, s[36:37]
	s_mov_b32 m0, s6
	s_nop 0
	global_load_lds_dwordx4 v[146:147], off
	v_lshl_add_u64 v[146:147], v[148:149], 0, s[36:37]
	s_add_i32 m0, s6, 0x2000
	s_nop 0
	global_load_lds_dwordx4 v[146:147], off
	s_mov_b32 m0, s72
	v_lshl_add_u64 v[146:147], v[194:195], 0, s[36:37]
	ds_read_b128 v[174:177], v157 offset:49152
	ds_read_b128 v[178:181], v157 offset:50176
	ds_read_b128 v[182:185], v157 offset:51200
	ds_read_b128 v[206:209], v157 offset:52224
	ds_read_b128 v[210:213], v157 offset:53248
	ds_read_b128 v[214:217], v157 offset:54272
	ds_read_b128 v[218:221], v157 offset:55296
	ds_read_b128 v[222:225], v157 offset:56320
	global_load_lds_dwordx4 v[146:147], off
	v_lshl_add_u64 v[146:147], v[196:197], 0, s[36:37]
	s_mov_b32 m0, s73
	s_nop 0
	global_load_lds_dwordx4 v[146:147], off
	s_add_u32 s54, s54, 0x40080
	s_addc_u32 s55, s55, 0
	s_add_i32 s6, s19, s57
	v_lshl_add_u64 v[146:147], s[54:55], 0, v[140:141]
	s_mov_b32 m0, s6
	s_nop 0
	global_load_lds_dwordx4 v[146:147], off
	v_lshl_add_u64 v[146:147], s[54:55], 0, v[132:133]
	s_add_i32 m0, s6, 0x2000
	s_nop 0
	global_load_lds_dwordx4 v[146:147], off
	s_add_i32 s81, s81, 2
	s_add_u32 s52, s52, 0x100
	s_addc_u32 s53, s53, 0
	s_cmp_gt_u32 s81, 13
	s_waitcnt vmcnt(8)
	s_waitcnt lgkmcnt(0)
	s_barrier
	v_mfma_f32_16x16x32_bf16 v[60:63], v[158:161], v[174:177], v[60:63]
	v_mfma_f32_16x16x32_bf16 v[56:59], v[166:169], v[174:177], v[56:59]
	v_mfma_f32_16x16x32_bf16 v[52:55], v[158:161], v[182:185], v[52:55]
	v_mfma_f32_16x16x32_bf16 v[48:51], v[166:169], v[182:185], v[48:51]
	v_mfma_f32_16x16x32_bf16 v[44:47], v[158:161], v[210:213], v[44:47]
	v_mfma_f32_16x16x32_bf16 v[40:43], v[166:169], v[210:213], v[40:43]
	v_mfma_f32_16x16x32_bf16 v[36:39], v[158:161], v[218:221], v[36:39]
	v_mfma_f32_16x16x32_bf16 v[32:35], v[166:169], v[218:221], v[32:35]
	v_mfma_f32_16x16x32_bf16 v[60:63], v[162:165], v[178:181], v[60:63]
	v_mfma_f32_16x16x32_bf16 v[56:59], v[170:173], v[178:181], v[56:59]
	v_mfma_f32_16x16x32_bf16 v[52:55], v[162:165], v[206:209], v[52:55]
	v_mfma_f32_16x16x32_bf16 v[48:51], v[170:173], v[206:209], v[48:51]
	v_mfma_f32_16x16x32_bf16 v[44:47], v[162:165], v[214:217], v[44:47]
	v_mfma_f32_16x16x32_bf16 v[40:43], v[170:173], v[214:217], v[40:43]
	v_mfma_f32_16x16x32_bf16 v[36:39], v[162:165], v[222:225], v[36:39]
	v_mfma_f32_16x16x32_bf16 v[32:35], v[170:173], v[222:225], v[32:35]
	v_mfma_f32_16x16x32_bf16 v[28:31], v[226:229], v[174:177], v[28:31]
	v_mfma_f32_16x16x32_bf16 v[24:27], v[234:237], v[174:177], v[24:27]
	v_mfma_f32_16x16x32_bf16 v[20:23], v[226:229], v[182:185], v[20:23]
	v_mfma_f32_16x16x32_bf16 v[16:19], v[234:237], v[182:185], v[16:19]
	v_mfma_f32_16x16x32_bf16 v[12:15], v[226:229], v[210:213], v[12:15]
	v_mfma_f32_16x16x32_bf16 v[8:11], v[234:237], v[210:213], v[8:11]
	v_mfma_f32_16x16x32_bf16 v[4:7], v[226:229], v[218:221], v[4:7]
	v_mfma_f32_16x16x32_bf16 v[0:3], v[234:237], v[218:221], v[0:3]
	v_mfma_f32_16x16x32_bf16 v[28:31], v[230:233], v[178:181], v[28:31]
	v_mfma_f32_16x16x32_bf16 v[24:27], v[238:241], v[178:181], v[24:27]
	v_mfma_f32_16x16x32_bf16 v[20:23], v[230:233], v[206:209], v[20:23]
	v_mfma_f32_16x16x32_bf16 v[16:19], v[238:241], v[206:209], v[16:19]
	v_mfma_f32_16x16x32_bf16 v[12:15], v[230:233], v[214:217], v[12:15]
	v_mfma_f32_16x16x32_bf16 v[8:11], v[238:241], v[214:217], v[8:11]
	v_mfma_f32_16x16x32_bf16 v[4:7], v[230:233], v[222:225], v[4:7]
	v_mfma_f32_16x16x32_bf16 v[0:3], v[238:241], v[222:225], v[0:3]
	s_barrier
	s_cbranch_scc0 .LBB0_386
	s_mov_b32 s100, 1
	v_lshl_add_u32 v158, s75, 10, v155
	ds_read2_b32 v[146:147], v158 offset1:16
	ds_read2_b32 v[208:209], v158 offset0:32 offset1:48
	ds_read2_b32 v[210:211], v158 offset0:128 offset1:144
	ds_read2_b32 v[212:213], v158 offset0:160 offset1:176
	s_add_u32 s52, s10, 0xffffff00
	s_addc_u32 s53, s11, -1
	s_ashr_i32 s35, s34, 31
	s_lshl_b64 s[10:11], s[34:35], 8
	s_waitcnt lgkmcnt(0)
	v_mul_f32_e32 v184, 0xbfb8aa3b, v146
	v_mul_f32_e32 v206, v146, v146
	v_pk_mul_f32 v[168:169], v[124:125], v[184:185] op_sel_hi:[1,0]
	v_pk_mul_f32 v[170:171], v[126:127], v[184:185] op_sel_hi:[1,0]
	v_pk_mul_f32 v[172:173], v[120:121], v[184:185] op_sel_hi:[1,0]
	v_pk_mul_f32 v[174:175], v[122:123], v[184:185] op_sel_hi:[1,0]
	v_exp_f32_e32 v168, v168
	v_exp_f32_e32 v169, v169
	v_exp_f32_e32 v170, v170
	v_exp_f32_e32 v171, v171
	v_exp_f32_e32 v172, v172
	v_exp_f32_e32 v173, v173
	v_exp_f32_e32 v174, v174
	v_exp_f32_e32 v175, v175
	v_pk_mul_f32 v[176:177], v[124:125], v[92:93]
	v_pk_mul_f32 v[178:179], v[126:127], v[94:95]
	v_pk_mul_f32 v[180:181], v[120:121], v[88:89]
	v_pk_mul_f32 v[182:183], v[122:123], v[90:91]
	v_pk_add_f32 v[168:169], v[168:169], 1.0 op_sel_hi:[1,0]
	v_pk_add_f32 v[170:171], v[170:171], 1.0 op_sel_hi:[1,0]
	v_pk_add_f32 v[172:173], v[172:173], 1.0 op_sel_hi:[1,0]
	v_pk_add_f32 v[174:175], v[174:175], 1.0 op_sel_hi:[1,0]
	v_rcp_f32_e32 v168, v168
	v_rcp_f32_e32 v169, v169
	v_rcp_f32_e32 v170, v170
	v_rcp_f32_e32 v171, v171
	v_rcp_f32_e32 v172, v172
	v_rcp_f32_e32 v173, v173
	v_rcp_f32_e32 v174, v174
	v_rcp_f32_e32 v175, v175
	v_pk_mul_f32 v[176:177], v[176:177], v[206:207] op_sel_hi:[1,0]
	v_pk_mul_f32 v[178:179], v[178:179], v[206:207] op_sel_hi:[1,0]
	v_pk_mul_f32 v[180:181], v[180:181], v[206:207] op_sel_hi:[1,0]
	v_pk_mul_f32 v[182:183], v[182:183], v[206:207] op_sel_hi:[1,0]
	v_pk_mul_f32 v[176:177], v[176:177], v[168:169]
	v_pk_mul_f32 v[178:179], v[178:179], v[170:171]
	v_pk_mul_f32 v[180:181], v[180:181], v[172:173]
	v_pk_mul_f32 v[182:183], v[182:183], v[174:175]
	v_cvt_pk_bf16_f32 v160, v176, v177
	v_cvt_pk_bf16_f32 v161, v178, v179
	v_cvt_pk_bf16_f32 v162, v180, v181
	v_cvt_pk_bf16_f32 v163, v182, v183
	v_lshl_add_u64 v[152:153], v[134:135], 0, s[10:11]
	s_movk_i32 s6, 0x1600
	v_lshl_or_b32 v150, s74, 7, v156
	v_ashrrev_i32_e32 v151, 31, v150
	s_nop 1
	v_mov_b64_e32 v[148:149], s[30:31]
	v_mad_u64_u32 v[148:149], s[10:11], v152, s6, v[148:149]
	v_mov_b32_e32 v146, v149
	v_mad_u64_u32 v[152:153], s[10:11], v153, s6, v[146:147]
	v_mov_b32_e32 v149, v152
	v_mov_b32_e32 v146, v147
	v_lshl_add_u64 v[150:151], v[150:151], 1, v[148:149]
	global_store_dwordx4 v[150:151], v[160:163], off
	v_mul_f32_e32 v184, 0xbfb8aa3b, v146
	v_mul_f32_e32 v206, v146, v146
	v_pk_mul_f32 v[168:169], v[116:117], v[184:185] op_sel_hi:[1,0]
	v_pk_mul_f32 v[170:171], v[118:119], v[184:185] op_sel_hi:[1,0]
	v_pk_mul_f32 v[172:173], v[112:113], v[184:185] op_sel_hi:[1,0]
	v_pk_mul_f32 v[174:175], v[114:115], v[184:185] op_sel_hi:[1,0]
	v_exp_f32_e32 v168, v168
	v_exp_f32_e32 v169, v169
	v_exp_f32_e32 v170, v170
	v_exp_f32_e32 v171, v171
	v_exp_f32_e32 v172, v172
	v_exp_f32_e32 v173, v173
	v_exp_f32_e32 v174, v174
	v_exp_f32_e32 v175, v175
	v_pk_mul_f32 v[176:177], v[116:117], v[84:85]
	v_pk_mul_f32 v[178:179], v[118:119], v[86:87]
	v_pk_mul_f32 v[180:181], v[112:113], v[80:81]
	v_pk_mul_f32 v[182:183], v[114:115], v[82:83]
	v_pk_add_f32 v[168:169], v[168:169], 1.0 op_sel_hi:[1,0]
	v_pk_add_f32 v[170:171], v[170:171], 1.0 op_sel_hi:[1,0]
	v_pk_add_f32 v[172:173], v[172:173], 1.0 op_sel_hi:[1,0]
	v_pk_add_f32 v[174:175], v[174:175], 1.0 op_sel_hi:[1,0]
	v_rcp_f32_e32 v168, v168
	v_rcp_f32_e32 v169, v169
	v_rcp_f32_e32 v170, v170
	v_rcp_f32_e32 v171, v171
	v_rcp_f32_e32 v172, v172
	v_rcp_f32_e32 v173, v173
	v_rcp_f32_e32 v174, v174
	v_rcp_f32_e32 v175, v175
	v_pk_mul_f32 v[176:177], v[176:177], v[206:207] op_sel_hi:[1,0]
	v_pk_mul_f32 v[178:179], v[178:179], v[206:207] op_sel_hi:[1,0]
	v_pk_mul_f32 v[180:181], v[180:181], v[206:207] op_sel_hi:[1,0]
	v_pk_mul_f32 v[182:183], v[182:183], v[206:207] op_sel_hi:[1,0]
	v_pk_mul_f32 v[176:177], v[176:177], v[168:169]
	v_pk_mul_f32 v[178:179], v[178:179], v[170:171]
	v_pk_mul_f32 v[180:181], v[180:181], v[172:173]
	v_pk_mul_f32 v[182:183], v[182:183], v[174:175]
	v_cvt_pk_bf16_f32 v160, v176, v177
	v_cvt_pk_bf16_f32 v161, v178, v179
	v_cvt_pk_bf16_f32 v162, v180, v181
	v_cvt_pk_bf16_f32 v163, v182, v183
	s_mov_b32 s6, 0x16000
	s_nop 1
	v_add_co_u32_e32 v146, vcc, s6, v150
	s_nop 0
	v_addc_co_u32_e32 v147, vcc, 0, v151, vcc
	global_store_dwordx4 v[146:147], v[160:163], off
	v_mov_b32_e32 v146, v208
	v_mov_b32_e32 v147, v209
	s_mov_b32 s6, 0x2c000
	s_waitcnt lgkmcnt(0)
	v_mul_f32_e32 v184, 0xbfb8aa3b, v146
	v_mul_f32_e32 v206, v146, v146
	v_pk_mul_f32 v[168:169], v[108:109], v[184:185] op_sel_hi:[1,0]
	v_pk_mul_f32 v[170:171], v[110:111], v[184:185] op_sel_hi:[1,0]
	v_pk_mul_f32 v[172:173], v[104:105], v[184:185] op_sel_hi:[1,0]
	v_pk_mul_f32 v[174:175], v[106:107], v[184:185] op_sel_hi:[1,0]
	v_exp_f32_e32 v168, v168
	v_exp_f32_e32 v169, v169
	v_exp_f32_e32 v170, v170
	v_exp_f32_e32 v171, v171
	v_exp_f32_e32 v172, v172
	v_exp_f32_e32 v173, v173
	v_exp_f32_e32 v174, v174
	v_exp_f32_e32 v175, v175
	v_pk_mul_f32 v[176:177], v[108:109], v[76:77]
	v_pk_mul_f32 v[178:179], v[110:111], v[78:79]
	v_pk_mul_f32 v[180:181], v[104:105], v[72:73]
	v_pk_mul_f32 v[182:183], v[106:107], v[74:75]
	v_pk_add_f32 v[168:169], v[168:169], 1.0 op_sel_hi:[1,0]
	v_pk_add_f32 v[170:171], v[170:171], 1.0 op_sel_hi:[1,0]
	v_pk_add_f32 v[172:173], v[172:173], 1.0 op_sel_hi:[1,0]
	v_pk_add_f32 v[174:175], v[174:175], 1.0 op_sel_hi:[1,0]
	v_rcp_f32_e32 v168, v168
	v_rcp_f32_e32 v169, v169
	v_rcp_f32_e32 v170, v170
	v_rcp_f32_e32 v171, v171
	v_rcp_f32_e32 v172, v172
	v_rcp_f32_e32 v173, v173
	v_rcp_f32_e32 v174, v174
	v_rcp_f32_e32 v175, v175
	v_pk_mul_f32 v[176:177], v[176:177], v[206:207] op_sel_hi:[1,0]
	v_pk_mul_f32 v[178:179], v[178:179], v[206:207] op_sel_hi:[1,0]
	v_pk_mul_f32 v[180:181], v[180:181], v[206:207] op_sel_hi:[1,0]
	v_pk_mul_f32 v[182:183], v[182:183], v[206:207] op_sel_hi:[1,0]
	v_pk_mul_f32 v[176:177], v[176:177], v[168:169]
	v_pk_mul_f32 v[178:179], v[178:179], v[170:171]
	v_pk_mul_f32 v[180:181], v[180:181], v[172:173]
	v_pk_mul_f32 v[182:183], v[182:183], v[174:175]
	v_cvt_pk_bf16_f32 v160, v176, v177
	v_cvt_pk_bf16_f32 v161, v178, v179
	v_cvt_pk_bf16_f32 v162, v180, v181
	v_cvt_pk_bf16_f32 v163, v182, v183
	s_nop 1
	v_mov_b32_e32 v146, v147
	v_add_co_u32_e32 v148, vcc, s6, v150
	v_addc_co_u32_e32 v149, vcc, 0, v151, vcc
	global_store_dwordx4 v[148:149], v[160:163], off
	v_mul_f32_e32 v184, 0xbfb8aa3b, v146
	v_mul_f32_e32 v206, v146, v146
	v_pk_mul_f32 v[168:169], v[100:101], v[184:185] op_sel_hi:[1,0]
	v_pk_mul_f32 v[170:171], v[102:103], v[184:185] op_sel_hi:[1,0]
	v_pk_mul_f32 v[172:173], v[96:97], v[184:185] op_sel_hi:[1,0]
	v_pk_mul_f32 v[174:175], v[98:99], v[184:185] op_sel_hi:[1,0]
	v_exp_f32_e32 v168, v168
	v_exp_f32_e32 v169, v169
	v_exp_f32_e32 v170, v170
	v_exp_f32_e32 v171, v171
	v_exp_f32_e32 v172, v172
	v_exp_f32_e32 v173, v173
	v_exp_f32_e32 v174, v174
	v_exp_f32_e32 v175, v175
	v_pk_mul_f32 v[176:177], v[100:101], v[68:69]
	v_pk_mul_f32 v[178:179], v[102:103], v[70:71]
	v_pk_mul_f32 v[180:181], v[96:97], v[64:65]
	v_pk_mul_f32 v[182:183], v[98:99], v[66:67]
	v_pk_add_f32 v[168:169], v[168:169], 1.0 op_sel_hi:[1,0]
	v_pk_add_f32 v[170:171], v[170:171], 1.0 op_sel_hi:[1,0]
	v_pk_add_f32 v[172:173], v[172:173], 1.0 op_sel_hi:[1,0]
	v_pk_add_f32 v[174:175], v[174:175], 1.0 op_sel_hi:[1,0]
	v_rcp_f32_e32 v168, v168
	v_rcp_f32_e32 v169, v169
	v_rcp_f32_e32 v170, v170
	v_rcp_f32_e32 v171, v171
	v_rcp_f32_e32 v172, v172
	v_rcp_f32_e32 v173, v173
	v_rcp_f32_e32 v174, v174
	v_rcp_f32_e32 v175, v175
	v_pk_mul_f32 v[176:177], v[176:177], v[206:207] op_sel_hi:[1,0]
	v_pk_mul_f32 v[178:179], v[178:179], v[206:207] op_sel_hi:[1,0]
	v_pk_mul_f32 v[180:181], v[180:181], v[206:207] op_sel_hi:[1,0]
	v_pk_mul_f32 v[182:183], v[182:183], v[206:207] op_sel_hi:[1,0]
	v_pk_mul_f32 v[176:177], v[176:177], v[168:169]
	v_pk_mul_f32 v[178:179], v[178:179], v[170:171]
	v_pk_mul_f32 v[180:181], v[180:181], v[172:173]
	v_pk_mul_f32 v[182:183], v[182:183], v[174:175]
	v_cvt_pk_bf16_f32 v160, v176, v177
	v_cvt_pk_bf16_f32 v161, v178, v179
	v_cvt_pk_bf16_f32 v162, v180, v181
	v_cvt_pk_bf16_f32 v163, v182, v183
	s_mov_b32 s6, 0x42000
	s_nop 1
	v_add_co_u32_e32 v146, vcc, s6, v150
	s_nop 0
	v_addc_co_u32_e32 v147, vcc, 0, v151, vcc
	global_store_dwordx4 v[146:147], v[160:163], off
	v_mov_b32_e32 v146, v210
	v_mov_b32_e32 v147, v211
	s_mov_b32 s6, 0xb0000
	s_waitcnt lgkmcnt(0)
	v_mul_f32_e32 v184, 0xbfb8aa3b, v146
	v_mul_f32_e32 v206, v146, v146
	v_pk_mul_f32 v[168:169], v[60:61], v[184:185] op_sel_hi:[1,0]
	v_pk_mul_f32 v[170:171], v[62:63], v[184:185] op_sel_hi:[1,0]
	v_pk_mul_f32 v[172:173], v[56:57], v[184:185] op_sel_hi:[1,0]
	v_pk_mul_f32 v[174:175], v[58:59], v[184:185] op_sel_hi:[1,0]
	v_exp_f32_e32 v168, v168
	v_exp_f32_e32 v169, v169
	v_exp_f32_e32 v170, v170
	v_exp_f32_e32 v171, v171
	v_exp_f32_e32 v172, v172
	v_exp_f32_e32 v173, v173
	v_exp_f32_e32 v174, v174
	v_exp_f32_e32 v175, v175
	v_pk_mul_f32 v[176:177], v[60:61], v[28:29]
	v_pk_mul_f32 v[178:179], v[62:63], v[30:31]
	v_pk_mul_f32 v[180:181], v[56:57], v[24:25]
	v_pk_mul_f32 v[182:183], v[58:59], v[26:27]
	v_pk_add_f32 v[168:169], v[168:169], 1.0 op_sel_hi:[1,0]
	v_pk_add_f32 v[170:171], v[170:171], 1.0 op_sel_hi:[1,0]
	v_pk_add_f32 v[172:173], v[172:173], 1.0 op_sel_hi:[1,0]
	v_pk_add_f32 v[174:175], v[174:175], 1.0 op_sel_hi:[1,0]
	v_rcp_f32_e32 v168, v168
	v_rcp_f32_e32 v169, v169
	v_rcp_f32_e32 v170, v170
	v_rcp_f32_e32 v171, v171
	v_rcp_f32_e32 v172, v172
	v_rcp_f32_e32 v173, v173
	v_rcp_f32_e32 v174, v174
	v_rcp_f32_e32 v175, v175
	v_pk_mul_f32 v[176:177], v[176:177], v[206:207] op_sel_hi:[1,0]
	v_pk_mul_f32 v[178:179], v[178:179], v[206:207] op_sel_hi:[1,0]
	v_pk_mul_f32 v[180:181], v[180:181], v[206:207] op_sel_hi:[1,0]
	v_pk_mul_f32 v[182:183], v[182:183], v[206:207] op_sel_hi:[1,0]
	v_pk_mul_f32 v[176:177], v[176:177], v[168:169]
	v_pk_mul_f32 v[178:179], v[178:179], v[170:171]
	v_pk_mul_f32 v[180:181], v[180:181], v[172:173]
	v_pk_mul_f32 v[182:183], v[182:183], v[174:175]
	v_cvt_pk_bf16_f32 v160, v176, v177
	v_cvt_pk_bf16_f32 v161, v178, v179
	v_cvt_pk_bf16_f32 v162, v180, v181
	v_cvt_pk_bf16_f32 v163, v182, v183
	s_nop 1
	v_mov_b32_e32 v146, v147
	v_add_co_u32_e32 v148, vcc, s6, v150
	v_addc_co_u32_e32 v149, vcc, 0, v151, vcc
	global_store_dwordx4 v[148:149], v[160:163], off
	v_mul_f32_e32 v184, 0xbfb8aa3b, v146
	v_mul_f32_e32 v206, v146, v146
	v_pk_mul_f32 v[168:169], v[52:53], v[184:185] op_sel_hi:[1,0]
	v_pk_mul_f32 v[170:171], v[54:55], v[184:185] op_sel_hi:[1,0]
	v_pk_mul_f32 v[172:173], v[48:49], v[184:185] op_sel_hi:[1,0]
	v_pk_mul_f32 v[174:175], v[50:51], v[184:185] op_sel_hi:[1,0]
	v_exp_f32_e32 v168, v168
	v_exp_f32_e32 v169, v169
	v_exp_f32_e32 v170, v170
	v_exp_f32_e32 v171, v171
	v_exp_f32_e32 v172, v172
	v_exp_f32_e32 v173, v173
	v_exp_f32_e32 v174, v174
	v_exp_f32_e32 v175, v175
	v_pk_mul_f32 v[176:177], v[52:53], v[20:21]
	v_pk_mul_f32 v[178:179], v[54:55], v[22:23]
	v_pk_mul_f32 v[180:181], v[48:49], v[16:17]
	v_pk_mul_f32 v[182:183], v[50:51], v[18:19]
	v_pk_add_f32 v[168:169], v[168:169], 1.0 op_sel_hi:[1,0]
	v_pk_add_f32 v[170:171], v[170:171], 1.0 op_sel_hi:[1,0]
	v_pk_add_f32 v[172:173], v[172:173], 1.0 op_sel_hi:[1,0]
	v_pk_add_f32 v[174:175], v[174:175], 1.0 op_sel_hi:[1,0]
	v_rcp_f32_e32 v168, v168
	v_rcp_f32_e32 v169, v169
	v_rcp_f32_e32 v170, v170
	v_rcp_f32_e32 v171, v171
	v_rcp_f32_e32 v172, v172
	v_rcp_f32_e32 v173, v173
	v_rcp_f32_e32 v174, v174
	v_rcp_f32_e32 v175, v175
	v_pk_mul_f32 v[176:177], v[176:177], v[206:207] op_sel_hi:[1,0]
	v_pk_mul_f32 v[178:179], v[178:179], v[206:207] op_sel_hi:[1,0]
	v_pk_mul_f32 v[180:181], v[180:181], v[206:207] op_sel_hi:[1,0]
	v_pk_mul_f32 v[182:183], v[182:183], v[206:207] op_sel_hi:[1,0]
	v_pk_mul_f32 v[176:177], v[176:177], v[168:169]
	v_pk_mul_f32 v[178:179], v[178:179], v[170:171]
	v_pk_mul_f32 v[180:181], v[180:181], v[172:173]
	v_pk_mul_f32 v[182:183], v[182:183], v[174:175]
	v_cvt_pk_bf16_f32 v160, v176, v177
	v_cvt_pk_bf16_f32 v161, v178, v179
	v_cvt_pk_bf16_f32 v162, v180, v181
	v_cvt_pk_bf16_f32 v163, v182, v183
	s_mov_b32 s6, 0xc6000
	s_nop 1
	v_add_co_u32_e32 v146, vcc, s6, v150
	s_nop 0
	v_addc_co_u32_e32 v147, vcc, 0, v151, vcc
	global_store_dwordx4 v[146:147], v[160:163], off
	v_mov_b32_e32 v146, v212
	v_mov_b32_e32 v147, v213
	s_mov_b32 s6, 0xdc000
	s_waitcnt lgkmcnt(0)
	v_mul_f32_e32 v184, 0xbfb8aa3b, v146
	v_mul_f32_e32 v206, v146, v146
	v_pk_mul_f32 v[168:169], v[44:45], v[184:185] op_sel_hi:[1,0]
	v_pk_mul_f32 v[170:171], v[46:47], v[184:185] op_sel_hi:[1,0]
	v_pk_mul_f32 v[172:173], v[40:41], v[184:185] op_sel_hi:[1,0]
	v_pk_mul_f32 v[174:175], v[42:43], v[184:185] op_sel_hi:[1,0]
	v_exp_f32_e32 v168, v168
	v_exp_f32_e32 v169, v169
	v_exp_f32_e32 v170, v170
	v_exp_f32_e32 v171, v171
	v_exp_f32_e32 v172, v172
	v_exp_f32_e32 v173, v173
	v_exp_f32_e32 v174, v174
	v_exp_f32_e32 v175, v175
	v_pk_mul_f32 v[176:177], v[44:45], v[12:13]
	v_pk_mul_f32 v[178:179], v[46:47], v[14:15]
	v_pk_mul_f32 v[180:181], v[40:41], v[8:9]
	v_pk_mul_f32 v[182:183], v[42:43], v[10:11]
	v_pk_add_f32 v[168:169], v[168:169], 1.0 op_sel_hi:[1,0]
	v_pk_add_f32 v[170:171], v[170:171], 1.0 op_sel_hi:[1,0]
	v_pk_add_f32 v[172:173], v[172:173], 1.0 op_sel_hi:[1,0]
	v_pk_add_f32 v[174:175], v[174:175], 1.0 op_sel_hi:[1,0]
	v_rcp_f32_e32 v168, v168
	v_rcp_f32_e32 v169, v169
	v_rcp_f32_e32 v170, v170
	v_rcp_f32_e32 v171, v171
	v_rcp_f32_e32 v172, v172
	v_rcp_f32_e32 v173, v173
	v_rcp_f32_e32 v174, v174
	v_rcp_f32_e32 v175, v175
	v_pk_mul_f32 v[176:177], v[176:177], v[206:207] op_sel_hi:[1,0]
	v_pk_mul_f32 v[178:179], v[178:179], v[206:207] op_sel_hi:[1,0]
	v_pk_mul_f32 v[180:181], v[180:181], v[206:207] op_sel_hi:[1,0]
	v_pk_mul_f32 v[182:183], v[182:183], v[206:207] op_sel_hi:[1,0]
	v_pk_mul_f32 v[176:177], v[176:177], v[168:169]
	v_pk_mul_f32 v[178:179], v[178:179], v[170:171]
	v_pk_mul_f32 v[180:181], v[180:181], v[172:173]
	v_pk_mul_f32 v[182:183], v[182:183], v[174:175]
	v_cvt_pk_bf16_f32 v158, v176, v177
	v_cvt_pk_bf16_f32 v159, v178, v179
	v_cvt_pk_bf16_f32 v160, v180, v181
	v_cvt_pk_bf16_f32 v161, v182, v183
	s_nop 1
	v_mov_b32_e32 v146, v147
	v_add_co_u32_e32 v148, vcc, s6, v150
	v_addc_co_u32_e32 v149, vcc, 0, v151, vcc
	global_store_dwordx4 v[148:149], v[158:161], off
	v_mul_f32_e32 v184, 0xbfb8aa3b, v146
	v_mul_f32_e32 v206, v146, v146
	v_pk_mul_f32 v[168:169], v[36:37], v[184:185] op_sel_hi:[1,0]
	v_pk_mul_f32 v[170:171], v[38:39], v[184:185] op_sel_hi:[1,0]
	v_pk_mul_f32 v[172:173], v[32:33], v[184:185] op_sel_hi:[1,0]
	v_pk_mul_f32 v[174:175], v[34:35], v[184:185] op_sel_hi:[1,0]
	v_exp_f32_e32 v168, v168
	v_exp_f32_e32 v169, v169
	v_exp_f32_e32 v170, v170
	v_exp_f32_e32 v171, v171
	v_exp_f32_e32 v172, v172
	v_exp_f32_e32 v173, v173
	v_exp_f32_e32 v174, v174
	v_exp_f32_e32 v175, v175
	v_pk_mul_f32 v[176:177], v[36:37], v[4:5]
	v_pk_mul_f32 v[178:179], v[38:39], v[6:7]
	v_pk_mul_f32 v[180:181], v[32:33], v[0:1]
	v_pk_mul_f32 v[182:183], v[34:35], v[2:3]
	v_pk_add_f32 v[168:169], v[168:169], 1.0 op_sel_hi:[1,0]
	v_pk_add_f32 v[170:171], v[170:171], 1.0 op_sel_hi:[1,0]
	v_pk_add_f32 v[172:173], v[172:173], 1.0 op_sel_hi:[1,0]
	v_pk_add_f32 v[174:175], v[174:175], 1.0 op_sel_hi:[1,0]
	v_rcp_f32_e32 v168, v168
	v_rcp_f32_e32 v169, v169
	v_rcp_f32_e32 v170, v170
	v_rcp_f32_e32 v171, v171
	v_rcp_f32_e32 v172, v172
	v_rcp_f32_e32 v173, v173
	v_rcp_f32_e32 v174, v174
	v_rcp_f32_e32 v175, v175
	v_pk_mul_f32 v[176:177], v[176:177], v[206:207] op_sel_hi:[1,0]
	v_pk_mul_f32 v[178:179], v[178:179], v[206:207] op_sel_hi:[1,0]
	v_pk_mul_f32 v[180:181], v[180:181], v[206:207] op_sel_hi:[1,0]
	v_pk_mul_f32 v[182:183], v[182:183], v[206:207] op_sel_hi:[1,0]
	v_pk_mul_f32 v[176:177], v[176:177], v[168:169]
	v_pk_mul_f32 v[178:179], v[178:179], v[170:171]
	v_pk_mul_f32 v[180:181], v[180:181], v[172:173]
	v_pk_mul_f32 v[182:183], v[182:183], v[174:175]
	v_cvt_pk_bf16_f32 v158, v176, v177
	v_cvt_pk_bf16_f32 v159, v178, v179
	v_cvt_pk_bf16_f32 v160, v180, v181
	v_cvt_pk_bf16_f32 v161, v182, v183
	s_nop 1
	v_add_co_u32_e32 v146, vcc, 0xf2000, v150
	s_nop 0
	v_addc_co_u32_e32 v147, vcc, 0, v151, vcc
	s_andn2_b64 vcc, exec, s[44:45]
	global_store_dwordx4 v[146:147], v[158:161], off
	s_cbranch_vccz .LBB0_382
	s_mov_b64 s[48:49], s[52:53]
	s_andn2_b64 vcc, exec, s[42:43]
	s_mov_b64 s[52:53], s[48:49]
	s_cbranch_vccnz .LBB0_383
